# GEMM K-loops: address and counter SALU plus hoisted LDS-DMA address prep moved from the tail of each MFMA segment to behind its closing barrier
# speedup vs baseline: 1.0140x; 1.0031x over previous
; #define WAIT_V(n) asm volatile("s_waitcnt vmcnt(" #n ")" ::: "memory")
; #define WAIT_L(n) asm volatile("s_waitcnt lgkmcnt(" #n ")" ::: "memory")
; #define BAR __builtin_amdgcn_s_barrier()
; #define SCHED __builtin_amdgcn_sched_barrier(0)
; template <class Get, class Epi>
; DI void gemm_stream(LAS unsigned char* lds, const int K, const int ld, Get get, Epi epi) {
;     ...
;             LDB(B0, 0, 0); SCHED; LDA(At, 0, 0); STAGE(SAo(1, 1), a1 + hstep);
;             WAIT_L(8); BAR; WAIT_L(0); MMA(0, 0, At, B0); BAR; SCHED;
;             LDB(B1, 0, 1); STAGE(SBo(0, 0), b2);
;             BAR; WAIT_L(0); MMA(0, 1, At, B1); BAR;
;             LDA(At, 0, 1); STAGE(SAo(0, 0), a2);
;             BAR; WAIT_L(0); MMA(1, 0, At, B0); BAR; SCHED;
;             STAGE(SBo(0, 1), b2 + hstep);
;             WAIT_V(6); BAR; MMA(1, 1, At, B1); BAR;
;             LDB(B0, 1, 0); SCHED; LDA(At, 1, 0); STAGE(SAo(0, 1), a2 + hstep);
;             WAIT_L(8); BAR; WAIT_L(0); MMA(0, 0, At, B0); BAR; SCHED;
;             LDB(B1, 1, 1); STAGE(SBo(1, 0), b3);
;             BAR; WAIT_L(0); MMA(0, 1, At, B1); BAR;
.LBB0_726:
	ds_read_b128 v[128:131], v167
	ds_read_b128 v[132:135], v167 offset:1024
	ds_read_b128 v[136:139], v167 offset:2048
	ds_read_b128 v[154:157], v167 offset:3072
	s_add_u32 s6, s4, 0xfff80080
	s_addc_u32 s7, s5, -1
	s_cmp_eq_u32 vcc_lo, 28
	s_cselect_b32 s63, s59, s7
	s_cselect_b32 s62, s58, s6
	s_cselect_b32 s7, s61, s55
	s_cselect_b32 s6, s60, s29
	v_lshl_add_u64 v[140:141], s[4:5], 0, v[148:149]
	s_add_i32 m0, s74, 0xc000
	ds_read_b128 v[158:161], v168
	ds_read_b128 v[162:165], v168 offset:1024
	ds_read_b128 v[170:173], v168 offset:2048
	ds_read_b128 v[174:177], v168 offset:3072
	ds_read_b128 v[178:181], v168 offset:4096
	ds_read_b128 v[182:185], v168 offset:5120
	ds_read_b128 v[186:189], v168 offset:6144
	ds_read_b128 v[190:193], v168 offset:7168
	global_load_lds_dwordx4 v[140:141], off
	v_lshl_add_u64 v[140:141], s[4:5], 0, v[150:151]
	s_add_i32 m0, s74, 0xe000
	s_nop 0
	global_load_lds_dwordx4 v[140:141], off
	s_waitcnt lgkmcnt(8)
	s_barrier
	s_waitcnt lgkmcnt(0)
	v_mfma_f32_16x16x32_bf16 v[124:127], v[128:131], v[158:161], v[124:127]
	v_mfma_f32_16x16x32_bf16 v[120:123], v[136:139], v[158:161], v[120:123]
	v_mfma_f32_16x16x32_bf16 v[112:115], v[128:131], v[170:173], v[112:115]
	v_mfma_f32_16x16x32_bf16 v[108:111], v[136:139], v[170:173], v[108:111]
	v_mfma_f32_16x16x32_bf16 v[100:103], v[128:131], v[178:181], v[100:103]
	v_mfma_f32_16x16x32_bf16 v[92:95], v[136:139], v[178:181], v[92:95]
	v_mfma_f32_16x16x32_bf16 v[84:87], v[128:131], v[186:189], v[84:87]
	v_mfma_f32_16x16x32_bf16 v[76:79], v[136:139], v[186:189], v[76:79]
	v_mfma_f32_16x16x32_bf16 v[124:127], v[132:135], v[162:165], v[124:127]
	v_mfma_f32_16x16x32_bf16 v[120:123], v[154:157], v[162:165], v[120:123]
	v_mfma_f32_16x16x32_bf16 v[112:115], v[132:135], v[174:177], v[112:115]
	v_mfma_f32_16x16x32_bf16 v[108:111], v[154:157], v[174:177], v[108:111]
	v_mfma_f32_16x16x32_bf16 v[100:103], v[132:135], v[182:185], v[100:103]
	v_mfma_f32_16x16x32_bf16 v[92:95], v[154:157], v[182:185], v[92:95]
	v_mfma_f32_16x16x32_bf16 v[84:87], v[132:135], v[190:193], v[84:87]
	v_mfma_f32_16x16x32_bf16 v[76:79], v[154:157], v[190:193], v[76:79]
	s_barrier
	s_add_i32 s86, s85, s35
	v_lshl_add_u64 v[140:141], s[6:7], 0, v[142:143]
	s_mov_b32 m0, s86
	ds_read_b128 v[194:197], v169
	ds_read_b128 v[198:201], v169 offset:1024
	ds_read_b128 v[202:205], v169 offset:2048
	ds_read_b128 v[208:211], v169 offset:3072
	global_load_lds_dwordx4 v[140:141], off
	v_lshl_add_u64 v[212:213], s[6:7], 0, v[144:145]
	s_add_i32 m0, s86, 0x2000
	s_nop 0
	global_load_lds_dwordx4 v[212:213], off
	s_barrier
	s_waitcnt lgkmcnt(0)
	v_mfma_f32_16x16x32_bf16 v[116:119], v[194:197], v[158:161], v[116:119]
	v_mfma_f32_16x16x32_bf16 v[104:107], v[202:205], v[158:161], v[104:107]
	v_mfma_f32_16x16x32_bf16 v[96:99], v[194:197], v[170:173], v[96:99]
	v_mfma_f32_16x16x32_bf16 v[88:91], v[202:205], v[170:173], v[88:91]
	v_mfma_f32_16x16x32_bf16 v[80:83], v[194:197], v[178:181], v[80:83]
	v_mfma_f32_16x16x32_bf16 v[72:75], v[202:205], v[178:181], v[72:75]
	v_mfma_f32_16x16x32_bf16 v[68:71], v[194:197], v[186:189], v[68:71]
	v_mfma_f32_16x16x32_bf16 v[64:67], v[202:205], v[186:189], v[64:67]
	v_mfma_f32_16x16x32_bf16 v[116:119], v[198:201], v[162:165], v[116:119]
	v_mfma_f32_16x16x32_bf16 v[104:107], v[208:211], v[162:165], v[104:107]
	v_mfma_f32_16x16x32_bf16 v[96:99], v[198:201], v[174:177], v[96:99]
	v_mfma_f32_16x16x32_bf16 v[88:91], v[208:211], v[174:177], v[88:91]
	v_mfma_f32_16x16x32_bf16 v[80:83], v[198:201], v[182:185], v[80:83]
	v_mfma_f32_16x16x32_bf16 v[72:75], v[208:211], v[182:185], v[72:75]
	v_mfma_f32_16x16x32_bf16 v[68:71], v[198:201], v[190:193], v[68:71]
	v_mfma_f32_16x16x32_bf16 v[64:67], v[208:211], v[190:193], v[64:67]
	s_barrier
	s_mov_b32 m0, s74
	v_lshl_add_u64 v[214:215], s[62:63], 0, v[142:143]
	ds_read_b128 v[158:161], v168 offset:16384
	ds_read_b128 v[162:165], v168 offset:17408
	ds_read_b128 v[170:173], v168 offset:18432
	ds_read_b128 v[174:177], v168 offset:19456
	ds_read_b128 v[178:181], v168 offset:20480
	ds_read_b128 v[182:185], v168 offset:21504
	ds_read_b128 v[186:189], v168 offset:22528
	ds_read_b128 v[190:193], v168 offset:23552
	global_load_lds_dwordx4 v[214:215], off
	v_lshl_add_u64 v[216:217], s[62:63], 0, v[144:145]
	s_mov_b32 m0, s75
	s_nop 0
	global_load_lds_dwordx4 v[216:217], off
	s_barrier
	s_waitcnt lgkmcnt(0)
	v_mfma_f32_16x16x32_bf16 v[60:63], v[128:131], v[158:161], v[60:63]
	v_mfma_f32_16x16x32_bf16 v[56:59], v[136:139], v[158:161], v[56:59]
	v_mfma_f32_16x16x32_bf16 v[52:55], v[128:131], v[170:173], v[52:55]
	v_mfma_f32_16x16x32_bf16 v[44:47], v[136:139], v[170:173], v[44:47]
	v_mfma_f32_16x16x32_bf16 v[36:39], v[128:131], v[178:181], v[36:39]
	v_mfma_f32_16x16x32_bf16 v[28:31], v[136:139], v[178:181], v[28:31]
	v_mfma_f32_16x16x32_bf16 v[20:23], v[128:131], v[186:189], v[20:23]
	v_mfma_f32_16x16x32_bf16 v[12:15], v[136:139], v[186:189], v[12:15]
	v_mfma_f32_16x16x32_bf16 v[60:63], v[132:135], v[162:165], v[60:63]
	v_mfma_f32_16x16x32_bf16 v[56:59], v[154:157], v[162:165], v[56:59]
	v_mfma_f32_16x16x32_bf16 v[52:55], v[132:135], v[174:177], v[52:55]
	v_mfma_f32_16x16x32_bf16 v[44:47], v[154:157], v[174:177], v[44:47]
	v_mfma_f32_16x16x32_bf16 v[36:39], v[132:135], v[182:185], v[36:39]
	v_mfma_f32_16x16x32_bf16 v[28:31], v[154:157], v[182:185], v[28:31]
	v_mfma_f32_16x16x32_bf16 v[20:23], v[132:135], v[190:193], v[20:23]
	v_mfma_f32_16x16x32_bf16 v[12:15], v[154:157], v[190:193], v[12:15]
	s_barrier
; #define WAIT_V(n) asm volatile("s_waitcnt vmcnt(" #n ")" ::: "memory")
; #define WAIT_L(n) asm volatile("s_waitcnt lgkmcnt(" #n ")" ::: "memory")
; #define BAR __builtin_amdgcn_s_barrier()
; #define SCHED __builtin_amdgcn_sched_barrier(0)
; template <class Get, class Epi>
; DI void gemm_stream(LAS unsigned char* lds, const int K, const int ld, Get get, Epi epi) {
;     ...
;             BAR; WAIT_L(0); MMA(1, 0, At, B0); BAR; SCHED;
;             STAGE(SBo(0, 1), b2 + hstep);
;             WAIT_V(6); BAR; MMA(1, 1, At, B1); BAR;
;             LDB(B0, 1, 0); SCHED; LDA(At, 1, 0); STAGE(SAo(0, 1), a2 + hstep);
;             WAIT_L(8); BAR; WAIT_L(0); MMA(0, 0, At, B0); BAR; SCHED;
;             LDB(B1, 1, 1); STAGE(SBo(1, 0), b3);
;             BAR; WAIT_L(0); MMA(0, 1, At, B1); BAR;
;             LDA(At, 1, 1); STAGE(SAo(1, 0), a3);
;             BAR; WAIT_L(0); MMA(1, 0, At, B0); BAR; SCHED;
;             STAGE(SBo(1, 1), b3 + hstep);
;             WAIT_V(6); BAR; MMA(1, 1, At, B1); BAR;
	s_add_u32 s86, s6, 0x80000
	s_addc_u32 s87, s7, 0
	s_add_i32 s88, s96, s35
	v_lshl_add_u64 v[128:129], s[86:87], 0, v[142:143]
	s_mov_b32 m0, s88
	s_nop 0
	global_load_lds_dwordx4 v[128:129], off
	v_lshl_add_u64 v[128:129], s[86:87], 0, v[144:145]
	s_add_i32 m0, s88, 0x2000
	s_nop 0
	global_load_lds_dwordx4 v[128:129], off
	s_waitcnt vmcnt(6)
	s_barrier
	v_mfma_f32_16x16x32_bf16 v[48:51], v[194:197], v[158:161], v[48:51]
	v_mfma_f32_16x16x32_bf16 v[40:43], v[202:205], v[158:161], v[40:43]
	v_mfma_f32_16x16x32_bf16 v[32:35], v[194:197], v[170:173], v[32:35]
	v_mfma_f32_16x16x32_bf16 v[24:27], v[202:205], v[170:173], v[24:27]
	v_mfma_f32_16x16x32_bf16 v[16:19], v[194:197], v[178:181], v[16:19]
	v_mfma_f32_16x16x32_bf16 v[8:11], v[202:205], v[178:181], v[8:11]
	v_mfma_f32_16x16x32_bf16 v[4:7], v[194:197], v[186:189], v[4:7]
	v_mfma_f32_16x16x32_bf16 v[0:3], v[202:205], v[186:189], v[0:3]
	v_mfma_f32_16x16x32_bf16 v[48:51], v[198:201], v[162:165], v[48:51]
	v_mfma_f32_16x16x32_bf16 v[40:43], v[208:211], v[162:165], v[40:43]
	v_mfma_f32_16x16x32_bf16 v[32:35], v[198:201], v[174:177], v[32:35]
	v_mfma_f32_16x16x32_bf16 v[24:27], v[208:211], v[174:177], v[24:27]
	v_mfma_f32_16x16x32_bf16 v[16:19], v[198:201], v[182:185], v[16:19]
	v_mfma_f32_16x16x32_bf16 v[8:11], v[208:211], v[182:185], v[8:11]
	v_mfma_f32_16x16x32_bf16 v[4:7], v[198:201], v[190:193], v[4:7]
	v_mfma_f32_16x16x32_bf16 v[0:3], v[208:211], v[190:193], v[0:3]
	s_add_i32 s86, 16, 0x18000
	v_add_u32_e32 v146, s86, v166
	s_barrier
	ds_read_b128 v[128:131], v146
	ds_read_b128 v[132:135], v146 offset:1024
	ds_read_b128 v[136:139], v146 offset:2048
	ds_read_b128 v[154:157], v146 offset:3072
	s_add_u32 s62, s62, 0x80000
	s_addc_u32 s63, s63, 0
	s_mov_b32 m0, s76
	v_lshl_add_u64 v[194:195], s[62:63], 0, v[142:143]
	ds_read_b128 v[158:161], v168 offset:32768
	ds_read_b128 v[162:165], v168 offset:33792
	ds_read_b128 v[170:173], v168 offset:34816
	ds_read_b128 v[174:177], v168 offset:35840
	ds_read_b128 v[178:181], v168 offset:36864
	ds_read_b128 v[182:185], v168 offset:37888
	ds_read_b128 v[186:189], v168 offset:38912
	ds_read_b128 v[190:193], v168 offset:39936
	global_load_lds_dwordx4 v[194:195], off
	v_lshl_add_u64 v[194:195], s[62:63], 0, v[144:145]
	s_mov_b32 m0, s77
	s_nop 0
	global_load_lds_dwordx4 v[194:195], off
	s_waitcnt lgkmcnt(8)
	s_barrier
	s_waitcnt lgkmcnt(0)
	v_mfma_f32_16x16x32_bf16 v[124:127], v[128:131], v[158:161], v[124:127]
	v_mfma_f32_16x16x32_bf16 v[120:123], v[136:139], v[158:161], v[120:123]
	v_mfma_f32_16x16x32_bf16 v[112:115], v[128:131], v[170:173], v[112:115]
	v_mfma_f32_16x16x32_bf16 v[108:111], v[136:139], v[170:173], v[108:111]
	v_mfma_f32_16x16x32_bf16 v[100:103], v[128:131], v[178:181], v[100:103]
	v_mfma_f32_16x16x32_bf16 v[92:95], v[136:139], v[178:181], v[92:95]
	v_mfma_f32_16x16x32_bf16 v[84:87], v[128:131], v[186:189], v[84:87]
	v_mfma_f32_16x16x32_bf16 v[76:79], v[136:139], v[186:189], v[76:79]
	v_mfma_f32_16x16x32_bf16 v[124:127], v[132:135], v[162:165], v[124:127]
	v_mfma_f32_16x16x32_bf16 v[120:123], v[154:157], v[162:165], v[120:123]
	v_mfma_f32_16x16x32_bf16 v[112:115], v[132:135], v[174:177], v[112:115]
	v_mfma_f32_16x16x32_bf16 v[108:111], v[154:157], v[174:177], v[108:111]
	v_mfma_f32_16x16x32_bf16 v[100:103], v[132:135], v[182:185], v[100:103]
	v_mfma_f32_16x16x32_bf16 v[92:95], v[154:157], v[182:185], v[92:95]
	v_mfma_f32_16x16x32_bf16 v[84:87], v[132:135], v[190:193], v[84:87]
	v_mfma_f32_16x16x32_bf16 v[76:79], v[154:157], v[190:193], v[76:79]
	s_barrier
	s_add_i32 s62, 16, 0x1c000
	s_add_i32 s63, s86, s35
	v_add_u32_e32 v146, s62, v166
	v_lshl_add_u64 v[140:141], v[140:141], 0, s[0:1]
	s_mov_b32 m0, s63
	ds_read_b128 v[194:197], v146
	ds_read_b128 v[198:201], v146 offset:1024
	ds_read_b128 v[202:205], v146 offset:2048
	ds_read_b128 v[208:211], v146 offset:3072
	global_load_lds_dwordx4 v[140:141], off
	v_lshl_add_u64 v[140:141], v[212:213], 0, s[0:1]
	s_add_i32 m0, s63, 0x2000
	s_nop 0
	global_load_lds_dwordx4 v[140:141], off
	s_barrier
	s_waitcnt lgkmcnt(0)
	v_mfma_f32_16x16x32_bf16 v[116:119], v[194:197], v[158:161], v[116:119]
	v_mfma_f32_16x16x32_bf16 v[104:107], v[202:205], v[158:161], v[104:107]
	v_mfma_f32_16x16x32_bf16 v[96:99], v[194:197], v[170:173], v[96:99]
	v_mfma_f32_16x16x32_bf16 v[88:91], v[202:205], v[170:173], v[88:91]
	v_mfma_f32_16x16x32_bf16 v[80:83], v[194:197], v[178:181], v[80:83]
	v_mfma_f32_16x16x32_bf16 v[72:75], v[202:205], v[178:181], v[72:75]
	v_mfma_f32_16x16x32_bf16 v[68:71], v[194:197], v[186:189], v[68:71]
	v_mfma_f32_16x16x32_bf16 v[64:67], v[202:205], v[186:189], v[64:67]
	v_mfma_f32_16x16x32_bf16 v[116:119], v[198:201], v[162:165], v[116:119]
	v_mfma_f32_16x16x32_bf16 v[104:107], v[208:211], v[162:165], v[104:107]
	v_mfma_f32_16x16x32_bf16 v[96:99], v[198:201], v[174:177], v[96:99]
	v_mfma_f32_16x16x32_bf16 v[88:91], v[208:211], v[174:177], v[88:91]
	v_mfma_f32_16x16x32_bf16 v[80:83], v[198:201], v[182:185], v[80:83]
	v_mfma_f32_16x16x32_bf16 v[72:75], v[208:211], v[182:185], v[72:75]
	v_mfma_f32_16x16x32_bf16 v[68:71], v[198:201], v[190:193], v[68:71]
	v_mfma_f32_16x16x32_bf16 v[64:67], v[208:211], v[190:193], v[64:67]
	s_barrier
; template <class Get, class Epi>
; DI void gemm_stream(LAS unsigned char* lds, const int K, const int ld, Get get, Epi epi) {
;     ...
;             LDB(B0, 1, 0); SCHED; LDA(At, 1, 0); STAGE(SAo(0, 1), a2 + hstep);
;             WAIT_L(8); BAR; WAIT_L(0); MMA(0, 0, At, B0); BAR; SCHED;
;             LDB(B1, 1, 1); STAGE(SBo(1, 0), b3);
;             BAR; WAIT_L(0); MMA(0, 1, At, B1); BAR;
;             LDA(At, 1, 1); STAGE(SAo(1, 0), a3);
;             BAR; WAIT_L(0); MMA(1, 0, At, B0); BAR; SCHED;
;             STAGE(SBo(1, 1), b3 + hstep);
;             WAIT_V(6); BAR; MMA(1, 1, At, B1); BAR;
; template <int R>
; DI void epi_rope(const Acc& acc, const P& p, int brow, bf16_t* __restrict__ dst, int ld, int coff, int bstride, const float* rs, int nblk_valid) {
;     EPI_IDX
;     const float* __restrict__ cosT = (const float*)(p.ws + (R == 128 ? O_COSA : O_COSB));
;     const float* __restrict__ sinT = (const float*)(p.ws + (R == 128 ? O_SINA : O_SINB));
;     const int b = brow / PB, p0 = brow - b * PB;
;     const bool ctx = p0 < CTXL;
; #pragma unroll
;     for (int ai = 0; ai < 2; ++ai)
; #pragma unroll
;         for (int m = 0; m < 4; ++m) {
;             const int lr = ai * 128 + wr * 64 + m * 16 + fr;
;             const float s = rs ? rs[lr] : 1.f;
;             const int sq = p0 + lr - CTXL;
; #pragma unroll
;             for (int bj = 0; bj < 2; ++bj) {
;                 const int blk = R == 128 ? bj : bj * 2 + (wc >> 1);
;                 const int d0 = (R == 128 ? wc * 16 : (wc & 1) * 16) + fq * 4;
;                 if (blk < nblk_valid) {
;                     f32x4 cv = {1.f, 1.f, 1.f, 1.f}, sv = {0.f, 0.f, 0.f, 0.f};
; DI void phase_inproj0(const P& p, char* shm) {
;     ...
;     auto epi = [&](const Acc& acc, const Unit& u) {
;         const int brow = u.pm * 256, pn = u.pn;
;         if (pn == 5) epi_T<64>(acc, 0, brow, (bf16_t*)(p.ws + O_VAT), 256, nullptr);
;         else if (pn < 4) epi_rope<128>(acc, p, brow, (bf16_t*)(p.ws + O_QA), 1024, pn * 256, 128, nullptr, 2);
;         else if (pn == 4) epi_rope<128>(acc, p, brow, (bf16_t*)(p.ws + O_KA), 256, 0, 128, nullptr, 2);
;         else if (pn < 8) epi_plain(acc, brow, (bf16_t*)(p.ws + O_QLAT), 512, (pn - 6) * 256, nullptr);
;         else if (pn == 8) epi_plain(acc, brow, (bf16_t*)(p.ws + O_KVLAT), 256, 0, nullptr);
;         else epi_rope<64>(acc, p, brow, (bf16_t*)(p.ws + O_KR), 64, 0, 64, nullptr, 1);
	s_mov_b32 m0, s80
	v_lshl_add_u64 v[140:141], v[214:215], 0, s[0:1]
	ds_read_b128 v[158:161], v168 offset:49152
	ds_read_b128 v[162:165], v168 offset:50176
	ds_read_b128 v[170:173], v168 offset:51200
	ds_read_b128 v[174:177], v168 offset:52224
	ds_read_b128 v[178:181], v168 offset:53248
	ds_read_b128 v[182:185], v168 offset:54272
	ds_read_b128 v[186:189], v168 offset:55296
	ds_read_b128 v[190:193], v168 offset:56320
	global_load_lds_dwordx4 v[140:141], off
	v_lshl_add_u64 v[140:141], v[216:217], 0, s[0:1]
	s_mov_b32 m0, s81
	s_nop 0
	global_load_lds_dwordx4 v[140:141], off
	s_barrier
	s_waitcnt lgkmcnt(0)
	v_mfma_f32_16x16x32_bf16 v[60:63], v[128:131], v[158:161], v[60:63]
	v_mfma_f32_16x16x32_bf16 v[56:59], v[136:139], v[158:161], v[56:59]
	v_mfma_f32_16x16x32_bf16 v[52:55], v[128:131], v[170:173], v[52:55]
	v_mfma_f32_16x16x32_bf16 v[44:47], v[136:139], v[170:173], v[44:47]
	v_mfma_f32_16x16x32_bf16 v[36:39], v[128:131], v[178:181], v[36:39]
	v_mfma_f32_16x16x32_bf16 v[28:31], v[136:139], v[178:181], v[28:31]
	v_mfma_f32_16x16x32_bf16 v[20:23], v[128:131], v[186:189], v[20:23]
	v_mfma_f32_16x16x32_bf16 v[12:15], v[136:139], v[186:189], v[12:15]
	v_mfma_f32_16x16x32_bf16 v[60:63], v[132:135], v[162:165], v[60:63]
	v_mfma_f32_16x16x32_bf16 v[56:59], v[154:157], v[162:165], v[56:59]
	v_mfma_f32_16x16x32_bf16 v[52:55], v[132:135], v[174:177], v[52:55]
	v_mfma_f32_16x16x32_bf16 v[44:47], v[154:157], v[174:177], v[44:47]
	v_mfma_f32_16x16x32_bf16 v[36:39], v[132:135], v[182:185], v[36:39]
	v_mfma_f32_16x16x32_bf16 v[28:31], v[154:157], v[182:185], v[28:31]
	v_mfma_f32_16x16x32_bf16 v[20:23], v[132:135], v[190:193], v[20:23]
	v_mfma_f32_16x16x32_bf16 v[12:15], v[154:157], v[190:193], v[12:15]
	s_barrier
	s_add_u32 s6, s6, 0x80080
	s_addc_u32 s7, s7, 0
	s_add_i32 s62, s62, s35
	v_lshl_add_u64 v[128:129], s[6:7], 0, v[142:143]
	s_mov_b32 m0, s62
	s_nop 0
	global_load_lds_dwordx4 v[128:129], off
	v_lshl_add_u64 v[128:129], s[6:7], 0, v[144:145]
	s_add_i32 m0, s62, 0x2000
	s_nop 0
	global_load_lds_dwordx4 v[128:129], off
	s_waitcnt vmcnt(6)
	s_barrier
	v_mfma_f32_16x16x32_bf16 v[48:51], v[194:197], v[158:161], v[48:51]
	v_mfma_f32_16x16x32_bf16 v[40:43], v[202:205], v[158:161], v[40:43]
	v_mfma_f32_16x16x32_bf16 v[32:35], v[194:197], v[170:173], v[32:35]
	v_mfma_f32_16x16x32_bf16 v[24:27], v[202:205], v[170:173], v[24:27]
	v_mfma_f32_16x16x32_bf16 v[16:19], v[194:197], v[178:181], v[16:19]
	v_mfma_f32_16x16x32_bf16 v[8:11], v[202:205], v[178:181], v[8:11]
	v_mfma_f32_16x16x32_bf16 v[4:7], v[194:197], v[186:189], v[4:7]
	v_mfma_f32_16x16x32_bf16 v[0:3], v[202:205], v[186:189], v[0:3]
	v_mfma_f32_16x16x32_bf16 v[48:51], v[198:201], v[162:165], v[48:51]
	v_mfma_f32_16x16x32_bf16 v[40:43], v[208:211], v[162:165], v[40:43]
	v_mfma_f32_16x16x32_bf16 v[32:35], v[198:201], v[174:177], v[32:35]
	v_mfma_f32_16x16x32_bf16 v[24:27], v[208:211], v[174:177], v[24:27]
	v_mfma_f32_16x16x32_bf16 v[16:19], v[198:201], v[182:185], v[16:19]
	v_mfma_f32_16x16x32_bf16 v[8:11], v[208:211], v[182:185], v[8:11]
	v_mfma_f32_16x16x32_bf16 v[4:7], v[198:201], v[190:193], v[4:7]
	v_mfma_f32_16x16x32_bf16 v[0:3], v[208:211], v[190:193], v[0:3]
	s_barrier
	s_add_i32 vcc_lo, vcc_lo, 2
	s_add_u32 s4, s4, 0x100
	s_addc_u32 s5, s5, 0
	s_add_u32 s29, s29, 0x100
	s_addc_u32 s55, s55, 0
	s_cmp_gt_u32 vcc_lo, 29
	s_cbranch_scc0 .LBB0_726
	s_lshl_b32 s29, s21, 8
	s_cmp_lg_u32 s28, 5
	s_mov_b64 s[4:5], -1
	s_cbranch_scc0 .LBB0_849
	s_cmp_gt_i32 s28, 3
	s_cbranch_scc0 .LBB0_814
	s_cmp_lg_u32 s28, 4
	s_cbranch_scc0 .LBB0_779
	s_cmp_gt_u32 s28, 7
	s_cbranch_scc0 .LBB0_776
	s_cmp_lg_u32 s28, 8
	s_cbranch_scc0 .LBB0_773
	s_mul_hi_i32 s4, s29, 0x78787879
	s_lshr_b32 s5, s4, 31
	s_ashr_i32 s4, s4, 11
	v_mov_b32_e32 v128, v206
	s_add_i32 s4, s4, s5
	s_mulk_i32 s4, 0x1100
	v_and_b32_e32 v129, 15, v128
	v_ashrrev_i32_e32 v130, 2, v128
	s_sub_i32 s55, s29, s4
	v_and_or_b32 v154, v130, s97, v129
	v_lshrrev_b32_e32 v129, 2, v128
	s_cmpk_gt_i32 s55, 0xff
	v_and_b32_e32 v129, 28, v129
	s_cselect_b64 s[4:5], -1, 0
	v_lshlrev_b32_e32 v146, 2, v129
	v_and_b32_e32 v128, 0x80, v128
	v_lshl_add_u64 v[138:139], s[14:15], 0, v[146:147]
	v_lshl_add_u64 v[140:141], s[12:13], 0, v[146:147]
	v_lshlrev_b32_e32 v146, 1, v129
	v_cmp_eq_u32_e64 s[6:7], 0, v128
	v_cndmask_b32_e64 v128, 0, 1, s[4:5]
	s_addk_i32 s55, 0xff00
	v_lshl_add_u64 v[136:137], s[10:11], 0, v[146:147]
	v_cmp_ne_u32_e64 s[4:5], 1, v128
	s_and_saveexec_b64 s[62:63], s[6:7]
	s_cbranch_execz .LBB0_737
	s_and_b64 vcc, exec, s[4:5]
	s_cbranch_vccnz .LBB0_735
	v_add_u32_e32 v128, s55, v154
	v_ashrrev_i32_e32 v129, 31, v128
	v_lshlrev_b64 v[128:129], 7, v[128:129]
	v_lshl_add_u64 v[132:133], v[138:139], 0, v[128:129]
	v_lshl_add_u64 v[128:129], v[140:141], 0, v[128:129]
	global_load_dwordx4 v[128:131], v[128:129], off
	s_nop 0
	global_load_dwordx4 v[132:135], v[132:133], off
	s_branch .LBB0_736

; #define WAIT_V(n) asm volatile("s_waitcnt vmcnt(" #n ")" ::: "memory")
; #define WAIT_L(n) asm volatile("s_waitcnt lgkmcnt(" #n ")" ::: "memory")
; #define BAR __builtin_amdgcn_s_barrier()
; #define SCHED __builtin_amdgcn_sched_barrier(0)
; DI void gemm_tile(const bf16_t* __restrict__ A, const bf16_t* __restrict__ Bt, const int K, const int brow, const int bcol, LAS unsigned char* lds, Acc& acc) {
;     ...
;         LDB(B0, 0, 0); SCHED; LDA(At, 0, 0); STAGE(SAo(1, 1), a1 + hstep);
;         WAIT_L(8); BAR; WAIT_L(0); MMA(0, 0, At, B0); BAR; SCHED;
;         LDB(B1, 0, 1); STAGE(SBo(0, 0), b2);
;         BAR; WAIT_L(0); MMA(0, 1, At, B1); BAR;
;         LDA(At, 0, 1); STAGE(SAo(0, 0), a2);
;         BAR; WAIT_L(0); MMA(1, 0, At, B0); BAR; SCHED;
;         STAGE(SBo(0, 1), b2 + hstep);
;         WAIT_V(6); BAR; MMA(1, 1, At, B1); BAR;
.LBB0_930:
	s_add_i32 s6, 16, 0x10000
	v_add_u32_e32 v154, s6, v149
	ds_read_b128 v[150:153], v154
	ds_read_b128 v[160:163], v154 offset:1024
	ds_read_b128 v[164:167], v154 offset:2048
	ds_read_b128 v[168:171], v154 offset:3072
	s_add_i32 s62, s62, 2
	v_lshl_add_u64 v[154:155], v[134:135], 0, s[60:61]
	s_add_i32 s81, s86, 0xc000
	v_lshl_add_u64 v[204:205], v[154:155], 0, s[36:37]
	s_mov_b32 m0, s81
	ds_read_b128 v[172:175], v148
	ds_read_b128 v[176:179], v148 offset:1024
	ds_read_b128 v[180:183], v148 offset:2048
	ds_read_b128 v[184:187], v148 offset:3072
	ds_read_b128 v[188:191], v148 offset:4096
	ds_read_b128 v[192:195], v148 offset:5120
	ds_read_b128 v[196:199], v148 offset:6144
	ds_read_b128 v[200:203], v148 offset:7168
	global_load_lds_dwordx4 v[204:205], off
	v_lshl_add_u64 v[204:205], v[136:137], 0, s[60:61]
	s_add_i32 s63, s86, 0xe000
	v_lshl_add_u64 v[208:209], v[204:205], 0, s[36:37]
	s_mov_b32 m0, s63
	s_nop 0
	global_load_lds_dwordx4 v[208:209], off
	s_waitcnt lgkmcnt(8)
	s_barrier
	s_waitcnt lgkmcnt(0)
	v_mfma_f32_16x16x32_bf16 v[124:127], v[150:153], v[172:175], v[124:127]
	v_mfma_f32_16x16x32_bf16 v[120:123], v[164:167], v[172:175], v[120:123]
	v_mfma_f32_16x16x32_bf16 v[116:119], v[150:153], v[180:183], v[116:119]
	v_mfma_f32_16x16x32_bf16 v[112:115], v[164:167], v[180:183], v[112:115]
	v_mfma_f32_16x16x32_bf16 v[108:111], v[150:153], v[188:191], v[108:111]
	v_mfma_f32_16x16x32_bf16 v[104:107], v[164:167], v[188:191], v[104:107]
	v_mfma_f32_16x16x32_bf16 v[100:103], v[150:153], v[196:199], v[100:103]
	v_mfma_f32_16x16x32_bf16 v[96:99], v[164:167], v[196:199], v[96:99]
	v_mfma_f32_16x16x32_bf16 v[124:127], v[160:163], v[176:179], v[124:127]
	v_mfma_f32_16x16x32_bf16 v[120:123], v[168:171], v[176:179], v[120:123]
	v_mfma_f32_16x16x32_bf16 v[116:119], v[160:163], v[184:187], v[116:119]
	v_mfma_f32_16x16x32_bf16 v[112:115], v[168:171], v[184:187], v[112:115]
	v_mfma_f32_16x16x32_bf16 v[108:111], v[160:163], v[192:195], v[108:111]
	v_mfma_f32_16x16x32_bf16 v[104:107], v[168:171], v[192:195], v[104:107]
	v_mfma_f32_16x16x32_bf16 v[100:103], v[160:163], v[200:203], v[100:103]
	v_mfma_f32_16x16x32_bf16 v[96:99], v[168:171], v[200:203], v[96:99]
	s_barrier
	s_add_i32 s7, 16, 0x14000
	v_lshl_add_u64 v[224:225], v[138:139], 0, s[60:61]
	s_add_i32 s6, s6, s18
	v_add_u32_e32 v159, s7, v149
	v_lshl_add_u64 v[226:227], v[224:225], 0, s[38:39]
	s_mov_b32 m0, s6
	ds_read_b128 v[208:211], v159
	ds_read_b128 v[212:215], v159 offset:1024
	ds_read_b128 v[216:219], v159 offset:2048
	ds_read_b128 v[220:223], v159 offset:3072
	global_load_lds_dwordx4 v[226:227], off
	v_lshl_add_u64 v[226:227], v[140:141], 0, s[60:61]
	v_lshl_add_u64 v[228:229], v[226:227], 0, s[38:39]
	s_add_i32 m0, s6, 0x2000
	s_nop 0
	global_load_lds_dwordx4 v[228:229], off
	s_barrier
	s_waitcnt lgkmcnt(0)
	v_mfma_f32_16x16x32_bf16 v[92:95], v[208:211], v[172:175], v[92:95]
	v_mfma_f32_16x16x32_bf16 v[88:91], v[216:219], v[172:175], v[88:91]
	v_mfma_f32_16x16x32_bf16 v[84:87], v[208:211], v[180:183], v[84:87]
	v_mfma_f32_16x16x32_bf16 v[80:83], v[216:219], v[180:183], v[80:83]
	v_mfma_f32_16x16x32_bf16 v[76:79], v[208:211], v[188:191], v[76:79]
	v_mfma_f32_16x16x32_bf16 v[72:75], v[216:219], v[188:191], v[72:75]
	v_mfma_f32_16x16x32_bf16 v[68:71], v[208:211], v[196:199], v[68:71]
	v_mfma_f32_16x16x32_bf16 v[64:67], v[216:219], v[196:199], v[64:67]
	v_mfma_f32_16x16x32_bf16 v[92:95], v[212:215], v[176:179], v[92:95]
	v_mfma_f32_16x16x32_bf16 v[88:91], v[220:223], v[176:179], v[88:91]
	v_mfma_f32_16x16x32_bf16 v[84:87], v[212:215], v[184:187], v[84:87]
	v_mfma_f32_16x16x32_bf16 v[80:83], v[220:223], v[184:187], v[80:83]
	v_mfma_f32_16x16x32_bf16 v[76:79], v[212:215], v[192:195], v[76:79]
	v_mfma_f32_16x16x32_bf16 v[72:75], v[220:223], v[192:195], v[72:75]
	v_mfma_f32_16x16x32_bf16 v[68:71], v[212:215], v[200:203], v[68:71]
	v_mfma_f32_16x16x32_bf16 v[64:67], v[220:223], v[200:203], v[64:67]
	s_barrier
	v_lshl_add_u64 v[228:229], v[130:131], 0, s[60:61]
	s_mov_b32 m0, s86
	v_lshl_add_u64 v[230:231], v[228:229], 0, s[38:39]
	ds_read_b128 v[172:175], v148 offset:16384
	ds_read_b128 v[176:179], v148 offset:17408
	ds_read_b128 v[180:183], v148 offset:18432
	ds_read_b128 v[184:187], v148 offset:19456
	ds_read_b128 v[188:191], v148 offset:20480
	ds_read_b128 v[192:195], v148 offset:21504
	ds_read_b128 v[196:199], v148 offset:22528
	ds_read_b128 v[200:203], v148 offset:23552
	global_load_lds_dwordx4 v[230:231], off
	v_lshl_add_u64 v[230:231], v[132:133], 0, s[60:61]
	v_lshl_add_u64 v[232:233], v[230:231], 0, s[38:39]
	s_mov_b32 m0, s82
	s_nop 0
	global_load_lds_dwordx4 v[232:233], off
	s_barrier
	s_waitcnt lgkmcnt(0)
	v_mfma_f32_16x16x32_bf16 v[60:63], v[150:153], v[172:175], v[60:63]
	v_mfma_f32_16x16x32_bf16 v[56:59], v[164:167], v[172:175], v[56:59]
	v_mfma_f32_16x16x32_bf16 v[52:55], v[150:153], v[180:183], v[52:55]
	v_mfma_f32_16x16x32_bf16 v[48:51], v[164:167], v[180:183], v[48:51]
	v_mfma_f32_16x16x32_bf16 v[44:47], v[150:153], v[188:191], v[44:47]
	v_mfma_f32_16x16x32_bf16 v[40:43], v[164:167], v[188:191], v[40:43]
	v_mfma_f32_16x16x32_bf16 v[36:39], v[150:153], v[196:199], v[36:39]
	v_mfma_f32_16x16x32_bf16 v[32:35], v[164:167], v[196:199], v[32:35]
	v_mfma_f32_16x16x32_bf16 v[60:63], v[160:163], v[176:179], v[60:63]
	v_mfma_f32_16x16x32_bf16 v[56:59], v[168:171], v[176:179], v[56:59]
	v_mfma_f32_16x16x32_bf16 v[52:55], v[160:163], v[184:187], v[52:55]
	v_mfma_f32_16x16x32_bf16 v[48:51], v[168:171], v[184:187], v[48:51]
	v_mfma_f32_16x16x32_bf16 v[44:47], v[160:163], v[192:195], v[44:47]
	v_mfma_f32_16x16x32_bf16 v[40:43], v[168:171], v[192:195], v[40:43]
	v_mfma_f32_16x16x32_bf16 v[36:39], v[160:163], v[200:203], v[36:39]
	v_mfma_f32_16x16x32_bf16 v[32:35], v[168:171], v[200:203], v[32:35]
	s_barrier
; #define WAIT_V(n) asm volatile("s_waitcnt vmcnt(" #n ")" ::: "memory")
; #define WAIT_L(n) asm volatile("s_waitcnt lgkmcnt(" #n ")" ::: "memory")
; #define BAR __builtin_amdgcn_s_barrier()
; #define SCHED __builtin_amdgcn_sched_barrier(0)
; DI void gemm_tile(const bf16_t* __restrict__ A, const bf16_t* __restrict__ Bt, const int K, const int brow, const int bcol, LAS unsigned char* lds, Acc& acc) {
;     ...
;         WAIT_V(6); BAR; MMA(1, 1, At, B1); BAR;
;         LDB(B0, 1, 0); SCHED; LDA(At, 1, 0); STAGE(SAo(0, 1), a2 + hstep);
;         WAIT_L(8); BAR; WAIT_L(0); MMA(0, 0, At, B0); BAR; SCHED;
;         LDB(B1, 1, 1); STAGE(SBo(1, 0), b3);
;         BAR; WAIT_L(0); MMA(0, 1, At, B1); BAR;
;         LDA(At, 1, 1); STAGE(SAo(1, 0), a3);
	v_lshl_add_u64 v[232:233], v[144:145], 0, s[60:61]
	s_add_i32 s6, s7, s18
	v_lshl_add_u64 v[150:151], v[232:233], 0, s[38:39]
	s_mov_b32 m0, s6
	v_lshl_add_u64 v[234:235], v[146:147], 0, s[60:61]
	global_load_lds_dwordx4 v[150:151], off
	v_lshl_add_u64 v[150:151], v[234:235], 0, s[38:39]
	s_add_i32 m0, s6, 0x2000
	s_nop 0
	global_load_lds_dwordx4 v[150:151], off
	s_waitcnt vmcnt(6)
	s_barrier
	v_mfma_f32_16x16x32_bf16 v[28:31], v[208:211], v[172:175], v[28:31]
	v_mfma_f32_16x16x32_bf16 v[24:27], v[216:219], v[172:175], v[24:27]
	v_mfma_f32_16x16x32_bf16 v[20:23], v[208:211], v[180:183], v[20:23]
	v_mfma_f32_16x16x32_bf16 v[16:19], v[216:219], v[180:183], v[16:19]
	v_mfma_f32_16x16x32_bf16 v[12:15], v[208:211], v[188:191], v[12:15]
	v_mfma_f32_16x16x32_bf16 v[8:11], v[216:219], v[188:191], v[8:11]
	v_mfma_f32_16x16x32_bf16 v[4:7], v[208:211], v[196:199], v[4:7]
	v_mfma_f32_16x16x32_bf16 v[0:3], v[216:219], v[196:199], v[0:3]
	v_mfma_f32_16x16x32_bf16 v[28:31], v[212:215], v[176:179], v[28:31]
	v_mfma_f32_16x16x32_bf16 v[24:27], v[220:223], v[176:179], v[24:27]
	v_mfma_f32_16x16x32_bf16 v[20:23], v[212:215], v[184:187], v[20:23]
	v_mfma_f32_16x16x32_bf16 v[16:19], v[220:223], v[184:187], v[16:19]
	v_mfma_f32_16x16x32_bf16 v[12:15], v[212:215], v[192:195], v[12:15]
	v_mfma_f32_16x16x32_bf16 v[8:11], v[220:223], v[192:195], v[8:11]
	v_mfma_f32_16x16x32_bf16 v[4:7], v[212:215], v[200:203], v[4:7]
	v_mfma_f32_16x16x32_bf16 v[0:3], v[220:223], v[200:203], v[0:3]
	s_add_i32 s6, 16, 0x18000
	v_add_u32_e32 v159, s6, v149
	s_barrier
	ds_read_b128 v[150:153], v159
	ds_read_b128 v[160:163], v159 offset:1024
	ds_read_b128 v[164:167], v159 offset:2048
	ds_read_b128 v[168:171], v159 offset:3072
	s_mov_b32 m0, s83
	v_lshl_add_u64 v[154:155], v[154:155], 0, s[38:39]
	ds_read_b128 v[172:175], v148 offset:32768
	ds_read_b128 v[176:179], v148 offset:33792
	ds_read_b128 v[180:183], v148 offset:34816
	ds_read_b128 v[184:187], v148 offset:35840
	ds_read_b128 v[188:191], v148 offset:36864
	ds_read_b128 v[192:195], v148 offset:37888
	ds_read_b128 v[196:199], v148 offset:38912
	ds_read_b128 v[200:203], v148 offset:39936
	global_load_lds_dwordx4 v[154:155], off
	v_lshl_add_u64 v[154:155], v[204:205], 0, s[38:39]
	s_mov_b32 m0, s85
	s_nop 0
	global_load_lds_dwordx4 v[154:155], off
	s_waitcnt lgkmcnt(8)
	s_barrier
	s_waitcnt lgkmcnt(0)
	v_mfma_f32_16x16x32_bf16 v[124:127], v[150:153], v[172:175], v[124:127]
	v_mfma_f32_16x16x32_bf16 v[120:123], v[164:167], v[172:175], v[120:123]
	v_mfma_f32_16x16x32_bf16 v[116:119], v[150:153], v[180:183], v[116:119]
	v_mfma_f32_16x16x32_bf16 v[112:115], v[164:167], v[180:183], v[112:115]
	v_mfma_f32_16x16x32_bf16 v[108:111], v[150:153], v[188:191], v[108:111]
	v_mfma_f32_16x16x32_bf16 v[104:107], v[164:167], v[188:191], v[104:107]
	v_mfma_f32_16x16x32_bf16 v[100:103], v[150:153], v[196:199], v[100:103]
	v_mfma_f32_16x16x32_bf16 v[96:99], v[164:167], v[196:199], v[96:99]
	v_mfma_f32_16x16x32_bf16 v[124:127], v[160:163], v[176:179], v[124:127]
	v_mfma_f32_16x16x32_bf16 v[120:123], v[168:171], v[176:179], v[120:123]
	v_mfma_f32_16x16x32_bf16 v[116:119], v[160:163], v[184:187], v[116:119]
	v_mfma_f32_16x16x32_bf16 v[112:115], v[168:171], v[184:187], v[112:115]
	v_mfma_f32_16x16x32_bf16 v[108:111], v[160:163], v[192:195], v[108:111]
	v_mfma_f32_16x16x32_bf16 v[104:107], v[168:171], v[192:195], v[104:107]
	v_mfma_f32_16x16x32_bf16 v[100:103], v[160:163], v[200:203], v[100:103]
	v_mfma_f32_16x16x32_bf16 v[96:99], v[168:171], v[200:203], v[96:99]
	s_barrier
	s_add_i32 s7, 16, 0x1c000
	v_add_u32_e32 v154, s7, v149
	s_add_i32 s6, s6, s18
	ds_read_b128 v[208:211], v154
	ds_read_b128 v[212:215], v154 offset:1024
	ds_read_b128 v[216:219], v154 offset:2048
	ds_read_b128 v[220:223], v154 offset:3072
	v_lshl_add_u64 v[154:155], v[224:225], 0, s[40:41]
	s_mov_b32 m0, s6
	s_nop 0
	global_load_lds_dwordx4 v[154:155], off
	v_lshl_add_u64 v[154:155], v[226:227], 0, s[40:41]
	s_add_i32 m0, s6, 0x2000
	s_nop 0
	global_load_lds_dwordx4 v[154:155], off
	s_barrier
	s_waitcnt lgkmcnt(0)
	v_mfma_f32_16x16x32_bf16 v[92:95], v[208:211], v[172:175], v[92:95]
	v_mfma_f32_16x16x32_bf16 v[88:91], v[216:219], v[172:175], v[88:91]
	v_mfma_f32_16x16x32_bf16 v[84:87], v[208:211], v[180:183], v[84:87]
	v_mfma_f32_16x16x32_bf16 v[80:83], v[216:219], v[180:183], v[80:83]
	v_mfma_f32_16x16x32_bf16 v[76:79], v[208:211], v[188:191], v[76:79]
	v_mfma_f32_16x16x32_bf16 v[72:75], v[216:219], v[188:191], v[72:75]
	v_mfma_f32_16x16x32_bf16 v[68:71], v[208:211], v[196:199], v[68:71]
	v_mfma_f32_16x16x32_bf16 v[64:67], v[216:219], v[196:199], v[64:67]
	v_mfma_f32_16x16x32_bf16 v[92:95], v[212:215], v[176:179], v[92:95]
	v_mfma_f32_16x16x32_bf16 v[88:91], v[220:223], v[176:179], v[88:91]
	v_mfma_f32_16x16x32_bf16 v[84:87], v[212:215], v[184:187], v[84:87]
	v_mfma_f32_16x16x32_bf16 v[80:83], v[220:223], v[184:187], v[80:83]
	v_mfma_f32_16x16x32_bf16 v[76:79], v[212:215], v[192:195], v[76:79]
	v_mfma_f32_16x16x32_bf16 v[72:75], v[220:223], v[192:195], v[72:75]
	v_mfma_f32_16x16x32_bf16 v[68:71], v[212:215], v[200:203], v[68:71]
	v_mfma_f32_16x16x32_bf16 v[64:67], v[220:223], v[200:203], v[64:67]
	s_barrier
	s_mov_b32 m0, s97
	v_lshl_add_u64 v[154:155], v[228:229], 0, s[40:41]
	ds_read_b128 v[172:175], v148 offset:49152
	ds_read_b128 v[176:179], v148 offset:50176
	ds_read_b128 v[180:183], v148 offset:51200
	ds_read_b128 v[184:187], v148 offset:52224
	ds_read_b128 v[188:191], v148 offset:53248
	ds_read_b128 v[192:195], v148 offset:54272
	ds_read_b128 v[196:199], v148 offset:55296
	ds_read_b128 v[200:203], v148 offset:56320
	global_load_lds_dwordx4 v[154:155], off
	v_lshl_add_u64 v[154:155], v[230:231], 0, s[40:41]
	s_mov_b32 m0, vcc_lo
	s_nop 0
	global_load_lds_dwordx4 v[154:155], off
	s_barrier
; #define WAIT_V(n) asm volatile("s_waitcnt vmcnt(" #n ")" ::: "memory")
; #define WAIT_L(n) asm volatile("s_waitcnt lgkmcnt(" #n ")" ::: "memory")
; #define BAR __builtin_amdgcn_s_barrier()
; #define SCHED __builtin_amdgcn_sched_barrier(0)
; DI void gemm_tile(const bf16_t* __restrict__ A, const bf16_t* __restrict__ Bt, const int K, const int brow, const int bcol, LAS unsigned char* lds, Acc& acc) {
;     ...
;         BAR; WAIT_L(0); MMA(1, 0, At, B0); BAR; SCHED;
;         STAGE(SBo(1, 1), b3 + hstep);
;         WAIT_V(6); BAR; MMA(1, 1, At, B1); BAR;
;     }
;     { LDB(B0, 0, 0); LDA(At, 0, 0); STAGE(SAo(1, 1), cA + (size_t)(nt - 1) * kstep + hstep);
;       BAR; WAIT_L(0); MMA(0, 0, At, B0); BAR;
;       LDB(B1, 0, 1); BAR; WAIT_L(0); MMA(0, 1, At, B1); BAR;
;       LDA(At, 0, 1); WAIT_V(4); BAR; WAIT_L(0); MMA(1, 0, At, B0); MMA(1, 1, At, B1); BAR; }
	s_waitcnt lgkmcnt(0)
	v_mfma_f32_16x16x32_bf16 v[60:63], v[150:153], v[172:175], v[60:63]
	v_mfma_f32_16x16x32_bf16 v[56:59], v[164:167], v[172:175], v[56:59]
	v_mfma_f32_16x16x32_bf16 v[52:55], v[150:153], v[180:183], v[52:55]
	v_mfma_f32_16x16x32_bf16 v[48:51], v[164:167], v[180:183], v[48:51]
	v_mfma_f32_16x16x32_bf16 v[44:47], v[150:153], v[188:191], v[44:47]
	v_mfma_f32_16x16x32_bf16 v[40:43], v[164:167], v[188:191], v[40:43]
	v_mfma_f32_16x16x32_bf16 v[36:39], v[150:153], v[196:199], v[36:39]
	v_mfma_f32_16x16x32_bf16 v[32:35], v[164:167], v[196:199], v[32:35]
	v_mfma_f32_16x16x32_bf16 v[60:63], v[160:163], v[176:179], v[60:63]
	v_mfma_f32_16x16x32_bf16 v[56:59], v[168:171], v[176:179], v[56:59]
	v_mfma_f32_16x16x32_bf16 v[52:55], v[160:163], v[184:187], v[52:55]
	v_mfma_f32_16x16x32_bf16 v[48:51], v[168:171], v[184:187], v[48:51]
	v_mfma_f32_16x16x32_bf16 v[44:47], v[160:163], v[192:195], v[44:47]
	v_mfma_f32_16x16x32_bf16 v[40:43], v[168:171], v[192:195], v[40:43]
	v_mfma_f32_16x16x32_bf16 v[36:39], v[160:163], v[200:203], v[36:39]
	v_mfma_f32_16x16x32_bf16 v[32:35], v[168:171], v[200:203], v[32:35]
	s_barrier
	s_add_i32 s6, s7, s18
	v_lshl_add_u64 v[150:151], v[232:233], 0, s[40:41]
	s_mov_b32 m0, s6
	s_nop 0
	global_load_lds_dwordx4 v[150:151], off
	v_lshl_add_u64 v[150:151], v[234:235], 0, s[40:41]
	s_add_i32 m0, s6, 0x2000
	s_nop 0
	global_load_lds_dwordx4 v[150:151], off
	s_waitcnt vmcnt(6)
	s_barrier
	v_mfma_f32_16x16x32_bf16 v[28:31], v[208:211], v[172:175], v[28:31]
	v_mfma_f32_16x16x32_bf16 v[24:27], v[216:219], v[172:175], v[24:27]
	v_mfma_f32_16x16x32_bf16 v[20:23], v[208:211], v[180:183], v[20:23]
	v_mfma_f32_16x16x32_bf16 v[16:19], v[216:219], v[180:183], v[16:19]
	v_mfma_f32_16x16x32_bf16 v[12:15], v[208:211], v[188:191], v[12:15]
	v_mfma_f32_16x16x32_bf16 v[8:11], v[216:219], v[188:191], v[8:11]
	v_mfma_f32_16x16x32_bf16 v[4:7], v[208:211], v[196:199], v[4:7]
	v_mfma_f32_16x16x32_bf16 v[0:3], v[216:219], v[196:199], v[0:3]
	v_mfma_f32_16x16x32_bf16 v[28:31], v[212:215], v[176:179], v[28:31]
	v_mfma_f32_16x16x32_bf16 v[24:27], v[220:223], v[176:179], v[24:27]
	v_mfma_f32_16x16x32_bf16 v[20:23], v[212:215], v[184:187], v[20:23]
	v_mfma_f32_16x16x32_bf16 v[16:19], v[220:223], v[184:187], v[16:19]
	v_mfma_f32_16x16x32_bf16 v[12:15], v[212:215], v[192:195], v[12:15]
	v_mfma_f32_16x16x32_bf16 v[8:11], v[220:223], v[192:195], v[8:11]
	v_mfma_f32_16x16x32_bf16 v[4:7], v[212:215], v[200:203], v[4:7]
	v_mfma_f32_16x16x32_bf16 v[0:3], v[220:223], v[200:203], v[0:3]
	s_barrier
	s_add_u32 s60, s60, 0x100
	s_addc_u32 s61, s61, 0
	s_cmp_ge_u32 s62, vcc_hi
	s_cbranch_scc0 .LBB0_930
	s_add_i32 s18, s96, -1
	s_lshl_b64 s[6:7], s[18:19], 7
	s_add_u32 s4, s4, s6
	s_addc_u32 s5, s5, s7
	s_add_u32 s4, s4, s55
	v_add_u32_e32 v149, 16, v149
	s_addc_u32 s5, s5, 0
	s_mov_b32 m0, s81
	v_add_u32_e32 v144, 0x10000, v149
	v_lshl_add_u64 v[154:155], s[4:5], 0, v[142:143]
	ds_read_b128 v[130:133], v144
	ds_read_b128 v[134:137], v144 offset:1024
	ds_read_b128 v[138:141], v144 offset:2048
	ds_read_b128 v[144:147], v144 offset:3072
	ds_read_b128 v[150:153], v148
	ds_read_b128 v[160:163], v148 offset:1024
	ds_read_b128 v[164:167], v148 offset:2048
	ds_read_b128 v[168:171], v148 offset:3072
	ds_read_b128 v[172:175], v148 offset:4096
	ds_read_b128 v[176:179], v148 offset:5120
	ds_read_b128 v[180:183], v148 offset:6144
	ds_read_b128 v[184:187], v148 offset:7168
	global_load_lds_dwordx4 v[154:155], off
	v_lshl_add_u64 v[128:129], s[4:5], 0, v[128:129]
	s_mov_b32 m0, s63
	s_nop 0
	global_load_lds_dwordx4 v[128:129], off
	s_barrier
	s_waitcnt lgkmcnt(0)
	v_mfma_f32_16x16x32_bf16 v[124:127], v[130:133], v[150:153], v[124:127]
	v_mfma_f32_16x16x32_bf16 v[120:123], v[138:141], v[150:153], v[120:123]
	v_mfma_f32_16x16x32_bf16 v[116:119], v[130:133], v[164:167], v[116:119]
	v_mfma_f32_16x16x32_bf16 v[112:115], v[138:141], v[164:167], v[112:115]
	v_mfma_f32_16x16x32_bf16 v[100:103], v[130:133], v[180:183], v[100:103]
	v_mfma_f32_16x16x32_bf16 v[96:99], v[138:141], v[180:183], v[96:99]
	v_mfma_f32_16x16x32_bf16 v[124:127], v[134:137], v[160:163], v[124:127]
	v_mfma_f32_16x16x32_bf16 v[120:123], v[144:147], v[160:163], v[120:123]
	v_mfma_f32_16x16x32_bf16 v[116:119], v[134:137], v[168:171], v[116:119]
	v_mfma_f32_16x16x32_bf16 v[112:115], v[144:147], v[168:171], v[112:115]
	v_mfma_f32_16x16x32_bf16 v[108:111], v[130:133], v[172:175], v[108:111]
	v_mfma_f32_16x16x32_bf16 v[104:107], v[138:141], v[172:175], v[104:107]
	v_mfma_f32_16x16x32_bf16 v[100:103], v[134:137], v[184:187], v[100:103]
	v_mfma_f32_16x16x32_bf16 v[96:99], v[144:147], v[184:187], v[96:99]
	v_mfma_f32_16x16x32_bf16 v[188:191], v[134:137], v[176:179], v[108:111]
	v_mfma_f32_16x16x32_bf16 v[192:195], v[144:147], v[176:179], v[104:107]
	v_add_u32_e32 v128, 0x14000, v149
	s_barrier
	s_nop 0
	ds_read_b128 v[104:107], v128
	ds_read_b128 v[108:111], v128 offset:1024
	ds_read_b128 v[196:199], v128 offset:2048
	ds_read_b128 v[200:203], v128 offset:3072
	s_barrier
	s_waitcnt lgkmcnt(0)
	v_mfma_f32_16x16x32_bf16 v[84:87], v[104:107], v[164:167], v[84:87]
	v_mfma_f32_16x16x32_bf16 v[80:83], v[196:199], v[164:167], v[80:83]
	v_mfma_f32_16x16x32_bf16 v[68:71], v[104:107], v[180:183], v[68:71]
	v_mfma_f32_16x16x32_bf16 v[64:67], v[196:199], v[180:183], v[64:67]
	v_mfma_f32_16x16x32_bf16 v[92:95], v[104:107], v[150:153], v[92:95]
	v_mfma_f32_16x16x32_bf16 v[88:91], v[196:199], v[150:153], v[88:91]
	v_mfma_f32_16x16x32_bf16 v[84:87], v[108:111], v[168:171], v[84:87]
	v_mfma_f32_16x16x32_bf16 v[80:83], v[200:203], v[168:171], v[80:83]
	v_mfma_f32_16x16x32_bf16 v[76:79], v[104:107], v[172:175], v[76:79]
	v_mfma_f32_16x16x32_bf16 v[72:75], v[196:199], v[172:175], v[72:75]
	v_mfma_f32_16x16x32_bf16 v[68:71], v[108:111], v[184:187], v[68:71]
	v_mfma_f32_16x16x32_bf16 v[64:67], v[200:203], v[184:187], v[64:67]
	v_mfma_f32_16x16x32_bf16 v[208:211], v[108:111], v[160:163], v[92:95]
	v_mfma_f32_16x16x32_bf16 v[150:153], v[200:203], v[160:163], v[88:91]
	v_mfma_f32_16x16x32_bf16 v[160:163], v[108:111], v[176:179], v[76:79]
	v_mfma_f32_16x16x32_bf16 v[164:167], v[200:203], v[176:179], v[72:75]
	s_barrier
; #define WAIT_V(n) asm volatile("s_waitcnt vmcnt(" #n ")" ::: "memory")
; #define WAIT_L(n) asm volatile("s_waitcnt lgkmcnt(" #n ")" ::: "memory")
; #define BAR __builtin_amdgcn_s_barrier()
; DI void gemm_tile(const bf16_t* __restrict__ A, const bf16_t* __restrict__ Bt, const int K, const int brow, const int bcol, LAS unsigned char* lds, Acc& acc) {
;     ...
;       LDA(At, 0, 1); WAIT_V(4); BAR; WAIT_L(0); MMA(1, 0, At, B0); MMA(1, 1, At, B1); BAR; }
;     { LDB(B0, 1, 0); LDA(At, 1, 0); WAIT_V(2); BAR; WAIT_L(0); MMA(0, 0, At, B0); BAR;
;       LDB(B1, 1, 1); WAIT_V(0); BAR; WAIT_L(0); MMA(0, 1, At, B1); BAR;
	s_nop 0
	ds_read_b128 v[72:75], v148 offset:16384
	ds_read_b128 v[76:79], v148 offset:17408
	ds_read_b128 v[88:91], v148 offset:18432
	ds_read_b128 v[92:95], v148 offset:19456
	ds_read_b128 v[168:171], v148 offset:20480
	ds_read_b128 v[172:175], v148 offset:21504
	ds_read_b128 v[176:179], v148 offset:22528
	ds_read_b128 v[180:183], v148 offset:23552
	s_waitcnt vmcnt(4)
	s_barrier
	s_waitcnt lgkmcnt(0)
	v_mfma_f32_16x16x32_bf16 v[60:63], v[130:133], v[72:75], v[60:63]
	v_mfma_f32_16x16x32_bf16 v[56:59], v[138:141], v[72:75], v[56:59]
	v_mfma_f32_16x16x32_bf16 v[52:55], v[130:133], v[88:91], v[52:55]
	v_mfma_f32_16x16x32_bf16 v[48:51], v[138:141], v[88:91], v[48:51]
	v_mfma_f32_16x16x32_bf16 v[36:39], v[130:133], v[176:179], v[36:39]
	v_mfma_f32_16x16x32_bf16 v[32:35], v[138:141], v[176:179], v[32:35]
	v_mfma_f32_16x16x32_bf16 v[60:63], v[134:137], v[76:79], v[60:63]
	v_mfma_f32_16x16x32_bf16 v[56:59], v[144:147], v[76:79], v[56:59]
	v_mfma_f32_16x16x32_bf16 v[52:55], v[134:137], v[92:95], v[52:55]
	v_mfma_f32_16x16x32_bf16 v[48:51], v[144:147], v[92:95], v[48:51]
	v_mfma_f32_16x16x32_bf16 v[44:47], v[130:133], v[168:171], v[44:47]
	v_mfma_f32_16x16x32_bf16 v[40:43], v[138:141], v[168:171], v[40:43]
	v_mfma_f32_16x16x32_bf16 v[36:39], v[134:137], v[180:183], v[36:39]
	v_mfma_f32_16x16x32_bf16 v[32:35], v[144:147], v[180:183], v[32:35]
	v_mfma_f32_16x16x32_bf16 v[184:187], v[134:137], v[172:175], v[44:47]
	v_mfma_f32_16x16x32_bf16 v[212:215], v[144:147], v[172:175], v[40:43]
	v_mfma_f32_16x16x32_bf16 v[20:23], v[104:107], v[88:91], v[20:23]
	v_mfma_f32_16x16x32_bf16 v[16:19], v[196:199], v[88:91], v[16:19]
	v_mfma_f32_16x16x32_bf16 v[4:7], v[104:107], v[176:179], v[4:7]
	v_mfma_f32_16x16x32_bf16 v[0:3], v[196:199], v[176:179], v[0:3]
	v_mfma_f32_16x16x32_bf16 v[28:31], v[104:107], v[72:75], v[28:31]
	v_mfma_f32_16x16x32_bf16 v[24:27], v[196:199], v[72:75], v[24:27]
	v_mfma_f32_16x16x32_bf16 v[20:23], v[108:111], v[92:95], v[20:23]
	v_mfma_f32_16x16x32_bf16 v[16:19], v[200:203], v[92:95], v[16:19]
	v_mfma_f32_16x16x32_bf16 v[12:15], v[104:107], v[168:171], v[12:15]
	v_mfma_f32_16x16x32_bf16 v[8:11], v[196:199], v[168:171], v[8:11]
	v_mfma_f32_16x16x32_bf16 v[4:7], v[108:111], v[180:183], v[4:7]
	v_mfma_f32_16x16x32_bf16 v[0:3], v[200:203], v[180:183], v[0:3]
	v_mfma_f32_16x16x32_bf16 v[128:131], v[108:111], v[76:79], v[28:31]
	v_mfma_f32_16x16x32_bf16 v[132:135], v[200:203], v[76:79], v[24:27]
	v_mfma_f32_16x16x32_bf16 v[136:139], v[108:111], v[172:175], v[12:15]
	v_mfma_f32_16x16x32_bf16 v[144:147], v[200:203], v[172:175], v[8:11]
	v_add_u32_e32 v24, 0x18000, v149
	s_barrier
	ds_read_b128 v[8:11], v24
	ds_read_b128 v[12:15], v24 offset:1024
	ds_read_b128 v[168:171], v24 offset:2048
	ds_read_b128 v[172:175], v24 offset:3072
	ds_read_b128 v[24:27], v148 offset:32768
	ds_read_b128 v[28:31], v148 offset:33792
	ds_read_b128 v[40:43], v148 offset:34816
	ds_read_b128 v[44:47], v148 offset:35840
	ds_read_b128 v[176:179], v148 offset:36864
	ds_read_b128 v[180:183], v148 offset:37888
	ds_read_b128 v[196:199], v148 offset:38912
	ds_read_b128 v[200:203], v148 offset:39936
	s_waitcnt vmcnt(2)
	s_barrier
	s_waitcnt lgkmcnt(0)
	v_mfma_f32_16x16x32_bf16 v[72:75], v[8:11], v[24:27], v[124:127]
	v_mfma_f32_16x16x32_bf16 v[124:127], v[12:15], v[28:31], v[72:75]
	v_mfma_f32_16x16x32_bf16 v[72:75], v[168:171], v[24:27], v[120:123]
	v_mfma_f32_16x16x32_bf16 v[120:123], v[172:175], v[28:31], v[72:75]
	v_mfma_f32_16x16x32_bf16 v[72:75], v[8:11], v[40:43], v[116:119]
	v_mfma_f32_16x16x32_bf16 v[108:111], v[12:15], v[44:47], v[72:75]
	v_mfma_f32_16x16x32_bf16 v[72:75], v[168:171], v[40:43], v[112:115]
	v_mfma_f32_16x16x32_bf16 v[104:107], v[172:175], v[44:47], v[72:75]
	v_mfma_f32_16x16x32_bf16 v[72:75], v[8:11], v[176:179], v[188:191]
	v_mfma_f32_16x16x32_bf16 v[92:95], v[12:15], v[180:183], v[72:75]
	v_mfma_f32_16x16x32_bf16 v[72:75], v[168:171], v[176:179], v[192:195]
	v_mfma_f32_16x16x32_bf16 v[88:91], v[172:175], v[180:183], v[72:75]
	v_mfma_f32_16x16x32_bf16 v[72:75], v[8:11], v[196:199], v[100:103]
	v_mfma_f32_16x16x32_bf16 v[76:79], v[12:15], v[200:203], v[72:75]
	v_mfma_f32_16x16x32_bf16 v[72:75], v[168:171], v[196:199], v[96:99]
	v_mfma_f32_16x16x32_bf16 v[72:75], v[172:175], v[200:203], v[72:75]
	s_nop 0
	v_add_u32_e32 v96, 0x1c000, v149
	s_barrier
; #define WAIT_V(n) asm volatile("s_waitcnt vmcnt(" #n ")" ::: "memory")
; #define WAIT_L(n) asm volatile("s_waitcnt lgkmcnt(" #n ")" ::: "memory")
; #define BAR __builtin_amdgcn_s_barrier()
; DI void gemm_tile(const bf16_t* __restrict__ A, const bf16_t* __restrict__ Bt, const int K, const int brow, const int bcol, LAS unsigned char* lds, Acc& acc) {
;     ...
;       LDB(B1, 1, 1); WAIT_V(0); BAR; WAIT_L(0); MMA(0, 1, At, B1); BAR;
;       LDA(At, 1, 1); BAR; WAIT_L(0); MMA(1, 0, At, B0); MMA(1, 1, At, B1); BAR; }
;     if (wr == 0) BAR;
; DI void phase_qkvb(const P& p, char* shm) {
;     ...
;         if (isq) {
;             if (pn < 4) {
	ds_read_b128 v[188:191], v96
	ds_read_b128 v[192:195], v96 offset:1024
	ds_read_b128 v[216:219], v96 offset:2048
	ds_read_b128 v[220:223], v96 offset:3072
	s_waitcnt vmcnt(0)
	s_barrier
	s_waitcnt lgkmcnt(0)
	v_mfma_f32_16x16x32_bf16 v[96:99], v[188:191], v[24:27], v[208:211]
	v_mfma_f32_16x16x32_bf16 v[24:27], v[216:219], v[24:27], v[150:153]
	v_mfma_f32_16x16x32_bf16 v[112:115], v[220:223], v[28:31], v[24:27]
	v_mfma_f32_16x16x32_bf16 v[24:27], v[188:191], v[40:43], v[84:87]
	v_mfma_f32_16x16x32_bf16 v[100:103], v[192:195], v[44:47], v[24:27]
	v_mfma_f32_16x16x32_bf16 v[24:27], v[216:219], v[40:43], v[80:83]
	v_mfma_f32_16x16x32_bf16 v[116:119], v[192:195], v[28:31], v[96:99]
	v_mfma_f32_16x16x32_bf16 v[96:99], v[220:223], v[44:47], v[24:27]
	v_mfma_f32_16x16x32_bf16 v[24:27], v[188:191], v[176:179], v[160:163]
	v_mfma_f32_16x16x32_bf16 v[84:87], v[192:195], v[180:183], v[24:27]
	v_mfma_f32_16x16x32_bf16 v[24:27], v[216:219], v[176:179], v[164:167]
	v_mfma_f32_16x16x32_bf16 v[80:83], v[220:223], v[180:183], v[24:27]
	v_mfma_f32_16x16x32_bf16 v[24:27], v[188:191], v[196:199], v[68:71]
	v_mfma_f32_16x16x32_bf16 v[68:71], v[192:195], v[200:203], v[24:27]
	v_mfma_f32_16x16x32_bf16 v[24:27], v[216:219], v[196:199], v[64:67]
	v_mfma_f32_16x16x32_bf16 v[64:67], v[220:223], v[200:203], v[24:27]
	s_barrier
	ds_read_b128 v[150:153], v148 offset:49152
	ds_read_b128 v[160:163], v148 offset:50176
	ds_read_b128 v[164:167], v148 offset:51200
	ds_read_b128 v[176:179], v148 offset:52224
	ds_read_b128 v[180:183], v148 offset:53248
	ds_read_b128 v[196:199], v148 offset:54272
	ds_read_b128 v[200:203], v148 offset:55296
	ds_read_b128 v[208:211], v148 offset:56320
	s_barrier
	s_waitcnt lgkmcnt(0)
	v_mfma_f32_16x16x32_bf16 v[24:27], v[8:11], v[150:153], v[60:63]
	v_mfma_f32_16x16x32_bf16 v[60:63], v[12:15], v[160:163], v[24:27]
	v_mfma_f32_16x16x32_bf16 v[24:27], v[168:171], v[150:153], v[56:59]
	v_mfma_f32_16x16x32_bf16 v[56:59], v[172:175], v[160:163], v[24:27]
	v_mfma_f32_16x16x32_bf16 v[24:27], v[8:11], v[164:167], v[52:55]
	v_mfma_f32_16x16x32_bf16 v[44:47], v[12:15], v[176:179], v[24:27]
	v_mfma_f32_16x16x32_bf16 v[24:27], v[168:171], v[164:167], v[48:51]
	v_mfma_f32_16x16x32_bf16 v[40:43], v[172:175], v[176:179], v[24:27]
	v_mfma_f32_16x16x32_bf16 v[24:27], v[8:11], v[180:183], v[184:187]
	v_mfma_f32_16x16x32_bf16 v[8:11], v[8:11], v[200:203], v[36:39]
	v_mfma_f32_16x16x32_bf16 v[28:31], v[12:15], v[196:199], v[24:27]
	v_mfma_f32_16x16x32_bf16 v[24:27], v[168:171], v[180:183], v[212:215]
	v_mfma_f32_16x16x32_bf16 v[12:15], v[12:15], v[208:211], v[8:11]
	v_mfma_f32_16x16x32_bf16 v[8:11], v[168:171], v[200:203], v[32:35]
	v_mfma_f32_16x16x32_bf16 v[24:27], v[172:175], v[196:199], v[24:27]
	v_mfma_f32_16x16x32_bf16 v[8:11], v[172:175], v[208:211], v[8:11]
	v_mfma_f32_16x16x32_bf16 v[32:35], v[188:191], v[150:153], v[128:131]
	v_mfma_f32_16x16x32_bf16 v[52:55], v[192:195], v[160:163], v[32:35]
	v_mfma_f32_16x16x32_bf16 v[32:35], v[216:219], v[150:153], v[132:135]
	v_mfma_f32_16x16x32_bf16 v[16:19], v[216:219], v[164:167], v[16:19]
	v_mfma_f32_16x16x32_bf16 v[48:51], v[220:223], v[160:163], v[32:35]
	v_mfma_f32_16x16x32_bf16 v[20:23], v[188:191], v[164:167], v[20:23]
	v_mfma_f32_16x16x32_bf16 v[32:35], v[220:223], v[176:179], v[16:19]
	v_mfma_f32_16x16x32_bf16 v[16:19], v[188:191], v[180:183], v[136:139]
	v_mfma_f32_16x16x32_bf16 v[36:39], v[192:195], v[176:179], v[20:23]
	v_mfma_f32_16x16x32_bf16 v[20:23], v[192:195], v[196:199], v[16:19]
	v_mfma_f32_16x16x32_bf16 v[16:19], v[216:219], v[180:183], v[144:147]
	v_mfma_f32_16x16x32_bf16 v[4:7], v[188:191], v[200:203], v[4:7]
	v_mfma_f32_16x16x32_bf16 v[0:3], v[216:219], v[200:203], v[0:3]
	v_mfma_f32_16x16x32_bf16 v[16:19], v[220:223], v[196:199], v[16:19]
	v_mfma_f32_16x16x32_bf16 v[4:7], v[192:195], v[208:211], v[4:7]
	v_mfma_f32_16x16x32_bf16 v[0:3], v[220:223], v[208:211], v[0:3]
	s_cmpk_lt_u32 s29, 0x100
	s_mov_b32 s89, s23
	s_mov_b32 s90, s35
	s_mov_b32 s91, s8
	s_barrier
	s_cbranch_scc0 .LBB0_934
	s_barrier
	s_and_b64 vcc, exec, s[2:3]
	s_mov_b64 s[2:3], -1
	s_cbranch_vccz .LBB0_935

; #define WAIT_V(n) asm volatile("s_waitcnt vmcnt(" #n ")" ::: "memory")
; #define WAIT_L(n) asm volatile("s_waitcnt lgkmcnt(" #n ")" ::: "memory")
; #define BAR __builtin_amdgcn_s_barrier()
; #define SCHED __builtin_amdgcn_sched_barrier(0)
; template <class Get, class Epi>
; DI void gemm_stream(LAS unsigned char* lds, const int K, const int ld, Get get, Epi epi) {
;     ...
;             LDB(B0, 0, 0); SCHED; LDA(At, 0, 0); STAGE(SAo(1, 1), a1 + hstep);
;             WAIT_L(8); BAR; WAIT_L(0); MMA(0, 0, At, B0); BAR; SCHED;
;             LDB(B1, 0, 1); STAGE(SBo(0, 0), b2);
;             BAR; WAIT_L(0); MMA(0, 1, At, B1); BAR;
;             LDA(At, 0, 1); STAGE(SAo(0, 0), a2);
;             BAR; WAIT_L(0); MMA(1, 0, At, B0); BAR; SCHED;
;             STAGE(SBo(0, 1), b2 + hstep);
;             WAIT_V(6); BAR; MMA(1, 1, At, B1); BAR;
;             LDB(B0, 1, 0); SCHED; LDA(At, 1, 0); STAGE(SAo(0, 1), a2 + hstep);
;             WAIT_L(8); BAR; WAIT_L(0); MMA(0, 0, At, B0); BAR; SCHED;
;             LDB(B1, 1, 1); STAGE(SBo(1, 0), b3);
;             BAR; WAIT_L(0); MMA(0, 1, At, B1); BAR;
.LBB0_1238:
	ds_read_b128 v[128:131], v198
	ds_read_b128 v[132:135], v198 offset:1024
	ds_read_b128 v[136:139], v198 offset:2048
	ds_read_b128 v[140:143], v198 offset:3072
	s_add_u32 s8, s6, 0x100
	s_addc_u32 s9, s7, 0
	s_cmp_eq_u32 s18, 28
	s_cselect_b32 s13, s39, s9
	s_cselect_b32 s12, s38, s8
	s_cselect_b32 s11, s41, s17
	s_cselect_b32 s10, s40, s16
	s_mov_b32 m0, s74
	v_lshl_add_u64 v[186:187], s[6:7], 0, v[168:169]
	ds_read_b128 v[144:147], v199
	ds_read_b128 v[148:151], v199 offset:1024
	ds_read_b128 v[152:155], v199 offset:2048
	ds_read_b128 v[156:159], v199 offset:3072
	ds_read_b128 v[160:163], v199 offset:4096
	ds_read_b128 v[174:177], v199 offset:5120
	ds_read_b128 v[178:181], v199 offset:6144
	ds_read_b128 v[182:185], v199 offset:7168
	global_load_lds_dwordx4 v[186:187], off
	v_lshl_add_u64 v[186:187], s[6:7], 0, v[170:171]
	s_mov_b32 m0, s75
	s_nop 0
	global_load_lds_dwordx4 v[186:187], off
	s_waitcnt lgkmcnt(8)
	s_barrier
	s_waitcnt lgkmcnt(0)
	v_mfma_f32_16x16x32_bf16 v[124:127], v[128:131], v[144:147], v[124:127]
	v_mfma_f32_16x16x32_bf16 v[92:95], v[136:139], v[144:147], v[92:95]
	v_mfma_f32_16x16x32_bf16 v[120:123], v[128:131], v[152:155], v[120:123]
	v_mfma_f32_16x16x32_bf16 v[88:91], v[136:139], v[152:155], v[88:91]
	v_mfma_f32_16x16x32_bf16 v[116:119], v[128:131], v[160:163], v[116:119]
	v_mfma_f32_16x16x32_bf16 v[84:87], v[136:139], v[160:163], v[84:87]
	v_mfma_f32_16x16x32_bf16 v[112:115], v[128:131], v[178:181], v[112:115]
	v_mfma_f32_16x16x32_bf16 v[80:83], v[136:139], v[178:181], v[80:83]
	v_mfma_f32_16x16x32_bf16 v[124:127], v[132:135], v[148:151], v[124:127]
	v_mfma_f32_16x16x32_bf16 v[92:95], v[140:143], v[148:151], v[92:95]
	v_mfma_f32_16x16x32_bf16 v[120:123], v[132:135], v[156:159], v[120:123]
	v_mfma_f32_16x16x32_bf16 v[88:91], v[140:143], v[156:159], v[88:91]
	v_mfma_f32_16x16x32_bf16 v[116:119], v[132:135], v[174:177], v[116:119]
	v_mfma_f32_16x16x32_bf16 v[84:87], v[140:143], v[174:177], v[84:87]
	v_mfma_f32_16x16x32_bf16 v[112:115], v[132:135], v[182:185], v[112:115]
	v_mfma_f32_16x16x32_bf16 v[80:83], v[140:143], v[182:185], v[80:83]
	s_barrier
	s_mov_b32 m0, s80
	v_lshl_add_u64 v[204:205], s[10:11], 0, v[164:165]
	ds_read_b128 v[186:189], v200
	ds_read_b128 v[190:193], v200 offset:1024
	ds_read_b128 v[194:197], v200 offset:2048
	ds_read_b128 v[208:211], v200 offset:3072
	global_load_lds_dwordx4 v[204:205], off
	v_lshl_add_u64 v[212:213], s[10:11], 0, v[166:167]
	s_mov_b32 m0, s81
	s_nop 0
	global_load_lds_dwordx4 v[212:213], off
	s_barrier
	s_waitcnt lgkmcnt(0)
	v_mfma_f32_16x16x32_bf16 v[60:63], v[186:189], v[144:147], v[60:63]
	v_mfma_f32_16x16x32_bf16 v[28:31], v[194:197], v[144:147], v[28:31]
	v_mfma_f32_16x16x32_bf16 v[56:59], v[186:189], v[152:155], v[56:59]
	v_mfma_f32_16x16x32_bf16 v[24:27], v[194:197], v[152:155], v[24:27]
	v_mfma_f32_16x16x32_bf16 v[52:55], v[186:189], v[160:163], v[52:55]
	v_mfma_f32_16x16x32_bf16 v[20:23], v[194:197], v[160:163], v[20:23]
	v_mfma_f32_16x16x32_bf16 v[48:51], v[186:189], v[178:181], v[48:51]
	v_mfma_f32_16x16x32_bf16 v[16:19], v[194:197], v[178:181], v[16:19]
	v_mfma_f32_16x16x32_bf16 v[60:63], v[190:193], v[148:151], v[60:63]
	v_mfma_f32_16x16x32_bf16 v[28:31], v[208:211], v[148:151], v[28:31]
	v_mfma_f32_16x16x32_bf16 v[56:59], v[190:193], v[156:159], v[56:59]
	v_mfma_f32_16x16x32_bf16 v[24:27], v[208:211], v[156:159], v[24:27]
	v_mfma_f32_16x16x32_bf16 v[52:55], v[190:193], v[174:177], v[52:55]
	v_mfma_f32_16x16x32_bf16 v[20:23], v[208:211], v[174:177], v[20:23]
	v_mfma_f32_16x16x32_bf16 v[48:51], v[190:193], v[182:185], v[48:51]
	v_mfma_f32_16x16x32_bf16 v[16:19], v[208:211], v[182:185], v[16:19]
	s_barrier
	s_mov_b32 m0, s21
	v_lshl_add_u64 v[214:215], s[12:13], 0, v[164:165]
	ds_read_b128 v[144:147], v199 offset:16384
	ds_read_b128 v[148:151], v199 offset:17408
	ds_read_b128 v[152:155], v199 offset:18432
	ds_read_b128 v[156:159], v199 offset:19456
	ds_read_b128 v[160:163], v199 offset:20480
	ds_read_b128 v[174:177], v199 offset:21504
	ds_read_b128 v[178:181], v199 offset:22528
	ds_read_b128 v[182:185], v199 offset:23552
	global_load_lds_dwordx4 v[214:215], off
	v_lshl_add_u64 v[216:217], s[12:13], 0, v[166:167]
	s_mov_b32 m0, s58
	s_nop 0
	global_load_lds_dwordx4 v[216:217], off
	s_barrier
	s_waitcnt lgkmcnt(0)
	v_mfma_f32_16x16x32_bf16 v[108:111], v[128:131], v[144:147], v[108:111]
	v_mfma_f32_16x16x32_bf16 v[76:79], v[136:139], v[144:147], v[76:79]
	v_mfma_f32_16x16x32_bf16 v[104:107], v[128:131], v[152:155], v[104:107]
	v_mfma_f32_16x16x32_bf16 v[72:75], v[136:139], v[152:155], v[72:75]
	v_mfma_f32_16x16x32_bf16 v[100:103], v[128:131], v[160:163], v[100:103]
	v_mfma_f32_16x16x32_bf16 v[68:71], v[136:139], v[160:163], v[68:71]
	v_mfma_f32_16x16x32_bf16 v[96:99], v[128:131], v[178:181], v[96:99]
	v_mfma_f32_16x16x32_bf16 v[64:67], v[136:139], v[178:181], v[64:67]
	v_mfma_f32_16x16x32_bf16 v[108:111], v[132:135], v[148:151], v[108:111]
	v_mfma_f32_16x16x32_bf16 v[76:79], v[140:143], v[148:151], v[76:79]
	v_mfma_f32_16x16x32_bf16 v[104:107], v[132:135], v[156:159], v[104:107]
	v_mfma_f32_16x16x32_bf16 v[72:75], v[140:143], v[156:159], v[72:75]
	v_mfma_f32_16x16x32_bf16 v[100:103], v[132:135], v[174:177], v[100:103]
	v_mfma_f32_16x16x32_bf16 v[68:71], v[140:143], v[174:177], v[68:71]
	v_mfma_f32_16x16x32_bf16 v[96:99], v[132:135], v[182:185], v[96:99]
	v_mfma_f32_16x16x32_bf16 v[64:67], v[140:143], v[182:185], v[64:67]
	s_barrier
	s_add_u32 s6, s10, 0x80000
	s_addc_u32 s7, s11, 0
	s_mov_b32 m0, s82
	v_lshl_add_u64 v[128:129], s[6:7], 0, v[164:165]
	global_load_lds_dwordx4 v[128:129], off
	v_lshl_add_u64 v[128:129], s[6:7], 0, v[166:167]
	s_mov_b32 m0, s83
	s_nop 0
	global_load_lds_dwordx4 v[128:129], off
	s_waitcnt vmcnt(6)
	s_barrier
; #define WAIT_V(n) asm volatile("s_waitcnt vmcnt(" #n ")" ::: "memory")
; #define WAIT_L(n) asm volatile("s_waitcnt lgkmcnt(" #n ")" ::: "memory")
; #define BAR __builtin_amdgcn_s_barrier()
; #define SCHED __builtin_amdgcn_sched_barrier(0)
; template <class Get, class Epi>
; DI void gemm_stream(LAS unsigned char* lds, const int K, const int ld, Get get, Epi epi) {
;     ...
;             LDB(B0, 1, 0); SCHED; LDA(At, 1, 0); STAGE(SAo(0, 1), a2 + hstep);
;             WAIT_L(8); BAR; WAIT_L(0); MMA(0, 0, At, B0); BAR; SCHED;
;             LDB(B1, 1, 1); STAGE(SBo(1, 0), b3);
;             BAR; WAIT_L(0); MMA(0, 1, At, B1); BAR;
;             LDA(At, 1, 1); STAGE(SAo(1, 0), a3);
;             BAR; WAIT_L(0); MMA(1, 0, At, B0); BAR; SCHED;
;             STAGE(SBo(1, 1), b3 + hstep);
;             WAIT_V(6); BAR; MMA(1, 1, At, B1); BAR;
	v_mfma_f32_16x16x32_bf16 v[44:47], v[186:189], v[144:147], v[44:47]
	v_mfma_f32_16x16x32_bf16 v[12:15], v[194:197], v[144:147], v[12:15]
	v_mfma_f32_16x16x32_bf16 v[40:43], v[186:189], v[152:155], v[40:43]
	v_mfma_f32_16x16x32_bf16 v[8:11], v[194:197], v[152:155], v[8:11]
	v_mfma_f32_16x16x32_bf16 v[36:39], v[186:189], v[160:163], v[36:39]
	v_mfma_f32_16x16x32_bf16 v[4:7], v[194:197], v[160:163], v[4:7]
	v_mfma_f32_16x16x32_bf16 v[32:35], v[186:189], v[178:181], v[32:35]
	v_mfma_f32_16x16x32_bf16 v[0:3], v[194:197], v[178:181], v[0:3]
	v_mfma_f32_16x16x32_bf16 v[44:47], v[190:193], v[148:151], v[44:47]
	v_mfma_f32_16x16x32_bf16 v[12:15], v[208:211], v[148:151], v[12:15]
	v_mfma_f32_16x16x32_bf16 v[40:43], v[190:193], v[156:159], v[40:43]
	v_mfma_f32_16x16x32_bf16 v[8:11], v[208:211], v[156:159], v[8:11]
	v_mfma_f32_16x16x32_bf16 v[36:39], v[190:193], v[174:177], v[36:39]
	v_mfma_f32_16x16x32_bf16 v[4:7], v[208:211], v[174:177], v[4:7]
	v_mfma_f32_16x16x32_bf16 v[32:35], v[190:193], v[182:185], v[32:35]
	v_mfma_f32_16x16x32_bf16 v[0:3], v[208:211], v[182:185], v[0:3]
	s_barrier
	ds_read_b128 v[128:131], v201
	ds_read_b128 v[132:135], v201 offset:1024
	ds_read_b128 v[136:139], v201 offset:2048
	ds_read_b128 v[140:143], v201 offset:3072
	s_add_u32 s6, s12, 0x80000
	s_addc_u32 s7, s13, 0
	s_mov_b32 m0, s59
	v_lshl_add_u64 v[186:187], s[6:7], 0, v[164:165]
	ds_read_b128 v[144:147], v199 offset:32768
	ds_read_b128 v[148:151], v199 offset:33792
	ds_read_b128 v[152:155], v199 offset:34816
	ds_read_b128 v[156:159], v199 offset:35840
	ds_read_b128 v[160:163], v199 offset:36864
	ds_read_b128 v[174:177], v199 offset:37888
	ds_read_b128 v[178:181], v199 offset:38912
	ds_read_b128 v[182:185], v199 offset:39936
	global_load_lds_dwordx4 v[186:187], off
	v_lshl_add_u64 v[186:187], s[6:7], 0, v[166:167]
	s_mov_b32 m0, s60
	s_nop 0
	global_load_lds_dwordx4 v[186:187], off
	s_waitcnt lgkmcnt(8)
	s_barrier
	s_waitcnt lgkmcnt(0)
	v_mfma_f32_16x16x32_bf16 v[124:127], v[128:131], v[144:147], v[124:127]
	v_mfma_f32_16x16x32_bf16 v[92:95], v[136:139], v[144:147], v[92:95]
	v_mfma_f32_16x16x32_bf16 v[120:123], v[128:131], v[152:155], v[120:123]
	v_mfma_f32_16x16x32_bf16 v[88:91], v[136:139], v[152:155], v[88:91]
	v_mfma_f32_16x16x32_bf16 v[116:119], v[128:131], v[160:163], v[116:119]
	v_mfma_f32_16x16x32_bf16 v[84:87], v[136:139], v[160:163], v[84:87]
	v_mfma_f32_16x16x32_bf16 v[112:115], v[128:131], v[178:181], v[112:115]
	v_mfma_f32_16x16x32_bf16 v[80:83], v[136:139], v[178:181], v[80:83]
	v_mfma_f32_16x16x32_bf16 v[124:127], v[132:135], v[148:151], v[124:127]
	v_mfma_f32_16x16x32_bf16 v[92:95], v[140:143], v[148:151], v[92:95]
	v_mfma_f32_16x16x32_bf16 v[120:123], v[132:135], v[156:159], v[120:123]
	v_mfma_f32_16x16x32_bf16 v[88:91], v[140:143], v[156:159], v[88:91]
	v_mfma_f32_16x16x32_bf16 v[116:119], v[132:135], v[174:177], v[116:119]
	v_mfma_f32_16x16x32_bf16 v[84:87], v[140:143], v[174:177], v[84:87]
	v_mfma_f32_16x16x32_bf16 v[112:115], v[132:135], v[182:185], v[112:115]
	v_mfma_f32_16x16x32_bf16 v[80:83], v[140:143], v[182:185], v[80:83]
	s_barrier
	s_mov_b32 m0, s85
	v_lshl_add_u64 v[204:205], v[204:205], 0, s[0:1]
	ds_read_b128 v[186:189], v202
	ds_read_b128 v[190:193], v202 offset:1024
	ds_read_b128 v[194:197], v202 offset:2048
	ds_read_b128 v[208:211], v202 offset:3072
	global_load_lds_dwordx4 v[204:205], off
	v_lshl_add_u64 v[204:205], v[212:213], 0, s[0:1]
	s_mov_b32 m0, s96
	s_nop 0
	global_load_lds_dwordx4 v[204:205], off
	s_barrier
	s_waitcnt lgkmcnt(0)
	v_mfma_f32_16x16x32_bf16 v[60:63], v[186:189], v[144:147], v[60:63]
	v_mfma_f32_16x16x32_bf16 v[28:31], v[194:197], v[144:147], v[28:31]
	v_mfma_f32_16x16x32_bf16 v[56:59], v[186:189], v[152:155], v[56:59]
	v_mfma_f32_16x16x32_bf16 v[24:27], v[194:197], v[152:155], v[24:27]
	v_mfma_f32_16x16x32_bf16 v[52:55], v[186:189], v[160:163], v[52:55]
	v_mfma_f32_16x16x32_bf16 v[20:23], v[194:197], v[160:163], v[20:23]
	v_mfma_f32_16x16x32_bf16 v[48:51], v[186:189], v[178:181], v[48:51]
	v_mfma_f32_16x16x32_bf16 v[16:19], v[194:197], v[178:181], v[16:19]
	v_mfma_f32_16x16x32_bf16 v[60:63], v[190:193], v[148:151], v[60:63]
	v_mfma_f32_16x16x32_bf16 v[28:31], v[208:211], v[148:151], v[28:31]
	v_mfma_f32_16x16x32_bf16 v[56:59], v[190:193], v[156:159], v[56:59]
	v_mfma_f32_16x16x32_bf16 v[24:27], v[208:211], v[156:159], v[24:27]
	v_mfma_f32_16x16x32_bf16 v[52:55], v[190:193], v[174:177], v[52:55]
	v_mfma_f32_16x16x32_bf16 v[20:23], v[208:211], v[174:177], v[20:23]
	v_mfma_f32_16x16x32_bf16 v[48:51], v[190:193], v[182:185], v[48:51]
	v_mfma_f32_16x16x32_bf16 v[16:19], v[208:211], v[182:185], v[16:19]
	s_barrier
	s_mov_b32 m0, s61
	v_lshl_add_u64 v[204:205], v[214:215], 0, s[0:1]
	ds_read_b128 v[144:147], v199 offset:49152
	ds_read_b128 v[148:151], v199 offset:50176
	ds_read_b128 v[152:155], v199 offset:51200
	ds_read_b128 v[156:159], v199 offset:52224
	ds_read_b128 v[160:163], v199 offset:53248
	ds_read_b128 v[174:177], v199 offset:54272
	ds_read_b128 v[178:181], v199 offset:55296
	ds_read_b128 v[182:185], v199 offset:56320
	global_load_lds_dwordx4 v[204:205], off
	v_lshl_add_u64 v[204:205], v[216:217], 0, s[0:1]
	s_mov_b32 m0, s62
	s_nop 0
	global_load_lds_dwordx4 v[204:205], off
	s_barrier
; #define WAIT_V(n) asm volatile("s_waitcnt vmcnt(" #n ")" ::: "memory")
; #define WAIT_L(n) asm volatile("s_waitcnt lgkmcnt(" #n ")" ::: "memory")
; #define BAR __builtin_amdgcn_s_barrier()
; #define SCHED __builtin_amdgcn_sched_barrier(0)
; template <class Get, class Epi>
; DI void gemm_stream(LAS unsigned char* lds, const int K, const int ld, Get get, Epi epi) {
;     ...
;             BAR; WAIT_L(0); MMA(1, 0, At, B0); BAR; SCHED;
;             STAGE(SBo(1, 1), b3 + hstep);
;             WAIT_V(6); BAR; MMA(1, 1, At, B1); BAR;
; DI void epi_resid(const Acc& acc, const P& p, int brow, int bcol, int layer, int gch, bool from_input) {
;     EPI_IDX
;     const float* gate = modv(p, layer, brow, gch);
; #pragma unroll
;     for (int bj = 0; bj < 2; ++bj)
; #pragma unroll
;         for (int n = 0; n < 2; ++n) {
;             const int c0 = bcol + bj * 128 + wc * 32 + n * 16 + fq * 4;
;             const f32x4 g = *(const f32x4*)(gate + c0);
;             f32x4 xv[2][4];
; #pragma unroll
;             for (int ai = 0; ai < 2; ++ai)
; #pragma unroll
;                 for (int m = 0; m < 4; ++m) {
;                     const int r = brow + ai * 128 + wr * 64 + m * 16 + fr;
;                     const float* sp = (from_input ? inrow(p, r) : xrow(p, r)) + c0;
;                     xv[ai][m] = *(const f32x4*)sp;
;                 }
;             __builtin_amdgcn_sched_barrier(0);
; #pragma unroll
;             for (int ai = 0; ai < 2; ++ai)
; #pragma unroll
;                 for (int m = 0; m < 4; ++m) {
;                     const int r = brow + ai * 128 + wr * 64 + m * 16 + fr;
;                     *(f32x4*)(xrow(p, r) + c0) = xv[ai][m] + g * acc[ai][bj][m][n];
;                 }
	s_waitcnt lgkmcnt(0)
	v_mfma_f32_16x16x32_bf16 v[108:111], v[128:131], v[144:147], v[108:111]
	v_mfma_f32_16x16x32_bf16 v[76:79], v[136:139], v[144:147], v[76:79]
	v_mfma_f32_16x16x32_bf16 v[104:107], v[128:131], v[152:155], v[104:107]
	v_mfma_f32_16x16x32_bf16 v[72:75], v[136:139], v[152:155], v[72:75]
	v_mfma_f32_16x16x32_bf16 v[100:103], v[128:131], v[160:163], v[100:103]
	v_mfma_f32_16x16x32_bf16 v[68:71], v[136:139], v[160:163], v[68:71]
	v_mfma_f32_16x16x32_bf16 v[96:99], v[128:131], v[178:181], v[96:99]
	v_mfma_f32_16x16x32_bf16 v[64:67], v[136:139], v[178:181], v[64:67]
	v_mfma_f32_16x16x32_bf16 v[108:111], v[132:135], v[148:151], v[108:111]
	v_mfma_f32_16x16x32_bf16 v[76:79], v[140:143], v[148:151], v[76:79]
	v_mfma_f32_16x16x32_bf16 v[104:107], v[132:135], v[156:159], v[104:107]
	v_mfma_f32_16x16x32_bf16 v[72:75], v[140:143], v[156:159], v[72:75]
	v_mfma_f32_16x16x32_bf16 v[100:103], v[132:135], v[174:177], v[100:103]
	v_mfma_f32_16x16x32_bf16 v[68:71], v[140:143], v[174:177], v[68:71]
	v_mfma_f32_16x16x32_bf16 v[96:99], v[132:135], v[182:185], v[96:99]
	v_mfma_f32_16x16x32_bf16 v[64:67], v[140:143], v[182:185], v[64:67]
	s_barrier
	s_add_u32 s6, s10, 0x80080
	s_addc_u32 s7, s11, 0
	s_mov_b32 m0, s97
	v_lshl_add_u64 v[128:129], s[6:7], 0, v[164:165]
	global_load_lds_dwordx4 v[128:129], off
	v_lshl_add_u64 v[128:129], s[6:7], 0, v[166:167]
	s_add_i32 m0, s97, 0x2000
	s_nop 0
	global_load_lds_dwordx4 v[128:129], off
	s_waitcnt vmcnt(6)
	s_barrier
	v_mfma_f32_16x16x32_bf16 v[44:47], v[186:189], v[144:147], v[44:47]
	v_mfma_f32_16x16x32_bf16 v[12:15], v[194:197], v[144:147], v[12:15]
	v_mfma_f32_16x16x32_bf16 v[40:43], v[186:189], v[152:155], v[40:43]
	v_mfma_f32_16x16x32_bf16 v[8:11], v[194:197], v[152:155], v[8:11]
	v_mfma_f32_16x16x32_bf16 v[36:39], v[186:189], v[160:163], v[36:39]
	v_mfma_f32_16x16x32_bf16 v[4:7], v[194:197], v[160:163], v[4:7]
	v_mfma_f32_16x16x32_bf16 v[32:35], v[186:189], v[178:181], v[32:35]
	v_mfma_f32_16x16x32_bf16 v[0:3], v[194:197], v[178:181], v[0:3]
	v_mfma_f32_16x16x32_bf16 v[44:47], v[190:193], v[148:151], v[44:47]
	v_mfma_f32_16x16x32_bf16 v[12:15], v[208:211], v[148:151], v[12:15]
	v_mfma_f32_16x16x32_bf16 v[40:43], v[190:193], v[156:159], v[40:43]
	v_mfma_f32_16x16x32_bf16 v[8:11], v[208:211], v[156:159], v[8:11]
	v_mfma_f32_16x16x32_bf16 v[36:39], v[190:193], v[174:177], v[36:39]
	v_mfma_f32_16x16x32_bf16 v[4:7], v[208:211], v[174:177], v[4:7]
	v_mfma_f32_16x16x32_bf16 v[32:35], v[190:193], v[182:185], v[32:35]
	v_mfma_f32_16x16x32_bf16 v[0:3], v[208:211], v[182:185], v[0:3]
	s_barrier
	s_add_i32 s18, s18, 2
	s_add_u32 s16, s16, 0x100
	s_addc_u32 s17, s17, 0
	s_cmp_gt_u32 s18, 29
	s_mov_b64 s[6:7], s[8:9]
	s_cbranch_scc0 .LBB0_1238
	s_lshl_b32 s12, s15, 21
	s_lshl_b32 s13, s14, 10
	s_lshr_b32 s16, s15, 4
	s_add_u32 s12, s12, s13
	s_mul_i32 s16, s16, 6
	s_add_i32 s16, s16, 2
	s_lshl_b32 s16, s16, 13
	s_add_u32 s16, s16, s13
	s_add_u32 s10, s26, s16
	s_addc_u32 s11, s27, 0
	s_add_u32 s8, s52, s12
	s_addc_u32 s9, s53, 0
	s_add_u32 s6, s24, s12
	s_addc_u32 s7, s25, 0
	v_lshrrev_b32_e32 v224, 6, v206
	v_and_b32_e32 v225, 3, v224
	v_lshrrev_b32_e32 v224, 2, v224
	v_and_b32_e32 v205, 15, v206
	v_bfe_u32 v226, v206, 4, 2
	v_lshl_add_u32 v225, v225, 3, v226
	v_lshl_add_u32 v224, v224, 6, v205
	v_lshlrev_b32_e32 v205, 4, v225
	v_lshl_add_u32 v203, v224, 13, v205
	v_mov_b32_e32 v204, v203
	global_load_dwordx4 v[128:131], v205, s[10:11] offset:0
	global_load_dwordx4 v[132:135], v205, s[10:11] offset:64
	global_load_dwordx4 v[136:139], v205, s[10:11] offset:512
	global_load_dwordx4 v[140:143], v205, s[10:11] offset:576
	global_load_dwordx4 v[144:147], v203, s[8:9] offset:0
	global_load_dwordx4 v[148:151], v203, s[8:9] offset:64
	global_load_dwordx4 v[152:155], v203, s[8:9] offset:512
	global_load_dwordx4 v[156:159], v203, s[8:9] offset:576
	v_add_u32_e32 v203, 0x20000, v203
	global_load_dwordx4 v[160:163], v203, s[8:9] offset:0
	global_load_dwordx4 v[174:177], v203, s[8:9] offset:64
	global_load_dwordx4 v[178:181], v203, s[8:9] offset:512
	global_load_dwordx4 v[182:185], v203, s[8:9] offset:576
	v_add_u32_e32 v203, 0x20000, v203
	global_load_dwordx4 v[186:189], v203, s[8:9] offset:0
	global_load_dwordx4 v[190:193], v203, s[8:9] offset:64
	global_load_dwordx4 v[194:197], v203, s[8:9] offset:512
	global_load_dwordx4 v[208:211], v203, s[8:9] offset:576
	v_add_u32_e32 v203, 0x20000, v203
	global_load_dwordx4 v[212:215], v203, s[8:9] offset:0
	global_load_dwordx4 v[216:219], v203, s[8:9] offset:64
	global_load_dwordx4 v[220:223], v203, s[8:9] offset:512
	global_load_dwordx4 v[224:227], v203, s[8:9] offset:576
	v_add_u32_e32 v203, 0xa0000, v203
	s_waitcnt vmcnt(12)
	v_pk_fma_f32 v[124:125], v[124:125], v[128:129], v[144:145]
	v_pk_fma_f32 v[126:127], v[126:127], v[130:131], v[146:147]
	v_pk_fma_f32 v[92:93], v[92:93], v[132:133], v[148:149]
	v_pk_fma_f32 v[94:95], v[94:95], v[134:135], v[150:151]
	v_pk_fma_f32 v[60:61], v[60:61], v[136:137], v[152:153]
	v_pk_fma_f32 v[62:63], v[62:63], v[138:139], v[154:155]
	v_pk_fma_f32 v[28:29], v[28:29], v[140:141], v[156:157]
	v_pk_fma_f32 v[30:31], v[30:31], v[142:143], v[158:159]
	global_store_dwordx4 v204, v[124:127], s[6:7] offset:0
	global_store_dwordx4 v204, v[92:95], s[6:7] offset:64
	global_store_dwordx4 v204, v[60:63], s[6:7] offset:512
	global_store_dwordx4 v204, v[28:31], s[6:7] offset:576
	v_add_u32_e32 v204, 0x20000, v204
	global_load_dwordx4 v[144:147], v203, s[8:9] offset:0
	global_load_dwordx4 v[148:151], v203, s[8:9] offset:64
	global_load_dwordx4 v[152:155], v203, s[8:9] offset:512
	global_load_dwordx4 v[156:159], v203, s[8:9] offset:576
	v_add_u32_e32 v203, 0x20000, v203
	s_waitcnt vmcnt(16)
; #define EPI_DONE do { } while (0)
; DI void epi_resid(const Acc& acc, const P& p, int brow, int bcol, int layer, int gch, bool from_input) {
;     EPI_IDX
;     const float* gate = modv(p, layer, brow, gch);
; #pragma unroll
;     for (int bj = 0; bj < 2; ++bj)
; #pragma unroll
;         for (int n = 0; n < 2; ++n) {
;             const int c0 = bcol + bj * 128 + wc * 32 + n * 16 + fq * 4;
;             const f32x4 g = *(const f32x4*)(gate + c0);
;             f32x4 xv[2][4];
; #pragma unroll
;             for (int ai = 0; ai < 2; ++ai)
; #pragma unroll
;                 for (int m = 0; m < 4; ++m) {
;                     const int r = brow + ai * 128 + wr * 64 + m * 16 + fr;
;                     const float* sp = (from_input ? inrow(p, r) : xrow(p, r)) + c0;
;                     xv[ai][m] = *(const f32x4*)sp;
;                 }
;             __builtin_amdgcn_sched_barrier(0);
; #pragma unroll
;             for (int ai = 0; ai < 2; ++ai)
; #pragma unroll
;                 for (int m = 0; m < 4; ++m) {
;                     const int r = brow + ai * 128 + wr * 64 + m * 16 + fr;
;                     *(f32x4*)(xrow(p, r) + c0) = xv[ai][m] + g * acc[ai][bj][m][n];
;                 }
;             __builtin_amdgcn_sched_barrier(0);
;         }
;     EPI_DONE;
; }
	v_pk_fma_f32 v[120:121], v[120:121], v[128:129], v[160:161]
	v_pk_fma_f32 v[122:123], v[122:123], v[130:131], v[162:163]
	v_pk_fma_f32 v[88:89], v[88:89], v[132:133], v[174:175]
	v_pk_fma_f32 v[90:91], v[90:91], v[134:135], v[176:177]
	v_pk_fma_f32 v[56:57], v[56:57], v[136:137], v[178:179]
	v_pk_fma_f32 v[58:59], v[58:59], v[138:139], v[180:181]
	v_pk_fma_f32 v[24:25], v[24:25], v[140:141], v[182:183]
	v_pk_fma_f32 v[26:27], v[26:27], v[142:143], v[184:185]
	global_store_dwordx4 v204, v[120:123], s[6:7] offset:0
	global_store_dwordx4 v204, v[88:91], s[6:7] offset:64
	global_store_dwordx4 v204, v[56:59], s[6:7] offset:512
	global_store_dwordx4 v204, v[24:27], s[6:7] offset:576
	v_add_u32_e32 v204, 0x20000, v204
	global_load_dwordx4 v[160:163], v203, s[8:9] offset:0
	global_load_dwordx4 v[174:177], v203, s[8:9] offset:64
	global_load_dwordx4 v[178:181], v203, s[8:9] offset:512
	global_load_dwordx4 v[182:185], v203, s[8:9] offset:576
	v_add_u32_e32 v203, 0x20000, v203
	s_waitcnt vmcnt(20)
	v_pk_fma_f32 v[116:117], v[116:117], v[128:129], v[186:187]
	v_pk_fma_f32 v[118:119], v[118:119], v[130:131], v[188:189]
	v_pk_fma_f32 v[84:85], v[84:85], v[132:133], v[190:191]
	v_pk_fma_f32 v[86:87], v[86:87], v[134:135], v[192:193]
	v_pk_fma_f32 v[52:53], v[52:53], v[136:137], v[194:195]
	v_pk_fma_f32 v[54:55], v[54:55], v[138:139], v[196:197]
	v_pk_fma_f32 v[20:21], v[20:21], v[140:141], v[208:209]
	v_pk_fma_f32 v[22:23], v[22:23], v[142:143], v[210:211]
	global_store_dwordx4 v204, v[116:119], s[6:7] offset:0
	global_store_dwordx4 v204, v[84:87], s[6:7] offset:64
	global_store_dwordx4 v204, v[52:55], s[6:7] offset:512
	global_store_dwordx4 v204, v[20:23], s[6:7] offset:576
	v_add_u32_e32 v204, 0x20000, v204
	global_load_dwordx4 v[186:189], v203, s[8:9] offset:0
	global_load_dwordx4 v[190:193], v203, s[8:9] offset:64
	global_load_dwordx4 v[194:197], v203, s[8:9] offset:512
	global_load_dwordx4 v[208:211], v203, s[8:9] offset:576
	v_add_u32_e32 v203, 0x20000, v203
	s_waitcnt vmcnt(24)
	v_pk_fma_f32 v[112:113], v[112:113], v[128:129], v[212:213]
	v_pk_fma_f32 v[114:115], v[114:115], v[130:131], v[214:215]
	v_pk_fma_f32 v[80:81], v[80:81], v[132:133], v[216:217]
	v_pk_fma_f32 v[82:83], v[82:83], v[134:135], v[218:219]
	v_pk_fma_f32 v[48:49], v[48:49], v[136:137], v[220:221]
	v_pk_fma_f32 v[50:51], v[50:51], v[138:139], v[222:223]
	v_pk_fma_f32 v[16:17], v[16:17], v[140:141], v[224:225]
	v_pk_fma_f32 v[18:19], v[18:19], v[142:143], v[226:227]
	global_store_dwordx4 v204, v[112:115], s[6:7] offset:0
	global_store_dwordx4 v204, v[80:83], s[6:7] offset:64
	global_store_dwordx4 v204, v[48:51], s[6:7] offset:512
	global_store_dwordx4 v204, v[16:19], s[6:7] offset:576
	v_add_u32_e32 v204, 0xa0000, v204
	global_load_dwordx4 v[212:215], v203, s[8:9] offset:0
	global_load_dwordx4 v[216:219], v203, s[8:9] offset:64
	global_load_dwordx4 v[220:223], v203, s[8:9] offset:512
	global_load_dwordx4 v[224:227], v203, s[8:9] offset:576
	s_waitcnt vmcnt(24)
	v_pk_fma_f32 v[108:109], v[108:109], v[128:129], v[144:145]
	v_pk_fma_f32 v[110:111], v[110:111], v[130:131], v[146:147]
	v_pk_fma_f32 v[76:77], v[76:77], v[132:133], v[148:149]
	v_pk_fma_f32 v[78:79], v[78:79], v[134:135], v[150:151]
	v_pk_fma_f32 v[44:45], v[44:45], v[136:137], v[152:153]
	v_pk_fma_f32 v[46:47], v[46:47], v[138:139], v[154:155]
	v_pk_fma_f32 v[12:13], v[12:13], v[140:141], v[156:157]
	v_pk_fma_f32 v[14:15], v[14:15], v[142:143], v[158:159]
	global_store_dwordx4 v204, v[108:111], s[6:7] offset:0
	global_store_dwordx4 v204, v[76:79], s[6:7] offset:64
	global_store_dwordx4 v204, v[44:47], s[6:7] offset:512
	global_store_dwordx4 v204, v[12:15], s[6:7] offset:576
	v_add_u32_e32 v204, 0x20000, v204
	s_waitcnt vmcnt(20)
	v_pk_fma_f32 v[104:105], v[104:105], v[128:129], v[160:161]
	v_pk_fma_f32 v[106:107], v[106:107], v[130:131], v[162:163]
	v_pk_fma_f32 v[72:73], v[72:73], v[132:133], v[174:175]
	v_pk_fma_f32 v[74:75], v[74:75], v[134:135], v[176:177]
	v_pk_fma_f32 v[40:41], v[40:41], v[136:137], v[178:179]
	v_pk_fma_f32 v[42:43], v[42:43], v[138:139], v[180:181]
	v_pk_fma_f32 v[8:9], v[8:9], v[140:141], v[182:183]
	v_pk_fma_f32 v[10:11], v[10:11], v[142:143], v[184:185]
	global_store_dwordx4 v204, v[104:107], s[6:7] offset:0
	global_store_dwordx4 v204, v[72:75], s[6:7] offset:64
	global_store_dwordx4 v204, v[40:43], s[6:7] offset:512
	global_store_dwordx4 v204, v[8:11], s[6:7] offset:576
	v_add_u32_e32 v204, 0x20000, v204
	s_waitcnt vmcnt(16)
	v_pk_fma_f32 v[100:101], v[100:101], v[128:129], v[186:187]
	v_pk_fma_f32 v[102:103], v[102:103], v[130:131], v[188:189]
	v_pk_fma_f32 v[68:69], v[68:69], v[132:133], v[190:191]
	v_pk_fma_f32 v[70:71], v[70:71], v[134:135], v[192:193]
	v_pk_fma_f32 v[36:37], v[36:37], v[136:137], v[194:195]
	v_pk_fma_f32 v[38:39], v[38:39], v[138:139], v[196:197]
	v_pk_fma_f32 v[4:5], v[4:5], v[140:141], v[208:209]
	v_pk_fma_f32 v[6:7], v[6:7], v[142:143], v[210:211]
	global_store_dwordx4 v204, v[100:103], s[6:7] offset:0
	global_store_dwordx4 v204, v[68:71], s[6:7] offset:64
	global_store_dwordx4 v204, v[36:39], s[6:7] offset:512
	global_store_dwordx4 v204, v[4:7], s[6:7] offset:576
	v_add_u32_e32 v204, 0x20000, v204
	s_waitcnt vmcnt(12)
	v_pk_fma_f32 v[96:97], v[96:97], v[128:129], v[212:213]
	v_pk_fma_f32 v[98:99], v[98:99], v[130:131], v[214:215]
	v_pk_fma_f32 v[64:65], v[64:65], v[132:133], v[216:217]
	v_pk_fma_f32 v[66:67], v[66:67], v[134:135], v[218:219]
	v_pk_fma_f32 v[32:33], v[32:33], v[136:137], v[220:221]
	v_pk_fma_f32 v[34:35], v[34:35], v[138:139], v[222:223]
	v_pk_fma_f32 v[0:1], v[0:1], v[140:141], v[224:225]
	v_pk_fma_f32 v[2:3], v[2:3], v[142:143], v[226:227]
	global_store_dwordx4 v204, v[96:99], s[6:7] offset:0
	global_store_dwordx4 v204, v[64:67], s[6:7] offset:64
	global_store_dwordx4 v204, v[32:35], s[6:7] offset:512
	global_store_dwordx4 v204, v[0:3], s[6:7] offset:576
	s_branch .Lresid_latch_wout0

; #define WAIT_V(n) asm volatile("s_waitcnt vmcnt(" #n ")" ::: "memory")
; #define WAIT_L(n) asm volatile("s_waitcnt lgkmcnt(" #n ")" ::: "memory")
; #define BAR __builtin_amdgcn_s_barrier()
; #define SCHED __builtin_amdgcn_sched_barrier(0)
; template <class Get, class Epi>
; DI void gemm_stream(LAS unsigned char* lds, const int K, const int ld, Get get, Epi epi) {
;     ...
;             LDB(B0, 0, 0); SCHED; LDA(At, 0, 0); STAGE(SAo(1, 1), a1 + hstep);
;             WAIT_L(8); BAR; WAIT_L(0); MMA(0, 0, At, B0); BAR; SCHED;
;             LDB(B1, 0, 1); STAGE(SBo(0, 0), b2);
;             BAR; WAIT_L(0); MMA(0, 1, At, B1); BAR;
;             LDA(At, 0, 1); STAGE(SAo(0, 0), a2);
;             BAR; WAIT_L(0); MMA(1, 0, At, B0); BAR; SCHED;
;             STAGE(SBo(0, 1), b2 + hstep);
;             WAIT_V(6); BAR; MMA(1, 1, At, B1); BAR;
.LBB0_1630:
	ds_read_b128 v[148:151], v142
	ds_read_b128 v[152:155], v142 offset:1024
	ds_read_b128 v[156:159], v142 offset:2048
	ds_read_b128 v[160:163], v142 offset:3072
	s_add_u32 s12, s10, 0xfff80080
	s_addc_u32 s13, s11, -1
	s_cmp_eq_u32 s59, 28
	s_cselect_b32 s15, s7, s13
	s_cselect_b32 s14, s6, s12
	s_cselect_b32 s13, s9, s58
	s_cselect_b32 s12, s8, s57
	s_mov_b32 m0, s28
	v_lshl_add_u64 v[140:141], s[10:11], 0, v[134:135]
	ds_read_b128 v[164:167], v143
	ds_read_b128 v[168:171], v143 offset:1024
	ds_read_b128 v[172:175], v143 offset:2048
	ds_read_b128 v[176:179], v143 offset:3072
	ds_read_b128 v[180:183], v143 offset:4096
	ds_read_b128 v[184:187], v143 offset:5120
	ds_read_b128 v[188:191], v143 offset:6144
	ds_read_b128 v[192:195], v143 offset:7168
	global_load_lds_dwordx4 v[140:141], off
	v_lshl_add_u64 v[140:141], s[10:11], 0, v[136:137]
	s_mov_b32 m0, s29
	s_nop 0
	global_load_lds_dwordx4 v[140:141], off
	s_waitcnt lgkmcnt(8)
	s_barrier
	s_waitcnt lgkmcnt(0)
	v_mfma_f32_16x16x32_bf16 v[124:127], v[148:151], v[164:167], v[124:127]
	v_mfma_f32_16x16x32_bf16 v[116:119], v[156:159], v[164:167], v[116:119]
	v_mfma_f32_16x16x32_bf16 v[108:111], v[148:151], v[172:175], v[108:111]
	v_mfma_f32_16x16x32_bf16 v[100:103], v[156:159], v[172:175], v[100:103]
	v_mfma_f32_16x16x32_bf16 v[92:95], v[148:151], v[180:183], v[92:95]
	v_mfma_f32_16x16x32_bf16 v[84:87], v[156:159], v[180:183], v[84:87]
	v_mfma_f32_16x16x32_bf16 v[76:79], v[148:151], v[188:191], v[76:79]
	v_mfma_f32_16x16x32_bf16 v[68:71], v[156:159], v[188:191], v[68:71]
	v_mfma_f32_16x16x32_bf16 v[124:127], v[152:155], v[168:171], v[124:127]
	v_mfma_f32_16x16x32_bf16 v[116:119], v[160:163], v[168:171], v[116:119]
	v_mfma_f32_16x16x32_bf16 v[108:111], v[152:155], v[176:179], v[108:111]
	v_mfma_f32_16x16x32_bf16 v[100:103], v[160:163], v[176:179], v[100:103]
	v_mfma_f32_16x16x32_bf16 v[92:95], v[152:155], v[184:187], v[92:95]
	v_mfma_f32_16x16x32_bf16 v[84:87], v[160:163], v[184:187], v[84:87]
	v_mfma_f32_16x16x32_bf16 v[76:79], v[152:155], v[192:195], v[76:79]
	v_mfma_f32_16x16x32_bf16 v[68:71], v[160:163], v[192:195], v[68:71]
	s_barrier
	s_mov_b32 m0, s35
	v_lshl_add_u64 v[140:141], s[12:13], 0, v[130:131]
	ds_read_b128 v[196:199], v144
	ds_read_b128 v[200:203], v144 offset:1024
	ds_read_b128 v[208:211], v144 offset:2048
	ds_read_b128 v[212:215], v144 offset:3072
	global_load_lds_dwordx4 v[140:141], off
	v_lshl_add_u64 v[204:205], s[12:13], 0, v[128:129]
	s_mov_b32 m0, s36
	s_nop 0
	global_load_lds_dwordx4 v[204:205], off
	s_barrier
	s_waitcnt lgkmcnt(0)
	v_mfma_f32_16x16x32_bf16 v[120:123], v[196:199], v[164:167], v[120:123]
	v_mfma_f32_16x16x32_bf16 v[112:115], v[208:211], v[164:167], v[112:115]
	v_mfma_f32_16x16x32_bf16 v[104:107], v[196:199], v[172:175], v[104:107]
	v_mfma_f32_16x16x32_bf16 v[96:99], v[208:211], v[172:175], v[96:99]
	v_mfma_f32_16x16x32_bf16 v[88:91], v[196:199], v[180:183], v[88:91]
	v_mfma_f32_16x16x32_bf16 v[80:83], v[208:211], v[180:183], v[80:83]
	v_mfma_f32_16x16x32_bf16 v[72:75], v[196:199], v[188:191], v[72:75]
	v_mfma_f32_16x16x32_bf16 v[64:67], v[208:211], v[188:191], v[64:67]
	v_mfma_f32_16x16x32_bf16 v[120:123], v[200:203], v[168:171], v[120:123]
	v_mfma_f32_16x16x32_bf16 v[112:115], v[212:215], v[168:171], v[112:115]
	v_mfma_f32_16x16x32_bf16 v[104:107], v[200:203], v[176:179], v[104:107]
	v_mfma_f32_16x16x32_bf16 v[96:99], v[212:215], v[176:179], v[96:99]
	v_mfma_f32_16x16x32_bf16 v[88:91], v[200:203], v[184:187], v[88:91]
	v_mfma_f32_16x16x32_bf16 v[80:83], v[212:215], v[184:187], v[80:83]
	v_mfma_f32_16x16x32_bf16 v[72:75], v[200:203], v[192:195], v[72:75]
	v_mfma_f32_16x16x32_bf16 v[64:67], v[212:215], v[192:195], v[64:67]
	s_barrier
	s_mov_b32 m0, s3
	v_lshl_add_u64 v[216:217], s[14:15], 0, v[130:131]
	ds_read_b128 v[164:167], v143 offset:16384
	ds_read_b128 v[168:171], v143 offset:17408
	ds_read_b128 v[172:175], v143 offset:18432
	ds_read_b128 v[176:179], v143 offset:19456
	ds_read_b128 v[180:183], v143 offset:20480
	ds_read_b128 v[184:187], v143 offset:21504
	ds_read_b128 v[188:191], v143 offset:22528
	ds_read_b128 v[192:195], v143 offset:23552
	global_load_lds_dwordx4 v[216:217], off
	v_lshl_add_u64 v[218:219], s[14:15], 0, v[128:129]
	s_mov_b32 m0, s16
	s_nop 0
	global_load_lds_dwordx4 v[218:219], off
	s_barrier
	s_waitcnt lgkmcnt(0)
	v_mfma_f32_16x16x32_bf16 v[60:63], v[148:151], v[164:167], v[60:63]
	v_mfma_f32_16x16x32_bf16 v[52:55], v[156:159], v[164:167], v[52:55]
	v_mfma_f32_16x16x32_bf16 v[44:47], v[148:151], v[172:175], v[44:47]
	v_mfma_f32_16x16x32_bf16 v[36:39], v[156:159], v[172:175], v[36:39]
	v_mfma_f32_16x16x32_bf16 v[28:31], v[148:151], v[180:183], v[28:31]
	v_mfma_f32_16x16x32_bf16 v[20:23], v[156:159], v[180:183], v[20:23]
	v_mfma_f32_16x16x32_bf16 v[12:15], v[148:151], v[188:191], v[12:15]
	v_mfma_f32_16x16x32_bf16 v[4:7], v[156:159], v[188:191], v[4:7]
	v_mfma_f32_16x16x32_bf16 v[60:63], v[152:155], v[168:171], v[60:63]
	v_mfma_f32_16x16x32_bf16 v[52:55], v[160:163], v[168:171], v[52:55]
	v_mfma_f32_16x16x32_bf16 v[44:47], v[152:155], v[176:179], v[44:47]
	v_mfma_f32_16x16x32_bf16 v[36:39], v[160:163], v[176:179], v[36:39]
	v_mfma_f32_16x16x32_bf16 v[28:31], v[152:155], v[184:187], v[28:31]
	v_mfma_f32_16x16x32_bf16 v[20:23], v[160:163], v[184:187], v[20:23]
	v_mfma_f32_16x16x32_bf16 v[12:15], v[152:155], v[192:195], v[12:15]
	v_mfma_f32_16x16x32_bf16 v[4:7], v[160:163], v[192:195], v[4:7]
	s_barrier
	s_add_u32 s60, s12, 0x80000
	s_addc_u32 s61, s13, 0
	s_mov_b32 m0, s37
	v_lshl_add_u64 v[148:149], s[60:61], 0, v[130:131]
	global_load_lds_dwordx4 v[148:149], off
	v_lshl_add_u64 v[148:149], s[60:61], 0, v[128:129]
	s_mov_b32 m0, s38
	s_nop 0
	global_load_lds_dwordx4 v[148:149], off
	s_waitcnt vmcnt(6)
	s_barrier
; #define WAIT_V(n) asm volatile("s_waitcnt vmcnt(" #n ")" ::: "memory")
; #define WAIT_L(n) asm volatile("s_waitcnt lgkmcnt(" #n ")" ::: "memory")
; #define BAR __builtin_amdgcn_s_barrier()
; #define SCHED __builtin_amdgcn_sched_barrier(0)
; template <class Get, class Epi>
; DI void gemm_stream(LAS unsigned char* lds, const int K, const int ld, Get get, Epi epi) {
;     ...
;             WAIT_V(6); BAR; MMA(1, 1, At, B1); BAR;
;             LDB(B0, 1, 0); SCHED; LDA(At, 1, 0); STAGE(SAo(0, 1), a2 + hstep);
;             WAIT_L(8); BAR; WAIT_L(0); MMA(0, 0, At, B0); BAR; SCHED;
;             LDB(B1, 1, 1); STAGE(SBo(1, 0), b3);
;             BAR; WAIT_L(0); MMA(0, 1, At, B1); BAR;
;             LDA(At, 1, 1); STAGE(SAo(1, 0), a3);
;             BAR; WAIT_L(0); MMA(1, 0, At, B0); BAR; SCHED;
	v_mfma_f32_16x16x32_bf16 v[56:59], v[196:199], v[164:167], v[56:59]
	v_mfma_f32_16x16x32_bf16 v[48:51], v[208:211], v[164:167], v[48:51]
	v_mfma_f32_16x16x32_bf16 v[40:43], v[196:199], v[172:175], v[40:43]
	v_mfma_f32_16x16x32_bf16 v[32:35], v[208:211], v[172:175], v[32:35]
	v_mfma_f32_16x16x32_bf16 v[24:27], v[196:199], v[180:183], v[24:27]
	v_mfma_f32_16x16x32_bf16 v[16:19], v[208:211], v[180:183], v[16:19]
	v_mfma_f32_16x16x32_bf16 v[8:11], v[196:199], v[188:191], v[8:11]
	v_mfma_f32_16x16x32_bf16 v[0:3], v[208:211], v[188:191], v[0:3]
	v_mfma_f32_16x16x32_bf16 v[56:59], v[200:203], v[168:171], v[56:59]
	v_mfma_f32_16x16x32_bf16 v[48:51], v[212:215], v[168:171], v[48:51]
	v_mfma_f32_16x16x32_bf16 v[40:43], v[200:203], v[176:179], v[40:43]
	v_mfma_f32_16x16x32_bf16 v[32:35], v[212:215], v[176:179], v[32:35]
	v_mfma_f32_16x16x32_bf16 v[24:27], v[200:203], v[184:187], v[24:27]
	v_mfma_f32_16x16x32_bf16 v[16:19], v[212:215], v[184:187], v[16:19]
	v_mfma_f32_16x16x32_bf16 v[8:11], v[200:203], v[192:195], v[8:11]
	v_mfma_f32_16x16x32_bf16 v[0:3], v[212:215], v[192:195], v[0:3]
	s_barrier
	ds_read_b128 v[148:151], v145
	ds_read_b128 v[152:155], v145 offset:1024
	ds_read_b128 v[156:159], v145 offset:2048
	ds_read_b128 v[160:163], v145 offset:3072
	s_add_u32 s14, s14, 0x80000
	s_addc_u32 s15, s15, 0
	s_mov_b32 m0, s17
	v_lshl_add_u64 v[196:197], s[14:15], 0, v[130:131]
	ds_read_b128 v[164:167], v143 offset:32768
	ds_read_b128 v[168:171], v143 offset:33792
	ds_read_b128 v[172:175], v143 offset:34816
	ds_read_b128 v[176:179], v143 offset:35840
	ds_read_b128 v[180:183], v143 offset:36864
	ds_read_b128 v[184:187], v143 offset:37888
	ds_read_b128 v[188:191], v143 offset:38912
	ds_read_b128 v[192:195], v143 offset:39936
	global_load_lds_dwordx4 v[196:197], off
	v_lshl_add_u64 v[196:197], s[14:15], 0, v[128:129]
	s_mov_b32 m0, s18
	s_nop 0
	global_load_lds_dwordx4 v[196:197], off
	s_waitcnt lgkmcnt(8)
	s_barrier
	s_waitcnt lgkmcnt(0)
	v_mfma_f32_16x16x32_bf16 v[124:127], v[148:151], v[164:167], v[124:127]
	v_mfma_f32_16x16x32_bf16 v[116:119], v[156:159], v[164:167], v[116:119]
	v_mfma_f32_16x16x32_bf16 v[108:111], v[148:151], v[172:175], v[108:111]
	v_mfma_f32_16x16x32_bf16 v[100:103], v[156:159], v[172:175], v[100:103]
	v_mfma_f32_16x16x32_bf16 v[92:95], v[148:151], v[180:183], v[92:95]
	v_mfma_f32_16x16x32_bf16 v[84:87], v[156:159], v[180:183], v[84:87]
	v_mfma_f32_16x16x32_bf16 v[76:79], v[148:151], v[188:191], v[76:79]
	v_mfma_f32_16x16x32_bf16 v[68:71], v[156:159], v[188:191], v[68:71]
	v_mfma_f32_16x16x32_bf16 v[124:127], v[152:155], v[168:171], v[124:127]
	v_mfma_f32_16x16x32_bf16 v[116:119], v[160:163], v[168:171], v[116:119]
	v_mfma_f32_16x16x32_bf16 v[108:111], v[152:155], v[176:179], v[108:111]
	v_mfma_f32_16x16x32_bf16 v[100:103], v[160:163], v[176:179], v[100:103]
	v_mfma_f32_16x16x32_bf16 v[92:95], v[152:155], v[184:187], v[92:95]
	v_mfma_f32_16x16x32_bf16 v[84:87], v[160:163], v[184:187], v[84:87]
	v_mfma_f32_16x16x32_bf16 v[76:79], v[152:155], v[192:195], v[76:79]
	v_mfma_f32_16x16x32_bf16 v[68:71], v[160:163], v[192:195], v[68:71]
	s_barrier
	s_mov_b32 m0, s39
	v_lshl_add_u64 v[140:141], v[140:141], 0, s[0:1]
	ds_read_b128 v[196:199], v146
	ds_read_b128 v[200:203], v146 offset:1024
	ds_read_b128 v[208:211], v146 offset:2048
	ds_read_b128 v[212:215], v146 offset:3072
	global_load_lds_dwordx4 v[140:141], off
	v_lshl_add_u64 v[140:141], v[204:205], 0, s[0:1]
	s_mov_b32 m0, s40
	s_nop 0
	global_load_lds_dwordx4 v[140:141], off
	s_barrier
	s_waitcnt lgkmcnt(0)
	v_mfma_f32_16x16x32_bf16 v[120:123], v[196:199], v[164:167], v[120:123]
	v_mfma_f32_16x16x32_bf16 v[112:115], v[208:211], v[164:167], v[112:115]
	v_mfma_f32_16x16x32_bf16 v[104:107], v[196:199], v[172:175], v[104:107]
	v_mfma_f32_16x16x32_bf16 v[96:99], v[208:211], v[172:175], v[96:99]
	v_mfma_f32_16x16x32_bf16 v[88:91], v[196:199], v[180:183], v[88:91]
	v_mfma_f32_16x16x32_bf16 v[80:83], v[208:211], v[180:183], v[80:83]
	v_mfma_f32_16x16x32_bf16 v[72:75], v[196:199], v[188:191], v[72:75]
	v_mfma_f32_16x16x32_bf16 v[64:67], v[208:211], v[188:191], v[64:67]
	v_mfma_f32_16x16x32_bf16 v[120:123], v[200:203], v[168:171], v[120:123]
	v_mfma_f32_16x16x32_bf16 v[112:115], v[212:215], v[168:171], v[112:115]
	v_mfma_f32_16x16x32_bf16 v[104:107], v[200:203], v[176:179], v[104:107]
	v_mfma_f32_16x16x32_bf16 v[96:99], v[212:215], v[176:179], v[96:99]
	v_mfma_f32_16x16x32_bf16 v[88:91], v[200:203], v[184:187], v[88:91]
	v_mfma_f32_16x16x32_bf16 v[80:83], v[212:215], v[184:187], v[80:83]
	v_mfma_f32_16x16x32_bf16 v[72:75], v[200:203], v[192:195], v[72:75]
	v_mfma_f32_16x16x32_bf16 v[64:67], v[212:215], v[192:195], v[64:67]
	s_barrier
	s_mov_b32 m0, s20
	v_lshl_add_u64 v[140:141], v[216:217], 0, s[0:1]
	ds_read_b128 v[164:167], v143 offset:49152
	ds_read_b128 v[168:171], v143 offset:50176
	ds_read_b128 v[172:175], v143 offset:51200
	ds_read_b128 v[176:179], v143 offset:52224
	ds_read_b128 v[180:183], v143 offset:53248
	ds_read_b128 v[184:187], v143 offset:54272
	ds_read_b128 v[188:191], v143 offset:55296
	ds_read_b128 v[192:195], v143 offset:56320
	global_load_lds_dwordx4 v[140:141], off
	v_lshl_add_u64 v[140:141], v[218:219], 0, s[0:1]
	s_mov_b32 m0, s21
	s_nop 0
	global_load_lds_dwordx4 v[140:141], off
	s_barrier
; DI float silu_f(float g) { return g * __builtin_amdgcn_rcpf(1.f + __builtin_amdgcn_exp2f(-LOG2E * g)); }
; #define WAIT_V(n) asm volatile("s_waitcnt vmcnt(" #n ")" ::: "memory")
; #define WAIT_L(n) asm volatile("s_waitcnt lgkmcnt(" #n ")" ::: "memory")
; #define BAR __builtin_amdgcn_s_barrier()
; #define SCHED __builtin_amdgcn_sched_barrier(0)
; #define EPI_DONE do { } while (0)
; template <class Get, class Epi>
; DI void gemm_stream(LAS unsigned char* lds, const int K, const int ld, Get get, Epi epi) {
;     ...
;             BAR; WAIT_L(0); MMA(1, 0, At, B0); BAR; SCHED;
;             STAGE(SBo(1, 1), b3 + hstep);
;             WAIT_V(6); BAR; MMA(1, 1, At, B1); BAR;
; DI void epi_swiglu(const Acc& acc, int brow, int pn, bf16_t* hid) {
;     EPI_IDX
; #pragma unroll
;     for (int ai = 0; ai < 2; ++ai)
; #pragma unroll
;         for (int m = 0; m < 4; ++m) {
;             const int r = brow + ai * 128 + wr * 64 + m * 16 + fr;
;             bf16_t* rp = hid + (size_t)r * FF + pn * 128 + wc * 32 + fq * 4;
; #pragma unroll
;             for (int n = 0; n < 2; ++n) {
;                 const f32x4 g = acc[ai][0][m][n], u = acc[ai][1][m][n];
;                 float o[4];
; #pragma unroll
;                 for (int j = 0; j < 4; ++j) o[j] = silu_f(g[j]) * u[j];
;                 st4(rp + n * 16, o[0], o[1], o[2], o[3]);
;             }
;         }
;     EPI_DONE;
; }
	s_waitcnt lgkmcnt(0)
	v_mfma_f32_16x16x32_bf16 v[60:63], v[148:151], v[164:167], v[60:63]
	v_mfma_f32_16x16x32_bf16 v[52:55], v[156:159], v[164:167], v[52:55]
	v_mfma_f32_16x16x32_bf16 v[44:47], v[148:151], v[172:175], v[44:47]
	v_mfma_f32_16x16x32_bf16 v[36:39], v[156:159], v[172:175], v[36:39]
	v_mfma_f32_16x16x32_bf16 v[28:31], v[148:151], v[180:183], v[28:31]
	v_mfma_f32_16x16x32_bf16 v[20:23], v[156:159], v[180:183], v[20:23]
	v_mfma_f32_16x16x32_bf16 v[12:15], v[148:151], v[188:191], v[12:15]
	v_mfma_f32_16x16x32_bf16 v[4:7], v[156:159], v[188:191], v[4:7]
	v_mfma_f32_16x16x32_bf16 v[60:63], v[152:155], v[168:171], v[60:63]
	v_mfma_f32_16x16x32_bf16 v[52:55], v[160:163], v[168:171], v[52:55]
	v_mfma_f32_16x16x32_bf16 v[44:47], v[152:155], v[176:179], v[44:47]
	v_mfma_f32_16x16x32_bf16 v[36:39], v[160:163], v[176:179], v[36:39]
	v_mfma_f32_16x16x32_bf16 v[28:31], v[152:155], v[184:187], v[28:31]
	v_mfma_f32_16x16x32_bf16 v[20:23], v[160:163], v[184:187], v[20:23]
	v_mfma_f32_16x16x32_bf16 v[12:15], v[152:155], v[192:195], v[12:15]
	v_mfma_f32_16x16x32_bf16 v[4:7], v[160:163], v[192:195], v[4:7]
	s_barrier
	s_add_u32 s12, s12, 0x80080
	s_addc_u32 s13, s13, 0
	s_mov_b32 m0, s41
	v_lshl_add_u64 v[140:141], s[12:13], 0, v[130:131]
	global_load_lds_dwordx4 v[140:141], off
	v_lshl_add_u64 v[140:141], s[12:13], 0, v[128:129]
	s_mov_b32 m0, s52
	s_nop 0
	global_load_lds_dwordx4 v[140:141], off
	s_waitcnt vmcnt(6)
	s_barrier
	v_mfma_f32_16x16x32_bf16 v[56:59], v[196:199], v[164:167], v[56:59]
	v_mfma_f32_16x16x32_bf16 v[48:51], v[208:211], v[164:167], v[48:51]
	v_mfma_f32_16x16x32_bf16 v[40:43], v[196:199], v[172:175], v[40:43]
	v_mfma_f32_16x16x32_bf16 v[32:35], v[208:211], v[172:175], v[32:35]
	v_mfma_f32_16x16x32_bf16 v[24:27], v[196:199], v[180:183], v[24:27]
	v_mfma_f32_16x16x32_bf16 v[16:19], v[208:211], v[180:183], v[16:19]
	v_mfma_f32_16x16x32_bf16 v[8:11], v[196:199], v[188:191], v[8:11]
	v_mfma_f32_16x16x32_bf16 v[0:3], v[208:211], v[188:191], v[0:3]
	v_mfma_f32_16x16x32_bf16 v[56:59], v[200:203], v[168:171], v[56:59]
	v_mfma_f32_16x16x32_bf16 v[48:51], v[212:215], v[168:171], v[48:51]
	v_mfma_f32_16x16x32_bf16 v[40:43], v[200:203], v[176:179], v[40:43]
	v_mfma_f32_16x16x32_bf16 v[32:35], v[212:215], v[176:179], v[32:35]
	v_mfma_f32_16x16x32_bf16 v[24:27], v[200:203], v[184:187], v[24:27]
	v_mfma_f32_16x16x32_bf16 v[16:19], v[212:215], v[184:187], v[16:19]
	v_mfma_f32_16x16x32_bf16 v[8:11], v[200:203], v[192:195], v[8:11]
	v_mfma_f32_16x16x32_bf16 v[0:3], v[212:215], v[192:195], v[0:3]
	s_barrier
	s_add_i32 s59, s59, 2
	s_add_u32 s10, s10, 0x100
	s_addc_u32 s11, s11, 0
	s_add_u32 s57, s57, 0x100
	s_addc_u32 s58, s58, 0
	s_cmp_gt_u32 s59, 29
	s_cbranch_scc0 .LBB0_1630
	s_lshl_b32 s10, s55, 8
	v_mov_b32_e32 v132, v206
	v_mul_f32_e32 v149, 0xbfb8aa3b, v125
	v_and_or_b32 v141, v132, 15, s10
	s_lshl_b32 s10, s56, 7
	s_ashr_i32 s11, s10, 31
	s_lshl_b64 s[10:11], s[10:11], 1
	v_ashrrev_i32_e32 v140, 2, v132
	s_add_u32 s10, s80, s10
	v_and_b32_e32 v140, 0xffffffc0, v140
	s_addc_u32 s11, s81, s11
	v_lshrrev_b32_e32 v148, 1, v132
	v_and_b32_e32 v132, 0xc0, v132
	v_add_u32_e32 v147, v141, v140
	v_lshl_add_u64 v[140:141], s[10:11], 0, v[132:133]
	v_and_b32_e32 v132, 24, v148
	v_mul_f32_e32 v148, 0xbfb8aa3b, v124
	v_exp_f32_e32 v148, v148
	v_exp_f32_e32 v149, v149
	v_lshl_add_u64 v[140:141], v[140:141], 0, v[132:133]
	v_mad_i64_i32 v[152:153], s[10:11], v147, s23, v[140:141]
	v_add_f32_e32 v132, 1.0, v148
	v_rcp_f32_e32 v148, v132
	v_add_f32_e32 v132, 1.0, v149
	v_mul_f32_e32 v149, 0xbfb8aa3b, v126
	v_exp_f32_e32 v150, v149
	v_mul_f32_e32 v149, 0xbfb8aa3b, v127
	v_exp_f32_e32 v151, v149
	v_rcp_f32_e32 v149, v132
	v_add_f32_e32 v132, 1.0, v150
	v_rcp_f32_e32 v150, v132
	v_add_f32_e32 v132, 1.0, v151
	v_rcp_f32_e32 v151, v132
	v_pk_mul_f32 v[124:125], v[124:125], v[148:149]
	s_and_b64 vcc, exec, s[4:5]
	v_pk_mul_f32 v[120:121], v[124:125], v[120:121]
	v_pk_mul_f32 v[124:125], v[126:127], v[150:151]
	v_cvt_pk_bf16_f32 v120, v120, v121
	v_mul_f32_e32 v121, 0xbfb8aa3b, v116
	v_pk_mul_f32 v[122:123], v[124:125], v[122:123]
	v_exp_f32_e32 v124, v121
	v_mul_f32_e32 v121, 0xbfb8aa3b, v117
	v_exp_f32_e32 v125, v121
	v_cvt_pk_bf16_f32 v121, v122, v123
	v_add_f32_e32 v122, 1.0, v124
	v_mul_f32_e32 v124, 0xbfb8aa3b, v118
	v_add_f32_e32 v123, 1.0, v125
	v_mul_f32_e32 v125, 0xbfb8aa3b, v119
	v_exp_f32_e32 v124, v124
	v_exp_f32_e32 v125, v125
	v_rcp_f32_e32 v122, v122
	v_rcp_f32_e32 v123, v123
	v_add_f32_e32 v124, 1.0, v124
	v_add_f32_e32 v125, 1.0, v125
	v_rcp_f32_e32 v124, v124
	v_rcp_f32_e32 v125, v125
	v_pk_mul_f32 v[116:117], v[116:117], v[122:123]
	s_mov_b32 s56, s53
	v_pk_mul_f32 v[112:113], v[116:117], v[112:113]
	v_pk_mul_f32 v[116:117], v[118:119], v[124:125]
	v_cvt_pk_bf16_f32 v112, v112, v113
	v_pk_mul_f32 v[114:115], v[116:117], v[114:115]
	v_or_b32_e32 v116, 16, v147
	v_cvt_pk_bf16_f32 v113, v114, v115
	global_store_dwordx2 v[152:153], v[112:113], off offset:32
	v_mul_f32_e32 v112, 0xbfb8aa3b, v108
	v_mul_f32_e32 v113, 0xbfb8aa3b, v109
	v_exp_f32_e32 v112, v112
	v_exp_f32_e32 v113, v113
	v_mul_f32_e32 v114, 0xbfb8aa3b, v110
	v_mul_f32_e32 v115, 0xbfb8aa3b, v111
	v_exp_f32_e32 v114, v114
	v_exp_f32_e32 v115, v115
	v_add_f32_e32 v112, 1.0, v112
	v_add_f32_e32 v113, 1.0, v113
	v_rcp_f32_e32 v112, v112
	v_rcp_f32_e32 v113, v113
	v_add_f32_e32 v114, 1.0, v114
	v_add_f32_e32 v115, 1.0, v115
	v_rcp_f32_e32 v114, v114
	v_rcp_f32_e32 v115, v115
	v_pk_mul_f32 v[108:109], v[108:109], v[112:113]
	v_mad_i64_i32 v[116:117], s[10:11], v116, s23, v[140:141]
	v_pk_mul_f32 v[104:105], v[108:109], v[104:105]
	v_pk_mul_f32 v[108:109], v[110:111], v[114:115]
; DI float silu_f(float g) { return g * __builtin_amdgcn_rcpf(1.f + __builtin_amdgcn_exp2f(-LOG2E * g)); }
; DI void epi_swiglu(const Acc& acc, int brow, int pn, bf16_t* hid) {
;     ...
;         for (int m = 0; m < 4; ++m) {
;             const int r = brow + ai * 128 + wr * 64 + m * 16 + fr;
;             bf16_t* rp = hid + (size_t)r * FF + pn * 128 + wc * 32 + fq * 4;
; #pragma unroll
;             for (int n = 0; n < 2; ++n) {
;                 const f32x4 g = acc[ai][0][m][n], u = acc[ai][1][m][n];
;                 float o[4];
; #pragma unroll
;                 for (int j = 0; j < 4; ++j) o[j] = silu_f(g[j]) * u[j];
;                 st4(rp + n * 16, o[0], o[1], o[2], o[3]);
;             }
	v_cvt_pk_bf16_f32 v104, v104, v105
	v_mul_f32_e32 v105, 0xbfb8aa3b, v100
	v_pk_mul_f32 v[106:107], v[108:109], v[106:107]
	v_exp_f32_e32 v108, v105
	v_mul_f32_e32 v105, 0xbfb8aa3b, v101
	v_exp_f32_e32 v109, v105
	v_cvt_pk_bf16_f32 v105, v106, v107
	v_add_f32_e32 v106, 1.0, v108
	v_mul_f32_e32 v108, 0xbfb8aa3b, v102
	v_add_f32_e32 v107, 1.0, v109
	v_mul_f32_e32 v109, 0xbfb8aa3b, v103
	v_exp_f32_e32 v108, v108
	v_exp_f32_e32 v109, v109
	v_rcp_f32_e32 v106, v106
	v_rcp_f32_e32 v107, v107
	v_add_f32_e32 v108, 1.0, v108
	v_add_f32_e32 v109, 1.0, v109
	v_rcp_f32_e32 v108, v108
	v_rcp_f32_e32 v109, v109
	v_pk_mul_f32 v[100:101], v[100:101], v[106:107]
	s_mov_b32 s55, s54
	v_pk_mul_f32 v[96:97], v[100:101], v[96:97]
	v_pk_mul_f32 v[100:101], v[102:103], v[108:109]
	v_cvt_pk_bf16_f32 v96, v96, v97
	v_pk_mul_f32 v[98:99], v[100:101], v[98:99]
	v_or_b32_e32 v100, 32, v147
	v_cvt_pk_bf16_f32 v97, v98, v99
	global_store_dwordx2 v[116:117], v[96:97], off offset:32
	v_mul_f32_e32 v96, 0xbfb8aa3b, v92
	v_mul_f32_e32 v97, 0xbfb8aa3b, v93
	v_exp_f32_e32 v96, v96
	v_exp_f32_e32 v97, v97
	v_mul_f32_e32 v98, 0xbfb8aa3b, v94
	v_mul_f32_e32 v99, 0xbfb8aa3b, v95
	v_exp_f32_e32 v98, v98
	v_exp_f32_e32 v99, v99
	v_add_f32_e32 v96, 1.0, v96
	v_add_f32_e32 v97, 1.0, v97
	v_rcp_f32_e32 v96, v96
	v_rcp_f32_e32 v97, v97
	v_add_f32_e32 v98, 1.0, v98
	v_add_f32_e32 v99, 1.0, v99
	v_rcp_f32_e32 v98, v98
	v_rcp_f32_e32 v99, v99
	v_pk_mul_f32 v[92:93], v[92:93], v[96:97]
	v_mad_i64_i32 v[100:101], s[10:11], v100, s23, v[140:141]
	v_pk_mul_f32 v[88:89], v[92:93], v[88:89]
	v_pk_mul_f32 v[92:93], v[94:95], v[98:99]
	v_cvt_pk_bf16_f32 v88, v88, v89
	v_mul_f32_e32 v89, 0xbfb8aa3b, v84
	v_pk_mul_f32 v[90:91], v[92:93], v[90:91]
	v_exp_f32_e32 v92, v89
	v_mul_f32_e32 v89, 0xbfb8aa3b, v85
	v_exp_f32_e32 v93, v89
	v_cvt_pk_bf16_f32 v89, v90, v91
	v_add_f32_e32 v90, 1.0, v92
	v_mul_f32_e32 v92, 0xbfb8aa3b, v86
	v_add_f32_e32 v91, 1.0, v93
	v_mul_f32_e32 v93, 0xbfb8aa3b, v87
	v_exp_f32_e32 v92, v92
	v_exp_f32_e32 v93, v93
	v_rcp_f32_e32 v90, v90
	v_rcp_f32_e32 v91, v91
	v_add_f32_e32 v92, 1.0, v92
	v_add_f32_e32 v93, 1.0, v93
	v_rcp_f32_e32 v92, v92
	v_rcp_f32_e32 v93, v93
	v_pk_mul_f32 v[84:85], v[84:85], v[90:91]
	s_mov_b64 s[12:13], s[8:9]
	v_pk_mul_f32 v[80:81], v[84:85], v[80:81]
	v_pk_mul_f32 v[84:85], v[86:87], v[92:93]
	v_cvt_pk_bf16_f32 v80, v80, v81
	v_pk_mul_f32 v[82:83], v[84:85], v[82:83]
	v_or_b32_e32 v84, 48, v147
	v_cvt_pk_bf16_f32 v81, v82, v83
	global_store_dwordx2 v[100:101], v[80:81], off offset:32
	v_mul_f32_e32 v80, 0xbfb8aa3b, v76
	v_mul_f32_e32 v81, 0xbfb8aa3b, v77
	v_exp_f32_e32 v80, v80
	v_exp_f32_e32 v81, v81
	v_mul_f32_e32 v82, 0xbfb8aa3b, v78
	v_mul_f32_e32 v83, 0xbfb8aa3b, v79
	v_exp_f32_e32 v82, v82
	v_exp_f32_e32 v83, v83
	v_add_f32_e32 v80, 1.0, v80
	v_add_f32_e32 v81, 1.0, v81
	v_rcp_f32_e32 v80, v80
	v_rcp_f32_e32 v81, v81
	v_add_f32_e32 v82, 1.0, v82
	v_add_f32_e32 v83, 1.0, v83
	v_rcp_f32_e32 v82, v82
	v_rcp_f32_e32 v83, v83
	v_pk_mul_f32 v[76:77], v[76:77], v[80:81]
	v_mad_i64_i32 v[84:85], s[10:11], v84, s23, v[140:141]
	v_pk_mul_f32 v[72:73], v[76:77], v[72:73]
	v_pk_mul_f32 v[76:77], v[78:79], v[82:83]
	v_cvt_pk_bf16_f32 v72, v72, v73
	v_mul_f32_e32 v73, 0xbfb8aa3b, v68
	v_pk_mul_f32 v[74:75], v[76:77], v[74:75]
	v_exp_f32_e32 v76, v73
	v_mul_f32_e32 v73, 0xbfb8aa3b, v69
	v_exp_f32_e32 v77, v73
	v_cvt_pk_bf16_f32 v73, v74, v75
	v_add_f32_e32 v74, 1.0, v76
	v_mul_f32_e32 v76, 0xbfb8aa3b, v70
	v_add_f32_e32 v75, 1.0, v77
	v_mul_f32_e32 v77, 0xbfb8aa3b, v71
	v_exp_f32_e32 v76, v76
	v_exp_f32_e32 v77, v77
	v_rcp_f32_e32 v74, v74
	v_rcp_f32_e32 v75, v75
	v_add_f32_e32 v76, 1.0, v76
	v_add_f32_e32 v77, 1.0, v77
	v_rcp_f32_e32 v76, v76
	v_rcp_f32_e32 v77, v77
	v_pk_mul_f32 v[68:69], v[68:69], v[74:75]
	global_store_dwordx2 v[152:153], v[120:121], off
	v_pk_mul_f32 v[64:65], v[68:69], v[64:65]
	v_pk_mul_f32 v[68:69], v[70:71], v[76:77]
	v_cvt_pk_bf16_f32 v64, v64, v65
	v_pk_mul_f32 v[66:67], v[68:69], v[66:67]
	v_add_u32_e32 v68, 0x80, v147
	v_cvt_pk_bf16_f32 v65, v66, v67
	global_store_dwordx2 v[84:85], v[64:65], off offset:32
	v_mul_f32_e32 v64, 0xbfb8aa3b, v60
	v_mul_f32_e32 v65, 0xbfb8aa3b, v61
	v_exp_f32_e32 v64, v64
	v_exp_f32_e32 v65, v65
	v_mul_f32_e32 v66, 0xbfb8aa3b, v62
	v_mul_f32_e32 v67, 0xbfb8aa3b, v63
	v_exp_f32_e32 v66, v66
	v_exp_f32_e32 v67, v67
	v_add_f32_e32 v64, 1.0, v64
	v_add_f32_e32 v65, 1.0, v65
	v_rcp_f32_e32 v64, v64
	v_rcp_f32_e32 v65, v65
	v_add_f32_e32 v66, 1.0, v66
	v_add_f32_e32 v67, 1.0, v67
	v_rcp_f32_e32 v66, v66
	v_rcp_f32_e32 v67, v67
	v_pk_mul_f32 v[60:61], v[60:61], v[64:65]
	v_mad_i64_i32 v[68:69], s[10:11], v68, s23, v[140:141]
	v_pk_mul_f32 v[56:57], v[60:61], v[56:57]
	v_pk_mul_f32 v[60:61], v[62:63], v[66:67]
	v_cvt_pk_bf16_f32 v56, v56, v57
	v_mul_f32_e32 v57, 0xbfb8aa3b, v52
	v_pk_mul_f32 v[58:59], v[60:61], v[58:59]
	v_exp_f32_e32 v60, v57
	v_mul_f32_e32 v57, 0xbfb8aa3b, v53
	v_exp_f32_e32 v61, v57
	v_cvt_pk_bf16_f32 v57, v58, v59
	v_add_f32_e32 v58, 1.0, v60
	v_mul_f32_e32 v60, 0xbfb8aa3b, v54
	v_add_f32_e32 v59, 1.0, v61
	v_mul_f32_e32 v61, 0xbfb8aa3b, v55
	v_exp_f32_e32 v60, v60
	v_exp_f32_e32 v61, v61
	v_rcp_f32_e32 v58, v58
	v_rcp_f32_e32 v59, v59
	v_add_f32_e32 v60, 1.0, v60
	v_add_f32_e32 v61, 1.0, v61
	v_rcp_f32_e32 v60, v60
	v_rcp_f32_e32 v61, v61
; DI float silu_f(float g) { return g * __builtin_amdgcn_rcpf(1.f + __builtin_amdgcn_exp2f(-LOG2E * g)); }
; #define WAIT_V(n) asm volatile("s_waitcnt vmcnt(" #n ")" ::: "memory")
; #define BAR __builtin_amdgcn_s_barrier()
; template <class Get, class Epi>
; DI void gemm_stream(LAS unsigned char* lds, const int K, const int ld, Get get, Epi epi) {
;     ...
;         epi(acc, cur);
;         if (!has_next) break;
;         ZERO_ACC;
;         cur = nxt; cA = nA; cB = nB; ++ui;
;     }
;     WAIT_V(0);
;     if (wr == 0) BAR;
; DI void epi_swiglu(const Acc& acc, int brow, int pn, bf16_t* hid) {
;     ...
;             for (int n = 0; n < 2; ++n) {
;                 const f32x4 g = acc[ai][0][m][n], u = acc[ai][1][m][n];
;                 float o[4];
; #pragma unroll
;                 for (int j = 0; j < 4; ++j) o[j] = silu_f(g[j]) * u[j];
;                 st4(rp + n * 16, o[0], o[1], o[2], o[3]);
;             }
	v_pk_mul_f32 v[52:53], v[52:53], v[58:59]
	global_store_dwordx2 v[116:117], v[104:105], off
	v_pk_mul_f32 v[48:49], v[52:53], v[48:49]
	v_pk_mul_f32 v[52:53], v[54:55], v[60:61]
	v_cvt_pk_bf16_f32 v48, v48, v49
	v_pk_mul_f32 v[50:51], v[52:53], v[50:51]
	v_add_u32_e32 v52, 0x90, v147
	v_cvt_pk_bf16_f32 v49, v50, v51
	global_store_dwordx2 v[68:69], v[48:49], off offset:32
	v_mul_f32_e32 v48, 0xbfb8aa3b, v44
	v_mul_f32_e32 v49, 0xbfb8aa3b, v45
	v_exp_f32_e32 v48, v48
	v_exp_f32_e32 v49, v49
	v_mul_f32_e32 v50, 0xbfb8aa3b, v46
	v_mul_f32_e32 v51, 0xbfb8aa3b, v47
	v_exp_f32_e32 v50, v50
	v_exp_f32_e32 v51, v51
	v_add_f32_e32 v48, 1.0, v48
	v_add_f32_e32 v49, 1.0, v49
	v_rcp_f32_e32 v48, v48
	v_rcp_f32_e32 v49, v49
	v_add_f32_e32 v50, 1.0, v50
	v_add_f32_e32 v51, 1.0, v51
	v_rcp_f32_e32 v50, v50
	v_rcp_f32_e32 v51, v51
	v_pk_mul_f32 v[44:45], v[44:45], v[48:49]
	v_mad_i64_i32 v[52:53], s[10:11], v52, s23, v[140:141]
	v_pk_mul_f32 v[40:41], v[44:45], v[40:41]
	v_pk_mul_f32 v[44:45], v[46:47], v[50:51]
	v_cvt_pk_bf16_f32 v40, v40, v41
	v_mul_f32_e32 v41, 0xbfb8aa3b, v36
	v_pk_mul_f32 v[42:43], v[44:45], v[42:43]
	v_exp_f32_e32 v44, v41
	v_mul_f32_e32 v41, 0xbfb8aa3b, v37
	v_exp_f32_e32 v45, v41
	v_cvt_pk_bf16_f32 v41, v42, v43
	v_add_f32_e32 v42, 1.0, v44
	v_mul_f32_e32 v44, 0xbfb8aa3b, v38
	v_add_f32_e32 v43, 1.0, v45
	v_mul_f32_e32 v45, 0xbfb8aa3b, v39
	v_exp_f32_e32 v44, v44
	v_exp_f32_e32 v45, v45
	v_rcp_f32_e32 v42, v42
	v_rcp_f32_e32 v43, v43
	v_add_f32_e32 v44, 1.0, v44
	v_add_f32_e32 v45, 1.0, v45
	v_rcp_f32_e32 v44, v44
	v_rcp_f32_e32 v45, v45
	v_pk_mul_f32 v[36:37], v[36:37], v[42:43]
	global_store_dwordx2 v[100:101], v[88:89], off
	v_pk_mul_f32 v[32:33], v[36:37], v[32:33]
	v_pk_mul_f32 v[36:37], v[38:39], v[44:45]
	v_cvt_pk_bf16_f32 v32, v32, v33
	v_pk_mul_f32 v[34:35], v[36:37], v[34:35]
	v_add_u32_e32 v36, 0xa0, v147
	v_cvt_pk_bf16_f32 v33, v34, v35
	global_store_dwordx2 v[52:53], v[32:33], off offset:32
	v_mul_f32_e32 v32, 0xbfb8aa3b, v28
	v_mul_f32_e32 v33, 0xbfb8aa3b, v29
	v_exp_f32_e32 v32, v32
	v_exp_f32_e32 v33, v33
	v_mul_f32_e32 v34, 0xbfb8aa3b, v30
	v_mul_f32_e32 v35, 0xbfb8aa3b, v31
	v_exp_f32_e32 v34, v34
	v_exp_f32_e32 v35, v35
	v_add_f32_e32 v32, 1.0, v32
	v_add_f32_e32 v33, 1.0, v33
	v_rcp_f32_e32 v32, v32
	v_rcp_f32_e32 v33, v33
	v_add_f32_e32 v34, 1.0, v34
	v_add_f32_e32 v35, 1.0, v35
	v_rcp_f32_e32 v34, v34
	v_rcp_f32_e32 v35, v35
	v_pk_mul_f32 v[28:29], v[28:29], v[32:33]
	v_mad_i64_i32 v[36:37], s[10:11], v36, s23, v[140:141]
	v_pk_mul_f32 v[24:25], v[28:29], v[24:25]
	v_pk_mul_f32 v[28:29], v[30:31], v[34:35]
	v_cvt_pk_bf16_f32 v24, v24, v25
	v_mul_f32_e32 v25, 0xbfb8aa3b, v20
	v_pk_mul_f32 v[26:27], v[28:29], v[26:27]
	v_exp_f32_e32 v28, v25
	v_mul_f32_e32 v25, 0xbfb8aa3b, v21
	v_exp_f32_e32 v29, v25
	v_cvt_pk_bf16_f32 v25, v26, v27
	v_add_f32_e32 v26, 1.0, v28
	v_mul_f32_e32 v28, 0xbfb8aa3b, v22
	v_add_f32_e32 v27, 1.0, v29
	v_mul_f32_e32 v29, 0xbfb8aa3b, v23
	v_exp_f32_e32 v28, v28
	v_exp_f32_e32 v29, v29
	v_rcp_f32_e32 v26, v26
	v_rcp_f32_e32 v27, v27
	v_add_f32_e32 v28, 1.0, v28
	v_add_f32_e32 v29, 1.0, v29
	v_rcp_f32_e32 v28, v28
	v_rcp_f32_e32 v29, v29
	v_pk_mul_f32 v[20:21], v[20:21], v[26:27]
	global_store_dwordx2 v[84:85], v[72:73], off
	v_pk_mul_f32 v[16:17], v[20:21], v[16:17]
	v_pk_mul_f32 v[20:21], v[22:23], v[28:29]
	v_cvt_pk_bf16_f32 v16, v16, v17
	v_pk_mul_f32 v[18:19], v[20:21], v[18:19]
	v_add_u32_e32 v20, 0xb0, v147
	v_cvt_pk_bf16_f32 v17, v18, v19
	global_store_dwordx2 v[36:37], v[16:17], off offset:32
	v_mul_f32_e32 v16, 0xbfb8aa3b, v12
	v_mul_f32_e32 v17, 0xbfb8aa3b, v13
	v_exp_f32_e32 v16, v16
	v_exp_f32_e32 v17, v17
	v_mul_f32_e32 v18, 0xbfb8aa3b, v14
	v_mul_f32_e32 v19, 0xbfb8aa3b, v15
	v_exp_f32_e32 v18, v18
	v_exp_f32_e32 v19, v19
	v_add_f32_e32 v16, 1.0, v16
	v_add_f32_e32 v17, 1.0, v17
	v_rcp_f32_e32 v16, v16
	v_rcp_f32_e32 v17, v17
	v_add_f32_e32 v18, 1.0, v18
	v_add_f32_e32 v19, 1.0, v19
	v_rcp_f32_e32 v18, v18
	v_rcp_f32_e32 v19, v19
	v_pk_mul_f32 v[12:13], v[12:13], v[16:17]
	v_mad_i64_i32 v[20:21], s[10:11], v20, s23, v[140:141]
	v_pk_mul_f32 v[8:9], v[12:13], v[8:9]
	v_pk_mul_f32 v[12:13], v[14:15], v[18:19]
	v_cvt_pk_bf16_f32 v8, v8, v9
	v_mul_f32_e32 v9, 0xbfb8aa3b, v4
	v_pk_mul_f32 v[10:11], v[12:13], v[10:11]
	v_exp_f32_e32 v12, v9
	v_mul_f32_e32 v9, 0xbfb8aa3b, v5
	v_exp_f32_e32 v13, v9
	v_cvt_pk_bf16_f32 v9, v10, v11
	v_add_f32_e32 v10, 1.0, v12
	v_mul_f32_e32 v12, 0xbfb8aa3b, v6
	v_add_f32_e32 v11, 1.0, v13
	v_mul_f32_e32 v13, 0xbfb8aa3b, v7
	v_exp_f32_e32 v12, v12
	v_exp_f32_e32 v13, v13
	v_rcp_f32_e32 v10, v10
	v_rcp_f32_e32 v11, v11
	v_add_f32_e32 v12, 1.0, v12
	v_add_f32_e32 v13, 1.0, v13
	v_rcp_f32_e32 v12, v12
	v_rcp_f32_e32 v13, v13
	v_pk_mul_f32 v[4:5], v[4:5], v[10:11]
	s_mov_b64 s[10:11], s[6:7]
	v_pk_mul_f32 v[0:1], v[4:5], v[0:1]
	v_pk_mul_f32 v[4:5], v[6:7], v[12:13]
	v_cvt_pk_bf16_f32 v0, v0, v1
	v_pk_mul_f32 v[2:3], v[4:5], v[2:3]
	global_store_dwordx2 v[68:69], v[56:57], off
	v_cvt_pk_bf16_f32 v1, v2, v3
	global_store_dwordx2 v[52:53], v[40:41], off
	global_store_dwordx2 v[36:37], v[24:25], off
	global_store_dwordx2 v[20:21], v[8:9], off
	global_store_dwordx2 v[20:21], v[0:1], off offset:32
	s_cbranch_vccz .LBB0_1627
	s_waitcnt vmcnt(0)
	s_cmpk_gt_u32 s2, 0xff
	s_cbranch_scc1 .LBB0_1634
	s_barrier

; #define WAIT_V(n) asm volatile("s_waitcnt vmcnt(" #n ")" ::: "memory")
; #define WAIT_L(n) asm volatile("s_waitcnt lgkmcnt(" #n ")" ::: "memory")
; #define BAR __builtin_amdgcn_s_barrier()
; #define SCHED __builtin_amdgcn_sched_barrier(0)
; template <class Get, class Epi>
; DI void gemm_stream(LAS unsigned char* lds, const int K, const int ld, Get get, Epi epi) {
;     ...
;             LDB(B0, 0, 0); SCHED; LDA(At, 0, 0); STAGE(SAo(1, 1), a1 + hstep);
;             WAIT_L(8); BAR; WAIT_L(0); MMA(0, 0, At, B0); BAR; SCHED;
;             LDB(B1, 0, 1); STAGE(SBo(0, 0), b2);
;             BAR; WAIT_L(0); MMA(0, 1, At, B1); BAR;
;             LDA(At, 0, 1); STAGE(SAo(0, 0), a2);
;             BAR; WAIT_L(0); MMA(1, 0, At, B0); BAR; SCHED;
;             STAGE(SBo(0, 1), b2 + hstep);
;             WAIT_V(6); BAR; MMA(1, 1, At, B1); BAR;
.LBB0_1697:
	ds_read_b128 v[128:131], v199
	ds_read_b128 v[132:135], v199 offset:1024
	ds_read_b128 v[136:139], v199 offset:2048
	ds_read_b128 v[140:143], v199 offset:3072
	s_add_u32 s8, s6, 0x100
	s_addc_u32 s9, s7, 0
	s_cmpk_eq_i32 s16, 0x54
	s_cselect_b32 s13, s39, s9
	s_cselect_b32 s12, s38, s8
	s_cselect_b32 s11, s41, s15
	s_cselect_b32 s10, s40, s14
	s_mov_b32 m0, s63
	v_lshl_add_u64 v[186:187], s[6:7], 0, v[168:169]
	ds_read_b128 v[144:147], v200
	ds_read_b128 v[148:151], v200 offset:1024
	ds_read_b128 v[152:155], v200 offset:2048
	ds_read_b128 v[156:159], v200 offset:3072
	ds_read_b128 v[160:163], v200 offset:4096
	ds_read_b128 v[174:177], v200 offset:5120
	ds_read_b128 v[178:181], v200 offset:6144
	ds_read_b128 v[182:185], v200 offset:7168
	global_load_lds_dwordx4 v[186:187], off
	v_lshl_add_u64 v[186:187], s[6:7], 0, v[170:171]
	s_mov_b32 m0, s74
	s_nop 0
	global_load_lds_dwordx4 v[186:187], off
	s_waitcnt lgkmcnt(8)
	s_barrier
	s_waitcnt lgkmcnt(0)
	v_mfma_f32_16x16x32_bf16 v[124:127], v[128:131], v[144:147], v[124:127]
	v_mfma_f32_16x16x32_bf16 v[92:95], v[136:139], v[144:147], v[92:95]
	v_mfma_f32_16x16x32_bf16 v[120:123], v[128:131], v[152:155], v[120:123]
	v_mfma_f32_16x16x32_bf16 v[88:91], v[136:139], v[152:155], v[88:91]
	v_mfma_f32_16x16x32_bf16 v[116:119], v[128:131], v[160:163], v[116:119]
	v_mfma_f32_16x16x32_bf16 v[84:87], v[136:139], v[160:163], v[84:87]
	v_mfma_f32_16x16x32_bf16 v[112:115], v[128:131], v[178:181], v[112:115]
	v_mfma_f32_16x16x32_bf16 v[80:83], v[136:139], v[178:181], v[80:83]
	v_mfma_f32_16x16x32_bf16 v[124:127], v[132:135], v[148:151], v[124:127]
	v_mfma_f32_16x16x32_bf16 v[92:95], v[140:143], v[148:151], v[92:95]
	v_mfma_f32_16x16x32_bf16 v[120:123], v[132:135], v[156:159], v[120:123]
	v_mfma_f32_16x16x32_bf16 v[88:91], v[140:143], v[156:159], v[88:91]
	v_mfma_f32_16x16x32_bf16 v[116:119], v[132:135], v[174:177], v[116:119]
	v_mfma_f32_16x16x32_bf16 v[84:87], v[140:143], v[174:177], v[84:87]
	v_mfma_f32_16x16x32_bf16 v[112:115], v[132:135], v[182:185], v[112:115]
	v_mfma_f32_16x16x32_bf16 v[80:83], v[140:143], v[182:185], v[80:83]
	s_barrier
	s_mov_b32 m0, s75
	v_lshl_add_u64 v[208:209], s[10:11], 0, v[164:165]
	ds_read_b128 v[186:189], v201
	ds_read_b128 v[190:193], v201 offset:1024
	ds_read_b128 v[194:197], v201 offset:2048
	ds_read_b128 v[202:205], v201 offset:3072
	global_load_lds_dwordx4 v[208:209], off
	v_lshl_add_u64 v[210:211], s[10:11], 0, v[166:167]
	s_mov_b32 m0, s76
	s_nop 0
	global_load_lds_dwordx4 v[210:211], off
	s_barrier
	s_waitcnt lgkmcnt(0)
	v_mfma_f32_16x16x32_bf16 v[60:63], v[186:189], v[144:147], v[60:63]
	v_mfma_f32_16x16x32_bf16 v[28:31], v[194:197], v[144:147], v[28:31]
	v_mfma_f32_16x16x32_bf16 v[56:59], v[186:189], v[152:155], v[56:59]
	v_mfma_f32_16x16x32_bf16 v[24:27], v[194:197], v[152:155], v[24:27]
	v_mfma_f32_16x16x32_bf16 v[52:55], v[186:189], v[160:163], v[52:55]
	v_mfma_f32_16x16x32_bf16 v[20:23], v[194:197], v[160:163], v[20:23]
	v_mfma_f32_16x16x32_bf16 v[48:51], v[186:189], v[178:181], v[48:51]
	v_mfma_f32_16x16x32_bf16 v[16:19], v[194:197], v[178:181], v[16:19]
	v_mfma_f32_16x16x32_bf16 v[60:63], v[190:193], v[148:151], v[60:63]
	v_mfma_f32_16x16x32_bf16 v[28:31], v[202:205], v[148:151], v[28:31]
	v_mfma_f32_16x16x32_bf16 v[56:59], v[190:193], v[156:159], v[56:59]
	v_mfma_f32_16x16x32_bf16 v[24:27], v[202:205], v[156:159], v[24:27]
	v_mfma_f32_16x16x32_bf16 v[52:55], v[190:193], v[174:177], v[52:55]
	v_mfma_f32_16x16x32_bf16 v[20:23], v[202:205], v[174:177], v[20:23]
	v_mfma_f32_16x16x32_bf16 v[48:51], v[190:193], v[182:185], v[48:51]
	v_mfma_f32_16x16x32_bf16 v[16:19], v[202:205], v[182:185], v[16:19]
	s_barrier
	s_mov_b32 m0, s23
	v_lshl_add_u64 v[212:213], s[12:13], 0, v[164:165]
	ds_read_b128 v[144:147], v200 offset:16384
	ds_read_b128 v[148:151], v200 offset:17408
	ds_read_b128 v[152:155], v200 offset:18432
	ds_read_b128 v[156:159], v200 offset:19456
	ds_read_b128 v[160:163], v200 offset:20480
	ds_read_b128 v[174:177], v200 offset:21504
	ds_read_b128 v[178:181], v200 offset:22528
	ds_read_b128 v[182:185], v200 offset:23552
	global_load_lds_dwordx4 v[212:213], off
	v_lshl_add_u64 v[214:215], s[12:13], 0, v[166:167]
	s_mov_b32 m0, s35
	s_nop 0
	global_load_lds_dwordx4 v[214:215], off
	s_barrier
	s_waitcnt lgkmcnt(0)
	v_mfma_f32_16x16x32_bf16 v[108:111], v[128:131], v[144:147], v[108:111]
	v_mfma_f32_16x16x32_bf16 v[76:79], v[136:139], v[144:147], v[76:79]
	v_mfma_f32_16x16x32_bf16 v[104:107], v[128:131], v[152:155], v[104:107]
	v_mfma_f32_16x16x32_bf16 v[72:75], v[136:139], v[152:155], v[72:75]
	v_mfma_f32_16x16x32_bf16 v[100:103], v[128:131], v[160:163], v[100:103]
	v_mfma_f32_16x16x32_bf16 v[68:71], v[136:139], v[160:163], v[68:71]
	v_mfma_f32_16x16x32_bf16 v[96:99], v[128:131], v[178:181], v[96:99]
	v_mfma_f32_16x16x32_bf16 v[64:67], v[136:139], v[178:181], v[64:67]
	v_mfma_f32_16x16x32_bf16 v[108:111], v[132:135], v[148:151], v[108:111]
	v_mfma_f32_16x16x32_bf16 v[76:79], v[140:143], v[148:151], v[76:79]
	v_mfma_f32_16x16x32_bf16 v[104:107], v[132:135], v[156:159], v[104:107]
	v_mfma_f32_16x16x32_bf16 v[72:75], v[140:143], v[156:159], v[72:75]
	v_mfma_f32_16x16x32_bf16 v[100:103], v[132:135], v[174:177], v[100:103]
	v_mfma_f32_16x16x32_bf16 v[68:71], v[140:143], v[174:177], v[68:71]
	v_mfma_f32_16x16x32_bf16 v[96:99], v[132:135], v[182:185], v[96:99]
	v_mfma_f32_16x16x32_bf16 v[64:67], v[140:143], v[182:185], v[64:67]
	s_barrier
	s_add_u32 s6, s10, 0x160000
	s_addc_u32 s7, s11, 0
	s_mov_b32 m0, s77
	v_lshl_add_u64 v[128:129], s[6:7], 0, v[164:165]
	global_load_lds_dwordx4 v[128:129], off
	v_lshl_add_u64 v[128:129], s[6:7], 0, v[166:167]
	s_mov_b32 m0, s78
	s_nop 0
	global_load_lds_dwordx4 v[128:129], off
	s_waitcnt vmcnt(6)
	s_barrier
; #define WAIT_V(n) asm volatile("s_waitcnt vmcnt(" #n ")" ::: "memory")
; #define WAIT_L(n) asm volatile("s_waitcnt lgkmcnt(" #n ")" ::: "memory")
; #define BAR __builtin_amdgcn_s_barrier()
; #define SCHED __builtin_amdgcn_sched_barrier(0)
; template <class Get, class Epi>
; DI void gemm_stream(LAS unsigned char* lds, const int K, const int ld, Get get, Epi epi) {
;     ...
;             WAIT_V(6); BAR; MMA(1, 1, At, B1); BAR;
;             LDB(B0, 1, 0); SCHED; LDA(At, 1, 0); STAGE(SAo(0, 1), a2 + hstep);
;             WAIT_L(8); BAR; WAIT_L(0); MMA(0, 0, At, B0); BAR; SCHED;
;             LDB(B1, 1, 1); STAGE(SBo(1, 0), b3);
;             BAR; WAIT_L(0); MMA(0, 1, At, B1); BAR;
;             LDA(At, 1, 1); STAGE(SAo(1, 0), a3);
;             BAR; WAIT_L(0); MMA(1, 0, At, B0); BAR; SCHED;
	v_mfma_f32_16x16x32_bf16 v[44:47], v[186:189], v[144:147], v[44:47]
	v_mfma_f32_16x16x32_bf16 v[12:15], v[194:197], v[144:147], v[12:15]
	v_mfma_f32_16x16x32_bf16 v[40:43], v[186:189], v[152:155], v[40:43]
	v_mfma_f32_16x16x32_bf16 v[8:11], v[194:197], v[152:155], v[8:11]
	v_mfma_f32_16x16x32_bf16 v[36:39], v[186:189], v[160:163], v[36:39]
	v_mfma_f32_16x16x32_bf16 v[4:7], v[194:197], v[160:163], v[4:7]
	v_mfma_f32_16x16x32_bf16 v[32:35], v[186:189], v[178:181], v[32:35]
	v_mfma_f32_16x16x32_bf16 v[0:3], v[194:197], v[178:181], v[0:3]
	v_mfma_f32_16x16x32_bf16 v[44:47], v[190:193], v[148:151], v[44:47]
	v_mfma_f32_16x16x32_bf16 v[12:15], v[202:205], v[148:151], v[12:15]
	v_mfma_f32_16x16x32_bf16 v[40:43], v[190:193], v[156:159], v[40:43]
	v_mfma_f32_16x16x32_bf16 v[8:11], v[202:205], v[156:159], v[8:11]
	v_mfma_f32_16x16x32_bf16 v[36:39], v[190:193], v[174:177], v[36:39]
	v_mfma_f32_16x16x32_bf16 v[4:7], v[202:205], v[174:177], v[4:7]
	v_mfma_f32_16x16x32_bf16 v[32:35], v[190:193], v[182:185], v[32:35]
	v_mfma_f32_16x16x32_bf16 v[0:3], v[202:205], v[182:185], v[0:3]
	s_add_i32 s17, 16, 0x18000
	v_add_u32_e32 v140, s17, v198
	s_barrier
	ds_read_b128 v[128:131], v140
	ds_read_b128 v[132:135], v140 offset:1024
	ds_read_b128 v[136:139], v140 offset:2048
	ds_read_b128 v[140:143], v140 offset:3072
	s_add_u32 s6, s12, 0x160000
	s_addc_u32 s7, s13, 0
	s_mov_b32 m0, s54
	v_lshl_add_u64 v[186:187], s[6:7], 0, v[164:165]
	ds_read_b128 v[144:147], v200 offset:32768
	ds_read_b128 v[148:151], v200 offset:33792
	ds_read_b128 v[152:155], v200 offset:34816
	ds_read_b128 v[156:159], v200 offset:35840
	ds_read_b128 v[160:163], v200 offset:36864
	ds_read_b128 v[174:177], v200 offset:37888
	ds_read_b128 v[178:181], v200 offset:38912
	ds_read_b128 v[182:185], v200 offset:39936
	global_load_lds_dwordx4 v[186:187], off
	v_lshl_add_u64 v[186:187], s[6:7], 0, v[166:167]
	s_mov_b32 m0, s55
	s_nop 0
	global_load_lds_dwordx4 v[186:187], off
	s_waitcnt lgkmcnt(8)
	s_barrier
	s_waitcnt lgkmcnt(0)
	v_mfma_f32_16x16x32_bf16 v[124:127], v[128:131], v[144:147], v[124:127]
	v_mfma_f32_16x16x32_bf16 v[92:95], v[136:139], v[144:147], v[92:95]
	v_mfma_f32_16x16x32_bf16 v[120:123], v[128:131], v[152:155], v[120:123]
	v_mfma_f32_16x16x32_bf16 v[88:91], v[136:139], v[152:155], v[88:91]
	v_mfma_f32_16x16x32_bf16 v[116:119], v[128:131], v[160:163], v[116:119]
	v_mfma_f32_16x16x32_bf16 v[84:87], v[136:139], v[160:163], v[84:87]
	v_mfma_f32_16x16x32_bf16 v[112:115], v[128:131], v[178:181], v[112:115]
	v_mfma_f32_16x16x32_bf16 v[80:83], v[136:139], v[178:181], v[80:83]
	v_mfma_f32_16x16x32_bf16 v[124:127], v[132:135], v[148:151], v[124:127]
	v_mfma_f32_16x16x32_bf16 v[92:95], v[140:143], v[148:151], v[92:95]
	v_mfma_f32_16x16x32_bf16 v[120:123], v[132:135], v[156:159], v[120:123]
	v_mfma_f32_16x16x32_bf16 v[88:91], v[140:143], v[156:159], v[88:91]
	v_mfma_f32_16x16x32_bf16 v[116:119], v[132:135], v[174:177], v[116:119]
	v_mfma_f32_16x16x32_bf16 v[84:87], v[140:143], v[174:177], v[84:87]
	v_mfma_f32_16x16x32_bf16 v[112:115], v[132:135], v[182:185], v[112:115]
	v_mfma_f32_16x16x32_bf16 v[80:83], v[140:143], v[182:185], v[80:83]
	s_barrier
	s_add_i32 s12, 16, 0x1c000
	s_add_i32 s6, s17, s21
	v_add_u32_e32 v202, s12, v198
	v_lshl_add_u64 v[208:209], v[208:209], 0, s[0:1]
	s_mov_b32 m0, s6
	ds_read_b128 v[186:189], v202
	ds_read_b128 v[190:193], v202 offset:1024
	ds_read_b128 v[194:197], v202 offset:2048
	ds_read_b128 v[202:205], v202 offset:3072
	global_load_lds_dwordx4 v[208:209], off
	v_lshl_add_u64 v[208:209], v[210:211], 0, s[0:1]
	s_add_i32 m0, s6, 0x2000
	s_nop 0
	global_load_lds_dwordx4 v[208:209], off
	s_barrier
	s_waitcnt lgkmcnt(0)
	v_mfma_f32_16x16x32_bf16 v[60:63], v[186:189], v[144:147], v[60:63]
	v_mfma_f32_16x16x32_bf16 v[28:31], v[194:197], v[144:147], v[28:31]
	v_mfma_f32_16x16x32_bf16 v[56:59], v[186:189], v[152:155], v[56:59]
	v_mfma_f32_16x16x32_bf16 v[24:27], v[194:197], v[152:155], v[24:27]
	v_mfma_f32_16x16x32_bf16 v[52:55], v[186:189], v[160:163], v[52:55]
	v_mfma_f32_16x16x32_bf16 v[20:23], v[194:197], v[160:163], v[20:23]
	v_mfma_f32_16x16x32_bf16 v[48:51], v[186:189], v[178:181], v[48:51]
	v_mfma_f32_16x16x32_bf16 v[16:19], v[194:197], v[178:181], v[16:19]
	v_mfma_f32_16x16x32_bf16 v[60:63], v[190:193], v[148:151], v[60:63]
	v_mfma_f32_16x16x32_bf16 v[28:31], v[202:205], v[148:151], v[28:31]
	v_mfma_f32_16x16x32_bf16 v[56:59], v[190:193], v[156:159], v[56:59]
	v_mfma_f32_16x16x32_bf16 v[24:27], v[202:205], v[156:159], v[24:27]
	v_mfma_f32_16x16x32_bf16 v[52:55], v[190:193], v[174:177], v[52:55]
	v_mfma_f32_16x16x32_bf16 v[20:23], v[202:205], v[174:177], v[20:23]
	v_mfma_f32_16x16x32_bf16 v[48:51], v[190:193], v[182:185], v[48:51]
	v_mfma_f32_16x16x32_bf16 v[16:19], v[202:205], v[182:185], v[16:19]
	s_barrier
	s_mov_b32 m0, s56
	v_lshl_add_u64 v[208:209], v[212:213], 0, s[0:1]
	ds_read_b128 v[144:147], v200 offset:49152
	ds_read_b128 v[148:151], v200 offset:50176
	ds_read_b128 v[152:155], v200 offset:51200
	ds_read_b128 v[156:159], v200 offset:52224
	ds_read_b128 v[160:163], v200 offset:53248
	ds_read_b128 v[174:177], v200 offset:54272
	ds_read_b128 v[178:181], v200 offset:55296
	ds_read_b128 v[182:185], v200 offset:56320
	global_load_lds_dwordx4 v[208:209], off
	v_lshl_add_u64 v[208:209], v[214:215], 0, s[0:1]
	s_mov_b32 m0, s57
	s_nop 0
	global_load_lds_dwordx4 v[208:209], off
	s_barrier
; #define WAIT_V(n) asm volatile("s_waitcnt vmcnt(" #n ")" ::: "memory")
; #define WAIT_L(n) asm volatile("s_waitcnt lgkmcnt(" #n ")" ::: "memory")
; #define BAR __builtin_amdgcn_s_barrier()
; #define SCHED __builtin_amdgcn_sched_barrier(0)
; #define EPI_DONE do { } while (0)
; template <class Get, class Epi>
; DI void gemm_stream(LAS unsigned char* lds, const int K, const int ld, Get get, Epi epi) {
;     ...
;             BAR; WAIT_L(0); MMA(1, 0, At, B0); BAR; SCHED;
;             STAGE(SBo(1, 1), b3 + hstep);
;             WAIT_V(6); BAR; MMA(1, 1, At, B1); BAR;
; DI void epi_resid(const Acc& acc, const P& p, int brow, int bcol, int layer, int gch, bool from_input) {
;     EPI_IDX
;     const float* gate = modv(p, layer, brow, gch);
; #pragma unroll
;     for (int bj = 0; bj < 2; ++bj)
; #pragma unroll
;         for (int n = 0; n < 2; ++n) {
;             const int c0 = bcol + bj * 128 + wc * 32 + n * 16 + fq * 4;
;             const f32x4 g = *(const f32x4*)(gate + c0);
;             f32x4 xv[2][4];
; #pragma unroll
;             for (int ai = 0; ai < 2; ++ai)
; #pragma unroll
;                 for (int m = 0; m < 4; ++m) {
;                     const int r = brow + ai * 128 + wr * 64 + m * 16 + fr;
;                     const float* sp = (from_input ? inrow(p, r) : xrow(p, r)) + c0;
;                     xv[ai][m] = *(const f32x4*)sp;
;                 }
;             __builtin_amdgcn_sched_barrier(0);
; #pragma unroll
;             for (int ai = 0; ai < 2; ++ai)
; #pragma unroll
;                 for (int m = 0; m < 4; ++m) {
;                     const int r = brow + ai * 128 + wr * 64 + m * 16 + fr;
;                     *(f32x4*)(xrow(p, r) + c0) = xv[ai][m] + g * acc[ai][bj][m][n];
;                 }
;             __builtin_amdgcn_sched_barrier(0);
;         }
;     EPI_DONE;
; }
	s_waitcnt lgkmcnt(0)
	v_mfma_f32_16x16x32_bf16 v[108:111], v[128:131], v[144:147], v[108:111]
	v_mfma_f32_16x16x32_bf16 v[76:79], v[136:139], v[144:147], v[76:79]
	v_mfma_f32_16x16x32_bf16 v[104:107], v[128:131], v[152:155], v[104:107]
	v_mfma_f32_16x16x32_bf16 v[72:75], v[136:139], v[152:155], v[72:75]
	v_mfma_f32_16x16x32_bf16 v[100:103], v[128:131], v[160:163], v[100:103]
	v_mfma_f32_16x16x32_bf16 v[68:71], v[136:139], v[160:163], v[68:71]
	v_mfma_f32_16x16x32_bf16 v[96:99], v[128:131], v[178:181], v[96:99]
	v_mfma_f32_16x16x32_bf16 v[64:67], v[136:139], v[178:181], v[64:67]
	v_mfma_f32_16x16x32_bf16 v[108:111], v[132:135], v[148:151], v[108:111]
	v_mfma_f32_16x16x32_bf16 v[76:79], v[140:143], v[148:151], v[76:79]
	v_mfma_f32_16x16x32_bf16 v[104:107], v[132:135], v[156:159], v[104:107]
	v_mfma_f32_16x16x32_bf16 v[72:75], v[140:143], v[156:159], v[72:75]
	v_mfma_f32_16x16x32_bf16 v[100:103], v[132:135], v[174:177], v[100:103]
	v_mfma_f32_16x16x32_bf16 v[68:71], v[140:143], v[174:177], v[68:71]
	v_mfma_f32_16x16x32_bf16 v[96:99], v[132:135], v[182:185], v[96:99]
	v_mfma_f32_16x16x32_bf16 v[64:67], v[140:143], v[182:185], v[64:67]
	s_barrier
	s_add_u32 s6, s10, 0x160080
	s_addc_u32 s7, s11, 0
	s_add_i32 s10, s12, s21
	v_lshl_add_u64 v[128:129], s[6:7], 0, v[164:165]
	s_mov_b32 m0, s10
	s_nop 0
	global_load_lds_dwordx4 v[128:129], off
	v_lshl_add_u64 v[128:129], s[6:7], 0, v[166:167]
	s_add_i32 m0, s10, 0x2000
	s_nop 0
	global_load_lds_dwordx4 v[128:129], off
	s_waitcnt vmcnt(6)
	s_barrier
	v_mfma_f32_16x16x32_bf16 v[44:47], v[186:189], v[144:147], v[44:47]
	v_mfma_f32_16x16x32_bf16 v[12:15], v[194:197], v[144:147], v[12:15]
	v_mfma_f32_16x16x32_bf16 v[40:43], v[186:189], v[152:155], v[40:43]
	v_mfma_f32_16x16x32_bf16 v[8:11], v[194:197], v[152:155], v[8:11]
	v_mfma_f32_16x16x32_bf16 v[36:39], v[186:189], v[160:163], v[36:39]
	v_mfma_f32_16x16x32_bf16 v[4:7], v[194:197], v[160:163], v[4:7]
	v_mfma_f32_16x16x32_bf16 v[32:35], v[186:189], v[178:181], v[32:35]
	v_mfma_f32_16x16x32_bf16 v[0:3], v[194:197], v[178:181], v[0:3]
	v_mfma_f32_16x16x32_bf16 v[44:47], v[190:193], v[148:151], v[44:47]
	v_mfma_f32_16x16x32_bf16 v[12:15], v[202:205], v[148:151], v[12:15]
	v_mfma_f32_16x16x32_bf16 v[40:43], v[190:193], v[156:159], v[40:43]
	v_mfma_f32_16x16x32_bf16 v[8:11], v[202:205], v[156:159], v[8:11]
	v_mfma_f32_16x16x32_bf16 v[36:39], v[190:193], v[174:177], v[36:39]
	v_mfma_f32_16x16x32_bf16 v[4:7], v[202:205], v[174:177], v[4:7]
	v_mfma_f32_16x16x32_bf16 v[32:35], v[190:193], v[182:185], v[32:35]
	v_mfma_f32_16x16x32_bf16 v[0:3], v[202:205], v[182:185], v[0:3]
	s_barrier
	s_add_i32 s16, s16, 2
	s_add_u32 s14, s14, 0x100
	s_addc_u32 s15, s15, 0
	s_cmpk_gt_u32 s16, 0x55
	s_mov_b64 s[6:7], s[8:9]
	s_cbranch_scc0 .LBB0_1697
	s_lshl_b32 s12, s3, 21
	s_lshl_b32 s13, s2, 10
	s_lshr_b32 s16, s3, 4
	s_add_u32 s12, s12, s13
	s_mul_i32 s16, s16, 6
	s_add_i32 s16, s16, 5
	s_lshl_b32 s16, s16, 13
	s_add_u32 s16, s16, s13
	s_add_u32 s10, s26, s16
	s_addc_u32 s11, s27, 0
	s_add_u32 s6, s24, s12
	s_addc_u32 s7, s25, 0
	v_lshrrev_b32_e32 v224, 6, v206
	v_and_b32_e32 v225, 3, v224
	v_lshrrev_b32_e32 v224, 2, v224
	v_and_b32_e32 v205, 15, v206
	v_bfe_u32 v226, v206, 4, 2
	v_lshl_add_u32 v225, v225, 3, v226
	v_lshl_add_u32 v224, v224, 6, v205
	v_lshlrev_b32_e32 v205, 4, v225
	v_lshl_add_u32 v203, v224, 13, v205
	v_mov_b32_e32 v204, v203
	global_load_dwordx4 v[128:131], v205, s[10:11] offset:0
	global_load_dwordx4 v[132:135], v205, s[10:11] offset:64
	global_load_dwordx4 v[136:139], v205, s[10:11] offset:512
	global_load_dwordx4 v[140:143], v205, s[10:11] offset:576
	global_load_dwordx4 v[144:147], v203, s[6:7] offset:0
	global_load_dwordx4 v[148:151], v203, s[6:7] offset:64
	global_load_dwordx4 v[152:155], v203, s[6:7] offset:512
	global_load_dwordx4 v[156:159], v203, s[6:7] offset:576
	v_add_u32_e32 v203, 0x20000, v203
	global_load_dwordx4 v[160:163], v203, s[6:7] offset:0
	global_load_dwordx4 v[174:177], v203, s[6:7] offset:64
	global_load_dwordx4 v[178:181], v203, s[6:7] offset:512
	global_load_dwordx4 v[182:185], v203, s[6:7] offset:576
	v_add_u32_e32 v203, 0x20000, v203
	global_load_dwordx4 v[186:189], v203, s[6:7] offset:0
	global_load_dwordx4 v[190:193], v203, s[6:7] offset:64
	global_load_dwordx4 v[194:197], v203, s[6:7] offset:512
	global_load_dwordx4 v[208:211], v203, s[6:7] offset:576
	v_add_u32_e32 v203, 0x20000, v203
	global_load_dwordx4 v[212:215], v203, s[6:7] offset:0
	global_load_dwordx4 v[216:219], v203, s[6:7] offset:64
	global_load_dwordx4 v[220:223], v203, s[6:7] offset:512
	global_load_dwordx4 v[224:227], v203, s[6:7] offset:576
	v_add_u32_e32 v203, 0xa0000, v203
	s_waitcnt vmcnt(12)
	v_pk_fma_f32 v[124:125], v[124:125], v[128:129], v[144:145]
	v_pk_fma_f32 v[126:127], v[126:127], v[130:131], v[146:147]
	v_pk_fma_f32 v[92:93], v[92:93], v[132:133], v[148:149]
	v_pk_fma_f32 v[94:95], v[94:95], v[134:135], v[150:151]
	v_pk_fma_f32 v[60:61], v[60:61], v[136:137], v[152:153]
	v_pk_fma_f32 v[62:63], v[62:63], v[138:139], v[154:155]
	v_pk_fma_f32 v[28:29], v[28:29], v[140:141], v[156:157]
	v_pk_fma_f32 v[30:31], v[30:31], v[142:143], v[158:159]
	global_store_dwordx4 v204, v[124:127], s[6:7] offset:0
	global_store_dwordx4 v204, v[92:95], s[6:7] offset:64
	global_store_dwordx4 v204, v[60:63], s[6:7] offset:512
	global_store_dwordx4 v204, v[28:31], s[6:7] offset:576
	v_add_u32_e32 v204, 0x20000, v204
	global_load_dwordx4 v[144:147], v203, s[6:7] offset:0
	global_load_dwordx4 v[148:151], v203, s[6:7] offset:64
	global_load_dwordx4 v[152:155], v203, s[6:7] offset:512
	global_load_dwordx4 v[156:159], v203, s[6:7] offset:576
	v_add_u32_e32 v203, 0x20000, v203
	s_waitcnt vmcnt(16)
; DI void epi_resid(const Acc& acc, const P& p, int brow, int bcol, int layer, int gch, bool from_input) {
;     ...
; #pragma unroll
;             for (int ai = 0; ai < 2; ++ai)
; #pragma unroll
;                 for (int m = 0; m < 4; ++m) {
;                     const int r = brow + ai * 128 + wr * 64 + m * 16 + fr;
;                     const float* sp = (from_input ? inrow(p, r) : xrow(p, r)) + c0;
;                     xv[ai][m] = *(const f32x4*)sp;
;                 }
;             __builtin_amdgcn_sched_barrier(0);
; #pragma unroll
;             for (int ai = 0; ai < 2; ++ai)
; #pragma unroll
;                 for (int m = 0; m < 4; ++m) {
;                     const int r = brow + ai * 128 + wr * 64 + m * 16 + fr;
;                     *(f32x4*)(xrow(p, r) + c0) = xv[ai][m] + g * acc[ai][bj][m][n];
;                 }
;             __builtin_amdgcn_sched_barrier(0);
	v_pk_fma_f32 v[120:121], v[120:121], v[128:129], v[160:161]
	v_pk_fma_f32 v[122:123], v[122:123], v[130:131], v[162:163]
	v_pk_fma_f32 v[88:89], v[88:89], v[132:133], v[174:175]
	v_pk_fma_f32 v[90:91], v[90:91], v[134:135], v[176:177]
	v_pk_fma_f32 v[56:57], v[56:57], v[136:137], v[178:179]
	v_pk_fma_f32 v[58:59], v[58:59], v[138:139], v[180:181]
	v_pk_fma_f32 v[24:25], v[24:25], v[140:141], v[182:183]
	v_pk_fma_f32 v[26:27], v[26:27], v[142:143], v[184:185]
	global_store_dwordx4 v204, v[120:123], s[6:7] offset:0
	global_store_dwordx4 v204, v[88:91], s[6:7] offset:64
	global_store_dwordx4 v204, v[56:59], s[6:7] offset:512
	global_store_dwordx4 v204, v[24:27], s[6:7] offset:576
	v_add_u32_e32 v204, 0x20000, v204
	global_load_dwordx4 v[160:163], v203, s[6:7] offset:0
	global_load_dwordx4 v[174:177], v203, s[6:7] offset:64
	global_load_dwordx4 v[178:181], v203, s[6:7] offset:512
	global_load_dwordx4 v[182:185], v203, s[6:7] offset:576
	v_add_u32_e32 v203, 0x20000, v203
	s_waitcnt vmcnt(20)
	v_pk_fma_f32 v[116:117], v[116:117], v[128:129], v[186:187]
	v_pk_fma_f32 v[118:119], v[118:119], v[130:131], v[188:189]
	v_pk_fma_f32 v[84:85], v[84:85], v[132:133], v[190:191]
	v_pk_fma_f32 v[86:87], v[86:87], v[134:135], v[192:193]
	v_pk_fma_f32 v[52:53], v[52:53], v[136:137], v[194:195]
	v_pk_fma_f32 v[54:55], v[54:55], v[138:139], v[196:197]
	v_pk_fma_f32 v[20:21], v[20:21], v[140:141], v[208:209]
	v_pk_fma_f32 v[22:23], v[22:23], v[142:143], v[210:211]
	global_store_dwordx4 v204, v[116:119], s[6:7] offset:0
	global_store_dwordx4 v204, v[84:87], s[6:7] offset:64
	global_store_dwordx4 v204, v[52:55], s[6:7] offset:512
	global_store_dwordx4 v204, v[20:23], s[6:7] offset:576
	v_add_u32_e32 v204, 0x20000, v204
	global_load_dwordx4 v[186:189], v203, s[6:7] offset:0
	global_load_dwordx4 v[190:193], v203, s[6:7] offset:64
	global_load_dwordx4 v[194:197], v203, s[6:7] offset:512
	global_load_dwordx4 v[208:211], v203, s[6:7] offset:576
	v_add_u32_e32 v203, 0x20000, v203
	s_waitcnt vmcnt(24)
	v_pk_fma_f32 v[112:113], v[112:113], v[128:129], v[212:213]
	v_pk_fma_f32 v[114:115], v[114:115], v[130:131], v[214:215]
	v_pk_fma_f32 v[80:81], v[80:81], v[132:133], v[216:217]
	v_pk_fma_f32 v[82:83], v[82:83], v[134:135], v[218:219]
	v_pk_fma_f32 v[48:49], v[48:49], v[136:137], v[220:221]
	v_pk_fma_f32 v[50:51], v[50:51], v[138:139], v[222:223]
	v_pk_fma_f32 v[16:17], v[16:17], v[140:141], v[224:225]
	v_pk_fma_f32 v[18:19], v[18:19], v[142:143], v[226:227]
	global_store_dwordx4 v204, v[112:115], s[6:7] offset:0
	global_store_dwordx4 v204, v[80:83], s[6:7] offset:64
	global_store_dwordx4 v204, v[48:51], s[6:7] offset:512
	global_store_dwordx4 v204, v[16:19], s[6:7] offset:576
	v_add_u32_e32 v204, 0xa0000, v204
	global_load_dwordx4 v[212:215], v203, s[6:7] offset:0
	global_load_dwordx4 v[216:219], v203, s[6:7] offset:64
	global_load_dwordx4 v[220:223], v203, s[6:7] offset:512
	global_load_dwordx4 v[224:227], v203, s[6:7] offset:576
	s_waitcnt vmcnt(24)
	v_pk_fma_f32 v[108:109], v[108:109], v[128:129], v[144:145]
	v_pk_fma_f32 v[110:111], v[110:111], v[130:131], v[146:147]
	v_pk_fma_f32 v[76:77], v[76:77], v[132:133], v[148:149]
	v_pk_fma_f32 v[78:79], v[78:79], v[134:135], v[150:151]
	v_pk_fma_f32 v[44:45], v[44:45], v[136:137], v[152:153]
	v_pk_fma_f32 v[46:47], v[46:47], v[138:139], v[154:155]
	v_pk_fma_f32 v[12:13], v[12:13], v[140:141], v[156:157]
	v_pk_fma_f32 v[14:15], v[14:15], v[142:143], v[158:159]
	global_store_dwordx4 v204, v[108:111], s[6:7] offset:0
	global_store_dwordx4 v204, v[76:79], s[6:7] offset:64
	global_store_dwordx4 v204, v[44:47], s[6:7] offset:512
	global_store_dwordx4 v204, v[12:15], s[6:7] offset:576
	v_add_u32_e32 v204, 0x20000, v204
	s_waitcnt vmcnt(20)
	v_pk_fma_f32 v[104:105], v[104:105], v[128:129], v[160:161]
	v_pk_fma_f32 v[106:107], v[106:107], v[130:131], v[162:163]
	v_pk_fma_f32 v[72:73], v[72:73], v[132:133], v[174:175]
	v_pk_fma_f32 v[74:75], v[74:75], v[134:135], v[176:177]
	v_pk_fma_f32 v[40:41], v[40:41], v[136:137], v[178:179]
	v_pk_fma_f32 v[42:43], v[42:43], v[138:139], v[180:181]
	v_pk_fma_f32 v[8:9], v[8:9], v[140:141], v[182:183]
	v_pk_fma_f32 v[10:11], v[10:11], v[142:143], v[184:185]
	global_store_dwordx4 v204, v[104:107], s[6:7] offset:0
	global_store_dwordx4 v204, v[72:75], s[6:7] offset:64
	global_store_dwordx4 v204, v[40:43], s[6:7] offset:512
	global_store_dwordx4 v204, v[8:11], s[6:7] offset:576
	v_add_u32_e32 v204, 0x20000, v204
	s_waitcnt vmcnt(16)
	v_pk_fma_f32 v[100:101], v[100:101], v[128:129], v[186:187]
	v_pk_fma_f32 v[102:103], v[102:103], v[130:131], v[188:189]
	v_pk_fma_f32 v[68:69], v[68:69], v[132:133], v[190:191]
	v_pk_fma_f32 v[70:71], v[70:71], v[134:135], v[192:193]
	v_pk_fma_f32 v[36:37], v[36:37], v[136:137], v[194:195]
	v_pk_fma_f32 v[38:39], v[38:39], v[138:139], v[196:197]
	v_pk_fma_f32 v[4:5], v[4:5], v[140:141], v[208:209]
	v_pk_fma_f32 v[6:7], v[6:7], v[142:143], v[210:211]
	global_store_dwordx4 v204, v[100:103], s[6:7] offset:0
	global_store_dwordx4 v204, v[68:71], s[6:7] offset:64
	global_store_dwordx4 v204, v[36:39], s[6:7] offset:512
	global_store_dwordx4 v204, v[4:7], s[6:7] offset:576
	v_add_u32_e32 v204, 0x20000, v204
	s_waitcnt vmcnt(12)
	v_pk_fma_f32 v[96:97], v[96:97], v[128:129], v[212:213]
	v_pk_fma_f32 v[98:99], v[98:99], v[130:131], v[214:215]
	v_pk_fma_f32 v[64:65], v[64:65], v[132:133], v[216:217]
	v_pk_fma_f32 v[66:67], v[66:67], v[134:135], v[218:219]
	v_pk_fma_f32 v[32:33], v[32:33], v[136:137], v[220:221]
	v_pk_fma_f32 v[34:35], v[34:35], v[138:139], v[222:223]
	v_pk_fma_f32 v[0:1], v[0:1], v[140:141], v[224:225]
	v_pk_fma_f32 v[2:3], v[2:3], v[142:143], v[226:227]
	global_store_dwordx4 v204, v[96:99], s[6:7] offset:0
	global_store_dwordx4 v204, v[64:67], s[6:7] offset:64
	global_store_dwordx4 v204, v[32:35], s[6:7] offset:512
	global_store_dwordx4 v204, v[0:3], s[6:7] offset:576
	s_branch .Lresid_latch_ffndL0

; #define WAIT_V(n) asm volatile("s_waitcnt vmcnt(" #n ")" ::: "memory")
; #define WAIT_L(n) asm volatile("s_waitcnt lgkmcnt(" #n ")" ::: "memory")
; #define BAR __builtin_amdgcn_s_barrier()
; #define SCHED __builtin_amdgcn_sched_barrier(0)
; template <class Get, class Epi>
; DI void gemm_stream(LAS unsigned char* lds, const int K, const int ld, Get get, Epi epi) {
;     ...
;             LDB(B0, 0, 0); SCHED; LDA(At, 0, 0); STAGE(SAo(1, 1), a1 + hstep);
;             WAIT_L(8); BAR; WAIT_L(0); MMA(0, 0, At, B0); BAR; SCHED;
;             LDB(B1, 0, 1); STAGE(SBo(0, 0), b2);
;             BAR; WAIT_L(0); MMA(0, 1, At, B1); BAR;
;             LDA(At, 0, 1); STAGE(SAo(0, 0), a2);
;             BAR; WAIT_L(0); MMA(1, 0, At, B0); BAR; SCHED;
;             STAGE(SBo(0, 1), b2 + hstep);
;             WAIT_V(6); BAR; MMA(1, 1, At, B1); BAR;
.LBB0_1964:
	ds_read_b128 v[144:147], v141
	ds_read_b128 v[148:151], v141 offset:1024
	ds_read_b128 v[152:155], v141 offset:2048
	ds_read_b128 v[156:159], v141 offset:3072
	s_add_u32 s38, s36, 0x100
	s_addc_u32 s39, s37, 0
	s_cmp_eq_u32 s77, 4
	s_cselect_b32 s53, s17, s39
	s_cselect_b32 s52, s16, s38
	s_cselect_b32 s41, s19, s76
	s_cselect_b32 s40, s18, s0
	v_lshl_add_u64 v[192:193], s[36:37], 0, v[134:135]
	s_add_i32 m0, s20, 0xc000
	ds_read_b128 v[160:163], v142
	ds_read_b128 v[164:167], v142 offset:1024
	ds_read_b128 v[168:171], v142 offset:2048
	ds_read_b128 v[172:175], v142 offset:3072
	ds_read_b128 v[176:179], v142 offset:4096
	ds_read_b128 v[180:183], v142 offset:5120
	ds_read_b128 v[184:187], v142 offset:6144
	ds_read_b128 v[188:191], v142 offset:7168
	global_load_lds_dwordx4 v[192:193], off
	v_lshl_add_u64 v[192:193], s[36:37], 0, v[136:137]
	s_add_i32 m0, s20, 0xe000
	s_nop 0
	global_load_lds_dwordx4 v[192:193], off
	s_waitcnt lgkmcnt(8)
	s_barrier
	s_waitcnt lgkmcnt(0)
	v_mfma_f32_16x16x32_bf16 v[124:127], v[144:147], v[160:163], v[124:127]
	v_mfma_f32_16x16x32_bf16 v[120:123], v[152:155], v[160:163], v[120:123]
	v_mfma_f32_16x16x32_bf16 v[116:119], v[144:147], v[168:171], v[116:119]
	v_mfma_f32_16x16x32_bf16 v[112:115], v[152:155], v[168:171], v[112:115]
	v_mfma_f32_16x16x32_bf16 v[104:107], v[144:147], v[176:179], v[104:107]
	v_mfma_f32_16x16x32_bf16 v[96:99], v[152:155], v[176:179], v[96:99]
	v_mfma_f32_16x16x32_bf16 v[88:91], v[144:147], v[184:187], v[88:91]
	v_mfma_f32_16x16x32_bf16 v[80:83], v[152:155], v[184:187], v[80:83]
	v_mfma_f32_16x16x32_bf16 v[124:127], v[148:151], v[164:167], v[124:127]
	v_mfma_f32_16x16x32_bf16 v[120:123], v[156:159], v[164:167], v[120:123]
	v_mfma_f32_16x16x32_bf16 v[116:119], v[148:151], v[172:175], v[116:119]
	v_mfma_f32_16x16x32_bf16 v[112:115], v[156:159], v[172:175], v[112:115]
	v_mfma_f32_16x16x32_bf16 v[104:107], v[148:151], v[180:183], v[104:107]
	v_mfma_f32_16x16x32_bf16 v[96:99], v[156:159], v[180:183], v[96:99]
	v_mfma_f32_16x16x32_bf16 v[88:91], v[148:151], v[188:191], v[88:91]
	v_mfma_f32_16x16x32_bf16 v[80:83], v[156:159], v[188:191], v[80:83]
	s_barrier
	s_add_i32 s36, s56, s3
	v_lshl_add_u64 v[204:205], s[40:41], 0, v[130:131]
	s_mov_b32 m0, s36
	ds_read_b128 v[192:195], v143
	ds_read_b128 v[196:199], v143 offset:1024
	ds_read_b128 v[200:203], v143 offset:2048
	ds_read_b128 v[208:211], v143 offset:3072
	global_load_lds_dwordx4 v[204:205], off
	v_lshl_add_u64 v[212:213], s[40:41], 0, v[128:129]
	s_add_i32 m0, s36, 0x2000
	s_nop 0
	global_load_lds_dwordx4 v[212:213], off
	s_barrier
	s_waitcnt lgkmcnt(0)
	v_mfma_f32_16x16x32_bf16 v[108:111], v[192:195], v[160:163], v[108:111]
	v_mfma_f32_16x16x32_bf16 v[100:103], v[200:203], v[160:163], v[100:103]
	v_mfma_f32_16x16x32_bf16 v[92:95], v[192:195], v[168:171], v[92:95]
	v_mfma_f32_16x16x32_bf16 v[84:87], v[200:203], v[168:171], v[84:87]
	v_mfma_f32_16x16x32_bf16 v[76:79], v[192:195], v[176:179], v[76:79]
	v_mfma_f32_16x16x32_bf16 v[72:75], v[200:203], v[176:179], v[72:75]
	v_mfma_f32_16x16x32_bf16 v[68:71], v[192:195], v[184:187], v[68:71]
	v_mfma_f32_16x16x32_bf16 v[64:67], v[200:203], v[184:187], v[64:67]
	v_mfma_f32_16x16x32_bf16 v[108:111], v[196:199], v[164:167], v[108:111]
	v_mfma_f32_16x16x32_bf16 v[100:103], v[208:211], v[164:167], v[100:103]
	v_mfma_f32_16x16x32_bf16 v[92:95], v[196:199], v[172:175], v[92:95]
	v_mfma_f32_16x16x32_bf16 v[84:87], v[208:211], v[172:175], v[84:87]
	v_mfma_f32_16x16x32_bf16 v[76:79], v[196:199], v[180:183], v[76:79]
	v_mfma_f32_16x16x32_bf16 v[72:75], v[208:211], v[180:183], v[72:75]
	v_mfma_f32_16x16x32_bf16 v[68:71], v[196:199], v[188:191], v[68:71]
	v_mfma_f32_16x16x32_bf16 v[64:67], v[208:211], v[188:191], v[64:67]
	s_barrier
	s_mov_b32 m0, s20
	v_lshl_add_u64 v[214:215], s[52:53], 0, v[130:131]
	ds_read_b128 v[160:163], v142 offset:16384
	ds_read_b128 v[164:167], v142 offset:17408
	ds_read_b128 v[168:171], v142 offset:18432
	ds_read_b128 v[172:175], v142 offset:19456
	ds_read_b128 v[176:179], v142 offset:20480
	ds_read_b128 v[180:183], v142 offset:21504
	ds_read_b128 v[184:187], v142 offset:22528
	ds_read_b128 v[188:191], v142 offset:23552
	global_load_lds_dwordx4 v[214:215], off
	v_lshl_add_u64 v[216:217], s[52:53], 0, v[128:129]
	s_mov_b32 m0, s21
	s_nop 0
	global_load_lds_dwordx4 v[216:217], off
	s_barrier
	s_waitcnt lgkmcnt(0)
	v_mfma_f32_16x16x32_bf16 v[60:63], v[144:147], v[160:163], v[60:63]
	v_mfma_f32_16x16x32_bf16 v[56:59], v[152:155], v[160:163], v[56:59]
	v_mfma_f32_16x16x32_bf16 v[52:55], v[144:147], v[168:171], v[52:55]
	v_mfma_f32_16x16x32_bf16 v[48:51], v[152:155], v[168:171], v[48:51]
	v_mfma_f32_16x16x32_bf16 v[40:43], v[144:147], v[176:179], v[40:43]
	v_mfma_f32_16x16x32_bf16 v[32:35], v[152:155], v[176:179], v[32:35]
	v_mfma_f32_16x16x32_bf16 v[24:27], v[144:147], v[184:187], v[24:27]
	v_mfma_f32_16x16x32_bf16 v[16:19], v[152:155], v[184:187], v[16:19]
	v_mfma_f32_16x16x32_bf16 v[60:63], v[148:151], v[164:167], v[60:63]
	v_mfma_f32_16x16x32_bf16 v[56:59], v[156:159], v[164:167], v[56:59]
	v_mfma_f32_16x16x32_bf16 v[52:55], v[148:151], v[172:175], v[52:55]
	v_mfma_f32_16x16x32_bf16 v[48:51], v[156:159], v[172:175], v[48:51]
	v_mfma_f32_16x16x32_bf16 v[40:43], v[148:151], v[180:183], v[40:43]
	v_mfma_f32_16x16x32_bf16 v[32:35], v[156:159], v[180:183], v[32:35]
	v_mfma_f32_16x16x32_bf16 v[24:27], v[148:151], v[188:191], v[24:27]
	v_mfma_f32_16x16x32_bf16 v[16:19], v[156:159], v[188:191], v[16:19]
	s_barrier
; #define WAIT_V(n) asm volatile("s_waitcnt vmcnt(" #n ")" ::: "memory")
; #define WAIT_L(n) asm volatile("s_waitcnt lgkmcnt(" #n ")" ::: "memory")
; #define BAR __builtin_amdgcn_s_barrier()
; #define SCHED __builtin_amdgcn_sched_barrier(0)
; template <class Get, class Epi>
; DI void gemm_stream(LAS unsigned char* lds, const int K, const int ld, Get get, Epi epi) {
;     ...
;             STAGE(SBo(0, 1), b2 + hstep);
;             WAIT_V(6); BAR; MMA(1, 1, At, B1); BAR;
;             LDB(B0, 1, 0); SCHED; LDA(At, 1, 0); STAGE(SAo(0, 1), a2 + hstep);
;             WAIT_L(8); BAR; WAIT_L(0); MMA(0, 0, At, B0); BAR; SCHED;
;             LDB(B1, 1, 1); STAGE(SBo(1, 0), b3);
;             BAR; WAIT_L(0); MMA(0, 1, At, B1); BAR;
;             LDA(At, 1, 1); STAGE(SAo(1, 0), a3);
;             BAR; WAIT_L(0); MMA(1, 0, At, B0); BAR; SCHED;
	s_add_u32 s36, s40, 0x160000
	s_addc_u32 s37, s41, 0
	s_add_i32 s78, s57, s3
	v_lshl_add_u64 v[144:145], s[36:37], 0, v[130:131]
	s_mov_b32 m0, s78
	s_nop 0
	global_load_lds_dwordx4 v[144:145], off
	v_lshl_add_u64 v[144:145], s[36:37], 0, v[128:129]
	s_add_i32 m0, s78, 0x2000
	s_nop 0
	global_load_lds_dwordx4 v[144:145], off
	s_waitcnt vmcnt(6)
	s_barrier
	v_mfma_f32_16x16x32_bf16 v[44:47], v[192:195], v[160:163], v[44:47]
	v_mfma_f32_16x16x32_bf16 v[36:39], v[200:203], v[160:163], v[36:39]
	v_mfma_f32_16x16x32_bf16 v[28:31], v[192:195], v[168:171], v[28:31]
	v_mfma_f32_16x16x32_bf16 v[20:23], v[200:203], v[168:171], v[20:23]
	v_mfma_f32_16x16x32_bf16 v[12:15], v[192:195], v[176:179], v[12:15]
	v_mfma_f32_16x16x32_bf16 v[8:11], v[200:203], v[176:179], v[8:11]
	v_mfma_f32_16x16x32_bf16 v[4:7], v[192:195], v[184:187], v[4:7]
	v_mfma_f32_16x16x32_bf16 v[0:3], v[200:203], v[184:187], v[0:3]
	v_mfma_f32_16x16x32_bf16 v[44:47], v[196:199], v[164:167], v[44:47]
	v_mfma_f32_16x16x32_bf16 v[36:39], v[208:211], v[164:167], v[36:39]
	v_mfma_f32_16x16x32_bf16 v[28:31], v[196:199], v[172:175], v[28:31]
	v_mfma_f32_16x16x32_bf16 v[20:23], v[208:211], v[172:175], v[20:23]
	v_mfma_f32_16x16x32_bf16 v[12:15], v[196:199], v[180:183], v[12:15]
	v_mfma_f32_16x16x32_bf16 v[8:11], v[208:211], v[180:183], v[8:11]
	v_mfma_f32_16x16x32_bf16 v[4:7], v[196:199], v[188:191], v[4:7]
	v_mfma_f32_16x16x32_bf16 v[0:3], v[208:211], v[188:191], v[0:3]
	s_add_i32 s78, 16, 0x18000
	v_add_u32_e32 v132, s78, v140
	s_barrier
	ds_read_b128 v[144:147], v132
	ds_read_b128 v[148:151], v132 offset:1024
	ds_read_b128 v[152:155], v132 offset:2048
	ds_read_b128 v[156:159], v132 offset:3072
	s_add_u32 s36, s52, 0x160000
	s_addc_u32 s37, s53, 0
	s_mov_b32 m0, s23
	v_lshl_add_u64 v[192:193], s[36:37], 0, v[130:131]
	ds_read_b128 v[160:163], v142 offset:32768
	ds_read_b128 v[164:167], v142 offset:33792
	ds_read_b128 v[168:171], v142 offset:34816
	ds_read_b128 v[172:175], v142 offset:35840
	ds_read_b128 v[176:179], v142 offset:36864
	ds_read_b128 v[180:183], v142 offset:37888
	ds_read_b128 v[184:187], v142 offset:38912
	ds_read_b128 v[188:191], v142 offset:39936
	global_load_lds_dwordx4 v[192:193], off
	v_lshl_add_u64 v[192:193], s[36:37], 0, v[128:129]
	s_mov_b32 m0, s28
	s_nop 0
	global_load_lds_dwordx4 v[192:193], off
	s_waitcnt lgkmcnt(8)
	s_barrier
	s_waitcnt lgkmcnt(0)
	v_mfma_f32_16x16x32_bf16 v[124:127], v[144:147], v[160:163], v[124:127]
	v_mfma_f32_16x16x32_bf16 v[120:123], v[152:155], v[160:163], v[120:123]
	v_mfma_f32_16x16x32_bf16 v[116:119], v[144:147], v[168:171], v[116:119]
	v_mfma_f32_16x16x32_bf16 v[112:115], v[152:155], v[168:171], v[112:115]
	v_mfma_f32_16x16x32_bf16 v[104:107], v[144:147], v[176:179], v[104:107]
	v_mfma_f32_16x16x32_bf16 v[96:99], v[152:155], v[176:179], v[96:99]
	v_mfma_f32_16x16x32_bf16 v[88:91], v[144:147], v[184:187], v[88:91]
	v_mfma_f32_16x16x32_bf16 v[80:83], v[152:155], v[184:187], v[80:83]
	v_mfma_f32_16x16x32_bf16 v[124:127], v[148:151], v[164:167], v[124:127]
	v_mfma_f32_16x16x32_bf16 v[120:123], v[156:159], v[164:167], v[120:123]
	v_mfma_f32_16x16x32_bf16 v[116:119], v[148:151], v[172:175], v[116:119]
	v_mfma_f32_16x16x32_bf16 v[112:115], v[156:159], v[172:175], v[112:115]
	v_mfma_f32_16x16x32_bf16 v[104:107], v[148:151], v[180:183], v[104:107]
	v_mfma_f32_16x16x32_bf16 v[96:99], v[156:159], v[180:183], v[96:99]
	v_mfma_f32_16x16x32_bf16 v[88:91], v[148:151], v[188:191], v[88:91]
	v_mfma_f32_16x16x32_bf16 v[80:83], v[156:159], v[188:191], v[80:83]
	s_barrier
	s_add_i32 s52, 16, 0x1c000
	s_add_i32 s36, s78, s3
	v_add_u32_e32 v132, s52, v140
	v_lshl_add_u64 v[204:205], v[204:205], 0, s[8:9]
	s_mov_b32 m0, s36
	ds_read_b128 v[192:195], v132
	ds_read_b128 v[196:199], v132 offset:1024
	ds_read_b128 v[200:203], v132 offset:2048
	ds_read_b128 v[208:211], v132 offset:3072
	global_load_lds_dwordx4 v[204:205], off
	v_lshl_add_u64 v[204:205], v[212:213], 0, s[8:9]
	s_add_i32 m0, s36, 0x2000
	s_nop 0
	global_load_lds_dwordx4 v[204:205], off
	s_barrier
	s_waitcnt lgkmcnt(0)
	v_mfma_f32_16x16x32_bf16 v[108:111], v[192:195], v[160:163], v[108:111]
	v_mfma_f32_16x16x32_bf16 v[100:103], v[200:203], v[160:163], v[100:103]
	v_mfma_f32_16x16x32_bf16 v[92:95], v[192:195], v[168:171], v[92:95]
	v_mfma_f32_16x16x32_bf16 v[84:87], v[200:203], v[168:171], v[84:87]
	v_mfma_f32_16x16x32_bf16 v[76:79], v[192:195], v[176:179], v[76:79]
	v_mfma_f32_16x16x32_bf16 v[72:75], v[200:203], v[176:179], v[72:75]
	v_mfma_f32_16x16x32_bf16 v[68:71], v[192:195], v[184:187], v[68:71]
	v_mfma_f32_16x16x32_bf16 v[64:67], v[200:203], v[184:187], v[64:67]
	v_mfma_f32_16x16x32_bf16 v[108:111], v[196:199], v[164:167], v[108:111]
	v_mfma_f32_16x16x32_bf16 v[100:103], v[208:211], v[164:167], v[100:103]
	v_mfma_f32_16x16x32_bf16 v[92:95], v[196:199], v[172:175], v[92:95]
	v_mfma_f32_16x16x32_bf16 v[84:87], v[208:211], v[172:175], v[84:87]
	v_mfma_f32_16x16x32_bf16 v[76:79], v[196:199], v[180:183], v[76:79]
	v_mfma_f32_16x16x32_bf16 v[72:75], v[208:211], v[180:183], v[72:75]
	v_mfma_f32_16x16x32_bf16 v[68:71], v[196:199], v[188:191], v[68:71]
	v_mfma_f32_16x16x32_bf16 v[64:67], v[208:211], v[188:191], v[64:67]
	s_barrier
	s_mov_b32 m0, s29
	v_lshl_add_u64 v[204:205], v[214:215], 0, s[8:9]
	ds_read_b128 v[160:163], v142 offset:49152
	ds_read_b128 v[164:167], v142 offset:50176
	ds_read_b128 v[168:171], v142 offset:51200
	ds_read_b128 v[172:175], v142 offset:52224
	ds_read_b128 v[176:179], v142 offset:53248
	ds_read_b128 v[180:183], v142 offset:54272
	ds_read_b128 v[184:187], v142 offset:55296
	ds_read_b128 v[188:191], v142 offset:56320
	global_load_lds_dwordx4 v[204:205], off
	v_lshl_add_u64 v[204:205], v[216:217], 0, s[8:9]
	s_mov_b32 m0, s35
	s_nop 0
	global_load_lds_dwordx4 v[204:205], off
	s_barrier
; #define WAIT_V(n) asm volatile("s_waitcnt vmcnt(" #n ")" ::: "memory")
; #define WAIT_L(n) asm volatile("s_waitcnt lgkmcnt(" #n ")" ::: "memory")
; #define BAR __builtin_amdgcn_s_barrier()
; #define SCHED __builtin_amdgcn_sched_barrier(0)
; #define EPI_DONE do { } while (0)
; template <class Get, class Epi>
; DI void gemm_stream(LAS unsigned char* lds, const int K, const int ld, Get get, Epi epi) {
;     ...
;             BAR; WAIT_L(0); MMA(1, 0, At, B0); BAR; SCHED;
;             STAGE(SBo(1, 1), b3 + hstep);
;             WAIT_V(6); BAR; MMA(1, 1, At, B1); BAR;
; DI void epi_part(const Acc& acc, const P& p, int brow, int bcol, int sl) {
;     EPI_IDX
;     const int b = brow / PB;
;     float* part = (float*)(p.ws + O_PART) + ((size_t)sl * (NBATCH * CTXL) + b * CTXL) * DM;
; #pragma unroll
;     for (int ai = 0; ai < 2; ++ai)
; #pragma unroll
;         for (int m = 0; m < 4; ++m) {
;             float* rp = part + (size_t)(ai * 128 + wr * 64 + m * 16 + fr) * DM + bcol + wc * 32 + fq * 4;
; #pragma unroll
;             for (int bj = 0; bj < 2; ++bj)
; #pragma unroll
;                 for (int n = 0; n < 2; ++n) *(f32x4*)(rp + bj * 128 + n * 16) = acc[ai][bj][m][n];
;         }
;     EPI_DONE;
; }
	s_waitcnt lgkmcnt(0)
	v_mfma_f32_16x16x32_bf16 v[60:63], v[144:147], v[160:163], v[60:63]
	v_mfma_f32_16x16x32_bf16 v[56:59], v[152:155], v[160:163], v[56:59]
	v_mfma_f32_16x16x32_bf16 v[52:55], v[144:147], v[168:171], v[52:55]
	v_mfma_f32_16x16x32_bf16 v[48:51], v[152:155], v[168:171], v[48:51]
	v_mfma_f32_16x16x32_bf16 v[40:43], v[144:147], v[176:179], v[40:43]
	v_mfma_f32_16x16x32_bf16 v[32:35], v[152:155], v[176:179], v[32:35]
	v_mfma_f32_16x16x32_bf16 v[24:27], v[144:147], v[184:187], v[24:27]
	v_mfma_f32_16x16x32_bf16 v[16:19], v[152:155], v[184:187], v[16:19]
	v_mfma_f32_16x16x32_bf16 v[60:63], v[148:151], v[164:167], v[60:63]
	v_mfma_f32_16x16x32_bf16 v[56:59], v[156:159], v[164:167], v[56:59]
	v_mfma_f32_16x16x32_bf16 v[52:55], v[148:151], v[172:175], v[52:55]
	v_mfma_f32_16x16x32_bf16 v[48:51], v[156:159], v[172:175], v[48:51]
	v_mfma_f32_16x16x32_bf16 v[40:43], v[148:151], v[180:183], v[40:43]
	v_mfma_f32_16x16x32_bf16 v[32:35], v[156:159], v[180:183], v[32:35]
	v_mfma_f32_16x16x32_bf16 v[24:27], v[148:151], v[188:191], v[24:27]
	v_mfma_f32_16x16x32_bf16 v[16:19], v[156:159], v[188:191], v[16:19]
	s_barrier
	s_add_u32 s36, s40, 0x160080
	s_addc_u32 s37, s41, 0
	s_add_i32 s40, s52, s3
	v_lshl_add_u64 v[144:145], s[36:37], 0, v[130:131]
	s_mov_b32 m0, s40
	s_nop 0
	global_load_lds_dwordx4 v[144:145], off
	v_lshl_add_u64 v[144:145], s[36:37], 0, v[128:129]
	s_add_i32 m0, s40, 0x2000
	s_nop 0
	global_load_lds_dwordx4 v[144:145], off
	s_waitcnt vmcnt(6)
	s_barrier
	v_mfma_f32_16x16x32_bf16 v[44:47], v[192:195], v[160:163], v[44:47]
	v_mfma_f32_16x16x32_bf16 v[36:39], v[200:203], v[160:163], v[36:39]
	v_mfma_f32_16x16x32_bf16 v[28:31], v[192:195], v[168:171], v[28:31]
	v_mfma_f32_16x16x32_bf16 v[20:23], v[200:203], v[168:171], v[20:23]
	v_mfma_f32_16x16x32_bf16 v[12:15], v[192:195], v[176:179], v[12:15]
	v_mfma_f32_16x16x32_bf16 v[8:11], v[200:203], v[176:179], v[8:11]
	v_mfma_f32_16x16x32_bf16 v[4:7], v[192:195], v[184:187], v[4:7]
	v_mfma_f32_16x16x32_bf16 v[0:3], v[200:203], v[184:187], v[0:3]
	v_mfma_f32_16x16x32_bf16 v[44:47], v[196:199], v[164:167], v[44:47]
	v_mfma_f32_16x16x32_bf16 v[36:39], v[208:211], v[164:167], v[36:39]
	v_mfma_f32_16x16x32_bf16 v[28:31], v[196:199], v[172:175], v[28:31]
	v_mfma_f32_16x16x32_bf16 v[20:23], v[208:211], v[172:175], v[20:23]
	v_mfma_f32_16x16x32_bf16 v[12:15], v[196:199], v[180:183], v[12:15]
	v_mfma_f32_16x16x32_bf16 v[8:11], v[208:211], v[180:183], v[8:11]
	v_mfma_f32_16x16x32_bf16 v[4:7], v[196:199], v[188:191], v[4:7]
	v_mfma_f32_16x16x32_bf16 v[0:3], v[208:211], v[188:191], v[0:3]
	s_barrier
	s_add_i32 s77, s77, 2
	s_add_u32 s0, s0, 0x100
	s_addc_u32 s76, s76, 0
	s_cmp_gt_u32 s77, 5
	s_mov_b64 s[36:37], s[38:39]
	s_cbranch_scc0 .LBB0_1964
	s_mul_hi_i32 s0, s75, 0x78787879
	s_lshr_b32 s37, s0, 31
	s_lshr_b32 s0, s0, 3
	s_ashr_i32 s36, s61, 4
	s_add_i32 s0, s0, s37
	s_ashr_i32 s37, s36, 31
	s_lshl_b32 s38, s0, 8
	s_ashr_i32 s39, s38, 31
	s_lshl_b64 s[36:37], s[36:37], 23
	s_add_u32 s0, s54, s36
	s_addc_u32 s40, s55, s37
	s_lshl_b64 s[36:37], s[38:39], 13
	s_add_u32 s0, s0, s36
	v_mov_b32_e32 v145, v206
	s_addc_u32 s37, s40, s37
	s_lshl_b32 s36, s61, 10
	s_and_b32 s36, s36, 0x3c00
	v_and_b32_e32 v132, 15, v145
	v_ashrrev_i32_e32 v144, 2, v145
	v_and_or_b32 v144, v144, s58, v132
	s_add_u32 s36, s0, s36
	v_lshlrev_b32_e32 v132, 1, v145
	s_addc_u32 s37, s37, 0
	v_and_b32_e32 v132, 0x180, v132
	v_lshl_add_u64 v[146:147], s[36:37], 0, v[132:133]
	v_and_b32_e32 v132, 48, v145
	v_ashrrev_i32_e32 v145, 31, v144
	v_lshl_add_u64 v[146:147], v[146:147], 0, v[132:133]
	v_lshlrev_b64 v[148:149], 13, v[144:145]
	v_lshl_add_u64 v[148:149], v[146:147], 0, v[148:149]
	global_store_dwordx4 v[148:149], v[124:127], off
	global_store_dwordx4 v[148:149], v[120:123], off offset:64
	global_store_dwordx4 v[148:149], v[108:111], off offset:512
	global_store_dwordx4 v[148:149], v[100:103], off offset:576
	s_mov_b32 s61, s74
	s_mov_b32 s75, s63
	v_or_b32_e32 v100, 16, v144
	v_ashrrev_i32_e32 v101, 31, v100
	v_lshlrev_b64 v[100:101], 13, v[100:101]
	v_lshl_add_u64 v[100:101], v[146:147], 0, v[100:101]
	global_store_dwordx4 v[100:101], v[116:119], off
	global_store_dwordx4 v[100:101], v[112:115], off offset:64
	global_store_dwordx4 v[100:101], v[92:95], off offset:512
	global_store_dwordx4 v[100:101], v[84:87], off offset:576
	s_mov_b64 s[38:39], s[18:19]
	s_mov_b64 s[36:37], s[16:17]
	v_or_b32_e32 v84, 32, v144
	v_ashrrev_i32_e32 v85, 31, v84
	v_lshlrev_b64 v[84:85], 13, v[84:85]
	v_lshl_add_u64 v[84:85], v[146:147], 0, v[84:85]
	global_store_dwordx4 v[84:85], v[104:107], off
	global_store_dwordx4 v[84:85], v[96:99], off offset:64
	global_store_dwordx4 v[84:85], v[76:79], off offset:512
	global_store_dwordx4 v[84:85], v[72:75], off offset:576
	s_nop 1
	v_or_b32_e32 v72, 48, v144
	v_ashrrev_i32_e32 v73, 31, v72
	v_lshlrev_b64 v[72:73], 13, v[72:73]
	v_lshl_add_u64 v[72:73], v[146:147], 0, v[72:73]
	global_store_dwordx4 v[72:73], v[88:91], off
	global_store_dwordx4 v[72:73], v[80:83], off offset:64
	global_store_dwordx4 v[72:73], v[68:71], off offset:512
	global_store_dwordx4 v[72:73], v[64:67], off offset:576
	s_nop 1
	v_add_co_u32_e32 v66, vcc, s59, v148
	v_lshl_add_u64 v[64:65], v[148:149], 0, s[10:11]
	s_nop 0
	v_addc_co_u32_e32 v67, vcc, 0, v149, vcc
	global_store_dwordx4 v[66:67], v[60:63], off
	global_store_dwordx4 v[64:65], v[56:59], off offset:64
	global_store_dwordx4 v[64:65], v[44:47], off offset:512
	global_store_dwordx4 v[64:65], v[36:39], off offset:576
	s_nop 1
	v_add_co_u32_e32 v38, vcc, s60, v148
	v_lshl_add_u64 v[36:37], v[148:149], 0, s[12:13]
	s_nop 0
	v_addc_co_u32_e32 v39, vcc, 0, v149, vcc
	global_store_dwordx4 v[38:39], v[52:55], off
	global_store_dwordx4 v[36:37], v[48:51], off offset:64
	global_store_dwordx4 v[36:37], v[28:31], off offset:512
	global_store_dwordx4 v[36:37], v[20:23], off offset:576
	s_nop 1
	v_add_co_u32_e32 v22, vcc, 0x140000, v148
	v_lshl_add_u64 v[20:21], v[148:149], 0, s[14:15]
	s_nop 0
	v_addc_co_u32_e32 v23, vcc, 0, v149, vcc
	global_store_dwordx4 v[22:23], v[40:43], off
	global_store_dwordx4 v[20:21], v[32:35], off offset:64
	global_store_dwordx4 v[20:21], v[12:15], off offset:512
	global_store_dwordx4 v[20:21], v[8:11], off offset:576
	s_nop 1
	v_add_co_u32_e32 v10, vcc, 0x160000, v148
	v_lshl_add_u64 v[8:9], v[148:149], 0, s[6:7]
	s_nop 0
	v_addc_co_u32_e32 v11, vcc, 0, v149, vcc
	s_and_b64 vcc, exec, s[4:5]
	global_store_dwordx4 v[10:11], v[24:27], off
	global_store_dwordx4 v[8:9], v[16:19], off offset:64
	global_store_dwordx4 v[8:9], v[4:7], off offset:512
	global_store_dwordx4 v[8:9], v[0:3], off offset:576
	s_cbranch_vccz .LBB0_1961
	s_waitcnt vmcnt(0)
	s_cmpk_gt_u32 s2, 0xff
	s_cbranch_scc1 .LBB0_1968
	s_barrier

; #define WAIT_V(n) asm volatile("s_waitcnt vmcnt(" #n ")" ::: "memory")
; #define WAIT_L(n) asm volatile("s_waitcnt lgkmcnt(" #n ")" ::: "memory")
; #define BAR __builtin_amdgcn_s_barrier()
; #define SCHED __builtin_amdgcn_sched_barrier(0)
; template <class Get, class Epi>
; DI void gemm_stream(LAS unsigned char* lds, const int K, const int ld, Get get, Epi epi) {
;     ...
;             LDB(B0, 0, 0); SCHED; LDA(At, 0, 0); STAGE(SAo(1, 1), a1 + hstep);
;             WAIT_L(8); BAR; WAIT_L(0); MMA(0, 0, At, B0); BAR; SCHED;
;             LDB(B1, 0, 1); STAGE(SBo(0, 0), b2);
;             BAR; WAIT_L(0); MMA(0, 1, At, B1); BAR;
;             LDA(At, 0, 1); STAGE(SAo(0, 0), a2);
;             BAR; WAIT_L(0); MMA(1, 0, At, B0); BAR; SCHED;
;             STAGE(SBo(0, 1), b2 + hstep);
;             WAIT_V(6); BAR; MMA(1, 1, At, B1); BAR;
.LBB0_2102:
	ds_read_b128 v[128:131], v209
	ds_read_b128 v[132:135], v209 offset:1024
	ds_read_b128 v[136:139], v209 offset:2048
	ds_read_b128 v[156:159], v209 offset:3072
	s_add_u32 s28, s64, 0xfff80080
	s_addc_u32 s29, s65, -1
	s_cmp_eq_u32 s7, 28
	s_cselect_b32 s77, s59, s29
	s_cselect_b32 s76, s58, s28
	s_cselect_b32 s75, s61, s3
	s_cselect_b32 s74, s60, s2
	v_lshl_add_u64 v[140:141], s[64:65], 0, v[148:149]
	s_add_i32 m0, s23, 0xc000
	ds_read_b128 v[160:163], v210
	ds_read_b128 v[164:167], v210 offset:1024
	ds_read_b128 v[168:171], v210 offset:2048
	ds_read_b128 v[172:175], v210 offset:3072
	ds_read_b128 v[176:179], v210 offset:4096
	ds_read_b128 v[180:183], v210 offset:5120
	ds_read_b128 v[184:187], v210 offset:6144
	ds_read_b128 v[188:191], v210 offset:7168
	global_load_lds_dwordx4 v[140:141], off
	v_lshl_add_u64 v[140:141], s[64:65], 0, v[150:151]
	s_add_i32 m0, s23, 0xe000
	s_nop 0
	global_load_lds_dwordx4 v[140:141], off
	s_waitcnt lgkmcnt(8)
	s_barrier
	s_waitcnt lgkmcnt(0)
	v_mfma_f32_16x16x32_bf16 v[124:127], v[128:131], v[160:163], v[124:127]
	v_mfma_f32_16x16x32_bf16 v[116:119], v[136:139], v[160:163], v[116:119]
	v_mfma_f32_16x16x32_bf16 v[108:111], v[128:131], v[168:171], v[108:111]
	v_mfma_f32_16x16x32_bf16 v[100:103], v[136:139], v[168:171], v[100:103]
	v_mfma_f32_16x16x32_bf16 v[92:95], v[128:131], v[176:179], v[92:95]
	v_mfma_f32_16x16x32_bf16 v[84:87], v[136:139], v[176:179], v[84:87]
	v_mfma_f32_16x16x32_bf16 v[76:79], v[128:131], v[184:187], v[76:79]
	v_mfma_f32_16x16x32_bf16 v[68:71], v[136:139], v[184:187], v[68:71]
	v_mfma_f32_16x16x32_bf16 v[124:127], v[132:135], v[164:167], v[124:127]
	v_mfma_f32_16x16x32_bf16 v[116:119], v[156:159], v[164:167], v[116:119]
	v_mfma_f32_16x16x32_bf16 v[108:111], v[132:135], v[172:175], v[108:111]
	v_mfma_f32_16x16x32_bf16 v[100:103], v[156:159], v[172:175], v[100:103]
	v_mfma_f32_16x16x32_bf16 v[92:95], v[132:135], v[180:183], v[92:95]
	v_mfma_f32_16x16x32_bf16 v[84:87], v[156:159], v[180:183], v[84:87]
	v_mfma_f32_16x16x32_bf16 v[76:79], v[132:135], v[188:191], v[76:79]
	v_mfma_f32_16x16x32_bf16 v[68:71], v[156:159], v[188:191], v[68:71]
	s_barrier
	s_add_i32 s28, s90, s21
	v_lshl_add_u64 v[140:141], s[74:75], 0, v[142:143]
	s_mov_b32 m0, s28
	ds_read_b128 v[192:195], v211
	ds_read_b128 v[196:199], v211 offset:1024
	ds_read_b128 v[200:203], v211 offset:2048
	ds_read_b128 v[212:215], v211 offset:3072
	global_load_lds_dwordx4 v[140:141], off
	v_lshl_add_u64 v[204:205], s[74:75], 0, v[144:145]
	s_add_i32 m0, s28, 0x2000
	s_nop 0
	global_load_lds_dwordx4 v[204:205], off
	s_barrier
	s_waitcnt lgkmcnt(0)
	v_mfma_f32_16x16x32_bf16 v[120:123], v[192:195], v[160:163], v[120:123]
	v_mfma_f32_16x16x32_bf16 v[112:115], v[200:203], v[160:163], v[112:115]
	v_mfma_f32_16x16x32_bf16 v[104:107], v[192:195], v[168:171], v[104:107]
	v_mfma_f32_16x16x32_bf16 v[96:99], v[200:203], v[168:171], v[96:99]
	v_mfma_f32_16x16x32_bf16 v[88:91], v[192:195], v[176:179], v[88:91]
	v_mfma_f32_16x16x32_bf16 v[80:83], v[200:203], v[176:179], v[80:83]
	v_mfma_f32_16x16x32_bf16 v[72:75], v[192:195], v[184:187], v[72:75]
	v_mfma_f32_16x16x32_bf16 v[64:67], v[200:203], v[184:187], v[64:67]
	v_mfma_f32_16x16x32_bf16 v[120:123], v[196:199], v[164:167], v[120:123]
	v_mfma_f32_16x16x32_bf16 v[112:115], v[212:215], v[164:167], v[112:115]
	v_mfma_f32_16x16x32_bf16 v[104:107], v[196:199], v[172:175], v[104:107]
	v_mfma_f32_16x16x32_bf16 v[96:99], v[212:215], v[172:175], v[96:99]
	v_mfma_f32_16x16x32_bf16 v[88:91], v[196:199], v[180:183], v[88:91]
	v_mfma_f32_16x16x32_bf16 v[80:83], v[212:215], v[180:183], v[80:83]
	v_mfma_f32_16x16x32_bf16 v[72:75], v[196:199], v[188:191], v[72:75]
	v_mfma_f32_16x16x32_bf16 v[64:67], v[212:215], v[188:191], v[64:67]
	s_barrier
	s_mov_b32 m0, s23
	v_lshl_add_u64 v[216:217], s[76:77], 0, v[142:143]
	ds_read_b128 v[160:163], v210 offset:16384
	ds_read_b128 v[164:167], v210 offset:17408
	ds_read_b128 v[168:171], v210 offset:18432
	ds_read_b128 v[172:175], v210 offset:19456
	ds_read_b128 v[176:179], v210 offset:20480
	ds_read_b128 v[180:183], v210 offset:21504
	ds_read_b128 v[184:187], v210 offset:22528
	ds_read_b128 v[188:191], v210 offset:23552
	global_load_lds_dwordx4 v[216:217], off
	v_lshl_add_u64 v[218:219], s[76:77], 0, v[144:145]
	s_mov_b32 m0, s35
	s_nop 0
	global_load_lds_dwordx4 v[218:219], off
	s_barrier
	s_waitcnt lgkmcnt(0)
	v_mfma_f32_16x16x32_bf16 v[60:63], v[128:131], v[160:163], v[60:63]
	v_mfma_f32_16x16x32_bf16 v[52:55], v[136:139], v[160:163], v[52:55]
	v_mfma_f32_16x16x32_bf16 v[44:47], v[128:131], v[168:171], v[44:47]
	v_mfma_f32_16x16x32_bf16 v[36:39], v[136:139], v[168:171], v[36:39]
	v_mfma_f32_16x16x32_bf16 v[28:31], v[128:131], v[176:179], v[28:31]
	v_mfma_f32_16x16x32_bf16 v[20:23], v[136:139], v[176:179], v[20:23]
	v_mfma_f32_16x16x32_bf16 v[12:15], v[128:131], v[184:187], v[12:15]
	v_mfma_f32_16x16x32_bf16 v[4:7], v[136:139], v[184:187], v[4:7]
	v_mfma_f32_16x16x32_bf16 v[60:63], v[132:135], v[164:167], v[60:63]
	v_mfma_f32_16x16x32_bf16 v[52:55], v[156:159], v[164:167], v[52:55]
	v_mfma_f32_16x16x32_bf16 v[44:47], v[132:135], v[172:175], v[44:47]
	v_mfma_f32_16x16x32_bf16 v[36:39], v[156:159], v[172:175], v[36:39]
	v_mfma_f32_16x16x32_bf16 v[28:31], v[132:135], v[180:183], v[28:31]
	v_mfma_f32_16x16x32_bf16 v[20:23], v[156:159], v[180:183], v[20:23]
	v_mfma_f32_16x16x32_bf16 v[12:15], v[132:135], v[188:191], v[12:15]
	v_mfma_f32_16x16x32_bf16 v[4:7], v[156:159], v[188:191], v[4:7]
	s_barrier
; #define WAIT_V(n) asm volatile("s_waitcnt vmcnt(" #n ")" ::: "memory")
; #define WAIT_L(n) asm volatile("s_waitcnt lgkmcnt(" #n ")" ::: "memory")
; #define BAR __builtin_amdgcn_s_barrier()
; #define SCHED __builtin_amdgcn_sched_barrier(0)
; template <class Get, class Epi>
; DI void gemm_stream(LAS unsigned char* lds, const int K, const int ld, Get get, Epi epi) {
;     ...
;             WAIT_V(6); BAR; MMA(1, 1, At, B1); BAR;
;             LDB(B0, 1, 0); SCHED; LDA(At, 1, 0); STAGE(SAo(0, 1), a2 + hstep);
;             WAIT_L(8); BAR; WAIT_L(0); MMA(0, 0, At, B0); BAR; SCHED;
;             LDB(B1, 1, 1); STAGE(SBo(1, 0), b3);
;             BAR; WAIT_L(0); MMA(0, 1, At, B1); BAR;
;             LDA(At, 1, 1); STAGE(SAo(1, 0), a3);
;             BAR; WAIT_L(0); MMA(1, 0, At, B0); BAR; SCHED;
	s_add_u32 s28, s74, 0x80000
	s_addc_u32 s29, s75, 0
	s_add_i32 s57, s91, s21
	v_lshl_add_u64 v[128:129], s[28:29], 0, v[142:143]
	s_mov_b32 m0, s57
	s_nop 0
	global_load_lds_dwordx4 v[128:129], off
	v_lshl_add_u64 v[128:129], s[28:29], 0, v[144:145]
	s_add_i32 m0, s57, 0x2000
	s_nop 0
	global_load_lds_dwordx4 v[128:129], off
	s_waitcnt vmcnt(6)
	s_barrier
	v_mfma_f32_16x16x32_bf16 v[56:59], v[192:195], v[160:163], v[56:59]
	v_mfma_f32_16x16x32_bf16 v[48:51], v[200:203], v[160:163], v[48:51]
	v_mfma_f32_16x16x32_bf16 v[40:43], v[192:195], v[168:171], v[40:43]
	v_mfma_f32_16x16x32_bf16 v[32:35], v[200:203], v[168:171], v[32:35]
	v_mfma_f32_16x16x32_bf16 v[24:27], v[192:195], v[176:179], v[24:27]
	v_mfma_f32_16x16x32_bf16 v[16:19], v[200:203], v[176:179], v[16:19]
	v_mfma_f32_16x16x32_bf16 v[8:11], v[192:195], v[184:187], v[8:11]
	v_mfma_f32_16x16x32_bf16 v[0:3], v[200:203], v[184:187], v[0:3]
	v_mfma_f32_16x16x32_bf16 v[56:59], v[196:199], v[164:167], v[56:59]
	v_mfma_f32_16x16x32_bf16 v[48:51], v[212:215], v[164:167], v[48:51]
	v_mfma_f32_16x16x32_bf16 v[40:43], v[196:199], v[172:175], v[40:43]
	v_mfma_f32_16x16x32_bf16 v[32:35], v[212:215], v[172:175], v[32:35]
	v_mfma_f32_16x16x32_bf16 v[24:27], v[196:199], v[180:183], v[24:27]
	v_mfma_f32_16x16x32_bf16 v[16:19], v[212:215], v[180:183], v[16:19]
	v_mfma_f32_16x16x32_bf16 v[8:11], v[196:199], v[188:191], v[8:11]
	v_mfma_f32_16x16x32_bf16 v[0:3], v[212:215], v[188:191], v[0:3]
	s_add_i32 s57, 16, 0x18000
	v_add_u32_e32 v146, s57, v208
	s_barrier
	ds_read_b128 v[128:131], v146
	ds_read_b128 v[132:135], v146 offset:1024
	ds_read_b128 v[136:139], v146 offset:2048
	ds_read_b128 v[156:159], v146 offset:3072
	s_add_u32 s28, s76, 0x80000
	s_addc_u32 s29, s77, 0
	s_mov_b32 m0, s55
	v_lshl_add_u64 v[192:193], s[28:29], 0, v[142:143]
	ds_read_b128 v[160:163], v210 offset:32768
	ds_read_b128 v[164:167], v210 offset:33792
	ds_read_b128 v[168:171], v210 offset:34816
	ds_read_b128 v[172:175], v210 offset:35840
	ds_read_b128 v[176:179], v210 offset:36864
	ds_read_b128 v[180:183], v210 offset:37888
	ds_read_b128 v[184:187], v210 offset:38912
	ds_read_b128 v[188:191], v210 offset:39936
	global_load_lds_dwordx4 v[192:193], off
	v_lshl_add_u64 v[192:193], s[28:29], 0, v[144:145]
	s_mov_b32 m0, s82
	s_nop 0
	global_load_lds_dwordx4 v[192:193], off
	s_waitcnt lgkmcnt(8)
	s_barrier
	s_waitcnt lgkmcnt(0)
	v_mfma_f32_16x16x32_bf16 v[124:127], v[128:131], v[160:163], v[124:127]
	v_mfma_f32_16x16x32_bf16 v[116:119], v[136:139], v[160:163], v[116:119]
	v_mfma_f32_16x16x32_bf16 v[108:111], v[128:131], v[168:171], v[108:111]
	v_mfma_f32_16x16x32_bf16 v[100:103], v[136:139], v[168:171], v[100:103]
	v_mfma_f32_16x16x32_bf16 v[92:95], v[128:131], v[176:179], v[92:95]
	v_mfma_f32_16x16x32_bf16 v[84:87], v[136:139], v[176:179], v[84:87]
	v_mfma_f32_16x16x32_bf16 v[76:79], v[128:131], v[184:187], v[76:79]
	v_mfma_f32_16x16x32_bf16 v[68:71], v[136:139], v[184:187], v[68:71]
	v_mfma_f32_16x16x32_bf16 v[124:127], v[132:135], v[164:167], v[124:127]
	v_mfma_f32_16x16x32_bf16 v[116:119], v[156:159], v[164:167], v[116:119]
	v_mfma_f32_16x16x32_bf16 v[108:111], v[132:135], v[172:175], v[108:111]
	v_mfma_f32_16x16x32_bf16 v[100:103], v[156:159], v[172:175], v[100:103]
	v_mfma_f32_16x16x32_bf16 v[92:95], v[132:135], v[180:183], v[92:95]
	v_mfma_f32_16x16x32_bf16 v[84:87], v[156:159], v[180:183], v[84:87]
	v_mfma_f32_16x16x32_bf16 v[76:79], v[132:135], v[188:191], v[76:79]
	v_mfma_f32_16x16x32_bf16 v[68:71], v[156:159], v[188:191], v[68:71]
	s_barrier
	s_add_i32 s63, 16, 0x1c000
	s_add_i32 s28, s57, s21
	v_add_u32_e32 v146, s63, v208
	v_lshl_add_u64 v[140:141], v[140:141], 0, s[0:1]
	s_mov_b32 m0, s28
	ds_read_b128 v[192:195], v146
	ds_read_b128 v[196:199], v146 offset:1024
	ds_read_b128 v[200:203], v146 offset:2048
	ds_read_b128 v[212:215], v146 offset:3072
	global_load_lds_dwordx4 v[140:141], off
	v_lshl_add_u64 v[140:141], v[204:205], 0, s[0:1]
	s_add_i32 m0, s28, 0x2000
	s_nop 0
	global_load_lds_dwordx4 v[140:141], off
	s_barrier
	s_waitcnt lgkmcnt(0)
	v_mfma_f32_16x16x32_bf16 v[120:123], v[192:195], v[160:163], v[120:123]
	v_mfma_f32_16x16x32_bf16 v[112:115], v[200:203], v[160:163], v[112:115]
	v_mfma_f32_16x16x32_bf16 v[104:107], v[192:195], v[168:171], v[104:107]
	v_mfma_f32_16x16x32_bf16 v[96:99], v[200:203], v[168:171], v[96:99]
	v_mfma_f32_16x16x32_bf16 v[88:91], v[192:195], v[176:179], v[88:91]
	v_mfma_f32_16x16x32_bf16 v[80:83], v[200:203], v[176:179], v[80:83]
	v_mfma_f32_16x16x32_bf16 v[72:75], v[192:195], v[184:187], v[72:75]
	v_mfma_f32_16x16x32_bf16 v[64:67], v[200:203], v[184:187], v[64:67]
	v_mfma_f32_16x16x32_bf16 v[120:123], v[196:199], v[164:167], v[120:123]
	v_mfma_f32_16x16x32_bf16 v[112:115], v[212:215], v[164:167], v[112:115]
	v_mfma_f32_16x16x32_bf16 v[104:107], v[196:199], v[172:175], v[104:107]
	v_mfma_f32_16x16x32_bf16 v[96:99], v[212:215], v[172:175], v[96:99]
	v_mfma_f32_16x16x32_bf16 v[88:91], v[196:199], v[180:183], v[88:91]
	v_mfma_f32_16x16x32_bf16 v[80:83], v[212:215], v[180:183], v[80:83]
	v_mfma_f32_16x16x32_bf16 v[72:75], v[196:199], v[188:191], v[72:75]
	v_mfma_f32_16x16x32_bf16 v[64:67], v[212:215], v[188:191], v[64:67]
	s_barrier
	s_mov_b32 m0, s83
	v_lshl_add_u64 v[140:141], v[216:217], 0, s[0:1]
	ds_read_b128 v[160:163], v210 offset:49152
	ds_read_b128 v[164:167], v210 offset:50176
	ds_read_b128 v[168:171], v210 offset:51200
	ds_read_b128 v[172:175], v210 offset:52224
	ds_read_b128 v[176:179], v210 offset:53248
	ds_read_b128 v[180:183], v210 offset:54272
	ds_read_b128 v[184:187], v210 offset:55296
	ds_read_b128 v[188:191], v210 offset:56320
	global_load_lds_dwordx4 v[140:141], off
	v_lshl_add_u64 v[140:141], v[218:219], 0, s[0:1]
	s_mov_b32 m0, s85
	s_nop 0
	global_load_lds_dwordx4 v[140:141], off
	s_barrier
; #define WAIT_V(n) asm volatile("s_waitcnt vmcnt(" #n ")" ::: "memory")
; #define WAIT_L(n) asm volatile("s_waitcnt lgkmcnt(" #n ")" ::: "memory")
; #define BAR __builtin_amdgcn_s_barrier()
; #define SCHED __builtin_amdgcn_sched_barrier(0)
; template <class Get, class Epi>
; DI void gemm_stream(LAS unsigned char* lds, const int K, const int ld, Get get, Epi epi) {
;     ...
;             BAR; WAIT_L(0); MMA(1, 0, At, B0); BAR; SCHED;
;             STAGE(SBo(1, 1), b3 + hstep);
;             WAIT_V(6); BAR; MMA(1, 1, At, B1); BAR;
; DI void phase_inproj1(const P& p, char* shm) {
;     ...
;     auto epi = [&](const Acc& acc, const Unit& u) {
;         const int brow = u.pm * 256, pn = u.pn;
;         const int b = u.pm / 17, pt = u.pm % 17;
;         const size_t latrow0 = (size_t)b * SEQ + (pt - 1) * 256;
;         if (pn < 8) epi_rope256(acc, p, brow, (bf16_t*)(p.ws + O_Q1), latrow0, pn * 256, 1.f);
;         else if (pn < 16) epi_rope256(acc, p, brow, (bf16_t*)(p.ws + O_K1), (size_t)brow, (pn - 8) * 256, 0.0625f);
;         else if (pn < 32) epi_T<32>(acc, (pn - 16) * 256, brow, (bf16_t*)(p.ws + O_V1T), 4096, nullptr);
;         else epi_plain(acc, 0, (bf16_t*)(p.ws + O_G1) + latrow0 * 4096, 4096, (pn - 32) * 256, nullptr);
	s_waitcnt lgkmcnt(0)
	v_mfma_f32_16x16x32_bf16 v[60:63], v[128:131], v[160:163], v[60:63]
	v_mfma_f32_16x16x32_bf16 v[52:55], v[136:139], v[160:163], v[52:55]
	v_mfma_f32_16x16x32_bf16 v[44:47], v[128:131], v[168:171], v[44:47]
	v_mfma_f32_16x16x32_bf16 v[36:39], v[136:139], v[168:171], v[36:39]
	v_mfma_f32_16x16x32_bf16 v[28:31], v[128:131], v[176:179], v[28:31]
	v_mfma_f32_16x16x32_bf16 v[20:23], v[136:139], v[176:179], v[20:23]
	v_mfma_f32_16x16x32_bf16 v[12:15], v[128:131], v[184:187], v[12:15]
	v_mfma_f32_16x16x32_bf16 v[4:7], v[136:139], v[184:187], v[4:7]
	v_mfma_f32_16x16x32_bf16 v[60:63], v[132:135], v[164:167], v[60:63]
	v_mfma_f32_16x16x32_bf16 v[52:55], v[156:159], v[164:167], v[52:55]
	v_mfma_f32_16x16x32_bf16 v[44:47], v[132:135], v[172:175], v[44:47]
	v_mfma_f32_16x16x32_bf16 v[36:39], v[156:159], v[172:175], v[36:39]
	v_mfma_f32_16x16x32_bf16 v[28:31], v[132:135], v[180:183], v[28:31]
	v_mfma_f32_16x16x32_bf16 v[20:23], v[156:159], v[180:183], v[20:23]
	v_mfma_f32_16x16x32_bf16 v[12:15], v[132:135], v[188:191], v[12:15]
	v_mfma_f32_16x16x32_bf16 v[4:7], v[156:159], v[188:191], v[4:7]
	s_barrier
	s_add_u32 s28, s74, 0x80080
	s_addc_u32 s29, s75, 0
	s_add_i32 s57, s63, s21
	v_lshl_add_u64 v[128:129], s[28:29], 0, v[142:143]
	s_mov_b32 m0, s57
	s_nop 0
	global_load_lds_dwordx4 v[128:129], off
	v_lshl_add_u64 v[128:129], s[28:29], 0, v[144:145]
	s_add_i32 m0, s57, 0x2000
	s_nop 0
	global_load_lds_dwordx4 v[128:129], off
	s_waitcnt vmcnt(6)
	s_barrier
	v_mfma_f32_16x16x32_bf16 v[56:59], v[192:195], v[160:163], v[56:59]
	v_mfma_f32_16x16x32_bf16 v[48:51], v[200:203], v[160:163], v[48:51]
	v_mfma_f32_16x16x32_bf16 v[40:43], v[192:195], v[168:171], v[40:43]
	v_mfma_f32_16x16x32_bf16 v[32:35], v[200:203], v[168:171], v[32:35]
	v_mfma_f32_16x16x32_bf16 v[24:27], v[192:195], v[176:179], v[24:27]
	v_mfma_f32_16x16x32_bf16 v[16:19], v[200:203], v[176:179], v[16:19]
	v_mfma_f32_16x16x32_bf16 v[8:11], v[192:195], v[184:187], v[8:11]
	v_mfma_f32_16x16x32_bf16 v[0:3], v[200:203], v[184:187], v[0:3]
	v_mfma_f32_16x16x32_bf16 v[56:59], v[196:199], v[164:167], v[56:59]
	v_mfma_f32_16x16x32_bf16 v[48:51], v[212:215], v[164:167], v[48:51]
	v_mfma_f32_16x16x32_bf16 v[40:43], v[196:199], v[172:175], v[40:43]
	v_mfma_f32_16x16x32_bf16 v[32:35], v[212:215], v[172:175], v[32:35]
	v_mfma_f32_16x16x32_bf16 v[24:27], v[196:199], v[180:183], v[24:27]
	v_mfma_f32_16x16x32_bf16 v[16:19], v[212:215], v[180:183], v[16:19]
	v_mfma_f32_16x16x32_bf16 v[8:11], v[196:199], v[188:191], v[8:11]
	v_mfma_f32_16x16x32_bf16 v[0:3], v[212:215], v[188:191], v[0:3]
	s_barrier
	s_add_i32 s7, s7, 2
	s_add_u32 s64, s64, 0x100
	s_addc_u32 s65, s65, 0
	s_add_u32 s2, s2, 0x100
	s_addc_u32 s3, s3, 0
	s_cmp_gt_u32 s7, 29
	s_cbranch_scc0 .LBB0_2102
	s_mul_hi_i32 s2, s6, 0x78787879
	s_lshr_b32 s3, s2, 31
	s_ashr_i32 s2, s2, 3
	s_add_i32 s76, s2, s3
	s_mul_i32 s2, s76, 17
	s_lshl_b32 s74, s6, 8
	s_sub_i32 s6, s6, s2
	s_lshl_b32 s6, s6, 8
	s_ashr_i32 s77, s76, 31
	s_addk_i32 s6, 0xff00
	s_lshl_b64 s[2:3], s[76:77], 12
	s_ashr_i32 s7, s6, 31
	s_add_u32 s64, s2, s6
	s_addc_u32 s65, s3, s7
	s_cmp_gt_i32 s62, 7
	s_mov_b64 s[6:7], -1
	s_cbranch_scc0 .LBB0_2145
	s_cmp_gt_u32 s62, 15
	s_cbranch_scc0 .LBB0_2110
	s_cmp_gt_u32 s62, 31
	v_cvt_pk_bf16_f32 v204, v124, v125
	v_cvt_pk_bf16_f32 v205, v126, v127
	v_cvt_pk_bf16_f32 v202, v116, v117
	v_cvt_pk_bf16_f32 v203, v118, v119
	v_cvt_pk_bf16_f32 v200, v120, v121
	v_cvt_pk_bf16_f32 v201, v122, v123
	v_cvt_pk_bf16_f32 v198, v112, v113
	v_cvt_pk_bf16_f32 v199, v114, v115
	v_cvt_pk_bf16_f32 v196, v108, v109
	v_cvt_pk_bf16_f32 v197, v110, v111
	v_cvt_pk_bf16_f32 v194, v100, v101
	v_cvt_pk_bf16_f32 v195, v102, v103
	v_cvt_pk_bf16_f32 v192, v104, v105
	v_cvt_pk_bf16_f32 v193, v106, v107
	v_cvt_pk_bf16_f32 v190, v96, v97
	v_cvt_pk_bf16_f32 v191, v98, v99
	v_cvt_pk_bf16_f32 v188, v92, v93
	v_cvt_pk_bf16_f32 v189, v94, v95
	v_cvt_pk_bf16_f32 v186, v84, v85
	v_cvt_pk_bf16_f32 v187, v86, v87
	v_cvt_pk_bf16_f32 v184, v88, v89
	v_cvt_pk_bf16_f32 v185, v90, v91
	v_cvt_pk_bf16_f32 v182, v80, v81
	v_cvt_pk_bf16_f32 v183, v82, v83
	v_cvt_pk_bf16_f32 v180, v76, v77
	v_cvt_pk_bf16_f32 v181, v78, v79
	v_cvt_pk_bf16_f32 v178, v68, v69
	v_cvt_pk_bf16_f32 v179, v70, v71
	v_cvt_pk_bf16_f32 v176, v72, v73
	v_cvt_pk_bf16_f32 v177, v74, v75
	v_cvt_pk_bf16_f32 v174, v64, v65
	v_cvt_pk_bf16_f32 v175, v66, v67
	v_cvt_pk_bf16_f32 v172, v60, v61
	v_cvt_pk_bf16_f32 v173, v62, v63
	v_cvt_pk_bf16_f32 v170, v52, v53
	v_cvt_pk_bf16_f32 v171, v54, v55
	v_cvt_pk_bf16_f32 v168, v56, v57
	v_cvt_pk_bf16_f32 v169, v58, v59
	v_cvt_pk_bf16_f32 v166, v48, v49
	v_cvt_pk_bf16_f32 v167, v50, v51
	v_cvt_pk_bf16_f32 v164, v44, v45
	v_cvt_pk_bf16_f32 v165, v46, v47
	v_cvt_pk_bf16_f32 v162, v36, v37
	v_cvt_pk_bf16_f32 v163, v38, v39
	v_cvt_pk_bf16_f32 v160, v40, v41
	v_cvt_pk_bf16_f32 v161, v42, v43
	v_cvt_pk_bf16_f32 v158, v32, v33
	v_cvt_pk_bf16_f32 v159, v34, v35
	v_cvt_pk_bf16_f32 v156, v28, v29
	v_cvt_pk_bf16_f32 v157, v30, v31
	v_cvt_pk_bf16_f32 v140, v20, v21
	v_cvt_pk_bf16_f32 v141, v22, v23
	v_cvt_pk_bf16_f32 v138, v24, v25
	v_cvt_pk_bf16_f32 v139, v26, v27
	v_cvt_pk_bf16_f32 v136, v16, v17
	v_cvt_pk_bf16_f32 v137, v18, v19
	v_cvt_pk_bf16_f32 v134, v12, v13
	v_cvt_pk_bf16_f32 v135, v14, v15
	v_cvt_pk_bf16_f32 v132, v4, v5
	v_cvt_pk_bf16_f32 v133, v6, v7
	v_cvt_pk_bf16_f32 v130, v8, v9
	v_cvt_pk_bf16_f32 v131, v10, v11
	v_cvt_pk_bf16_f32 v128, v0, v1
	v_cvt_pk_bf16_f32 v129, v2, v3
	s_cbranch_scc0 .LBB0_2107
; #define EPI_DONE do { } while (0)
; DI void epi_plain(const Acc& acc, int brow, bf16_t* dst, int ld, int coff, const float* rs) {
;     EPI_IDX
; #pragma unroll
;     for (int ai = 0; ai < 2; ++ai)
; #pragma unroll
;         for (int m = 0; m < 4; ++m) {
;             const int lr = ai * 128 + wr * 64 + m * 16 + fr;
;             const float s = rs ? rs[lr] : 1.f;
;             bf16_t* rp = dst + (size_t)(brow + lr) * ld + coff + wc * 32 + fq * 4;
; #pragma unroll
;             for (int bj = 0; bj < 2; ++bj)
; #pragma unroll
;                 for (int n = 0; n < 2; ++n) { const f32x4 v = acc[ai][bj][m][n]; st4(rp + bj * 128 + n * 16, v[0] * s, v[1] * s, v[2] * s, v[3] * s); }
;         }
;     EPI_DONE;
; }
	s_lshl_b64 s[2:3], s[64:65], 13
	s_add_u32 s2, s26, s2
	s_addc_u32 s3, s27, s3
	v_mov_b32_e32 v146, v206
	s_lshl_b32 s6, s62, 9
	s_add_u32 s2, s2, s6
	v_and_b32_e32 v212, 15, v146
	v_ashrrev_i32_e32 v213, 2, v146
	v_and_or_b32 v212, v213, s92, v212
	s_addc_u32 s3, s3, 0
	v_lshrrev_b32_e32 v213, 1, v146
	v_and_b32_e32 v146, 0xc0, v146
	v_lshl_add_u64 v[214:215], s[2:3], 0, v[146:147]
	v_and_b32_e32 v146, 24, v213
	v_or_b32_e32 v218, 16, v212
	v_lshl_add_u64 v[214:215], v[214:215], 0, v[146:147]
	s_mov_b64 s[2:3], 0x1a3fc000
	v_ashrrev_i32_e32 v213, 31, v212
	v_ashrrev_i32_e32 v219, 31, v218
	v_lshl_add_u64 v[214:215], v[214:215], 0, s[2:3]
	v_lshlrev_b64 v[216:217], 13, v[212:213]
	v_lshlrev_b64 v[218:219], 13, v[218:219]
	v_lshl_add_u64 v[216:217], v[214:215], 0, v[216:217]
	v_lshl_add_u64 v[218:219], v[214:215], 0, v[218:219]
	global_store_dwordx2 v[216:217], v[204:205], off
	global_store_dwordx2 v[216:217], v[202:203], off offset:32
	global_store_dwordx2 v[216:217], v[200:201], off offset:256
	global_store_dwordx2 v[216:217], v[198:199], off offset:288
	global_store_dwordx2 v[218:219], v[196:197], off
	global_store_dwordx2 v[218:219], v[194:195], off offset:32
	global_store_dwordx2 v[218:219], v[192:193], off offset:256
	global_store_dwordx2 v[218:219], v[190:191], off offset:288
	v_or_b32_e32 v218, 32, v212
	v_or_b32_e32 v212, 48, v212
	v_ashrrev_i32_e32 v219, 31, v218
	v_ashrrev_i32_e32 v213, 31, v212
	v_lshlrev_b64 v[218:219], 13, v[218:219]
	v_lshlrev_b64 v[212:213], 13, v[212:213]
	v_lshl_add_u64 v[218:219], v[214:215], 0, v[218:219]
	v_lshl_add_u64 v[212:213], v[214:215], 0, v[212:213]
	s_mov_b64 s[2:3], 0x100000
	global_store_dwordx2 v[218:219], v[188:189], off
	global_store_dwordx2 v[218:219], v[186:187], off offset:32
	global_store_dwordx2 v[218:219], v[184:185], off offset:256
	global_store_dwordx2 v[218:219], v[182:183], off offset:288
	global_store_dwordx2 v[212:213], v[180:181], off
	global_store_dwordx2 v[212:213], v[178:179], off offset:32
	global_store_dwordx2 v[212:213], v[176:177], off offset:256
	global_store_dwordx2 v[212:213], v[174:175], off offset:288
	v_lshl_add_u64 v[212:213], v[216:217], 0, s[2:3]
	s_mov_b32 s2, 0x100000
	v_add_co_u32_e32 v214, vcc, s2, v216
	s_mov_b64 s[2:3], 0x120000
	s_nop 0
	v_addc_co_u32_e32 v215, vcc, 0, v217, vcc
	global_store_dwordx2 v[214:215], v[172:173], off
	global_store_dwordx2 v[212:213], v[170:171], off offset:32
	global_store_dwordx2 v[212:213], v[168:169], off offset:256
	global_store_dwordx2 v[212:213], v[166:167], off offset:288
	v_add_co_u32_e32 v214, vcc, s93, v216
	v_lshl_add_u64 v[212:213], v[216:217], 0, s[2:3]
	s_nop 0
	v_addc_co_u32_e32 v215, vcc, 0, v217, vcc
	global_store_dwordx2 v[214:215], v[164:165], off
	global_store_dwordx2 v[212:213], v[162:163], off offset:32
	global_store_dwordx2 v[212:213], v[160:161], off offset:256
	global_store_dwordx2 v[212:213], v[158:159], off offset:288
	v_add_co_u32_e32 v214, vcc, s94, v216
	v_lshl_add_u64 v[212:213], v[216:217], 0, s[16:17]
	s_nop 0
	v_addc_co_u32_e32 v215, vcc, 0, v217, vcc
	global_store_dwordx2 v[214:215], v[156:157], off
	global_store_dwordx2 v[212:213], v[140:141], off offset:32
	global_store_dwordx2 v[212:213], v[138:139], off offset:256
	global_store_dwordx2 v[212:213], v[136:137], off offset:288
	v_add_co_u32_e32 v214, vcc, s95, v216
	v_lshl_add_u64 v[212:213], v[216:217], 0, s[18:19]
	s_nop 0
	v_addc_co_u32_e32 v215, vcc, 0, v217, vcc
	global_store_dwordx2 v[214:215], v[134:135], off
	global_store_dwordx2 v[212:213], v[132:133], off offset:32
	global_store_dwordx2 v[212:213], v[130:131], off offset:256
	global_store_dwordx2 v[212:213], v[128:129], off offset:288
	s_mov_b64 s[6:7], 0

; #define WAIT_V(n) asm volatile("s_waitcnt vmcnt(" #n ")" ::: "memory")
; #define WAIT_L(n) asm volatile("s_waitcnt lgkmcnt(" #n ")" ::: "memory")
; #define BAR __builtin_amdgcn_s_barrier()
; #define SCHED __builtin_amdgcn_sched_barrier(0)
; template <class Get, class Epi>
; DI void gemm_stream(LAS unsigned char* lds, const int K, const int ld, Get get, Epi epi) {
;     ...
;             LDB(B0, 0, 0); SCHED; LDA(At, 0, 0); STAGE(SAo(1, 1), a1 + hstep);
;             WAIT_L(8); BAR; WAIT_L(0); MMA(0, 0, At, B0); BAR; SCHED;
;             LDB(B1, 0, 1); STAGE(SBo(0, 0), b2);
;             BAR; WAIT_L(0); MMA(0, 1, At, B1); BAR;
;             LDA(At, 0, 1); STAGE(SAo(0, 0), a2);
;             BAR; WAIT_L(0); MMA(1, 0, At, B0); BAR; SCHED;
;             STAGE(SBo(0, 1), b2 + hstep);
;             WAIT_V(6); BAR; MMA(1, 1, At, B1); BAR;
.LBB0_2670:
	ds_read_b128 v[128:131], v198
	ds_read_b128 v[132:135], v198 offset:1024
	ds_read_b128 v[136:139], v198 offset:2048
	ds_read_b128 v[140:143], v198 offset:3072
	s_add_u32 s8, s6, 0x100
	s_addc_u32 s9, s7, 0
	s_cmp_eq_u32 s16, 60
	s_cselect_b32 s13, s39, s9
	s_cselect_b32 s12, s38, s8
	s_cselect_b32 s11, s41, s15
	s_cselect_b32 s10, s40, s14
	s_mov_b32 m0, s52
	v_lshl_add_u64 v[186:187], s[6:7], 0, v[168:169]
	ds_read_b128 v[144:147], v199
	ds_read_b128 v[148:151], v199 offset:1024
	ds_read_b128 v[152:155], v199 offset:2048
	ds_read_b128 v[156:159], v199 offset:3072
	ds_read_b128 v[160:163], v199 offset:4096
	ds_read_b128 v[174:177], v199 offset:5120
	ds_read_b128 v[178:181], v199 offset:6144
	ds_read_b128 v[182:185], v199 offset:7168
	global_load_lds_dwordx4 v[186:187], off
	v_lshl_add_u64 v[186:187], s[6:7], 0, v[170:171]
	s_mov_b32 m0, s53
	s_nop 0
	global_load_lds_dwordx4 v[186:187], off
	s_waitcnt lgkmcnt(8)
	s_barrier
	s_waitcnt lgkmcnt(0)
	v_mfma_f32_16x16x32_bf16 v[124:127], v[128:131], v[144:147], v[124:127]
	v_mfma_f32_16x16x32_bf16 v[92:95], v[136:139], v[144:147], v[92:95]
	v_mfma_f32_16x16x32_bf16 v[120:123], v[128:131], v[152:155], v[120:123]
	v_mfma_f32_16x16x32_bf16 v[88:91], v[136:139], v[152:155], v[88:91]
	v_mfma_f32_16x16x32_bf16 v[116:119], v[128:131], v[160:163], v[116:119]
	v_mfma_f32_16x16x32_bf16 v[84:87], v[136:139], v[160:163], v[84:87]
	v_mfma_f32_16x16x32_bf16 v[112:115], v[128:131], v[178:181], v[112:115]
	v_mfma_f32_16x16x32_bf16 v[80:83], v[136:139], v[178:181], v[80:83]
	v_mfma_f32_16x16x32_bf16 v[124:127], v[132:135], v[148:151], v[124:127]
	v_mfma_f32_16x16x32_bf16 v[92:95], v[140:143], v[148:151], v[92:95]
	v_mfma_f32_16x16x32_bf16 v[120:123], v[132:135], v[156:159], v[120:123]
	v_mfma_f32_16x16x32_bf16 v[88:91], v[140:143], v[156:159], v[88:91]
	v_mfma_f32_16x16x32_bf16 v[116:119], v[132:135], v[174:177], v[116:119]
	v_mfma_f32_16x16x32_bf16 v[84:87], v[140:143], v[174:177], v[84:87]
	v_mfma_f32_16x16x32_bf16 v[112:115], v[132:135], v[182:185], v[112:115]
	v_mfma_f32_16x16x32_bf16 v[80:83], v[140:143], v[182:185], v[80:83]
	s_barrier
	s_mov_b32 m0, s58
	v_lshl_add_u64 v[204:205], s[10:11], 0, v[164:165]
	ds_read_b128 v[186:189], v200
	ds_read_b128 v[190:193], v200 offset:1024
	ds_read_b128 v[194:197], v200 offset:2048
	ds_read_b128 v[208:211], v200 offset:3072
	global_load_lds_dwordx4 v[204:205], off
	v_lshl_add_u64 v[212:213], s[10:11], 0, v[166:167]
	s_mov_b32 m0, s59
	s_nop 0
	global_load_lds_dwordx4 v[212:213], off
	s_barrier
	s_waitcnt lgkmcnt(0)
	v_mfma_f32_16x16x32_bf16 v[60:63], v[186:189], v[144:147], v[60:63]
	v_mfma_f32_16x16x32_bf16 v[28:31], v[194:197], v[144:147], v[28:31]
	v_mfma_f32_16x16x32_bf16 v[56:59], v[186:189], v[152:155], v[56:59]
	v_mfma_f32_16x16x32_bf16 v[24:27], v[194:197], v[152:155], v[24:27]
	v_mfma_f32_16x16x32_bf16 v[52:55], v[186:189], v[160:163], v[52:55]
	v_mfma_f32_16x16x32_bf16 v[20:23], v[194:197], v[160:163], v[20:23]
	v_mfma_f32_16x16x32_bf16 v[48:51], v[186:189], v[178:181], v[48:51]
	v_mfma_f32_16x16x32_bf16 v[16:19], v[194:197], v[178:181], v[16:19]
	v_mfma_f32_16x16x32_bf16 v[60:63], v[190:193], v[148:151], v[60:63]
	v_mfma_f32_16x16x32_bf16 v[28:31], v[208:211], v[148:151], v[28:31]
	v_mfma_f32_16x16x32_bf16 v[56:59], v[190:193], v[156:159], v[56:59]
	v_mfma_f32_16x16x32_bf16 v[24:27], v[208:211], v[156:159], v[24:27]
	v_mfma_f32_16x16x32_bf16 v[52:55], v[190:193], v[174:177], v[52:55]
	v_mfma_f32_16x16x32_bf16 v[20:23], v[208:211], v[174:177], v[20:23]
	v_mfma_f32_16x16x32_bf16 v[48:51], v[190:193], v[182:185], v[48:51]
	v_mfma_f32_16x16x32_bf16 v[16:19], v[208:211], v[182:185], v[16:19]
	s_barrier
	s_mov_b32 m0, s35
	v_lshl_add_u64 v[214:215], s[12:13], 0, v[164:165]
	ds_read_b128 v[144:147], v199 offset:16384
	ds_read_b128 v[148:151], v199 offset:17408
	ds_read_b128 v[152:155], v199 offset:18432
	ds_read_b128 v[156:159], v199 offset:19456
	ds_read_b128 v[160:163], v199 offset:20480
	ds_read_b128 v[174:177], v199 offset:21504
	ds_read_b128 v[178:181], v199 offset:22528
	ds_read_b128 v[182:185], v199 offset:23552
	global_load_lds_dwordx4 v[214:215], off
	v_lshl_add_u64 v[216:217], s[12:13], 0, v[166:167]
	s_mov_b32 m0, s44
	s_nop 0
	global_load_lds_dwordx4 v[216:217], off
	s_barrier
	s_waitcnt lgkmcnt(0)
	v_mfma_f32_16x16x32_bf16 v[108:111], v[128:131], v[144:147], v[108:111]
	v_mfma_f32_16x16x32_bf16 v[76:79], v[136:139], v[144:147], v[76:79]
	v_mfma_f32_16x16x32_bf16 v[104:107], v[128:131], v[152:155], v[104:107]
	v_mfma_f32_16x16x32_bf16 v[72:75], v[136:139], v[152:155], v[72:75]
	v_mfma_f32_16x16x32_bf16 v[100:103], v[128:131], v[160:163], v[100:103]
	v_mfma_f32_16x16x32_bf16 v[68:71], v[136:139], v[160:163], v[68:71]
	v_mfma_f32_16x16x32_bf16 v[96:99], v[128:131], v[178:181], v[96:99]
	v_mfma_f32_16x16x32_bf16 v[64:67], v[136:139], v[178:181], v[64:67]
	v_mfma_f32_16x16x32_bf16 v[108:111], v[132:135], v[148:151], v[108:111]
	v_mfma_f32_16x16x32_bf16 v[76:79], v[140:143], v[148:151], v[76:79]
	v_mfma_f32_16x16x32_bf16 v[104:107], v[132:135], v[156:159], v[104:107]
	v_mfma_f32_16x16x32_bf16 v[72:75], v[140:143], v[156:159], v[72:75]
	v_mfma_f32_16x16x32_bf16 v[100:103], v[132:135], v[174:177], v[100:103]
	v_mfma_f32_16x16x32_bf16 v[68:71], v[140:143], v[174:177], v[68:71]
	v_mfma_f32_16x16x32_bf16 v[96:99], v[132:135], v[182:185], v[96:99]
	v_mfma_f32_16x16x32_bf16 v[64:67], v[140:143], v[182:185], v[64:67]
	s_barrier
	s_add_u32 s6, s10, 0x100000
	s_addc_u32 s7, s11, 0
	s_mov_b32 m0, s60
	v_lshl_add_u64 v[128:129], s[6:7], 0, v[164:165]
	global_load_lds_dwordx4 v[128:129], off
	v_lshl_add_u64 v[128:129], s[6:7], 0, v[166:167]
	s_mov_b32 m0, s61
	s_nop 0
	global_load_lds_dwordx4 v[128:129], off
	s_waitcnt vmcnt(6)
	s_barrier
; #define WAIT_V(n) asm volatile("s_waitcnt vmcnt(" #n ")" ::: "memory")
; #define WAIT_L(n) asm volatile("s_waitcnt lgkmcnt(" #n ")" ::: "memory")
; #define BAR __builtin_amdgcn_s_barrier()
; #define SCHED __builtin_amdgcn_sched_barrier(0)
; template <class Get, class Epi>
; DI void gemm_stream(LAS unsigned char* lds, const int K, const int ld, Get get, Epi epi) {
;     ...
;             WAIT_V(6); BAR; MMA(1, 1, At, B1); BAR;
;             LDB(B0, 1, 0); SCHED; LDA(At, 1, 0); STAGE(SAo(0, 1), a2 + hstep);
;             WAIT_L(8); BAR; WAIT_L(0); MMA(0, 0, At, B0); BAR; SCHED;
;             LDB(B1, 1, 1); STAGE(SBo(1, 0), b3);
;             BAR; WAIT_L(0); MMA(0, 1, At, B1); BAR;
;             LDA(At, 1, 1); STAGE(SAo(1, 0), a3);
;             BAR; WAIT_L(0); MMA(1, 0, At, B0); BAR; SCHED;
	v_mfma_f32_16x16x32_bf16 v[44:47], v[186:189], v[144:147], v[44:47]
	v_mfma_f32_16x16x32_bf16 v[12:15], v[194:197], v[144:147], v[12:15]
	v_mfma_f32_16x16x32_bf16 v[40:43], v[186:189], v[152:155], v[40:43]
	v_mfma_f32_16x16x32_bf16 v[8:11], v[194:197], v[152:155], v[8:11]
	v_mfma_f32_16x16x32_bf16 v[36:39], v[186:189], v[160:163], v[36:39]
	v_mfma_f32_16x16x32_bf16 v[4:7], v[194:197], v[160:163], v[4:7]
	v_mfma_f32_16x16x32_bf16 v[32:35], v[186:189], v[178:181], v[32:35]
	v_mfma_f32_16x16x32_bf16 v[0:3], v[194:197], v[178:181], v[0:3]
	v_mfma_f32_16x16x32_bf16 v[44:47], v[190:193], v[148:151], v[44:47]
	v_mfma_f32_16x16x32_bf16 v[12:15], v[208:211], v[148:151], v[12:15]
	v_mfma_f32_16x16x32_bf16 v[40:43], v[190:193], v[156:159], v[40:43]
	v_mfma_f32_16x16x32_bf16 v[8:11], v[208:211], v[156:159], v[8:11]
	v_mfma_f32_16x16x32_bf16 v[36:39], v[190:193], v[174:177], v[36:39]
	v_mfma_f32_16x16x32_bf16 v[4:7], v[208:211], v[174:177], v[4:7]
	v_mfma_f32_16x16x32_bf16 v[32:35], v[190:193], v[182:185], v[32:35]
	v_mfma_f32_16x16x32_bf16 v[0:3], v[208:211], v[182:185], v[0:3]
	s_barrier
	ds_read_b128 v[128:131], v201
	ds_read_b128 v[132:135], v201 offset:1024
	ds_read_b128 v[136:139], v201 offset:2048
	ds_read_b128 v[140:143], v201 offset:3072
	s_add_u32 s6, s12, 0x100000
	s_addc_u32 s7, s13, 0
	s_mov_b32 m0, s45
	v_lshl_add_u64 v[186:187], s[6:7], 0, v[164:165]
	ds_read_b128 v[144:147], v199 offset:32768
	ds_read_b128 v[148:151], v199 offset:33792
	ds_read_b128 v[152:155], v199 offset:34816
	ds_read_b128 v[156:159], v199 offset:35840
	ds_read_b128 v[160:163], v199 offset:36864
	ds_read_b128 v[174:177], v199 offset:37888
	ds_read_b128 v[178:181], v199 offset:38912
	ds_read_b128 v[182:185], v199 offset:39936
	global_load_lds_dwordx4 v[186:187], off
	v_lshl_add_u64 v[186:187], s[6:7], 0, v[166:167]
	s_mov_b32 m0, s46
	s_nop 0
	global_load_lds_dwordx4 v[186:187], off
	s_waitcnt lgkmcnt(8)
	s_barrier
	s_waitcnt lgkmcnt(0)
	v_mfma_f32_16x16x32_bf16 v[124:127], v[128:131], v[144:147], v[124:127]
	v_mfma_f32_16x16x32_bf16 v[92:95], v[136:139], v[144:147], v[92:95]
	v_mfma_f32_16x16x32_bf16 v[120:123], v[128:131], v[152:155], v[120:123]
	v_mfma_f32_16x16x32_bf16 v[88:91], v[136:139], v[152:155], v[88:91]
	v_mfma_f32_16x16x32_bf16 v[116:119], v[128:131], v[160:163], v[116:119]
	v_mfma_f32_16x16x32_bf16 v[84:87], v[136:139], v[160:163], v[84:87]
	v_mfma_f32_16x16x32_bf16 v[112:115], v[128:131], v[178:181], v[112:115]
	v_mfma_f32_16x16x32_bf16 v[80:83], v[136:139], v[178:181], v[80:83]
	v_mfma_f32_16x16x32_bf16 v[124:127], v[132:135], v[148:151], v[124:127]
	v_mfma_f32_16x16x32_bf16 v[92:95], v[140:143], v[148:151], v[92:95]
	v_mfma_f32_16x16x32_bf16 v[120:123], v[132:135], v[156:159], v[120:123]
	v_mfma_f32_16x16x32_bf16 v[88:91], v[140:143], v[156:159], v[88:91]
	v_mfma_f32_16x16x32_bf16 v[116:119], v[132:135], v[174:177], v[116:119]
	v_mfma_f32_16x16x32_bf16 v[84:87], v[140:143], v[174:177], v[84:87]
	v_mfma_f32_16x16x32_bf16 v[112:115], v[132:135], v[182:185], v[112:115]
	v_mfma_f32_16x16x32_bf16 v[80:83], v[140:143], v[182:185], v[80:83]
	s_barrier
	s_mov_b32 m0, s64
	v_lshl_add_u64 v[204:205], v[204:205], 0, s[0:1]
	ds_read_b128 v[186:189], v202
	ds_read_b128 v[190:193], v202 offset:1024
	ds_read_b128 v[194:197], v202 offset:2048
	ds_read_b128 v[208:211], v202 offset:3072
	global_load_lds_dwordx4 v[204:205], off
	v_lshl_add_u64 v[204:205], v[212:213], 0, s[0:1]
	s_mov_b32 m0, s65
	s_nop 0
	global_load_lds_dwordx4 v[204:205], off
	s_barrier
	s_waitcnt lgkmcnt(0)
	v_mfma_f32_16x16x32_bf16 v[60:63], v[186:189], v[144:147], v[60:63]
	v_mfma_f32_16x16x32_bf16 v[28:31], v[194:197], v[144:147], v[28:31]
	v_mfma_f32_16x16x32_bf16 v[56:59], v[186:189], v[152:155], v[56:59]
	v_mfma_f32_16x16x32_bf16 v[24:27], v[194:197], v[152:155], v[24:27]
	v_mfma_f32_16x16x32_bf16 v[52:55], v[186:189], v[160:163], v[52:55]
	v_mfma_f32_16x16x32_bf16 v[20:23], v[194:197], v[160:163], v[20:23]
	v_mfma_f32_16x16x32_bf16 v[48:51], v[186:189], v[178:181], v[48:51]
	v_mfma_f32_16x16x32_bf16 v[16:19], v[194:197], v[178:181], v[16:19]
	v_mfma_f32_16x16x32_bf16 v[60:63], v[190:193], v[148:151], v[60:63]
	v_mfma_f32_16x16x32_bf16 v[28:31], v[208:211], v[148:151], v[28:31]
	v_mfma_f32_16x16x32_bf16 v[56:59], v[190:193], v[156:159], v[56:59]
	v_mfma_f32_16x16x32_bf16 v[24:27], v[208:211], v[156:159], v[24:27]
	v_mfma_f32_16x16x32_bf16 v[52:55], v[190:193], v[174:177], v[52:55]
	v_mfma_f32_16x16x32_bf16 v[20:23], v[208:211], v[174:177], v[20:23]
	v_mfma_f32_16x16x32_bf16 v[48:51], v[190:193], v[182:185], v[48:51]
	v_mfma_f32_16x16x32_bf16 v[16:19], v[208:211], v[182:185], v[16:19]
	s_barrier
	s_mov_b32 m0, s47
	v_lshl_add_u64 v[204:205], v[214:215], 0, s[0:1]
	ds_read_b128 v[144:147], v199 offset:49152
	ds_read_b128 v[148:151], v199 offset:50176
	ds_read_b128 v[152:155], v199 offset:51200
	ds_read_b128 v[156:159], v199 offset:52224
	ds_read_b128 v[160:163], v199 offset:53248
	ds_read_b128 v[174:177], v199 offset:54272
	ds_read_b128 v[178:181], v199 offset:55296
	ds_read_b128 v[182:185], v199 offset:56320
	global_load_lds_dwordx4 v[204:205], off
	v_lshl_add_u64 v[204:205], v[216:217], 0, s[0:1]
	s_mov_b32 m0, s48
	s_nop 0
	global_load_lds_dwordx4 v[204:205], off
	s_barrier
; #define WAIT_V(n) asm volatile("s_waitcnt vmcnt(" #n ")" ::: "memory")
; #define WAIT_L(n) asm volatile("s_waitcnt lgkmcnt(" #n ")" ::: "memory")
; #define BAR __builtin_amdgcn_s_barrier()
; #define SCHED __builtin_amdgcn_sched_barrier(0)
; #define EPI_DONE do { } while (0)
; template <class Get, class Epi>
; DI void gemm_stream(LAS unsigned char* lds, const int K, const int ld, Get get, Epi epi) {
;     ...
;             BAR; WAIT_L(0); MMA(1, 0, At, B0); BAR; SCHED;
;             STAGE(SBo(1, 1), b3 + hstep);
;             WAIT_V(6); BAR; MMA(1, 1, At, B1); BAR;
; DI void epi_resid(const Acc& acc, const P& p, int brow, int bcol, int layer, int gch, bool from_input) {
;     EPI_IDX
;     const float* gate = modv(p, layer, brow, gch);
; #pragma unroll
;     for (int bj = 0; bj < 2; ++bj)
; #pragma unroll
;         for (int n = 0; n < 2; ++n) {
;             const int c0 = bcol + bj * 128 + wc * 32 + n * 16 + fq * 4;
;             const f32x4 g = *(const f32x4*)(gate + c0);
;             f32x4 xv[2][4];
; #pragma unroll
;             for (int ai = 0; ai < 2; ++ai)
; #pragma unroll
;                 for (int m = 0; m < 4; ++m) {
;                     const int r = brow + ai * 128 + wr * 64 + m * 16 + fr;
;                     const float* sp = (from_input ? inrow(p, r) : xrow(p, r)) + c0;
;                     xv[ai][m] = *(const f32x4*)sp;
;                 }
;             __builtin_amdgcn_sched_barrier(0);
; #pragma unroll
;             for (int ai = 0; ai < 2; ++ai)
; #pragma unroll
;                 for (int m = 0; m < 4; ++m) {
;                     const int r = brow + ai * 128 + wr * 64 + m * 16 + fr;
;                     *(f32x4*)(xrow(p, r) + c0) = xv[ai][m] + g * acc[ai][bj][m][n];
;                 }
;             __builtin_amdgcn_sched_barrier(0);
;         }
;     EPI_DONE;
; }
	s_waitcnt lgkmcnt(0)
	v_mfma_f32_16x16x32_bf16 v[108:111], v[128:131], v[144:147], v[108:111]
	v_mfma_f32_16x16x32_bf16 v[76:79], v[136:139], v[144:147], v[76:79]
	v_mfma_f32_16x16x32_bf16 v[104:107], v[128:131], v[152:155], v[104:107]
	v_mfma_f32_16x16x32_bf16 v[72:75], v[136:139], v[152:155], v[72:75]
	v_mfma_f32_16x16x32_bf16 v[100:103], v[128:131], v[160:163], v[100:103]
	v_mfma_f32_16x16x32_bf16 v[68:71], v[136:139], v[160:163], v[68:71]
	v_mfma_f32_16x16x32_bf16 v[96:99], v[128:131], v[178:181], v[96:99]
	v_mfma_f32_16x16x32_bf16 v[64:67], v[136:139], v[178:181], v[64:67]
	v_mfma_f32_16x16x32_bf16 v[108:111], v[132:135], v[148:151], v[108:111]
	v_mfma_f32_16x16x32_bf16 v[76:79], v[140:143], v[148:151], v[76:79]
	v_mfma_f32_16x16x32_bf16 v[104:107], v[132:135], v[156:159], v[104:107]
	v_mfma_f32_16x16x32_bf16 v[72:75], v[140:143], v[156:159], v[72:75]
	v_mfma_f32_16x16x32_bf16 v[100:103], v[132:135], v[174:177], v[100:103]
	v_mfma_f32_16x16x32_bf16 v[68:71], v[140:143], v[174:177], v[68:71]
	v_mfma_f32_16x16x32_bf16 v[96:99], v[132:135], v[182:185], v[96:99]
	v_mfma_f32_16x16x32_bf16 v[64:67], v[140:143], v[182:185], v[64:67]
	s_barrier
	s_add_u32 s6, s10, 0x100080
	s_addc_u32 s7, s11, 0
	s_mov_b32 m0, s68
	v_lshl_add_u64 v[128:129], s[6:7], 0, v[164:165]
	global_load_lds_dwordx4 v[128:129], off
	v_lshl_add_u64 v[128:129], s[6:7], 0, v[166:167]
	s_mov_b32 m0, s69
	s_nop 0
	global_load_lds_dwordx4 v[128:129], off
	s_waitcnt vmcnt(6)
	s_barrier
	v_mfma_f32_16x16x32_bf16 v[44:47], v[186:189], v[144:147], v[44:47]
	v_mfma_f32_16x16x32_bf16 v[12:15], v[194:197], v[144:147], v[12:15]
	v_mfma_f32_16x16x32_bf16 v[40:43], v[186:189], v[152:155], v[40:43]
	v_mfma_f32_16x16x32_bf16 v[8:11], v[194:197], v[152:155], v[8:11]
	v_mfma_f32_16x16x32_bf16 v[36:39], v[186:189], v[160:163], v[36:39]
	v_mfma_f32_16x16x32_bf16 v[4:7], v[194:197], v[160:163], v[4:7]
	v_mfma_f32_16x16x32_bf16 v[32:35], v[186:189], v[178:181], v[32:35]
	v_mfma_f32_16x16x32_bf16 v[0:3], v[194:197], v[178:181], v[0:3]
	v_mfma_f32_16x16x32_bf16 v[44:47], v[190:193], v[148:151], v[44:47]
	v_mfma_f32_16x16x32_bf16 v[12:15], v[208:211], v[148:151], v[12:15]
	v_mfma_f32_16x16x32_bf16 v[40:43], v[190:193], v[156:159], v[40:43]
	v_mfma_f32_16x16x32_bf16 v[8:11], v[208:211], v[156:159], v[8:11]
	v_mfma_f32_16x16x32_bf16 v[36:39], v[190:193], v[174:177], v[36:39]
	v_mfma_f32_16x16x32_bf16 v[4:7], v[208:211], v[174:177], v[4:7]
	v_mfma_f32_16x16x32_bf16 v[32:35], v[190:193], v[182:185], v[32:35]
	v_mfma_f32_16x16x32_bf16 v[0:3], v[208:211], v[182:185], v[0:3]
	s_barrier
	s_add_i32 s16, s16, 2
	s_add_u32 s14, s14, 0x100
	s_addc_u32 s15, s15, 0
	s_cmp_gt_u32 s16, 61
	s_mov_b64 s[6:7], s[8:9]
	s_cbranch_scc0 .LBB0_2670
	s_lshl_b32 s12, s3, 21
	s_lshl_b32 s13, s2, 10
	s_lshr_b32 s16, s3, 4
	s_add_u32 s12, s12, s13
	s_mul_i32 s16, s16, 6
	s_add_i32 s16, s16, 32
	s_lshl_b32 s16, s16, 13
	s_add_u32 s16, s16, s13
	s_add_u32 s10, s26, s16
	s_addc_u32 s11, s27, 0
	s_add_u32 s6, s24, s12
	s_addc_u32 s7, s25, 0
	v_lshrrev_b32_e32 v224, 6, v206
	v_and_b32_e32 v225, 3, v224
	v_lshrrev_b32_e32 v224, 2, v224
	v_and_b32_e32 v205, 15, v206
	v_bfe_u32 v226, v206, 4, 2
	v_lshl_add_u32 v225, v225, 3, v226
	v_lshl_add_u32 v224, v224, 6, v205
	v_lshlrev_b32_e32 v205, 4, v225
	v_lshl_add_u32 v203, v224, 13, v205
	v_mov_b32_e32 v204, v203
	global_load_dwordx4 v[128:131], v205, s[10:11] offset:0
	global_load_dwordx4 v[132:135], v205, s[10:11] offset:64
	global_load_dwordx4 v[136:139], v205, s[10:11] offset:512
	global_load_dwordx4 v[140:143], v205, s[10:11] offset:576
	global_load_dwordx4 v[144:147], v203, s[6:7] offset:0
	global_load_dwordx4 v[148:151], v203, s[6:7] offset:64
	global_load_dwordx4 v[152:155], v203, s[6:7] offset:512
	global_load_dwordx4 v[156:159], v203, s[6:7] offset:576
	v_add_u32_e32 v203, 0x20000, v203
	global_load_dwordx4 v[160:163], v203, s[6:7] offset:0
	global_load_dwordx4 v[174:177], v203, s[6:7] offset:64
	global_load_dwordx4 v[178:181], v203, s[6:7] offset:512
	global_load_dwordx4 v[182:185], v203, s[6:7] offset:576
	v_add_u32_e32 v203, 0x20000, v203
	global_load_dwordx4 v[186:189], v203, s[6:7] offset:0
	global_load_dwordx4 v[190:193], v203, s[6:7] offset:64
	global_load_dwordx4 v[194:197], v203, s[6:7] offset:512
	global_load_dwordx4 v[208:211], v203, s[6:7] offset:576
	v_add_u32_e32 v203, 0x20000, v203
	global_load_dwordx4 v[212:215], v203, s[6:7] offset:0
	global_load_dwordx4 v[216:219], v203, s[6:7] offset:64
	global_load_dwordx4 v[220:223], v203, s[6:7] offset:512
	global_load_dwordx4 v[224:227], v203, s[6:7] offset:576
	v_add_u32_e32 v203, 0xa0000, v203
	s_waitcnt vmcnt(12)
	v_pk_fma_f32 v[124:125], v[124:125], v[128:129], v[144:145]
	v_pk_fma_f32 v[126:127], v[126:127], v[130:131], v[146:147]
	v_pk_fma_f32 v[92:93], v[92:93], v[132:133], v[148:149]
	v_pk_fma_f32 v[94:95], v[94:95], v[134:135], v[150:151]
	v_pk_fma_f32 v[60:61], v[60:61], v[136:137], v[152:153]
	v_pk_fma_f32 v[62:63], v[62:63], v[138:139], v[154:155]
	v_pk_fma_f32 v[28:29], v[28:29], v[140:141], v[156:157]
	v_pk_fma_f32 v[30:31], v[30:31], v[142:143], v[158:159]
	global_store_dwordx4 v204, v[124:127], s[6:7] offset:0
	global_store_dwordx4 v204, v[92:95], s[6:7] offset:64
	global_store_dwordx4 v204, v[60:63], s[6:7] offset:512
	global_store_dwordx4 v204, v[28:31], s[6:7] offset:576
	v_add_u32_e32 v204, 0x20000, v204
	global_load_dwordx4 v[144:147], v203, s[6:7] offset:0
	global_load_dwordx4 v[148:151], v203, s[6:7] offset:64
	global_load_dwordx4 v[152:155], v203, s[6:7] offset:512
	global_load_dwordx4 v[156:159], v203, s[6:7] offset:576
	v_add_u32_e32 v203, 0x20000, v203
	s_waitcnt vmcnt(16)
; DI void epi_resid(const Acc& acc, const P& p, int brow, int bcol, int layer, int gch, bool from_input) {
;     ...
; #pragma unroll
;             for (int ai = 0; ai < 2; ++ai)
; #pragma unroll
;                 for (int m = 0; m < 4; ++m) {
;                     const int r = brow + ai * 128 + wr * 64 + m * 16 + fr;
;                     const float* sp = (from_input ? inrow(p, r) : xrow(p, r)) + c0;
;                     xv[ai][m] = *(const f32x4*)sp;
;                 }
;             __builtin_amdgcn_sched_barrier(0);
; #pragma unroll
;             for (int ai = 0; ai < 2; ++ai)
; #pragma unroll
;                 for (int m = 0; m < 4; ++m) {
;                     const int r = brow + ai * 128 + wr * 64 + m * 16 + fr;
;                     *(f32x4*)(xrow(p, r) + c0) = xv[ai][m] + g * acc[ai][bj][m][n];
;                 }
;             __builtin_amdgcn_sched_barrier(0);
	v_pk_fma_f32 v[120:121], v[120:121], v[128:129], v[160:161]
	v_pk_fma_f32 v[122:123], v[122:123], v[130:131], v[162:163]
	v_pk_fma_f32 v[88:89], v[88:89], v[132:133], v[174:175]
	v_pk_fma_f32 v[90:91], v[90:91], v[134:135], v[176:177]
	v_pk_fma_f32 v[56:57], v[56:57], v[136:137], v[178:179]
	v_pk_fma_f32 v[58:59], v[58:59], v[138:139], v[180:181]
	v_pk_fma_f32 v[24:25], v[24:25], v[140:141], v[182:183]
	v_pk_fma_f32 v[26:27], v[26:27], v[142:143], v[184:185]
	global_store_dwordx4 v204, v[120:123], s[6:7] offset:0
	global_store_dwordx4 v204, v[88:91], s[6:7] offset:64
	global_store_dwordx4 v204, v[56:59], s[6:7] offset:512
	global_store_dwordx4 v204, v[24:27], s[6:7] offset:576
	v_add_u32_e32 v204, 0x20000, v204
	global_load_dwordx4 v[160:163], v203, s[6:7] offset:0
	global_load_dwordx4 v[174:177], v203, s[6:7] offset:64
	global_load_dwordx4 v[178:181], v203, s[6:7] offset:512
	global_load_dwordx4 v[182:185], v203, s[6:7] offset:576
	v_add_u32_e32 v203, 0x20000, v203
	s_waitcnt vmcnt(20)
	v_pk_fma_f32 v[116:117], v[116:117], v[128:129], v[186:187]
	v_pk_fma_f32 v[118:119], v[118:119], v[130:131], v[188:189]
	v_pk_fma_f32 v[84:85], v[84:85], v[132:133], v[190:191]
	v_pk_fma_f32 v[86:87], v[86:87], v[134:135], v[192:193]
	v_pk_fma_f32 v[52:53], v[52:53], v[136:137], v[194:195]
	v_pk_fma_f32 v[54:55], v[54:55], v[138:139], v[196:197]
	v_pk_fma_f32 v[20:21], v[20:21], v[140:141], v[208:209]
	v_pk_fma_f32 v[22:23], v[22:23], v[142:143], v[210:211]
	global_store_dwordx4 v204, v[116:119], s[6:7] offset:0
	global_store_dwordx4 v204, v[84:87], s[6:7] offset:64
	global_store_dwordx4 v204, v[52:55], s[6:7] offset:512
	global_store_dwordx4 v204, v[20:23], s[6:7] offset:576
	v_add_u32_e32 v204, 0x20000, v204
	global_load_dwordx4 v[186:189], v203, s[6:7] offset:0
	global_load_dwordx4 v[190:193], v203, s[6:7] offset:64
	global_load_dwordx4 v[194:197], v203, s[6:7] offset:512
	global_load_dwordx4 v[208:211], v203, s[6:7] offset:576
	v_add_u32_e32 v203, 0x20000, v203
	s_waitcnt vmcnt(24)
	v_pk_fma_f32 v[112:113], v[112:113], v[128:129], v[212:213]
	v_pk_fma_f32 v[114:115], v[114:115], v[130:131], v[214:215]
	v_pk_fma_f32 v[80:81], v[80:81], v[132:133], v[216:217]
	v_pk_fma_f32 v[82:83], v[82:83], v[134:135], v[218:219]
	v_pk_fma_f32 v[48:49], v[48:49], v[136:137], v[220:221]
	v_pk_fma_f32 v[50:51], v[50:51], v[138:139], v[222:223]
	v_pk_fma_f32 v[16:17], v[16:17], v[140:141], v[224:225]
	v_pk_fma_f32 v[18:19], v[18:19], v[142:143], v[226:227]
	global_store_dwordx4 v204, v[112:115], s[6:7] offset:0
	global_store_dwordx4 v204, v[80:83], s[6:7] offset:64
	global_store_dwordx4 v204, v[48:51], s[6:7] offset:512
	global_store_dwordx4 v204, v[16:19], s[6:7] offset:576
	v_add_u32_e32 v204, 0xa0000, v204
	global_load_dwordx4 v[212:215], v203, s[6:7] offset:0
	global_load_dwordx4 v[216:219], v203, s[6:7] offset:64
	global_load_dwordx4 v[220:223], v203, s[6:7] offset:512
	global_load_dwordx4 v[224:227], v203, s[6:7] offset:576
	s_waitcnt vmcnt(24)
	v_pk_fma_f32 v[108:109], v[108:109], v[128:129], v[144:145]
	v_pk_fma_f32 v[110:111], v[110:111], v[130:131], v[146:147]
	v_pk_fma_f32 v[76:77], v[76:77], v[132:133], v[148:149]
	v_pk_fma_f32 v[78:79], v[78:79], v[134:135], v[150:151]
	v_pk_fma_f32 v[44:45], v[44:45], v[136:137], v[152:153]
	v_pk_fma_f32 v[46:47], v[46:47], v[138:139], v[154:155]
	v_pk_fma_f32 v[12:13], v[12:13], v[140:141], v[156:157]
	v_pk_fma_f32 v[14:15], v[14:15], v[142:143], v[158:159]
	global_store_dwordx4 v204, v[108:111], s[6:7] offset:0
	global_store_dwordx4 v204, v[76:79], s[6:7] offset:64
	global_store_dwordx4 v204, v[44:47], s[6:7] offset:512
	global_store_dwordx4 v204, v[12:15], s[6:7] offset:576
	v_add_u32_e32 v204, 0x20000, v204
	s_waitcnt vmcnt(20)
	v_pk_fma_f32 v[104:105], v[104:105], v[128:129], v[160:161]
	v_pk_fma_f32 v[106:107], v[106:107], v[130:131], v[162:163]
	v_pk_fma_f32 v[72:73], v[72:73], v[132:133], v[174:175]
	v_pk_fma_f32 v[74:75], v[74:75], v[134:135], v[176:177]
	v_pk_fma_f32 v[40:41], v[40:41], v[136:137], v[178:179]
	v_pk_fma_f32 v[42:43], v[42:43], v[138:139], v[180:181]
	v_pk_fma_f32 v[8:9], v[8:9], v[140:141], v[182:183]
	v_pk_fma_f32 v[10:11], v[10:11], v[142:143], v[184:185]
	global_store_dwordx4 v204, v[104:107], s[6:7] offset:0
	global_store_dwordx4 v204, v[72:75], s[6:7] offset:64
	global_store_dwordx4 v204, v[40:43], s[6:7] offset:512
	global_store_dwordx4 v204, v[8:11], s[6:7] offset:576
	v_add_u32_e32 v204, 0x20000, v204
	s_waitcnt vmcnt(16)
	v_pk_fma_f32 v[100:101], v[100:101], v[128:129], v[186:187]
	v_pk_fma_f32 v[102:103], v[102:103], v[130:131], v[188:189]
	v_pk_fma_f32 v[68:69], v[68:69], v[132:133], v[190:191]
	v_pk_fma_f32 v[70:71], v[70:71], v[134:135], v[192:193]
	v_pk_fma_f32 v[36:37], v[36:37], v[136:137], v[194:195]
	v_pk_fma_f32 v[38:39], v[38:39], v[138:139], v[196:197]
	v_pk_fma_f32 v[4:5], v[4:5], v[140:141], v[208:209]
	v_pk_fma_f32 v[6:7], v[6:7], v[142:143], v[210:211]
	global_store_dwordx4 v204, v[100:103], s[6:7] offset:0
	global_store_dwordx4 v204, v[68:71], s[6:7] offset:64
	global_store_dwordx4 v204, v[36:39], s[6:7] offset:512
	global_store_dwordx4 v204, v[4:7], s[6:7] offset:576
	v_add_u32_e32 v204, 0x20000, v204
	s_waitcnt vmcnt(12)
	v_pk_fma_f32 v[96:97], v[96:97], v[128:129], v[212:213]
	v_pk_fma_f32 v[98:99], v[98:99], v[130:131], v[214:215]
	v_pk_fma_f32 v[64:65], v[64:65], v[132:133], v[216:217]
	v_pk_fma_f32 v[66:67], v[66:67], v[134:135], v[218:219]
	v_pk_fma_f32 v[32:33], v[32:33], v[136:137], v[220:221]
	v_pk_fma_f32 v[34:35], v[34:35], v[138:139], v[222:223]
	v_pk_fma_f32 v[0:1], v[0:1], v[140:141], v[224:225]
	v_pk_fma_f32 v[2:3], v[2:3], v[142:143], v[226:227]
	global_store_dwordx4 v204, v[96:99], s[6:7] offset:0
	global_store_dwordx4 v204, v[64:67], s[6:7] offset:64
	global_store_dwordx4 v204, v[32:35], s[6:7] offset:512
	global_store_dwordx4 v204, v[0:3], s[6:7] offset:576
	s_branch .Lresid_latch_wout1

; #define WAIT_V(n) asm volatile("s_waitcnt vmcnt(" #n ")" ::: "memory")
; #define WAIT_L(n) asm volatile("s_waitcnt lgkmcnt(" #n ")" ::: "memory")
; #define BAR __builtin_amdgcn_s_barrier()
; #define SCHED __builtin_amdgcn_sched_barrier(0)
; template <class Get, class Epi>
; DI void gemm_stream(LAS unsigned char* lds, const int K, const int ld, Get get, Epi epi) {
;     ...
;             LDB(B0, 0, 0); SCHED; LDA(At, 0, 0); STAGE(SAo(1, 1), a1 + hstep);
;             WAIT_L(8); BAR; WAIT_L(0); MMA(0, 0, At, B0); BAR; SCHED;
;             LDB(B1, 0, 1); STAGE(SBo(0, 0), b2);
;             BAR; WAIT_L(0); MMA(0, 1, At, B1); BAR;
;             LDA(At, 0, 1); STAGE(SAo(0, 0), a2);
;             BAR; WAIT_L(0); MMA(1, 0, At, B0); BAR; SCHED;
;             STAGE(SBo(0, 1), b2 + hstep);
;             WAIT_V(6); BAR; MMA(1, 1, At, B1); BAR;
.LBB0_3046:
	ds_read_b128 v[148:151], v142
	ds_read_b128 v[152:155], v142 offset:1024
	ds_read_b128 v[156:159], v142 offset:2048
	ds_read_b128 v[160:163], v142 offset:3072
	s_add_u32 s14, s12, 0xfff80080
	s_addc_u32 s15, s13, -1
	s_cmp_eq_u32 s56, 28
	s_cselect_b32 s17, s9, s15
	s_cselect_b32 s16, s8, s14
	s_cselect_b32 s15, s11, s55
	s_cselect_b32 s14, s10, s0
	s_mov_b32 m0, s38
	v_lshl_add_u64 v[140:141], s[12:13], 0, v[134:135]
	ds_read_b128 v[164:167], v143
	ds_read_b128 v[168:171], v143 offset:1024
	ds_read_b128 v[172:175], v143 offset:2048
	ds_read_b128 v[176:179], v143 offset:3072
	ds_read_b128 v[180:183], v143 offset:4096
	ds_read_b128 v[184:187], v143 offset:5120
	ds_read_b128 v[188:191], v143 offset:6144
	ds_read_b128 v[192:195], v143 offset:7168
	global_load_lds_dwordx4 v[140:141], off
	v_lshl_add_u64 v[140:141], s[12:13], 0, v[136:137]
	s_mov_b32 m0, s39
	s_nop 0
	global_load_lds_dwordx4 v[140:141], off
	s_waitcnt lgkmcnt(8)
	s_barrier
	s_waitcnt lgkmcnt(0)
	v_mfma_f32_16x16x32_bf16 v[124:127], v[148:151], v[164:167], v[124:127]
	v_mfma_f32_16x16x32_bf16 v[116:119], v[156:159], v[164:167], v[116:119]
	v_mfma_f32_16x16x32_bf16 v[108:111], v[148:151], v[172:175], v[108:111]
	v_mfma_f32_16x16x32_bf16 v[100:103], v[156:159], v[172:175], v[100:103]
	v_mfma_f32_16x16x32_bf16 v[92:95], v[148:151], v[180:183], v[92:95]
	v_mfma_f32_16x16x32_bf16 v[84:87], v[156:159], v[180:183], v[84:87]
	v_mfma_f32_16x16x32_bf16 v[76:79], v[148:151], v[188:191], v[76:79]
	v_mfma_f32_16x16x32_bf16 v[68:71], v[156:159], v[188:191], v[68:71]
	v_mfma_f32_16x16x32_bf16 v[124:127], v[152:155], v[168:171], v[124:127]
	v_mfma_f32_16x16x32_bf16 v[116:119], v[160:163], v[168:171], v[116:119]
	v_mfma_f32_16x16x32_bf16 v[108:111], v[152:155], v[176:179], v[108:111]
	v_mfma_f32_16x16x32_bf16 v[100:103], v[160:163], v[176:179], v[100:103]
	v_mfma_f32_16x16x32_bf16 v[92:95], v[152:155], v[184:187], v[92:95]
	v_mfma_f32_16x16x32_bf16 v[84:87], v[160:163], v[184:187], v[84:87]
	v_mfma_f32_16x16x32_bf16 v[76:79], v[152:155], v[192:195], v[76:79]
	v_mfma_f32_16x16x32_bf16 v[68:71], v[160:163], v[192:195], v[68:71]
	s_barrier
	s_mov_b32 m0, s40
	v_lshl_add_u64 v[140:141], s[14:15], 0, v[130:131]
	ds_read_b128 v[196:199], v144
	ds_read_b128 v[200:203], v144 offset:1024
	ds_read_b128 v[208:211], v144 offset:2048
	ds_read_b128 v[212:215], v144 offset:3072
	global_load_lds_dwordx4 v[140:141], off
	v_lshl_add_u64 v[204:205], s[14:15], 0, v[128:129]
	s_mov_b32 m0, s41
	s_nop 0
	global_load_lds_dwordx4 v[204:205], off
	s_barrier
	s_waitcnt lgkmcnt(0)
	v_mfma_f32_16x16x32_bf16 v[120:123], v[196:199], v[164:167], v[120:123]
	v_mfma_f32_16x16x32_bf16 v[112:115], v[208:211], v[164:167], v[112:115]
	v_mfma_f32_16x16x32_bf16 v[104:107], v[196:199], v[172:175], v[104:107]
	v_mfma_f32_16x16x32_bf16 v[96:99], v[208:211], v[172:175], v[96:99]
	v_mfma_f32_16x16x32_bf16 v[88:91], v[196:199], v[180:183], v[88:91]
	v_mfma_f32_16x16x32_bf16 v[80:83], v[208:211], v[180:183], v[80:83]
	v_mfma_f32_16x16x32_bf16 v[72:75], v[196:199], v[188:191], v[72:75]
	v_mfma_f32_16x16x32_bf16 v[64:67], v[208:211], v[188:191], v[64:67]
	v_mfma_f32_16x16x32_bf16 v[120:123], v[200:203], v[168:171], v[120:123]
	v_mfma_f32_16x16x32_bf16 v[112:115], v[212:215], v[168:171], v[112:115]
	v_mfma_f32_16x16x32_bf16 v[104:107], v[200:203], v[176:179], v[104:107]
	v_mfma_f32_16x16x32_bf16 v[96:99], v[212:215], v[176:179], v[96:99]
	v_mfma_f32_16x16x32_bf16 v[88:91], v[200:203], v[184:187], v[88:91]
	v_mfma_f32_16x16x32_bf16 v[80:83], v[212:215], v[184:187], v[80:83]
	v_mfma_f32_16x16x32_bf16 v[72:75], v[200:203], v[192:195], v[72:75]
	v_mfma_f32_16x16x32_bf16 v[64:67], v[212:215], v[192:195], v[64:67]
	s_barrier
	s_mov_b32 m0, s19
	v_lshl_add_u64 v[216:217], s[16:17], 0, v[130:131]
	ds_read_b128 v[164:167], v143 offset:16384
	ds_read_b128 v[168:171], v143 offset:17408
	ds_read_b128 v[172:175], v143 offset:18432
	ds_read_b128 v[176:179], v143 offset:19456
	ds_read_b128 v[180:183], v143 offset:20480
	ds_read_b128 v[184:187], v143 offset:21504
	ds_read_b128 v[188:191], v143 offset:22528
	ds_read_b128 v[192:195], v143 offset:23552
	global_load_lds_dwordx4 v[216:217], off
	v_lshl_add_u64 v[218:219], s[16:17], 0, v[128:129]
	s_mov_b32 m0, s20
	s_nop 0
	global_load_lds_dwordx4 v[218:219], off
	s_barrier
	s_waitcnt lgkmcnt(0)
	v_mfma_f32_16x16x32_bf16 v[60:63], v[148:151], v[164:167], v[60:63]
	v_mfma_f32_16x16x32_bf16 v[52:55], v[156:159], v[164:167], v[52:55]
	v_mfma_f32_16x16x32_bf16 v[44:47], v[148:151], v[172:175], v[44:47]
	v_mfma_f32_16x16x32_bf16 v[36:39], v[156:159], v[172:175], v[36:39]
	v_mfma_f32_16x16x32_bf16 v[28:31], v[148:151], v[180:183], v[28:31]
	v_mfma_f32_16x16x32_bf16 v[20:23], v[156:159], v[180:183], v[20:23]
	v_mfma_f32_16x16x32_bf16 v[12:15], v[148:151], v[188:191], v[12:15]
	v_mfma_f32_16x16x32_bf16 v[4:7], v[156:159], v[188:191], v[4:7]
	v_mfma_f32_16x16x32_bf16 v[60:63], v[152:155], v[168:171], v[60:63]
	v_mfma_f32_16x16x32_bf16 v[52:55], v[160:163], v[168:171], v[52:55]
	v_mfma_f32_16x16x32_bf16 v[44:47], v[152:155], v[176:179], v[44:47]
	v_mfma_f32_16x16x32_bf16 v[36:39], v[160:163], v[176:179], v[36:39]
	v_mfma_f32_16x16x32_bf16 v[28:31], v[152:155], v[184:187], v[28:31]
	v_mfma_f32_16x16x32_bf16 v[20:23], v[160:163], v[184:187], v[20:23]
	v_mfma_f32_16x16x32_bf16 v[12:15], v[152:155], v[192:195], v[12:15]
	v_mfma_f32_16x16x32_bf16 v[4:7], v[160:163], v[192:195], v[4:7]
	s_barrier
	s_add_u32 s58, s14, 0x80000
	s_addc_u32 s59, s15, 0
	s_mov_b32 m0, s42
	v_lshl_add_u64 v[148:149], s[58:59], 0, v[130:131]
	global_load_lds_dwordx4 v[148:149], off
	v_lshl_add_u64 v[148:149], s[58:59], 0, v[128:129]
	s_mov_b32 m0, s43
	s_nop 0
	global_load_lds_dwordx4 v[148:149], off
	s_waitcnt vmcnt(6)
	s_barrier
; #define WAIT_V(n) asm volatile("s_waitcnt vmcnt(" #n ")" ::: "memory")
; #define WAIT_L(n) asm volatile("s_waitcnt lgkmcnt(" #n ")" ::: "memory")
; #define BAR __builtin_amdgcn_s_barrier()
; #define SCHED __builtin_amdgcn_sched_barrier(0)
; template <class Get, class Epi>
; DI void gemm_stream(LAS unsigned char* lds, const int K, const int ld, Get get, Epi epi) {
;     ...
;             WAIT_V(6); BAR; MMA(1, 1, At, B1); BAR;
;             LDB(B0, 1, 0); SCHED; LDA(At, 1, 0); STAGE(SAo(0, 1), a2 + hstep);
;             WAIT_L(8); BAR; WAIT_L(0); MMA(0, 0, At, B0); BAR; SCHED;
;             LDB(B1, 1, 1); STAGE(SBo(1, 0), b3);
;             BAR; WAIT_L(0); MMA(0, 1, At, B1); BAR;
;             LDA(At, 1, 1); STAGE(SAo(1, 0), a3);
;             BAR; WAIT_L(0); MMA(1, 0, At, B0); BAR; SCHED;
	v_mfma_f32_16x16x32_bf16 v[56:59], v[196:199], v[164:167], v[56:59]
	v_mfma_f32_16x16x32_bf16 v[48:51], v[208:211], v[164:167], v[48:51]
	v_mfma_f32_16x16x32_bf16 v[40:43], v[196:199], v[172:175], v[40:43]
	v_mfma_f32_16x16x32_bf16 v[32:35], v[208:211], v[172:175], v[32:35]
	v_mfma_f32_16x16x32_bf16 v[24:27], v[196:199], v[180:183], v[24:27]
	v_mfma_f32_16x16x32_bf16 v[16:19], v[208:211], v[180:183], v[16:19]
	v_mfma_f32_16x16x32_bf16 v[8:11], v[196:199], v[188:191], v[8:11]
	v_mfma_f32_16x16x32_bf16 v[0:3], v[208:211], v[188:191], v[0:3]
	v_mfma_f32_16x16x32_bf16 v[56:59], v[200:203], v[168:171], v[56:59]
	v_mfma_f32_16x16x32_bf16 v[48:51], v[212:215], v[168:171], v[48:51]
	v_mfma_f32_16x16x32_bf16 v[40:43], v[200:203], v[176:179], v[40:43]
	v_mfma_f32_16x16x32_bf16 v[32:35], v[212:215], v[176:179], v[32:35]
	v_mfma_f32_16x16x32_bf16 v[24:27], v[200:203], v[184:187], v[24:27]
	v_mfma_f32_16x16x32_bf16 v[16:19], v[212:215], v[184:187], v[16:19]
	v_mfma_f32_16x16x32_bf16 v[8:11], v[200:203], v[192:195], v[8:11]
	v_mfma_f32_16x16x32_bf16 v[0:3], v[212:215], v[192:195], v[0:3]
	s_barrier
	ds_read_b128 v[148:151], v145
	ds_read_b128 v[152:155], v145 offset:1024
	ds_read_b128 v[156:159], v145 offset:2048
	ds_read_b128 v[160:163], v145 offset:3072
	s_add_u32 s16, s16, 0x80000
	s_addc_u32 s17, s17, 0
	s_mov_b32 m0, s21
	v_lshl_add_u64 v[196:197], s[16:17], 0, v[130:131]
	ds_read_b128 v[164:167], v143 offset:32768
	ds_read_b128 v[168:171], v143 offset:33792
	ds_read_b128 v[172:175], v143 offset:34816
	ds_read_b128 v[176:179], v143 offset:35840
	ds_read_b128 v[180:183], v143 offset:36864
	ds_read_b128 v[184:187], v143 offset:37888
	ds_read_b128 v[188:191], v143 offset:38912
	ds_read_b128 v[192:195], v143 offset:39936
	global_load_lds_dwordx4 v[196:197], off
	v_lshl_add_u64 v[196:197], s[16:17], 0, v[128:129]
	s_mov_b32 m0, s28
	s_nop 0
	global_load_lds_dwordx4 v[196:197], off
	s_waitcnt lgkmcnt(8)
	s_barrier
	s_waitcnt lgkmcnt(0)
	v_mfma_f32_16x16x32_bf16 v[124:127], v[148:151], v[164:167], v[124:127]
	v_mfma_f32_16x16x32_bf16 v[116:119], v[156:159], v[164:167], v[116:119]
	v_mfma_f32_16x16x32_bf16 v[108:111], v[148:151], v[172:175], v[108:111]
	v_mfma_f32_16x16x32_bf16 v[100:103], v[156:159], v[172:175], v[100:103]
	v_mfma_f32_16x16x32_bf16 v[92:95], v[148:151], v[180:183], v[92:95]
	v_mfma_f32_16x16x32_bf16 v[84:87], v[156:159], v[180:183], v[84:87]
	v_mfma_f32_16x16x32_bf16 v[76:79], v[148:151], v[188:191], v[76:79]
	v_mfma_f32_16x16x32_bf16 v[68:71], v[156:159], v[188:191], v[68:71]
	v_mfma_f32_16x16x32_bf16 v[124:127], v[152:155], v[168:171], v[124:127]
	v_mfma_f32_16x16x32_bf16 v[116:119], v[160:163], v[168:171], v[116:119]
	v_mfma_f32_16x16x32_bf16 v[108:111], v[152:155], v[176:179], v[108:111]
	v_mfma_f32_16x16x32_bf16 v[100:103], v[160:163], v[176:179], v[100:103]
	v_mfma_f32_16x16x32_bf16 v[92:95], v[152:155], v[184:187], v[92:95]
	v_mfma_f32_16x16x32_bf16 v[84:87], v[160:163], v[184:187], v[84:87]
	v_mfma_f32_16x16x32_bf16 v[76:79], v[152:155], v[192:195], v[76:79]
	v_mfma_f32_16x16x32_bf16 v[68:71], v[160:163], v[192:195], v[68:71]
	s_barrier
	s_mov_b32 m0, s44
	v_lshl_add_u64 v[140:141], v[140:141], 0, s[6:7]
	ds_read_b128 v[196:199], v146
	ds_read_b128 v[200:203], v146 offset:1024
	ds_read_b128 v[208:211], v146 offset:2048
	ds_read_b128 v[212:215], v146 offset:3072
	global_load_lds_dwordx4 v[140:141], off
	v_lshl_add_u64 v[140:141], v[204:205], 0, s[6:7]
	s_mov_b32 m0, s45
	s_nop 0
	global_load_lds_dwordx4 v[140:141], off
	s_barrier
	s_waitcnt lgkmcnt(0)
	v_mfma_f32_16x16x32_bf16 v[120:123], v[196:199], v[164:167], v[120:123]
	v_mfma_f32_16x16x32_bf16 v[112:115], v[208:211], v[164:167], v[112:115]
	v_mfma_f32_16x16x32_bf16 v[104:107], v[196:199], v[172:175], v[104:107]
	v_mfma_f32_16x16x32_bf16 v[96:99], v[208:211], v[172:175], v[96:99]
	v_mfma_f32_16x16x32_bf16 v[88:91], v[196:199], v[180:183], v[88:91]
	v_mfma_f32_16x16x32_bf16 v[80:83], v[208:211], v[180:183], v[80:83]
	v_mfma_f32_16x16x32_bf16 v[72:75], v[196:199], v[188:191], v[72:75]
	v_mfma_f32_16x16x32_bf16 v[64:67], v[208:211], v[188:191], v[64:67]
	v_mfma_f32_16x16x32_bf16 v[120:123], v[200:203], v[168:171], v[120:123]
	v_mfma_f32_16x16x32_bf16 v[112:115], v[212:215], v[168:171], v[112:115]
	v_mfma_f32_16x16x32_bf16 v[104:107], v[200:203], v[176:179], v[104:107]
	v_mfma_f32_16x16x32_bf16 v[96:99], v[212:215], v[176:179], v[96:99]
	v_mfma_f32_16x16x32_bf16 v[88:91], v[200:203], v[184:187], v[88:91]
	v_mfma_f32_16x16x32_bf16 v[80:83], v[212:215], v[184:187], v[80:83]
	v_mfma_f32_16x16x32_bf16 v[72:75], v[200:203], v[192:195], v[72:75]
	v_mfma_f32_16x16x32_bf16 v[64:67], v[212:215], v[192:195], v[64:67]
	s_barrier
	s_mov_b32 m0, s29
	v_lshl_add_u64 v[140:141], v[216:217], 0, s[6:7]
	ds_read_b128 v[164:167], v143 offset:49152
	ds_read_b128 v[168:171], v143 offset:50176
	ds_read_b128 v[172:175], v143 offset:51200
	ds_read_b128 v[176:179], v143 offset:52224
	ds_read_b128 v[180:183], v143 offset:53248
	ds_read_b128 v[184:187], v143 offset:54272
	ds_read_b128 v[188:191], v143 offset:55296
	ds_read_b128 v[192:195], v143 offset:56320
	global_load_lds_dwordx4 v[140:141], off
	v_lshl_add_u64 v[140:141], v[218:219], 0, s[6:7]
	s_mov_b32 m0, s36
	s_nop 0
	global_load_lds_dwordx4 v[140:141], off
	s_barrier
; DI float silu_f(float g) { return g * __builtin_amdgcn_rcpf(1.f + __builtin_amdgcn_exp2f(-LOG2E * g)); }
; #define WAIT_V(n) asm volatile("s_waitcnt vmcnt(" #n ")" ::: "memory")
; #define WAIT_L(n) asm volatile("s_waitcnt lgkmcnt(" #n ")" ::: "memory")
; #define BAR __builtin_amdgcn_s_barrier()
; #define SCHED __builtin_amdgcn_sched_barrier(0)
; #define EPI_DONE do { } while (0)
; template <class Get, class Epi>
; DI void gemm_stream(LAS unsigned char* lds, const int K, const int ld, Get get, Epi epi) {
;     ...
;             BAR; WAIT_L(0); MMA(1, 0, At, B0); BAR; SCHED;
;             STAGE(SBo(1, 1), b3 + hstep);
;             WAIT_V(6); BAR; MMA(1, 1, At, B1); BAR;
;         }
;         epi(acc, cur);
;         if (!has_next) break;
;         ZERO_ACC;
;         cur = nxt; cA = nA; cB = nB; ++ui;
;     }
; DI void epi_swiglu(const Acc& acc, int brow, int pn, bf16_t* hid) {
;     EPI_IDX
; #pragma unroll
;     for (int ai = 0; ai < 2; ++ai)
; #pragma unroll
;         for (int m = 0; m < 4; ++m) {
;             const int r = brow + ai * 128 + wr * 64 + m * 16 + fr;
;             bf16_t* rp = hid + (size_t)r * FF + pn * 128 + wc * 32 + fq * 4;
; #pragma unroll
;             for (int n = 0; n < 2; ++n) {
;                 const f32x4 g = acc[ai][0][m][n], u = acc[ai][1][m][n];
;                 float o[4];
; #pragma unroll
;                 for (int j = 0; j < 4; ++j) o[j] = silu_f(g[j]) * u[j];
;                 st4(rp + n * 16, o[0], o[1], o[2], o[3]);
;             }
;         }
;     EPI_DONE;
; }
	s_waitcnt lgkmcnt(0)
	v_mfma_f32_16x16x32_bf16 v[60:63], v[148:151], v[164:167], v[60:63]
	v_mfma_f32_16x16x32_bf16 v[52:55], v[156:159], v[164:167], v[52:55]
	v_mfma_f32_16x16x32_bf16 v[44:47], v[148:151], v[172:175], v[44:47]
	v_mfma_f32_16x16x32_bf16 v[36:39], v[156:159], v[172:175], v[36:39]
	v_mfma_f32_16x16x32_bf16 v[28:31], v[148:151], v[180:183], v[28:31]
	v_mfma_f32_16x16x32_bf16 v[20:23], v[156:159], v[180:183], v[20:23]
	v_mfma_f32_16x16x32_bf16 v[12:15], v[148:151], v[188:191], v[12:15]
	v_mfma_f32_16x16x32_bf16 v[4:7], v[156:159], v[188:191], v[4:7]
	v_mfma_f32_16x16x32_bf16 v[60:63], v[152:155], v[168:171], v[60:63]
	v_mfma_f32_16x16x32_bf16 v[52:55], v[160:163], v[168:171], v[52:55]
	v_mfma_f32_16x16x32_bf16 v[44:47], v[152:155], v[176:179], v[44:47]
	v_mfma_f32_16x16x32_bf16 v[36:39], v[160:163], v[176:179], v[36:39]
	v_mfma_f32_16x16x32_bf16 v[28:31], v[152:155], v[184:187], v[28:31]
	v_mfma_f32_16x16x32_bf16 v[20:23], v[160:163], v[184:187], v[20:23]
	v_mfma_f32_16x16x32_bf16 v[12:15], v[152:155], v[192:195], v[12:15]
	v_mfma_f32_16x16x32_bf16 v[4:7], v[160:163], v[192:195], v[4:7]
	s_barrier
	s_add_u32 s14, s14, 0x80080
	s_addc_u32 s15, s15, 0
	s_mov_b32 m0, s46
	v_lshl_add_u64 v[140:141], s[14:15], 0, v[130:131]
	global_load_lds_dwordx4 v[140:141], off
	v_lshl_add_u64 v[140:141], s[14:15], 0, v[128:129]
	s_mov_b32 m0, s47
	s_nop 0
	global_load_lds_dwordx4 v[140:141], off
	s_waitcnt vmcnt(6)
	s_barrier
	v_mfma_f32_16x16x32_bf16 v[56:59], v[196:199], v[164:167], v[56:59]
	v_mfma_f32_16x16x32_bf16 v[48:51], v[208:211], v[164:167], v[48:51]
	v_mfma_f32_16x16x32_bf16 v[40:43], v[196:199], v[172:175], v[40:43]
	v_mfma_f32_16x16x32_bf16 v[32:35], v[208:211], v[172:175], v[32:35]
	v_mfma_f32_16x16x32_bf16 v[24:27], v[196:199], v[180:183], v[24:27]
	v_mfma_f32_16x16x32_bf16 v[16:19], v[208:211], v[180:183], v[16:19]
	v_mfma_f32_16x16x32_bf16 v[8:11], v[196:199], v[188:191], v[8:11]
	v_mfma_f32_16x16x32_bf16 v[0:3], v[208:211], v[188:191], v[0:3]
	v_mfma_f32_16x16x32_bf16 v[56:59], v[200:203], v[168:171], v[56:59]
	v_mfma_f32_16x16x32_bf16 v[48:51], v[212:215], v[168:171], v[48:51]
	v_mfma_f32_16x16x32_bf16 v[40:43], v[200:203], v[176:179], v[40:43]
	v_mfma_f32_16x16x32_bf16 v[32:35], v[212:215], v[176:179], v[32:35]
	v_mfma_f32_16x16x32_bf16 v[24:27], v[200:203], v[184:187], v[24:27]
	v_mfma_f32_16x16x32_bf16 v[16:19], v[212:215], v[184:187], v[16:19]
	v_mfma_f32_16x16x32_bf16 v[8:11], v[200:203], v[192:195], v[8:11]
	v_mfma_f32_16x16x32_bf16 v[0:3], v[212:215], v[192:195], v[0:3]
	s_barrier
	s_add_i32 s56, s56, 2
	s_add_u32 s12, s12, 0x100
	s_addc_u32 s13, s13, 0
	s_add_u32 s0, s0, 0x100
	s_addc_u32 s55, s55, 0
	s_cmp_gt_u32 s56, 29
	s_cbranch_scc0 .LBB0_3046
	s_lshr_b32 s0, s53, 4
	s_lshl_b32 s12, s53, 8
	s_mulk_i32 s0, 0x1100
	s_and_b32 s12, s12, 0xf00
	s_add_i32 s0, s0, s12
	s_lshl_b32 s12, s54, 7
	s_ashr_i32 s13, s12, 31
	s_addk_i32 s0, 0x100
	v_mov_b32_e32 v132, v206
	s_lshl_b64 s[12:13], s[12:13], 1
	s_add_u32 s12, s23, s12
	v_ashrrev_i32_e32 v140, 2, v132
	v_and_b32_e32 v140, 0xffffffc0, v140
	v_and_or_b32 v141, v132, 15, s0
	s_addc_u32 s13, s35, s13
	v_lshrrev_b32_e32 v148, 1, v132
	v_and_b32_e32 v132, 0xc0, v132
	v_add_u32_e32 v147, v141, v140
	v_lshl_add_u64 v[140:141], s[12:13], 0, v[132:133]
	v_and_b32_e32 v132, 24, v148
	v_mul_f32_e32 v148, 0xbfb8aa3b, v124
	v_exp_f32_e32 v148, v148
	v_mul_f32_e32 v149, 0xbfb8aa3b, v125
	v_exp_f32_e32 v149, v149
	v_lshl_add_u64 v[140:141], v[140:141], 0, v[132:133]
	v_add_f32_e32 v132, 1.0, v148
	v_rcp_f32_e32 v148, v132
	v_add_f32_e32 v132, 1.0, v149
	v_mul_f32_e32 v149, 0xbfb8aa3b, v126
	v_exp_f32_e32 v150, v149
	v_mul_f32_e32 v149, 0xbfb8aa3b, v127
	v_exp_f32_e32 v151, v149
	v_rcp_f32_e32 v149, v132
	v_add_f32_e32 v132, 1.0, v150
	v_rcp_f32_e32 v150, v132
	v_add_f32_e32 v132, 1.0, v151
	v_rcp_f32_e32 v151, v132
	v_pk_mul_f32 v[124:125], v[124:125], v[148:149]
	v_mad_i64_i32 v[152:153], s[12:13], v147, s37, v[140:141]
	v_pk_mul_f32 v[120:121], v[124:125], v[120:121]
	v_pk_mul_f32 v[124:125], v[126:127], v[150:151]
	v_cvt_pk_bf16_f32 v120, v120, v121
	v_mul_f32_e32 v121, 0xbfb8aa3b, v116
	v_pk_mul_f32 v[122:123], v[124:125], v[122:123]
	v_exp_f32_e32 v124, v121
	v_mul_f32_e32 v121, 0xbfb8aa3b, v117
	v_exp_f32_e32 v125, v121
	v_cvt_pk_bf16_f32 v121, v122, v123
	v_add_f32_e32 v122, 1.0, v124
	v_mul_f32_e32 v124, 0xbfb8aa3b, v118
	v_add_f32_e32 v123, 1.0, v125
	v_mul_f32_e32 v125, 0xbfb8aa3b, v119
	v_exp_f32_e32 v124, v124
	v_exp_f32_e32 v125, v125
	v_rcp_f32_e32 v122, v122
	v_rcp_f32_e32 v123, v123
	v_add_f32_e32 v124, 1.0, v124
	v_add_f32_e32 v125, 1.0, v125
	v_rcp_f32_e32 v124, v124
	v_rcp_f32_e32 v125, v125
	v_pk_mul_f32 v[116:117], v[116:117], v[122:123]
	s_and_b64 vcc, exec, s[4:5]
	v_pk_mul_f32 v[112:113], v[116:117], v[112:113]
	v_pk_mul_f32 v[116:117], v[118:119], v[124:125]
	v_cvt_pk_bf16_f32 v112, v112, v113
	v_pk_mul_f32 v[114:115], v[116:117], v[114:115]
	v_or_b32_e32 v116, 16, v147
	v_cvt_pk_bf16_f32 v113, v114, v115
	global_store_dwordx2 v[152:153], v[112:113], off offset:32
	v_mul_f32_e32 v112, 0xbfb8aa3b, v108
	v_mul_f32_e32 v113, 0xbfb8aa3b, v109
	v_exp_f32_e32 v112, v112
	v_exp_f32_e32 v113, v113
	v_mul_f32_e32 v114, 0xbfb8aa3b, v110
	v_mul_f32_e32 v115, 0xbfb8aa3b, v111
	v_exp_f32_e32 v114, v114
	v_exp_f32_e32 v115, v115
	v_add_f32_e32 v112, 1.0, v112
	v_add_f32_e32 v113, 1.0, v113
	v_rcp_f32_e32 v112, v112
	v_rcp_f32_e32 v113, v113
	v_add_f32_e32 v114, 1.0, v114
	v_add_f32_e32 v115, 1.0, v115
	v_rcp_f32_e32 v114, v114
	v_rcp_f32_e32 v115, v115
	v_pk_mul_f32 v[108:109], v[108:109], v[112:113]
	v_mad_i64_i32 v[116:117], s[12:13], v116, s37, v[140:141]
; DI float silu_f(float g) { return g * __builtin_amdgcn_rcpf(1.f + __builtin_amdgcn_exp2f(-LOG2E * g)); }
; #define EPI_DONE do { } while (0)
; DI void epi_swiglu(const Acc& acc, int brow, int pn, bf16_t* hid) {
;     EPI_IDX
; #pragma unroll
;     for (int ai = 0; ai < 2; ++ai)
; #pragma unroll
;         for (int m = 0; m < 4; ++m) {
;             const int r = brow + ai * 128 + wr * 64 + m * 16 + fr;
;             bf16_t* rp = hid + (size_t)r * FF + pn * 128 + wc * 32 + fq * 4;
; #pragma unroll
;             for (int n = 0; n < 2; ++n) {
;                 const f32x4 g = acc[ai][0][m][n], u = acc[ai][1][m][n];
;                 float o[4];
; #pragma unroll
;                 for (int j = 0; j < 4; ++j) o[j] = silu_f(g[j]) * u[j];
;                 st4(rp + n * 16, o[0], o[1], o[2], o[3]);
;             }
;         }
;     EPI_DONE;
; }
	v_pk_mul_f32 v[104:105], v[108:109], v[104:105]
	v_pk_mul_f32 v[108:109], v[110:111], v[114:115]
	v_cvt_pk_bf16_f32 v104, v104, v105
	v_mul_f32_e32 v105, 0xbfb8aa3b, v100
	v_pk_mul_f32 v[106:107], v[108:109], v[106:107]
	v_exp_f32_e32 v108, v105
	v_mul_f32_e32 v105, 0xbfb8aa3b, v101
	v_exp_f32_e32 v109, v105
	v_cvt_pk_bf16_f32 v105, v106, v107
	v_add_f32_e32 v106, 1.0, v108
	v_mul_f32_e32 v108, 0xbfb8aa3b, v102
	v_add_f32_e32 v107, 1.0, v109
	v_mul_f32_e32 v109, 0xbfb8aa3b, v103
	v_exp_f32_e32 v108, v108
	v_exp_f32_e32 v109, v109
	v_rcp_f32_e32 v106, v106
	v_rcp_f32_e32 v107, v107
	v_add_f32_e32 v108, 1.0, v108
	v_add_f32_e32 v109, 1.0, v109
	v_rcp_f32_e32 v108, v108
	v_rcp_f32_e32 v109, v109
	v_pk_mul_f32 v[100:101], v[100:101], v[106:107]
	s_mov_b32 s54, s49
	v_pk_mul_f32 v[96:97], v[100:101], v[96:97]
	v_pk_mul_f32 v[100:101], v[102:103], v[108:109]
	v_cvt_pk_bf16_f32 v96, v96, v97
	v_pk_mul_f32 v[98:99], v[100:101], v[98:99]
	v_or_b32_e32 v100, 32, v147
	v_cvt_pk_bf16_f32 v97, v98, v99
	global_store_dwordx2 v[116:117], v[96:97], off offset:32
	v_mul_f32_e32 v96, 0xbfb8aa3b, v92
	v_mul_f32_e32 v97, 0xbfb8aa3b, v93
	v_exp_f32_e32 v96, v96
	v_exp_f32_e32 v97, v97
	v_mul_f32_e32 v98, 0xbfb8aa3b, v94
	v_mul_f32_e32 v99, 0xbfb8aa3b, v95
	v_exp_f32_e32 v98, v98
	v_exp_f32_e32 v99, v99
	v_add_f32_e32 v96, 1.0, v96
	v_add_f32_e32 v97, 1.0, v97
	v_rcp_f32_e32 v96, v96
	v_rcp_f32_e32 v97, v97
	v_add_f32_e32 v98, 1.0, v98
	v_add_f32_e32 v99, 1.0, v99
	v_rcp_f32_e32 v98, v98
	v_rcp_f32_e32 v99, v99
	v_pk_mul_f32 v[92:93], v[92:93], v[96:97]
	v_mad_i64_i32 v[100:101], s[12:13], v100, s37, v[140:141]
	v_pk_mul_f32 v[88:89], v[92:93], v[88:89]
	v_pk_mul_f32 v[92:93], v[94:95], v[98:99]
	v_cvt_pk_bf16_f32 v88, v88, v89
	v_mul_f32_e32 v89, 0xbfb8aa3b, v84
	v_pk_mul_f32 v[90:91], v[92:93], v[90:91]
	v_exp_f32_e32 v92, v89
	v_mul_f32_e32 v89, 0xbfb8aa3b, v85
	v_exp_f32_e32 v93, v89
	v_cvt_pk_bf16_f32 v89, v90, v91
	v_add_f32_e32 v90, 1.0, v92
	v_mul_f32_e32 v92, 0xbfb8aa3b, v86
	v_add_f32_e32 v91, 1.0, v93
	v_mul_f32_e32 v93, 0xbfb8aa3b, v87
	v_exp_f32_e32 v92, v92
	v_exp_f32_e32 v93, v93
	v_rcp_f32_e32 v90, v90
	v_rcp_f32_e32 v91, v91
	v_add_f32_e32 v92, 1.0, v92
	v_add_f32_e32 v93, 1.0, v93
	v_rcp_f32_e32 v92, v92
	v_rcp_f32_e32 v93, v93
	v_pk_mul_f32 v[84:85], v[84:85], v[90:91]
	s_mov_b32 s53, s52
	v_pk_mul_f32 v[80:81], v[84:85], v[80:81]
	v_pk_mul_f32 v[84:85], v[86:87], v[92:93]
	v_cvt_pk_bf16_f32 v80, v80, v81
	v_pk_mul_f32 v[82:83], v[84:85], v[82:83]
	v_or_b32_e32 v84, 48, v147
	v_cvt_pk_bf16_f32 v81, v82, v83
	global_store_dwordx2 v[100:101], v[80:81], off offset:32
	v_mul_f32_e32 v80, 0xbfb8aa3b, v76
	v_mul_f32_e32 v81, 0xbfb8aa3b, v77
	v_exp_f32_e32 v80, v80
	v_exp_f32_e32 v81, v81
	v_mul_f32_e32 v82, 0xbfb8aa3b, v78
	v_mul_f32_e32 v83, 0xbfb8aa3b, v79
	v_exp_f32_e32 v82, v82
	v_exp_f32_e32 v83, v83
	v_add_f32_e32 v80, 1.0, v80
	v_add_f32_e32 v81, 1.0, v81
	v_rcp_f32_e32 v80, v80
	v_rcp_f32_e32 v81, v81
	v_add_f32_e32 v82, 1.0, v82
	v_add_f32_e32 v83, 1.0, v83
	v_rcp_f32_e32 v82, v82
	v_rcp_f32_e32 v83, v83
	v_pk_mul_f32 v[76:77], v[76:77], v[80:81]
	v_mad_i64_i32 v[84:85], s[12:13], v84, s37, v[140:141]
	v_pk_mul_f32 v[72:73], v[76:77], v[72:73]
	v_pk_mul_f32 v[76:77], v[78:79], v[82:83]
	v_cvt_pk_bf16_f32 v72, v72, v73
	v_mul_f32_e32 v73, 0xbfb8aa3b, v68
	v_pk_mul_f32 v[74:75], v[76:77], v[74:75]
	v_exp_f32_e32 v76, v73
	v_mul_f32_e32 v73, 0xbfb8aa3b, v69
	v_exp_f32_e32 v77, v73
	v_cvt_pk_bf16_f32 v73, v74, v75
	v_add_f32_e32 v74, 1.0, v76
	v_mul_f32_e32 v76, 0xbfb8aa3b, v70
	v_add_f32_e32 v75, 1.0, v77
	v_mul_f32_e32 v77, 0xbfb8aa3b, v71
	v_exp_f32_e32 v76, v76
	v_exp_f32_e32 v77, v77
	v_rcp_f32_e32 v74, v74
	v_rcp_f32_e32 v75, v75
	v_add_f32_e32 v76, 1.0, v76
	v_add_f32_e32 v77, 1.0, v77
	v_rcp_f32_e32 v76, v76
	v_rcp_f32_e32 v77, v77
	v_pk_mul_f32 v[68:69], v[68:69], v[74:75]
	s_mov_b64 s[14:15], s[10:11]
	v_pk_mul_f32 v[64:65], v[68:69], v[64:65]
	v_pk_mul_f32 v[68:69], v[70:71], v[76:77]
	v_cvt_pk_bf16_f32 v64, v64, v65
	v_pk_mul_f32 v[66:67], v[68:69], v[66:67]
	v_add_u32_e32 v68, 0x80, v147
	v_cvt_pk_bf16_f32 v65, v66, v67
	global_store_dwordx2 v[84:85], v[64:65], off offset:32
	v_mul_f32_e32 v64, 0xbfb8aa3b, v60
	v_mul_f32_e32 v65, 0xbfb8aa3b, v61
	v_exp_f32_e32 v64, v64
	v_exp_f32_e32 v65, v65
	v_mul_f32_e32 v66, 0xbfb8aa3b, v62
	v_mul_f32_e32 v67, 0xbfb8aa3b, v63
	v_exp_f32_e32 v66, v66
	v_exp_f32_e32 v67, v67
	v_add_f32_e32 v64, 1.0, v64
	v_add_f32_e32 v65, 1.0, v65
	v_rcp_f32_e32 v64, v64
	v_rcp_f32_e32 v65, v65
	v_add_f32_e32 v66, 1.0, v66
	v_add_f32_e32 v67, 1.0, v67
	v_rcp_f32_e32 v66, v66
	v_rcp_f32_e32 v67, v67
	v_pk_mul_f32 v[60:61], v[60:61], v[64:65]
	v_mad_i64_i32 v[68:69], s[12:13], v68, s37, v[140:141]
	v_pk_mul_f32 v[56:57], v[60:61], v[56:57]
	v_pk_mul_f32 v[60:61], v[62:63], v[66:67]
	v_cvt_pk_bf16_f32 v56, v56, v57
	v_mul_f32_e32 v57, 0xbfb8aa3b, v52
	v_pk_mul_f32 v[58:59], v[60:61], v[58:59]
	v_exp_f32_e32 v60, v57
	v_mul_f32_e32 v57, 0xbfb8aa3b, v53
	v_exp_f32_e32 v61, v57
	v_cvt_pk_bf16_f32 v57, v58, v59
	v_add_f32_e32 v58, 1.0, v60
	v_mul_f32_e32 v60, 0xbfb8aa3b, v54
	v_add_f32_e32 v59, 1.0, v61
	v_mul_f32_e32 v61, 0xbfb8aa3b, v55
	v_exp_f32_e32 v60, v60
	v_exp_f32_e32 v61, v61
	v_rcp_f32_e32 v58, v58
	v_rcp_f32_e32 v59, v59
	v_add_f32_e32 v60, 1.0, v60
	v_add_f32_e32 v61, 1.0, v61
	v_rcp_f32_e32 v60, v60
; DI float silu_f(float g) { return g * __builtin_amdgcn_rcpf(1.f + __builtin_amdgcn_exp2f(-LOG2E * g)); }
; #define WAIT_V(n) asm volatile("s_waitcnt vmcnt(" #n ")" ::: "memory")
; #define BAR __builtin_amdgcn_s_barrier()
; #define EPI_DONE do { } while (0)
; template <class Get, class Epi>
; DI void gemm_stream(LAS unsigned char* lds, const int K, const int ld, Get get, Epi epi) {
;     ...
;         if (!has_next) break;
;         ZERO_ACC;
;         cur = nxt; cA = nA; cB = nB; ++ui;
;     }
;     WAIT_V(0);
;     if (wr == 0) BAR;
; DI void epi_swiglu(const Acc& acc, int brow, int pn, bf16_t* hid) {
;     EPI_IDX
; #pragma unroll
;     for (int ai = 0; ai < 2; ++ai)
; #pragma unroll
;         for (int m = 0; m < 4; ++m) {
;             const int r = brow + ai * 128 + wr * 64 + m * 16 + fr;
;             bf16_t* rp = hid + (size_t)r * FF + pn * 128 + wc * 32 + fq * 4;
; #pragma unroll
;             for (int n = 0; n < 2; ++n) {
;                 const f32x4 g = acc[ai][0][m][n], u = acc[ai][1][m][n];
;                 float o[4];
; #pragma unroll
;                 for (int j = 0; j < 4; ++j) o[j] = silu_f(g[j]) * u[j];
;                 st4(rp + n * 16, o[0], o[1], o[2], o[3]);
;             }
;         }
;     EPI_DONE;
; }
	v_rcp_f32_e32 v61, v61
	v_pk_mul_f32 v[52:53], v[52:53], v[58:59]
	global_store_dwordx2 v[152:153], v[120:121], off
	v_pk_mul_f32 v[48:49], v[52:53], v[48:49]
	v_pk_mul_f32 v[52:53], v[54:55], v[60:61]
	v_cvt_pk_bf16_f32 v48, v48, v49
	v_pk_mul_f32 v[50:51], v[52:53], v[50:51]
	v_add_u32_e32 v52, 0x90, v147
	v_cvt_pk_bf16_f32 v49, v50, v51
	global_store_dwordx2 v[68:69], v[48:49], off offset:32
	v_mul_f32_e32 v48, 0xbfb8aa3b, v44
	v_mul_f32_e32 v49, 0xbfb8aa3b, v45
	v_exp_f32_e32 v48, v48
	v_exp_f32_e32 v49, v49
	v_mul_f32_e32 v50, 0xbfb8aa3b, v46
	v_mul_f32_e32 v51, 0xbfb8aa3b, v47
	v_exp_f32_e32 v50, v50
	v_exp_f32_e32 v51, v51
	v_add_f32_e32 v48, 1.0, v48
	v_add_f32_e32 v49, 1.0, v49
	v_rcp_f32_e32 v48, v48
	v_rcp_f32_e32 v49, v49
	v_add_f32_e32 v50, 1.0, v50
	v_add_f32_e32 v51, 1.0, v51
	v_rcp_f32_e32 v50, v50
	v_rcp_f32_e32 v51, v51
	v_pk_mul_f32 v[44:45], v[44:45], v[48:49]
	v_mad_i64_i32 v[52:53], s[12:13], v52, s37, v[140:141]
	v_pk_mul_f32 v[40:41], v[44:45], v[40:41]
	v_pk_mul_f32 v[44:45], v[46:47], v[50:51]
	v_cvt_pk_bf16_f32 v40, v40, v41
	v_mul_f32_e32 v41, 0xbfb8aa3b, v36
	v_pk_mul_f32 v[42:43], v[44:45], v[42:43]
	v_exp_f32_e32 v44, v41
	v_mul_f32_e32 v41, 0xbfb8aa3b, v37
	v_exp_f32_e32 v45, v41
	v_cvt_pk_bf16_f32 v41, v42, v43
	v_add_f32_e32 v42, 1.0, v44
	v_mul_f32_e32 v44, 0xbfb8aa3b, v38
	v_add_f32_e32 v43, 1.0, v45
	v_mul_f32_e32 v45, 0xbfb8aa3b, v39
	v_exp_f32_e32 v44, v44
	v_exp_f32_e32 v45, v45
	v_rcp_f32_e32 v42, v42
	v_rcp_f32_e32 v43, v43
	v_add_f32_e32 v44, 1.0, v44
	v_add_f32_e32 v45, 1.0, v45
	v_rcp_f32_e32 v44, v44
	v_rcp_f32_e32 v45, v45
	v_pk_mul_f32 v[36:37], v[36:37], v[42:43]
	global_store_dwordx2 v[116:117], v[104:105], off
	v_pk_mul_f32 v[32:33], v[36:37], v[32:33]
	v_pk_mul_f32 v[36:37], v[38:39], v[44:45]
	v_cvt_pk_bf16_f32 v32, v32, v33
	v_pk_mul_f32 v[34:35], v[36:37], v[34:35]
	v_add_u32_e32 v36, 0xa0, v147
	v_cvt_pk_bf16_f32 v33, v34, v35
	global_store_dwordx2 v[52:53], v[32:33], off offset:32
	v_mul_f32_e32 v32, 0xbfb8aa3b, v28
	v_mul_f32_e32 v33, 0xbfb8aa3b, v29
	v_exp_f32_e32 v32, v32
	v_exp_f32_e32 v33, v33
	v_mul_f32_e32 v34, 0xbfb8aa3b, v30
	v_mul_f32_e32 v35, 0xbfb8aa3b, v31
	v_exp_f32_e32 v34, v34
	v_exp_f32_e32 v35, v35
	v_add_f32_e32 v32, 1.0, v32
	v_add_f32_e32 v33, 1.0, v33
	v_rcp_f32_e32 v32, v32
	v_rcp_f32_e32 v33, v33
	v_add_f32_e32 v34, 1.0, v34
	v_add_f32_e32 v35, 1.0, v35
	v_rcp_f32_e32 v34, v34
	v_rcp_f32_e32 v35, v35
	v_pk_mul_f32 v[28:29], v[28:29], v[32:33]
	v_mad_i64_i32 v[36:37], s[12:13], v36, s37, v[140:141]
	v_pk_mul_f32 v[24:25], v[28:29], v[24:25]
	v_pk_mul_f32 v[28:29], v[30:31], v[34:35]
	v_cvt_pk_bf16_f32 v24, v24, v25
	v_mul_f32_e32 v25, 0xbfb8aa3b, v20
	v_pk_mul_f32 v[26:27], v[28:29], v[26:27]
	v_exp_f32_e32 v28, v25
	v_mul_f32_e32 v25, 0xbfb8aa3b, v21
	v_exp_f32_e32 v29, v25
	v_cvt_pk_bf16_f32 v25, v26, v27
	v_add_f32_e32 v26, 1.0, v28
	v_mul_f32_e32 v28, 0xbfb8aa3b, v22
	v_add_f32_e32 v27, 1.0, v29
	v_mul_f32_e32 v29, 0xbfb8aa3b, v23
	v_exp_f32_e32 v28, v28
	v_exp_f32_e32 v29, v29
	v_rcp_f32_e32 v26, v26
	v_rcp_f32_e32 v27, v27
	v_add_f32_e32 v28, 1.0, v28
	v_add_f32_e32 v29, 1.0, v29
	v_rcp_f32_e32 v28, v28
	v_rcp_f32_e32 v29, v29
	v_pk_mul_f32 v[20:21], v[20:21], v[26:27]
	global_store_dwordx2 v[100:101], v[88:89], off
	v_pk_mul_f32 v[16:17], v[20:21], v[16:17]
	v_pk_mul_f32 v[20:21], v[22:23], v[28:29]
	v_cvt_pk_bf16_f32 v16, v16, v17
	v_pk_mul_f32 v[18:19], v[20:21], v[18:19]
	v_add_u32_e32 v20, 0xb0, v147
	v_cvt_pk_bf16_f32 v17, v18, v19
	global_store_dwordx2 v[36:37], v[16:17], off offset:32
	v_mul_f32_e32 v16, 0xbfb8aa3b, v12
	v_mul_f32_e32 v17, 0xbfb8aa3b, v13
	v_exp_f32_e32 v16, v16
	v_exp_f32_e32 v17, v17
	v_mul_f32_e32 v18, 0xbfb8aa3b, v14
	v_mul_f32_e32 v19, 0xbfb8aa3b, v15
	v_exp_f32_e32 v18, v18
	v_exp_f32_e32 v19, v19
	v_add_f32_e32 v16, 1.0, v16
	v_add_f32_e32 v17, 1.0, v17
	v_rcp_f32_e32 v16, v16
	v_rcp_f32_e32 v17, v17
	v_add_f32_e32 v18, 1.0, v18
	v_add_f32_e32 v19, 1.0, v19
	v_rcp_f32_e32 v18, v18
	v_rcp_f32_e32 v19, v19
	v_pk_mul_f32 v[12:13], v[12:13], v[16:17]
	v_mad_i64_i32 v[20:21], s[12:13], v20, s37, v[140:141]
	v_pk_mul_f32 v[8:9], v[12:13], v[8:9]
	v_pk_mul_f32 v[12:13], v[14:15], v[18:19]
	v_cvt_pk_bf16_f32 v8, v8, v9
	v_mul_f32_e32 v9, 0xbfb8aa3b, v4
	v_pk_mul_f32 v[10:11], v[12:13], v[10:11]
	v_exp_f32_e32 v12, v9
	v_mul_f32_e32 v9, 0xbfb8aa3b, v5
	v_exp_f32_e32 v13, v9
	v_cvt_pk_bf16_f32 v9, v10, v11
	v_add_f32_e32 v10, 1.0, v12
	v_mul_f32_e32 v12, 0xbfb8aa3b, v6
	v_add_f32_e32 v11, 1.0, v13
	v_mul_f32_e32 v13, 0xbfb8aa3b, v7
	v_exp_f32_e32 v12, v12
	v_exp_f32_e32 v13, v13
	v_rcp_f32_e32 v10, v10
	v_rcp_f32_e32 v11, v11
	v_add_f32_e32 v12, 1.0, v12
	v_add_f32_e32 v13, 1.0, v13
	v_rcp_f32_e32 v12, v12
	v_rcp_f32_e32 v13, v13
	v_pk_mul_f32 v[4:5], v[4:5], v[10:11]
	s_mov_b64 s[12:13], s[8:9]
	v_pk_mul_f32 v[0:1], v[4:5], v[0:1]
	v_pk_mul_f32 v[4:5], v[6:7], v[12:13]
	v_cvt_pk_bf16_f32 v0, v0, v1
	v_pk_mul_f32 v[2:3], v[4:5], v[2:3]
	global_store_dwordx2 v[84:85], v[72:73], off
	v_cvt_pk_bf16_f32 v1, v2, v3
	global_store_dwordx2 v[68:69], v[56:57], off
	global_store_dwordx2 v[52:53], v[40:41], off
	global_store_dwordx2 v[36:37], v[24:25], off
	global_store_dwordx2 v[20:21], v[8:9], off
	global_store_dwordx2 v[20:21], v[0:1], off offset:32
	s_cbranch_vccz .LBB0_3043
	s_waitcnt vmcnt(0)
	s_cmpk_gt_u32 s2, 0xff
	s_cbranch_scc1 .LBB0_3050
	s_barrier

; #define WAIT_V(n) asm volatile("s_waitcnt vmcnt(" #n ")" ::: "memory")
; #define WAIT_L(n) asm volatile("s_waitcnt lgkmcnt(" #n ")" ::: "memory")
; #define BAR __builtin_amdgcn_s_barrier()
; #define SCHED __builtin_amdgcn_sched_barrier(0)
; template <class Get, class Epi>
; DI void gemm_stream(LAS unsigned char* lds, const int K, const int ld, Get get, Epi epi) {
;     ...
;             LDB(B0, 0, 0); SCHED; LDA(At, 0, 0); STAGE(SAo(1, 1), a1 + hstep);
;             WAIT_L(8); BAR; WAIT_L(0); MMA(0, 0, At, B0); BAR; SCHED;
;             LDB(B1, 0, 1); STAGE(SBo(0, 0), b2);
;             BAR; WAIT_L(0); MMA(0, 1, At, B1); BAR;
;             LDA(At, 0, 1); STAGE(SAo(0, 0), a2);
;             BAR; WAIT_L(0); MMA(1, 0, At, B0); BAR; SCHED;
;             STAGE(SBo(0, 1), b2 + hstep);
;             WAIT_V(6); BAR; MMA(1, 1, At, B1); BAR;
.LBB0_3113:
	ds_read_b128 v[128:131], v199
	ds_read_b128 v[132:135], v199 offset:1024
	ds_read_b128 v[136:139], v199 offset:2048
	ds_read_b128 v[140:143], v199 offset:3072
	s_add_u32 s6, s4, 0x100
	s_addc_u32 s7, s5, 0
	s_cmpk_eq_i32 s16, 0x54
	s_cselect_b32 s11, s37, s7
	s_cselect_b32 s10, s36, s6
	s_cselect_b32 s9, s39, s15
	s_cselect_b32 s8, s38, s14
	s_mov_b32 m0, s54
	v_lshl_add_u64 v[186:187], s[4:5], 0, v[168:169]
	ds_read_b128 v[144:147], v200
	ds_read_b128 v[148:151], v200 offset:1024
	ds_read_b128 v[152:155], v200 offset:2048
	ds_read_b128 v[156:159], v200 offset:3072
	ds_read_b128 v[160:163], v200 offset:4096
	ds_read_b128 v[174:177], v200 offset:5120
	ds_read_b128 v[178:181], v200 offset:6144
	ds_read_b128 v[182:185], v200 offset:7168
	global_load_lds_dwordx4 v[186:187], off
	v_lshl_add_u64 v[186:187], s[4:5], 0, v[170:171]
	s_mov_b32 m0, s55
	s_nop 0
	global_load_lds_dwordx4 v[186:187], off
	s_waitcnt lgkmcnt(8)
	s_barrier
	s_waitcnt lgkmcnt(0)
	v_mfma_f32_16x16x32_bf16 v[124:127], v[128:131], v[144:147], v[124:127]
	v_mfma_f32_16x16x32_bf16 v[92:95], v[136:139], v[144:147], v[92:95]
	v_mfma_f32_16x16x32_bf16 v[120:123], v[128:131], v[152:155], v[120:123]
	v_mfma_f32_16x16x32_bf16 v[88:91], v[136:139], v[152:155], v[88:91]
	v_mfma_f32_16x16x32_bf16 v[116:119], v[128:131], v[160:163], v[116:119]
	v_mfma_f32_16x16x32_bf16 v[84:87], v[136:139], v[160:163], v[84:87]
	v_mfma_f32_16x16x32_bf16 v[112:115], v[128:131], v[178:181], v[112:115]
	v_mfma_f32_16x16x32_bf16 v[80:83], v[136:139], v[178:181], v[80:83]
	v_mfma_f32_16x16x32_bf16 v[124:127], v[132:135], v[148:151], v[124:127]
	v_mfma_f32_16x16x32_bf16 v[92:95], v[140:143], v[148:151], v[92:95]
	v_mfma_f32_16x16x32_bf16 v[120:123], v[132:135], v[156:159], v[120:123]
	v_mfma_f32_16x16x32_bf16 v[88:91], v[140:143], v[156:159], v[88:91]
	v_mfma_f32_16x16x32_bf16 v[116:119], v[132:135], v[174:177], v[116:119]
	v_mfma_f32_16x16x32_bf16 v[84:87], v[140:143], v[174:177], v[84:87]
	v_mfma_f32_16x16x32_bf16 v[112:115], v[132:135], v[182:185], v[112:115]
	v_mfma_f32_16x16x32_bf16 v[80:83], v[140:143], v[182:185], v[80:83]
	s_barrier
	s_mov_b32 m0, s56
	v_lshl_add_u64 v[208:209], s[8:9], 0, v[164:165]
	ds_read_b128 v[186:189], v201
	ds_read_b128 v[190:193], v201 offset:1024
	ds_read_b128 v[194:197], v201 offset:2048
	ds_read_b128 v[202:205], v201 offset:3072
	global_load_lds_dwordx4 v[208:209], off
	v_lshl_add_u64 v[210:211], s[8:9], 0, v[166:167]
	s_mov_b32 m0, s57
	s_nop 0
	global_load_lds_dwordx4 v[210:211], off
	s_barrier
	s_waitcnt lgkmcnt(0)
	v_mfma_f32_16x16x32_bf16 v[60:63], v[186:189], v[144:147], v[60:63]
	v_mfma_f32_16x16x32_bf16 v[28:31], v[194:197], v[144:147], v[28:31]
	v_mfma_f32_16x16x32_bf16 v[56:59], v[186:189], v[152:155], v[56:59]
	v_mfma_f32_16x16x32_bf16 v[24:27], v[194:197], v[152:155], v[24:27]
	v_mfma_f32_16x16x32_bf16 v[52:55], v[186:189], v[160:163], v[52:55]
	v_mfma_f32_16x16x32_bf16 v[20:23], v[194:197], v[160:163], v[20:23]
	v_mfma_f32_16x16x32_bf16 v[48:51], v[186:189], v[178:181], v[48:51]
	v_mfma_f32_16x16x32_bf16 v[16:19], v[194:197], v[178:181], v[16:19]
	v_mfma_f32_16x16x32_bf16 v[60:63], v[190:193], v[148:151], v[60:63]
	v_mfma_f32_16x16x32_bf16 v[28:31], v[202:205], v[148:151], v[28:31]
	v_mfma_f32_16x16x32_bf16 v[56:59], v[190:193], v[156:159], v[56:59]
	v_mfma_f32_16x16x32_bf16 v[24:27], v[202:205], v[156:159], v[24:27]
	v_mfma_f32_16x16x32_bf16 v[52:55], v[190:193], v[174:177], v[52:55]
	v_mfma_f32_16x16x32_bf16 v[20:23], v[202:205], v[174:177], v[20:23]
	v_mfma_f32_16x16x32_bf16 v[48:51], v[190:193], v[182:185], v[48:51]
	v_mfma_f32_16x16x32_bf16 v[16:19], v[202:205], v[182:185], v[16:19]
	s_barrier
	s_mov_b32 m0, s33
	v_lshl_add_u64 v[212:213], s[10:11], 0, v[164:165]
	ds_read_b128 v[144:147], v200 offset:16384
	ds_read_b128 v[148:151], v200 offset:17408
	ds_read_b128 v[152:155], v200 offset:18432
	ds_read_b128 v[156:159], v200 offset:19456
	ds_read_b128 v[160:163], v200 offset:20480
	ds_read_b128 v[174:177], v200 offset:21504
	ds_read_b128 v[178:181], v200 offset:22528
	ds_read_b128 v[182:185], v200 offset:23552
	global_load_lds_dwordx4 v[212:213], off
	v_lshl_add_u64 v[214:215], s[10:11], 0, v[166:167]
	s_mov_b32 m0, s42
	s_nop 0
	global_load_lds_dwordx4 v[214:215], off
	s_barrier
	s_waitcnt lgkmcnt(0)
	v_mfma_f32_16x16x32_bf16 v[108:111], v[128:131], v[144:147], v[108:111]
	v_mfma_f32_16x16x32_bf16 v[76:79], v[136:139], v[144:147], v[76:79]
	v_mfma_f32_16x16x32_bf16 v[104:107], v[128:131], v[152:155], v[104:107]
	v_mfma_f32_16x16x32_bf16 v[72:75], v[136:139], v[152:155], v[72:75]
	v_mfma_f32_16x16x32_bf16 v[100:103], v[128:131], v[160:163], v[100:103]
	v_mfma_f32_16x16x32_bf16 v[68:71], v[136:139], v[160:163], v[68:71]
	v_mfma_f32_16x16x32_bf16 v[96:99], v[128:131], v[178:181], v[96:99]
	v_mfma_f32_16x16x32_bf16 v[64:67], v[136:139], v[178:181], v[64:67]
	v_mfma_f32_16x16x32_bf16 v[108:111], v[132:135], v[148:151], v[108:111]
	v_mfma_f32_16x16x32_bf16 v[76:79], v[140:143], v[148:151], v[76:79]
	v_mfma_f32_16x16x32_bf16 v[104:107], v[132:135], v[156:159], v[104:107]
	v_mfma_f32_16x16x32_bf16 v[72:75], v[140:143], v[156:159], v[72:75]
	v_mfma_f32_16x16x32_bf16 v[100:103], v[132:135], v[174:177], v[100:103]
	v_mfma_f32_16x16x32_bf16 v[68:71], v[140:143], v[174:177], v[68:71]
	v_mfma_f32_16x16x32_bf16 v[96:99], v[132:135], v[182:185], v[96:99]
	v_mfma_f32_16x16x32_bf16 v[64:67], v[140:143], v[182:185], v[64:67]
	s_barrier
	s_add_u32 s4, s8, 0x160000
	s_addc_u32 s5, s9, 0
	s_mov_b32 m0, s58
	v_lshl_add_u64 v[128:129], s[4:5], 0, v[164:165]
	global_load_lds_dwordx4 v[128:129], off
	v_lshl_add_u64 v[128:129], s[4:5], 0, v[166:167]
	s_mov_b32 m0, s59
	s_nop 0
	global_load_lds_dwordx4 v[128:129], off
	s_waitcnt vmcnt(6)
	s_barrier
; #define WAIT_V(n) asm volatile("s_waitcnt vmcnt(" #n ")" ::: "memory")
; #define WAIT_L(n) asm volatile("s_waitcnt lgkmcnt(" #n ")" ::: "memory")
; #define BAR __builtin_amdgcn_s_barrier()
; #define SCHED __builtin_amdgcn_sched_barrier(0)
; template <class Get, class Epi>
; DI void gemm_stream(LAS unsigned char* lds, const int K, const int ld, Get get, Epi epi) {
;     ...
;             WAIT_V(6); BAR; MMA(1, 1, At, B1); BAR;
;             LDB(B0, 1, 0); SCHED; LDA(At, 1, 0); STAGE(SAo(0, 1), a2 + hstep);
;             WAIT_L(8); BAR; WAIT_L(0); MMA(0, 0, At, B0); BAR; SCHED;
;             LDB(B1, 1, 1); STAGE(SBo(1, 0), b3);
;             BAR; WAIT_L(0); MMA(0, 1, At, B1); BAR;
;             LDA(At, 1, 1); STAGE(SAo(1, 0), a3);
;             BAR; WAIT_L(0); MMA(1, 0, At, B0); BAR; SCHED;
	v_mfma_f32_16x16x32_bf16 v[44:47], v[186:189], v[144:147], v[44:47]
	v_mfma_f32_16x16x32_bf16 v[12:15], v[194:197], v[144:147], v[12:15]
	v_mfma_f32_16x16x32_bf16 v[40:43], v[186:189], v[152:155], v[40:43]
	v_mfma_f32_16x16x32_bf16 v[8:11], v[194:197], v[152:155], v[8:11]
	v_mfma_f32_16x16x32_bf16 v[36:39], v[186:189], v[160:163], v[36:39]
	v_mfma_f32_16x16x32_bf16 v[4:7], v[194:197], v[160:163], v[4:7]
	v_mfma_f32_16x16x32_bf16 v[32:35], v[186:189], v[178:181], v[32:35]
	v_mfma_f32_16x16x32_bf16 v[0:3], v[194:197], v[178:181], v[0:3]
	v_mfma_f32_16x16x32_bf16 v[44:47], v[190:193], v[148:151], v[44:47]
	v_mfma_f32_16x16x32_bf16 v[12:15], v[202:205], v[148:151], v[12:15]
	v_mfma_f32_16x16x32_bf16 v[40:43], v[190:193], v[156:159], v[40:43]
	v_mfma_f32_16x16x32_bf16 v[8:11], v[202:205], v[156:159], v[8:11]
	v_mfma_f32_16x16x32_bf16 v[36:39], v[190:193], v[174:177], v[36:39]
	v_mfma_f32_16x16x32_bf16 v[4:7], v[202:205], v[174:177], v[4:7]
	v_mfma_f32_16x16x32_bf16 v[32:35], v[190:193], v[182:185], v[32:35]
	v_mfma_f32_16x16x32_bf16 v[0:3], v[202:205], v[182:185], v[0:3]
	s_add_i32 s17, 16, 0x18000
	v_add_u32_e32 v140, s17, v198
	s_barrier
	ds_read_b128 v[128:131], v140
	ds_read_b128 v[132:135], v140 offset:1024
	ds_read_b128 v[136:139], v140 offset:2048
	ds_read_b128 v[140:143], v140 offset:3072
	s_add_u32 s4, s10, 0x160000
	s_addc_u32 s5, s11, 0
	s_mov_b32 m0, s43
	v_lshl_add_u64 v[186:187], s[4:5], 0, v[164:165]
	ds_read_b128 v[144:147], v200 offset:32768
	ds_read_b128 v[148:151], v200 offset:33792
	ds_read_b128 v[152:155], v200 offset:34816
	ds_read_b128 v[156:159], v200 offset:35840
	ds_read_b128 v[160:163], v200 offset:36864
	ds_read_b128 v[174:177], v200 offset:37888
	ds_read_b128 v[178:181], v200 offset:38912
	ds_read_b128 v[182:185], v200 offset:39936
	global_load_lds_dwordx4 v[186:187], off
	v_lshl_add_u64 v[186:187], s[4:5], 0, v[166:167]
	s_mov_b32 m0, s44
	s_nop 0
	global_load_lds_dwordx4 v[186:187], off
	s_waitcnt lgkmcnt(8)
	s_barrier
	s_waitcnt lgkmcnt(0)
	v_mfma_f32_16x16x32_bf16 v[124:127], v[128:131], v[144:147], v[124:127]
	v_mfma_f32_16x16x32_bf16 v[92:95], v[136:139], v[144:147], v[92:95]
	v_mfma_f32_16x16x32_bf16 v[120:123], v[128:131], v[152:155], v[120:123]
	v_mfma_f32_16x16x32_bf16 v[88:91], v[136:139], v[152:155], v[88:91]
	v_mfma_f32_16x16x32_bf16 v[116:119], v[128:131], v[160:163], v[116:119]
	v_mfma_f32_16x16x32_bf16 v[84:87], v[136:139], v[160:163], v[84:87]
	v_mfma_f32_16x16x32_bf16 v[112:115], v[128:131], v[178:181], v[112:115]
	v_mfma_f32_16x16x32_bf16 v[80:83], v[136:139], v[178:181], v[80:83]
	v_mfma_f32_16x16x32_bf16 v[124:127], v[132:135], v[148:151], v[124:127]
	v_mfma_f32_16x16x32_bf16 v[92:95], v[140:143], v[148:151], v[92:95]
	v_mfma_f32_16x16x32_bf16 v[120:123], v[132:135], v[156:159], v[120:123]
	v_mfma_f32_16x16x32_bf16 v[88:91], v[140:143], v[156:159], v[88:91]
	v_mfma_f32_16x16x32_bf16 v[116:119], v[132:135], v[174:177], v[116:119]
	v_mfma_f32_16x16x32_bf16 v[84:87], v[140:143], v[174:177], v[84:87]
	v_mfma_f32_16x16x32_bf16 v[112:115], v[132:135], v[182:185], v[112:115]
	v_mfma_f32_16x16x32_bf16 v[80:83], v[140:143], v[182:185], v[80:83]
	s_barrier
	s_add_i32 s10, 16, 0x1c000
	s_add_i32 s4, s17, s21
	v_add_u32_e32 v202, s10, v198
	v_lshl_add_u64 v[208:209], v[208:209], 0, s[0:1]
	s_mov_b32 m0, s4
	ds_read_b128 v[186:189], v202
	ds_read_b128 v[190:193], v202 offset:1024
	ds_read_b128 v[194:197], v202 offset:2048
	ds_read_b128 v[202:205], v202 offset:3072
	global_load_lds_dwordx4 v[208:209], off
	v_lshl_add_u64 v[208:209], v[210:211], 0, s[0:1]
	s_add_i32 m0, s4, 0x2000
	s_nop 0
	global_load_lds_dwordx4 v[208:209], off
	s_barrier
	s_waitcnt lgkmcnt(0)
	v_mfma_f32_16x16x32_bf16 v[60:63], v[186:189], v[144:147], v[60:63]
	v_mfma_f32_16x16x32_bf16 v[28:31], v[194:197], v[144:147], v[28:31]
	v_mfma_f32_16x16x32_bf16 v[56:59], v[186:189], v[152:155], v[56:59]
	v_mfma_f32_16x16x32_bf16 v[24:27], v[194:197], v[152:155], v[24:27]
	v_mfma_f32_16x16x32_bf16 v[52:55], v[186:189], v[160:163], v[52:55]
	v_mfma_f32_16x16x32_bf16 v[20:23], v[194:197], v[160:163], v[20:23]
	v_mfma_f32_16x16x32_bf16 v[48:51], v[186:189], v[178:181], v[48:51]
	v_mfma_f32_16x16x32_bf16 v[16:19], v[194:197], v[178:181], v[16:19]
	v_mfma_f32_16x16x32_bf16 v[60:63], v[190:193], v[148:151], v[60:63]
	v_mfma_f32_16x16x32_bf16 v[28:31], v[202:205], v[148:151], v[28:31]
	v_mfma_f32_16x16x32_bf16 v[56:59], v[190:193], v[156:159], v[56:59]
	v_mfma_f32_16x16x32_bf16 v[24:27], v[202:205], v[156:159], v[24:27]
	v_mfma_f32_16x16x32_bf16 v[52:55], v[190:193], v[174:177], v[52:55]
	v_mfma_f32_16x16x32_bf16 v[20:23], v[202:205], v[174:177], v[20:23]
	v_mfma_f32_16x16x32_bf16 v[48:51], v[190:193], v[182:185], v[48:51]
	v_mfma_f32_16x16x32_bf16 v[16:19], v[202:205], v[182:185], v[16:19]
	s_barrier
	s_mov_b32 m0, s45
	v_lshl_add_u64 v[208:209], v[212:213], 0, s[0:1]
	ds_read_b128 v[144:147], v200 offset:49152
	ds_read_b128 v[148:151], v200 offset:50176
	ds_read_b128 v[152:155], v200 offset:51200
	ds_read_b128 v[156:159], v200 offset:52224
	ds_read_b128 v[160:163], v200 offset:53248
	ds_read_b128 v[174:177], v200 offset:54272
	ds_read_b128 v[178:181], v200 offset:55296
	ds_read_b128 v[182:185], v200 offset:56320
	global_load_lds_dwordx4 v[208:209], off
	v_lshl_add_u64 v[208:209], v[214:215], 0, s[0:1]
	s_mov_b32 m0, s46
	s_nop 0
	global_load_lds_dwordx4 v[208:209], off
	s_barrier
; #define WAIT_V(n) asm volatile("s_waitcnt vmcnt(" #n ")" ::: "memory")
; #define WAIT_L(n) asm volatile("s_waitcnt lgkmcnt(" #n ")" ::: "memory")
; #define BAR __builtin_amdgcn_s_barrier()
; #define SCHED __builtin_amdgcn_sched_barrier(0)
; #define EPI_DONE do { } while (0)
; template <class Get, class Epi>
; DI void gemm_stream(LAS unsigned char* lds, const int K, const int ld, Get get, Epi epi) {
;     ...
;             BAR; WAIT_L(0); MMA(1, 0, At, B0); BAR; SCHED;
;             STAGE(SBo(1, 1), b3 + hstep);
;             WAIT_V(6); BAR; MMA(1, 1, At, B1); BAR;
;         }
;         epi(acc, cur);
;         if (!has_next) break;
;         ZERO_ACC;
;         cur = nxt; cA = nA; cB = nB; ++ui;
; DI void epi_resid(const Acc& acc, const P& p, int brow, int bcol, int layer, int gch, bool from_input) {
;     EPI_IDX
;     const float* gate = modv(p, layer, brow, gch);
; #pragma unroll
;     for (int bj = 0; bj < 2; ++bj)
; #pragma unroll
;         for (int n = 0; n < 2; ++n) {
;             const int c0 = bcol + bj * 128 + wc * 32 + n * 16 + fq * 4;
;             const f32x4 g = *(const f32x4*)(gate + c0);
;             f32x4 xv[2][4];
; #pragma unroll
;             for (int ai = 0; ai < 2; ++ai)
; #pragma unroll
;                 for (int m = 0; m < 4; ++m) {
;                     const int r = brow + ai * 128 + wr * 64 + m * 16 + fr;
;                     const float* sp = (from_input ? inrow(p, r) : xrow(p, r)) + c0;
;                     xv[ai][m] = *(const f32x4*)sp;
;                 }
;             __builtin_amdgcn_sched_barrier(0);
; #pragma unroll
;             for (int ai = 0; ai < 2; ++ai)
; #pragma unroll
;                 for (int m = 0; m < 4; ++m) {
;                     const int r = brow + ai * 128 + wr * 64 + m * 16 + fr;
;                     *(f32x4*)(xrow(p, r) + c0) = xv[ai][m] + g * acc[ai][bj][m][n];
;                 }
;             __builtin_amdgcn_sched_barrier(0);
;         }
;     EPI_DONE;
; }
	s_waitcnt lgkmcnt(0)
	v_mfma_f32_16x16x32_bf16 v[108:111], v[128:131], v[144:147], v[108:111]
	v_mfma_f32_16x16x32_bf16 v[76:79], v[136:139], v[144:147], v[76:79]
	v_mfma_f32_16x16x32_bf16 v[104:107], v[128:131], v[152:155], v[104:107]
	v_mfma_f32_16x16x32_bf16 v[72:75], v[136:139], v[152:155], v[72:75]
	v_mfma_f32_16x16x32_bf16 v[100:103], v[128:131], v[160:163], v[100:103]
	v_mfma_f32_16x16x32_bf16 v[68:71], v[136:139], v[160:163], v[68:71]
	v_mfma_f32_16x16x32_bf16 v[96:99], v[128:131], v[178:181], v[96:99]
	v_mfma_f32_16x16x32_bf16 v[64:67], v[136:139], v[178:181], v[64:67]
	v_mfma_f32_16x16x32_bf16 v[108:111], v[132:135], v[148:151], v[108:111]
	v_mfma_f32_16x16x32_bf16 v[76:79], v[140:143], v[148:151], v[76:79]
	v_mfma_f32_16x16x32_bf16 v[104:107], v[132:135], v[156:159], v[104:107]
	v_mfma_f32_16x16x32_bf16 v[72:75], v[140:143], v[156:159], v[72:75]
	v_mfma_f32_16x16x32_bf16 v[100:103], v[132:135], v[174:177], v[100:103]
	v_mfma_f32_16x16x32_bf16 v[68:71], v[140:143], v[174:177], v[68:71]
	v_mfma_f32_16x16x32_bf16 v[96:99], v[132:135], v[182:185], v[96:99]
	v_mfma_f32_16x16x32_bf16 v[64:67], v[140:143], v[182:185], v[64:67]
	s_barrier
	s_add_u32 s4, s8, 0x160080
	s_addc_u32 s5, s9, 0
	s_add_i32 s8, s10, s21
	v_lshl_add_u64 v[128:129], s[4:5], 0, v[164:165]
	s_mov_b32 m0, s8
	s_nop 0
	global_load_lds_dwordx4 v[128:129], off
	v_lshl_add_u64 v[128:129], s[4:5], 0, v[166:167]
	s_add_i32 m0, s8, 0x2000
	s_nop 0
	global_load_lds_dwordx4 v[128:129], off
	s_waitcnt vmcnt(6)
	s_barrier
	v_mfma_f32_16x16x32_bf16 v[44:47], v[186:189], v[144:147], v[44:47]
	v_mfma_f32_16x16x32_bf16 v[12:15], v[194:197], v[144:147], v[12:15]
	v_mfma_f32_16x16x32_bf16 v[40:43], v[186:189], v[152:155], v[40:43]
	v_mfma_f32_16x16x32_bf16 v[8:11], v[194:197], v[152:155], v[8:11]
	v_mfma_f32_16x16x32_bf16 v[36:39], v[186:189], v[160:163], v[36:39]
	v_mfma_f32_16x16x32_bf16 v[4:7], v[194:197], v[160:163], v[4:7]
	v_mfma_f32_16x16x32_bf16 v[32:35], v[186:189], v[178:181], v[32:35]
	v_mfma_f32_16x16x32_bf16 v[0:3], v[194:197], v[178:181], v[0:3]
	v_mfma_f32_16x16x32_bf16 v[44:47], v[190:193], v[148:151], v[44:47]
	v_mfma_f32_16x16x32_bf16 v[12:15], v[202:205], v[148:151], v[12:15]
	v_mfma_f32_16x16x32_bf16 v[40:43], v[190:193], v[156:159], v[40:43]
	v_mfma_f32_16x16x32_bf16 v[8:11], v[202:205], v[156:159], v[8:11]
	v_mfma_f32_16x16x32_bf16 v[36:39], v[190:193], v[174:177], v[36:39]
	v_mfma_f32_16x16x32_bf16 v[4:7], v[202:205], v[174:177], v[4:7]
	v_mfma_f32_16x16x32_bf16 v[32:35], v[190:193], v[182:185], v[32:35]
	v_mfma_f32_16x16x32_bf16 v[0:3], v[202:205], v[182:185], v[0:3]
	s_barrier
	s_add_i32 s16, s16, 2
	s_add_u32 s14, s14, 0x100
	s_addc_u32 s15, s15, 0
	s_cmpk_gt_u32 s16, 0x55
	s_mov_b64 s[4:5], s[6:7]
	s_cbranch_scc0 .LBB0_3113
	s_lshl_b32 s8, s13, 21
	s_lshl_b32 s9, s12, 10
	s_lshr_b32 s16, s13, 4
	s_add_u32 s8, s8, s9
	s_mul_i32 s16, s16, 6
	s_add_i32 s16, s16, 35
	s_lshl_b32 s16, s16, 13
	s_add_u32 s16, s16, s9
	s_add_u32 s10, s26, s16
	s_addc_u32 s11, s27, 0
	s_add_u32 s6, s24, s8
	s_addc_u32 s7, s25, 0
	v_lshrrev_b32_e32 v224, 6, v206
	v_and_b32_e32 v225, 3, v224
	v_lshrrev_b32_e32 v224, 2, v224
	v_and_b32_e32 v205, 15, v206
	v_bfe_u32 v226, v206, 4, 2
	v_lshl_add_u32 v225, v225, 3, v226
	v_lshl_add_u32 v224, v224, 6, v205
	v_lshlrev_b32_e32 v205, 4, v225
	v_lshl_add_u32 v203, v224, 13, v205
	v_mov_b32_e32 v204, v203
	global_load_dwordx4 v[128:131], v205, s[10:11] offset:0
	global_load_dwordx4 v[132:135], v205, s[10:11] offset:64
	global_load_dwordx4 v[136:139], v205, s[10:11] offset:512
	global_load_dwordx4 v[140:143], v205, s[10:11] offset:576
	global_load_dwordx4 v[144:147], v203, s[6:7] offset:0
	global_load_dwordx4 v[148:151], v203, s[6:7] offset:64
	global_load_dwordx4 v[152:155], v203, s[6:7] offset:512
	global_load_dwordx4 v[156:159], v203, s[6:7] offset:576
	v_add_u32_e32 v203, 0x20000, v203
	global_load_dwordx4 v[160:163], v203, s[6:7] offset:0
	global_load_dwordx4 v[174:177], v203, s[6:7] offset:64
	global_load_dwordx4 v[178:181], v203, s[6:7] offset:512
	global_load_dwordx4 v[182:185], v203, s[6:7] offset:576
	v_add_u32_e32 v203, 0x20000, v203
	global_load_dwordx4 v[186:189], v203, s[6:7] offset:0
	global_load_dwordx4 v[190:193], v203, s[6:7] offset:64
	global_load_dwordx4 v[194:197], v203, s[6:7] offset:512
	global_load_dwordx4 v[208:211], v203, s[6:7] offset:576
	v_add_u32_e32 v203, 0x20000, v203
	global_load_dwordx4 v[212:215], v203, s[6:7] offset:0
	global_load_dwordx4 v[216:219], v203, s[6:7] offset:64
	global_load_dwordx4 v[220:223], v203, s[6:7] offset:512
	global_load_dwordx4 v[224:227], v203, s[6:7] offset:576
	v_add_u32_e32 v203, 0xa0000, v203
	s_waitcnt vmcnt(12)
	v_pk_fma_f32 v[124:125], v[124:125], v[128:129], v[144:145]
	v_pk_fma_f32 v[126:127], v[126:127], v[130:131], v[146:147]
	v_pk_fma_f32 v[92:93], v[92:93], v[132:133], v[148:149]
	v_pk_fma_f32 v[94:95], v[94:95], v[134:135], v[150:151]
	v_pk_fma_f32 v[60:61], v[60:61], v[136:137], v[152:153]
	v_pk_fma_f32 v[62:63], v[62:63], v[138:139], v[154:155]
	v_pk_fma_f32 v[28:29], v[28:29], v[140:141], v[156:157]
	v_pk_fma_f32 v[30:31], v[30:31], v[142:143], v[158:159]
	global_store_dwordx4 v204, v[124:127], s[6:7] offset:0
	global_store_dwordx4 v204, v[92:95], s[6:7] offset:64
	global_store_dwordx4 v204, v[60:63], s[6:7] offset:512
	global_store_dwordx4 v204, v[28:31], s[6:7] offset:576
	v_add_u32_e32 v204, 0x20000, v204
	global_load_dwordx4 v[144:147], v203, s[6:7] offset:0
	global_load_dwordx4 v[148:151], v203, s[6:7] offset:64
	global_load_dwordx4 v[152:155], v203, s[6:7] offset:512
	global_load_dwordx4 v[156:159], v203, s[6:7] offset:576
	v_add_u32_e32 v203, 0x20000, v203
	s_waitcnt vmcnt(16)
; #define EPI_DONE do { } while (0)
; DI void epi_resid(const Acc& acc, const P& p, int brow, int bcol, int layer, int gch, bool from_input) {
;     EPI_IDX
;     const float* gate = modv(p, layer, brow, gch);
; #pragma unroll
;     for (int bj = 0; bj < 2; ++bj)
; #pragma unroll
;         for (int n = 0; n < 2; ++n) {
;             const int c0 = bcol + bj * 128 + wc * 32 + n * 16 + fq * 4;
;             const f32x4 g = *(const f32x4*)(gate + c0);
;             f32x4 xv[2][4];
; #pragma unroll
;             for (int ai = 0; ai < 2; ++ai)
; #pragma unroll
;                 for (int m = 0; m < 4; ++m) {
;                     const int r = brow + ai * 128 + wr * 64 + m * 16 + fr;
;                     const float* sp = (from_input ? inrow(p, r) : xrow(p, r)) + c0;
;                     xv[ai][m] = *(const f32x4*)sp;
;                 }
;             __builtin_amdgcn_sched_barrier(0);
; #pragma unroll
;             for (int ai = 0; ai < 2; ++ai)
; #pragma unroll
;                 for (int m = 0; m < 4; ++m) {
;                     const int r = brow + ai * 128 + wr * 64 + m * 16 + fr;
;                     *(f32x4*)(xrow(p, r) + c0) = xv[ai][m] + g * acc[ai][bj][m][n];
;                 }
;             __builtin_amdgcn_sched_barrier(0);
;         }
;     EPI_DONE;
; }
	v_pk_fma_f32 v[120:121], v[120:121], v[128:129], v[160:161]
	v_pk_fma_f32 v[122:123], v[122:123], v[130:131], v[162:163]
	v_pk_fma_f32 v[88:89], v[88:89], v[132:133], v[174:175]
	v_pk_fma_f32 v[90:91], v[90:91], v[134:135], v[176:177]
	v_pk_fma_f32 v[56:57], v[56:57], v[136:137], v[178:179]
	v_pk_fma_f32 v[58:59], v[58:59], v[138:139], v[180:181]
	v_pk_fma_f32 v[24:25], v[24:25], v[140:141], v[182:183]
	v_pk_fma_f32 v[26:27], v[26:27], v[142:143], v[184:185]
	global_store_dwordx4 v204, v[120:123], s[6:7] offset:0
	global_store_dwordx4 v204, v[88:91], s[6:7] offset:64
	global_store_dwordx4 v204, v[56:59], s[6:7] offset:512
	global_store_dwordx4 v204, v[24:27], s[6:7] offset:576
	v_add_u32_e32 v204, 0x20000, v204
	global_load_dwordx4 v[160:163], v203, s[6:7] offset:0
	global_load_dwordx4 v[174:177], v203, s[6:7] offset:64
	global_load_dwordx4 v[178:181], v203, s[6:7] offset:512
	global_load_dwordx4 v[182:185], v203, s[6:7] offset:576
	v_add_u32_e32 v203, 0x20000, v203
	s_waitcnt vmcnt(20)
	v_pk_fma_f32 v[116:117], v[116:117], v[128:129], v[186:187]
	v_pk_fma_f32 v[118:119], v[118:119], v[130:131], v[188:189]
	v_pk_fma_f32 v[84:85], v[84:85], v[132:133], v[190:191]
	v_pk_fma_f32 v[86:87], v[86:87], v[134:135], v[192:193]
	v_pk_fma_f32 v[52:53], v[52:53], v[136:137], v[194:195]
	v_pk_fma_f32 v[54:55], v[54:55], v[138:139], v[196:197]
	v_pk_fma_f32 v[20:21], v[20:21], v[140:141], v[208:209]
	v_pk_fma_f32 v[22:23], v[22:23], v[142:143], v[210:211]
	global_store_dwordx4 v204, v[116:119], s[6:7] offset:0
	global_store_dwordx4 v204, v[84:87], s[6:7] offset:64
	global_store_dwordx4 v204, v[52:55], s[6:7] offset:512
	global_store_dwordx4 v204, v[20:23], s[6:7] offset:576
	v_add_u32_e32 v204, 0x20000, v204
	global_load_dwordx4 v[186:189], v203, s[6:7] offset:0
	global_load_dwordx4 v[190:193], v203, s[6:7] offset:64
	global_load_dwordx4 v[194:197], v203, s[6:7] offset:512
	global_load_dwordx4 v[208:211], v203, s[6:7] offset:576
	v_add_u32_e32 v203, 0x20000, v203
	s_waitcnt vmcnt(24)
	v_pk_fma_f32 v[112:113], v[112:113], v[128:129], v[212:213]
	v_pk_fma_f32 v[114:115], v[114:115], v[130:131], v[214:215]
	v_pk_fma_f32 v[80:81], v[80:81], v[132:133], v[216:217]
	v_pk_fma_f32 v[82:83], v[82:83], v[134:135], v[218:219]
	v_pk_fma_f32 v[48:49], v[48:49], v[136:137], v[220:221]
	v_pk_fma_f32 v[50:51], v[50:51], v[138:139], v[222:223]
	v_pk_fma_f32 v[16:17], v[16:17], v[140:141], v[224:225]
	v_pk_fma_f32 v[18:19], v[18:19], v[142:143], v[226:227]
	global_store_dwordx4 v204, v[112:115], s[6:7] offset:0
	global_store_dwordx4 v204, v[80:83], s[6:7] offset:64
	global_store_dwordx4 v204, v[48:51], s[6:7] offset:512
	global_store_dwordx4 v204, v[16:19], s[6:7] offset:576
	v_add_u32_e32 v204, 0xa0000, v204
	global_load_dwordx4 v[212:215], v203, s[6:7] offset:0
	global_load_dwordx4 v[216:219], v203, s[6:7] offset:64
	global_load_dwordx4 v[220:223], v203, s[6:7] offset:512
	global_load_dwordx4 v[224:227], v203, s[6:7] offset:576
	s_waitcnt vmcnt(24)
	v_pk_fma_f32 v[108:109], v[108:109], v[128:129], v[144:145]
	v_pk_fma_f32 v[110:111], v[110:111], v[130:131], v[146:147]
	v_pk_fma_f32 v[76:77], v[76:77], v[132:133], v[148:149]
	v_pk_fma_f32 v[78:79], v[78:79], v[134:135], v[150:151]
	v_pk_fma_f32 v[44:45], v[44:45], v[136:137], v[152:153]
	v_pk_fma_f32 v[46:47], v[46:47], v[138:139], v[154:155]
	v_pk_fma_f32 v[12:13], v[12:13], v[140:141], v[156:157]
	v_pk_fma_f32 v[14:15], v[14:15], v[142:143], v[158:159]
	global_store_dwordx4 v204, v[108:111], s[6:7] offset:0
	global_store_dwordx4 v204, v[76:79], s[6:7] offset:64
	global_store_dwordx4 v204, v[44:47], s[6:7] offset:512
	global_store_dwordx4 v204, v[12:15], s[6:7] offset:576
	v_add_u32_e32 v204, 0x20000, v204
	s_waitcnt vmcnt(20)
	v_pk_fma_f32 v[104:105], v[104:105], v[128:129], v[160:161]
	v_pk_fma_f32 v[106:107], v[106:107], v[130:131], v[162:163]
	v_pk_fma_f32 v[72:73], v[72:73], v[132:133], v[174:175]
	v_pk_fma_f32 v[74:75], v[74:75], v[134:135], v[176:177]
	v_pk_fma_f32 v[40:41], v[40:41], v[136:137], v[178:179]
	v_pk_fma_f32 v[42:43], v[42:43], v[138:139], v[180:181]
	v_pk_fma_f32 v[8:9], v[8:9], v[140:141], v[182:183]
	v_pk_fma_f32 v[10:11], v[10:11], v[142:143], v[184:185]
	global_store_dwordx4 v204, v[104:107], s[6:7] offset:0
	global_store_dwordx4 v204, v[72:75], s[6:7] offset:64
	global_store_dwordx4 v204, v[40:43], s[6:7] offset:512
	global_store_dwordx4 v204, v[8:11], s[6:7] offset:576
	v_add_u32_e32 v204, 0x20000, v204
	s_waitcnt vmcnt(16)
	v_pk_fma_f32 v[100:101], v[100:101], v[128:129], v[186:187]
	v_pk_fma_f32 v[102:103], v[102:103], v[130:131], v[188:189]
	v_pk_fma_f32 v[68:69], v[68:69], v[132:133], v[190:191]
	v_pk_fma_f32 v[70:71], v[70:71], v[134:135], v[192:193]
	v_pk_fma_f32 v[36:37], v[36:37], v[136:137], v[194:195]
	v_pk_fma_f32 v[38:39], v[38:39], v[138:139], v[196:197]
	v_pk_fma_f32 v[4:5], v[4:5], v[140:141], v[208:209]
	v_pk_fma_f32 v[6:7], v[6:7], v[142:143], v[210:211]
	global_store_dwordx4 v204, v[100:103], s[6:7] offset:0
	global_store_dwordx4 v204, v[68:71], s[6:7] offset:64
	global_store_dwordx4 v204, v[36:39], s[6:7] offset:512
	global_store_dwordx4 v204, v[4:7], s[6:7] offset:576
	v_add_u32_e32 v204, 0x20000, v204
	s_waitcnt vmcnt(12)
	v_pk_fma_f32 v[96:97], v[96:97], v[128:129], v[212:213]
	v_pk_fma_f32 v[98:99], v[98:99], v[130:131], v[214:215]
	v_pk_fma_f32 v[64:65], v[64:65], v[132:133], v[216:217]
	v_pk_fma_f32 v[66:67], v[66:67], v[134:135], v[218:219]
	v_pk_fma_f32 v[32:33], v[32:33], v[136:137], v[220:221]
	v_pk_fma_f32 v[34:35], v[34:35], v[138:139], v[222:223]
	v_pk_fma_f32 v[0:1], v[0:1], v[140:141], v[224:225]
	v_pk_fma_f32 v[2:3], v[2:3], v[142:143], v[226:227]
	global_store_dwordx4 v204, v[96:99], s[6:7] offset:0
	global_store_dwordx4 v204, v[64:67], s[6:7] offset:64
	global_store_dwordx4 v204, v[32:35], s[6:7] offset:512
	global_store_dwordx4 v204, v[0:3], s[6:7] offset:576
	s_branch .Lresid_latch_ffndL1
